# GEMM K loops: per-phase priority flips deleted, one static s_setprio 1 for waves 0-3 at each unit head (doc recipe 6.3/7.4), on top of v90
# speedup vs baseline: 1.0141x; 1.0098x over previous
; #define PG8_STAGE(bufoff, gbase, voff) do { _Pragma("unroll") for (int _i = 0; _i < 2; ++_i) \
;         __builtin_amdgcn_global_load_lds((const unsigned*)((const char*)(gbase) + (voff)[_i]), (LAS unsigned*)(lds + (bufoff) + ldsw + _i * 8192), 16, 0, 0); } while (0)
; #define PG8_LDA(dst, b, h) do { _Pragma("unroll") for (int m = 0; m < 4; ++m) _Pragma("unroll") for (int k = 0; k < 2; ++k) dst[m][k] = *(const LAS bf16x8*)(lds + PG8_SA(b, h) + aoff + m * 2048 + k * 1024); } while (0)
; #define PG8_LDB(dst, b, h) do { _Pragma("unroll") for (int n = 0; n < 2; ++n) _Pragma("unroll") for (int k = 0; k < 2; ++k) dst[n][k] = *(const LAS bf16x8*)(lds + PG8_SB(b, h) + boff + n * 2048 + k * 1024); } while (0)
; #define PG8_MMA(ai, bj, At, Bt) do { __builtin_amdgcn_s_setprio(1); _Pragma("unroll") for (int m = 0; m < 4; ++m) _Pragma("unroll") for (int n = 0; n < 2; ++n) _Pragma("unroll") for (int k = 0; k < 2; ++k) \
;         acc[ai][bj][m][n] = __builtin_amdgcn_mfma_f32_16x16x32_bf16(Bt[n][k], At[m][k], acc[ai][bj][m][n], 0, 0, 0); __builtin_amdgcn_s_setprio(0); } while (0)
; #define PG8_WAIT_L(n) asm volatile("s_waitcnt lgkmcnt(" #n ")" ::: "memory")
; template <class Epi>
; __device__ __forceinline__ void gemm_phase(LAS unsigned char* lds, const Gemm g, const StaticOrder& S, const Epi& E) {
;     ...
;         const char* nA = has_next ? (const char*)g.A + (size_t)nxt.pm * tstepA : cA; const char* nB = has_next ? (const char*)g.Bt + (size_t)nxt.pn * tstepB : cB;
;         for (int t = 0; t < nt; t += 2) {
;             const bool last = (t == nt - 2);
;             const char* a1 = cA + (size_t)(t + 1) * kstep;
;             const char* a2 = last ? nA : cA + (size_t)(t + 2) * kstep; const char* b2 = last ? nB : cB + (size_t)(t + 2) * kstep;
;             const char* a3 = a2 + kstep; const char* b3 = b2 + kstep;
;             if (last) E.pre(cur, wr, fr, epre);
;             PG8_LDB(B0, 0, 0); PG8_SCHED; PG8_LDA(At, 0, 0); PG8_STAGE(PG8_SA(1, 1), a1 + hstepA, voffA);
;             PG8_WAIT_L(8); PG8_BAR; PG8_WAIT_L(0); PG8_MMA(0, 0, At, B0); PG8_BAR; PG8_SCHED;
;             PG8_LDB(B1, 0, 1); PG8_STAGE(PG8_SB(0, 0), b2, voffB);
;             PG8_BAR; PG8_WAIT_L(0); PG8_MMA(0, 1, At, B1); PG8_BAR;
;             PG8_LDA(At, 0, 1); PG8_STAGE(PG8_SA(0, 0), a2, voffA);
;             PG8_BAR; PG8_WAIT_L(0); PG8_MMA(1, 0, At, B0); PG8_BAR; PG8_SCHED;
.LBB0_204:
	s_ashr_i32 s13, s12, 31
	v_cmp_lt_i64_e32 vcc, s[14:15], v[142:143]
	s_lshl_b64 s[14:15], s[12:13], 19
	s_add_u32 s14, s76, s14
	s_addc_u32 s15, s77, s15
	s_and_b64 s[16:17], vcc, exec
	s_cselect_b32 s13, s15, s21
	s_cselect_b32 s19, s14, s20
	s_ashr_i32 s11, s10, 31
	s_lshl_b64 s[16:17], s[10:11], 19
	s_add_u32 s16, s74, s16
	s_addc_u32 s17, s75, s17
	s_and_b64 s[24:25], vcc, exec
	s_cselect_b32 s11, s17, s23
	s_cselect_b32 s44, s16, s22
	s_add_u32 s20, s20, 0x40080
	s_addc_u32 s21, s21, 0
	s_add_u32 s45, s22, 0x100
	s_addc_u32 s46, s23, 0
	s_mov_b32 s47, -2
	s_waitcnt lgkmcnt(0)
	ds_read_b128 v[146:149], v170
	ds_read_b128 v[154:157], v170 offset:1024
	ds_read_b128 v[158:161], v170 offset:2048
	ds_read_b128 v[162:165], v170 offset:3072
	s_add_u32 s22, s20, 0xfffc0080
	s_addc_u32 s23, s21, -1
	s_cmp_eq_u32 s47, 12
	s_cselect_b32 s25, s13, s23
	s_cselect_b32 s24, s19, s22
	s_cselect_b32 s23, s11, s46
	s_cselect_b32 s22, s44, s45
	v_lshl_add_u64 v[150:151], s[20:21], 0, v[138:139]
	s_add_i32 m0, s30, 0xc000
	ds_read_b128 v[174:177], v171
	ds_read_b128 v[178:181], v171 offset:1024
	ds_read_b128 v[182:185], v171 offset:2048
	ds_read_b128 v[186:189], v171 offset:3072
	ds_read_b128 v[190:193], v171 offset:4096
	ds_read_b128 v[194:197], v171 offset:5120
	ds_read_b128 v[198:201], v171 offset:6144
	ds_read_b128 v[202:205], v171 offset:7168
	global_load_lds_dwordx4 v[150:151], off
	v_lshl_add_u64 v[150:151], s[20:21], 0, v[140:141]
	s_add_i32 m0, s30, 0xe000
	s_nop 0
	global_load_lds_dwordx4 v[150:151], off
	s_waitcnt lgkmcnt(8)
	s_barrier
	s_waitcnt lgkmcnt(0)
	s_waitcnt lgkmcnt(0)
	v_mfma_f32_16x16x32_bf16 v[76:79], v[146:149], v[174:177], 0
	v_mfma_f32_16x16x32_bf16 v[64:67], v[158:161], v[174:177], 0
	v_mfma_f32_16x16x32_bf16 v[60:63], v[146:149], v[182:185], 0
	v_mfma_f32_16x16x32_bf16 v[56:59], v[158:161], v[182:185], 0
	v_mfma_f32_16x16x32_bf16 v[48:51], v[146:149], v[190:193], 0
	v_mfma_f32_16x16x32_bf16 v[40:43], v[158:161], v[190:193], 0
	v_mfma_f32_16x16x32_bf16 v[36:39], v[146:149], v[198:201], 0
	v_mfma_f32_16x16x32_bf16 v[32:35], v[158:161], v[198:201], 0
	v_mfma_f32_16x16x32_bf16 v[76:79], v[154:157], v[178:181], v[76:79]
	v_mfma_f32_16x16x32_bf16 v[64:67], v[162:165], v[178:181], v[64:67]
	v_mfma_f32_16x16x32_bf16 v[60:63], v[154:157], v[186:189], v[60:63]
	v_mfma_f32_16x16x32_bf16 v[56:59], v[162:165], v[186:189], v[56:59]
	v_mfma_f32_16x16x32_bf16 v[48:51], v[154:157], v[194:197], v[48:51]
	v_mfma_f32_16x16x32_bf16 v[40:43], v[162:165], v[194:197], v[40:43]
	v_mfma_f32_16x16x32_bf16 v[36:39], v[154:157], v[202:205], v[36:39]
	v_mfma_f32_16x16x32_bf16 v[32:35], v[162:165], v[202:205], v[32:35]
	s_barrier
	s_add_i32 s48, s39, s27
	v_lshl_add_u64 v[150:151], s[22:23], 0, v[132:133]
	s_mov_b32 m0, s48
	ds_read_b128 v[206:209], v172
	ds_read_b128 v[210:213], v172 offset:1024
	ds_read_b128 v[214:217], v172 offset:2048
	ds_read_b128 v[218:221], v172 offset:3072
	global_load_lds_dwordx4 v[150:151], off
	v_lshl_add_u64 v[166:167], s[22:23], 0, v[128:129]
	s_add_i32 m0, s48, 0x2000
	s_nop 0
	global_load_lds_dwordx4 v[166:167], off
	s_barrier
	s_waitcnt lgkmcnt(0)
	s_waitcnt lgkmcnt(0)
	v_mfma_f32_16x16x32_bf16 v[124:127], v[206:209], v[174:177], 0
	v_mfma_f32_16x16x32_bf16 v[120:123], v[214:217], v[174:177], 0
	v_mfma_f32_16x16x32_bf16 v[116:119], v[206:209], v[182:185], 0
	v_mfma_f32_16x16x32_bf16 v[112:115], v[214:217], v[182:185], 0
	v_mfma_f32_16x16x32_bf16 v[108:111], v[206:209], v[190:193], 0
	v_mfma_f32_16x16x32_bf16 v[104:107], v[214:217], v[190:193], 0
	v_mfma_f32_16x16x32_bf16 v[100:103], v[206:209], v[198:201], 0
	v_mfma_f32_16x16x32_bf16 v[96:99], v[214:217], v[198:201], 0
	v_mfma_f32_16x16x32_bf16 v[124:127], v[210:213], v[178:181], v[124:127]
	v_mfma_f32_16x16x32_bf16 v[120:123], v[218:221], v[178:181], v[120:123]
	v_mfma_f32_16x16x32_bf16 v[116:119], v[210:213], v[186:189], v[116:119]
	v_mfma_f32_16x16x32_bf16 v[112:115], v[218:221], v[186:189], v[112:115]
	v_mfma_f32_16x16x32_bf16 v[108:111], v[210:213], v[194:197], v[108:111]
	v_mfma_f32_16x16x32_bf16 v[104:107], v[218:221], v[194:197], v[104:107]
	v_mfma_f32_16x16x32_bf16 v[100:103], v[210:213], v[202:205], v[100:103]
	v_mfma_f32_16x16x32_bf16 v[96:99], v[218:221], v[202:205], v[96:99]
	s_mov_b32 m0, s30
	v_lshl_add_u64 v[222:223], s[24:25], 0, v[134:135]
	s_barrier
	ds_read_b128 v[174:177], v171 offset:16384
	ds_read_b128 v[178:181], v171 offset:17408
	ds_read_b128 v[182:185], v171 offset:18432
	ds_read_b128 v[186:189], v171 offset:19456
	ds_read_b128 v[190:193], v171 offset:20480
	ds_read_b128 v[194:197], v171 offset:21504
	ds_read_b128 v[198:201], v171 offset:22528
	ds_read_b128 v[202:205], v171 offset:23552
	global_load_lds_dwordx4 v[222:223], off
	v_lshl_add_u64 v[224:225], s[24:25], 0, v[130:131]
	s_mov_b32 m0, s31
	s_nop 0
	global_load_lds_dwordx4 v[224:225], off
	s_barrier
	s_waitcnt lgkmcnt(0)
	s_waitcnt lgkmcnt(0)
	v_mfma_f32_16x16x32_bf16 v[28:31], v[146:149], v[174:177], 0
	v_mfma_f32_16x16x32_bf16 v[24:27], v[158:161], v[174:177], 0
	v_mfma_f32_16x16x32_bf16 v[20:23], v[146:149], v[182:185], 0
	v_mfma_f32_16x16x32_bf16 v[16:19], v[158:161], v[182:185], 0
	v_mfma_f32_16x16x32_bf16 v[12:15], v[146:149], v[190:193], 0
	v_mfma_f32_16x16x32_bf16 v[8:11], v[158:161], v[190:193], 0
	v_mfma_f32_16x16x32_bf16 v[4:7], v[146:149], v[198:201], 0
	v_mfma_f32_16x16x32_bf16 v[0:3], v[158:161], v[198:201], 0
	v_mfma_f32_16x16x32_bf16 v[28:31], v[154:157], v[178:181], v[28:31]
	v_mfma_f32_16x16x32_bf16 v[24:27], v[162:165], v[178:181], v[24:27]
	v_mfma_f32_16x16x32_bf16 v[20:23], v[154:157], v[186:189], v[20:23]
	v_mfma_f32_16x16x32_bf16 v[16:19], v[162:165], v[186:189], v[16:19]
	v_mfma_f32_16x16x32_bf16 v[12:15], v[154:157], v[194:197], v[12:15]
	v_mfma_f32_16x16x32_bf16 v[8:11], v[162:165], v[194:197], v[8:11]
	v_mfma_f32_16x16x32_bf16 v[4:7], v[154:157], v[202:205], v[4:7]
	v_mfma_f32_16x16x32_bf16 v[0:3], v[162:165], v[202:205], v[0:3]
	s_barrier
; #define PG8_STAGE(bufoff, gbase, voff) do { _Pragma("unroll") for (int _i = 0; _i < 2; ++_i) \
;         __builtin_amdgcn_global_load_lds((const unsigned*)((const char*)(gbase) + (voff)[_i]), (LAS unsigned*)(lds + (bufoff) + ldsw + _i * 8192), 16, 0, 0); } while (0)
; #define PG8_LDA(dst, b, h) do { _Pragma("unroll") for (int m = 0; m < 4; ++m) _Pragma("unroll") for (int k = 0; k < 2; ++k) dst[m][k] = *(const LAS bf16x8*)(lds + PG8_SA(b, h) + aoff + m * 2048 + k * 1024); } while (0)
; #define PG8_LDB(dst, b, h) do { _Pragma("unroll") for (int n = 0; n < 2; ++n) _Pragma("unroll") for (int k = 0; k < 2; ++k) dst[n][k] = *(const LAS bf16x8*)(lds + PG8_SB(b, h) + boff + n * 2048 + k * 1024); } while (0)
; #define PG8_MMA(ai, bj, At, Bt) do { __builtin_amdgcn_s_setprio(1); _Pragma("unroll") for (int m = 0; m < 4; ++m) _Pragma("unroll") for (int n = 0; n < 2; ++n) _Pragma("unroll") for (int k = 0; k < 2; ++k) \
;         acc[ai][bj][m][n] = __builtin_amdgcn_mfma_f32_16x16x32_bf16(Bt[n][k], At[m][k], acc[ai][bj][m][n], 0, 0, 0); __builtin_amdgcn_s_setprio(0); } while (0)
; #define PG8_WAIT_V(n) asm volatile("s_waitcnt vmcnt(" #n ")" ::: "memory")
; #define PG8_WAIT_L(n) asm volatile("s_waitcnt lgkmcnt(" #n ")" ::: "memory")
; #define PG8_BAR __builtin_amdgcn_s_barrier()
; #define PG8_SCHED __builtin_amdgcn_sched_barrier(0)
; template <class Epi>
; __device__ __forceinline__ void gemm_phase(LAS unsigned char* lds, const Gemm g, const StaticOrder& S, const Epi& E) {
;     ...
;             PG8_STAGE(PG8_SB(0, 1), b2 + hstepB, voffB);
;             PG8_WAIT_V(6); PG8_BAR; PG8_MMA(1, 1, At, B1); PG8_BAR;
;             PG8_LDB(B0, 1, 0); PG8_SCHED; PG8_LDA(At, 1, 0); PG8_STAGE(PG8_SA(0, 1), a2 + hstepA, voffA);
;             PG8_WAIT_L(8); PG8_BAR; PG8_WAIT_L(0); PG8_MMA(0, 0, At, B0); PG8_BAR; PG8_SCHED;
;             PG8_LDB(B1, 1, 1); PG8_STAGE(PG8_SB(1, 0), b3, voffB);
;             PG8_BAR; PG8_WAIT_L(0); PG8_MMA(0, 1, At, B1); PG8_BAR;
;             PG8_LDA(At, 1, 1); PG8_STAGE(PG8_SA(1, 0), a3, voffA);
	s_add_u32 s48, s22, 0x40000
	s_addc_u32 s49, s23, 0
	s_add_i32 s50, s40, s27
	v_lshl_add_u64 v[146:147], s[48:49], 0, v[132:133]
	s_mov_b32 m0, s50
	s_nop 0
	global_load_lds_dwordx4 v[146:147], off
	v_lshl_add_u64 v[146:147], s[48:49], 0, v[128:129]
	s_add_i32 m0, s50, 0x2000
	s_nop 0
	global_load_lds_dwordx4 v[146:147], off
	s_waitcnt vmcnt(6)
	s_barrier
	v_mfma_f32_16x16x32_bf16 v[92:95], v[206:209], v[174:177], 0
	v_mfma_f32_16x16x32_bf16 v[88:91], v[214:217], v[174:177], 0
	v_mfma_f32_16x16x32_bf16 v[84:87], v[206:209], v[182:185], 0
	v_mfma_f32_16x16x32_bf16 v[80:83], v[214:217], v[182:185], 0
	v_mfma_f32_16x16x32_bf16 v[72:75], v[206:209], v[190:193], 0
	v_mfma_f32_16x16x32_bf16 v[68:71], v[214:217], v[190:193], 0
	v_mfma_f32_16x16x32_bf16 v[52:55], v[206:209], v[198:201], 0
	v_mfma_f32_16x16x32_bf16 v[44:47], v[214:217], v[198:201], 0
	v_mfma_f32_16x16x32_bf16 v[92:95], v[210:213], v[178:181], v[92:95]
	v_mfma_f32_16x16x32_bf16 v[88:91], v[218:221], v[178:181], v[88:91]
	v_mfma_f32_16x16x32_bf16 v[84:87], v[210:213], v[186:189], v[84:87]
	v_mfma_f32_16x16x32_bf16 v[80:83], v[218:221], v[186:189], v[80:83]
	v_mfma_f32_16x16x32_bf16 v[72:75], v[210:213], v[194:197], v[72:75]
	v_mfma_f32_16x16x32_bf16 v[68:71], v[218:221], v[194:197], v[68:71]
	v_mfma_f32_16x16x32_bf16 v[52:55], v[210:213], v[202:205], v[52:55]
	v_mfma_f32_16x16x32_bf16 v[44:47], v[218:221], v[202:205], v[44:47]
	s_add_i32 s48, 0, 0x18000
	v_add_u32_e32 v162, s48, v168
	s_barrier
	ds_read_b128 v[146:149], v162
	ds_read_b128 v[154:157], v162 offset:1024
	ds_read_b128 v[158:161], v162 offset:2048
	ds_read_b128 v[162:165], v162 offset:3072
	s_add_u32 s24, s24, 0x40000
	s_addc_u32 s25, s25, 0
	s_mov_b32 m0, s33
	v_lshl_add_u64 v[206:207], s[24:25], 0, v[134:135]
	ds_read_b128 v[174:177], v171 offset:32768
	ds_read_b128 v[178:181], v171 offset:33792
	ds_read_b128 v[182:185], v171 offset:34816
	ds_read_b128 v[186:189], v171 offset:35840
	ds_read_b128 v[190:193], v171 offset:36864
	ds_read_b128 v[194:197], v171 offset:37888
	ds_read_b128 v[198:201], v171 offset:38912
	ds_read_b128 v[202:205], v171 offset:39936
	global_load_lds_dwordx4 v[206:207], off
	v_lshl_add_u64 v[206:207], s[24:25], 0, v[130:131]
	s_mov_b32 m0, s34
	s_nop 0
	global_load_lds_dwordx4 v[206:207], off
	s_waitcnt lgkmcnt(8)
	s_barrier
	s_waitcnt lgkmcnt(0)
	s_waitcnt lgkmcnt(0)
	v_mfma_f32_16x16x32_bf16 v[76:79], v[146:149], v[174:177], v[76:79]
	v_mfma_f32_16x16x32_bf16 v[64:67], v[158:161], v[174:177], v[64:67]
	v_mfma_f32_16x16x32_bf16 v[60:63], v[146:149], v[182:185], v[60:63]
	v_mfma_f32_16x16x32_bf16 v[56:59], v[158:161], v[182:185], v[56:59]
	v_mfma_f32_16x16x32_bf16 v[48:51], v[146:149], v[190:193], v[48:51]
	v_mfma_f32_16x16x32_bf16 v[40:43], v[158:161], v[190:193], v[40:43]
	v_mfma_f32_16x16x32_bf16 v[36:39], v[146:149], v[198:201], v[36:39]
	v_mfma_f32_16x16x32_bf16 v[32:35], v[158:161], v[198:201], v[32:35]
	v_mfma_f32_16x16x32_bf16 v[76:79], v[154:157], v[178:181], v[76:79]
	v_mfma_f32_16x16x32_bf16 v[64:67], v[162:165], v[178:181], v[64:67]
	v_mfma_f32_16x16x32_bf16 v[60:63], v[154:157], v[186:189], v[60:63]
	v_mfma_f32_16x16x32_bf16 v[56:59], v[162:165], v[186:189], v[56:59]
	v_mfma_f32_16x16x32_bf16 v[48:51], v[154:157], v[194:197], v[48:51]
	v_mfma_f32_16x16x32_bf16 v[40:43], v[162:165], v[194:197], v[40:43]
	v_mfma_f32_16x16x32_bf16 v[36:39], v[154:157], v[202:205], v[36:39]
	v_mfma_f32_16x16x32_bf16 v[32:35], v[162:165], v[202:205], v[32:35]
	s_barrier
	s_add_i32 s24, 0, 0x1c000
	s_add_i32 s25, s48, s27
	v_add_u32_e32 v218, s24, v168
	v_lshl_add_u64 v[150:151], v[150:151], 0, s[6:7]
	s_mov_b32 m0, s25
	ds_read_b128 v[206:209], v218
	ds_read_b128 v[210:213], v218 offset:1024
	ds_read_b128 v[214:217], v218 offset:2048
	ds_read_b128 v[218:221], v218 offset:3072
	global_load_lds_dwordx4 v[150:151], off
	v_lshl_add_u64 v[150:151], v[166:167], 0, s[6:7]
	s_add_i32 m0, s25, 0x2000
	s_nop 0
	global_load_lds_dwordx4 v[150:151], off
	s_barrier
	s_waitcnt lgkmcnt(0)
	s_waitcnt lgkmcnt(0)
	v_mfma_f32_16x16x32_bf16 v[124:127], v[206:209], v[174:177], v[124:127]
	v_mfma_f32_16x16x32_bf16 v[120:123], v[214:217], v[174:177], v[120:123]
	v_mfma_f32_16x16x32_bf16 v[116:119], v[206:209], v[182:185], v[116:119]
	v_mfma_f32_16x16x32_bf16 v[112:115], v[214:217], v[182:185], v[112:115]
	v_mfma_f32_16x16x32_bf16 v[108:111], v[206:209], v[190:193], v[108:111]
	v_mfma_f32_16x16x32_bf16 v[104:107], v[214:217], v[190:193], v[104:107]
	v_mfma_f32_16x16x32_bf16 v[100:103], v[206:209], v[198:201], v[100:103]
	v_mfma_f32_16x16x32_bf16 v[96:99], v[214:217], v[198:201], v[96:99]
	v_mfma_f32_16x16x32_bf16 v[124:127], v[210:213], v[178:181], v[124:127]
	v_mfma_f32_16x16x32_bf16 v[120:123], v[218:221], v[178:181], v[120:123]
	v_mfma_f32_16x16x32_bf16 v[116:119], v[210:213], v[186:189], v[116:119]
	v_mfma_f32_16x16x32_bf16 v[112:115], v[218:221], v[186:189], v[112:115]
	v_mfma_f32_16x16x32_bf16 v[108:111], v[210:213], v[194:197], v[108:111]
	v_mfma_f32_16x16x32_bf16 v[104:107], v[218:221], v[194:197], v[104:107]
	v_mfma_f32_16x16x32_bf16 v[100:103], v[210:213], v[202:205], v[100:103]
	v_mfma_f32_16x16x32_bf16 v[96:99], v[218:221], v[202:205], v[96:99]
	s_mov_b32 m0, s36
	v_lshl_add_u64 v[150:151], v[222:223], 0, s[6:7]
	s_barrier
	ds_read_b128 v[174:177], v171 offset:49152
	ds_read_b128 v[178:181], v171 offset:50176
	ds_read_b128 v[182:185], v171 offset:51200
	ds_read_b128 v[186:189], v171 offset:52224
	ds_read_b128 v[190:193], v171 offset:53248
	ds_read_b128 v[194:197], v171 offset:54272
	ds_read_b128 v[198:201], v171 offset:55296
	ds_read_b128 v[202:205], v171 offset:56320
	global_load_lds_dwordx4 v[150:151], off
	v_lshl_add_u64 v[150:151], v[224:225], 0, s[6:7]
	s_mov_b32 m0, s37
	s_nop 0
	global_load_lds_dwordx4 v[150:151], off
	s_barrier
; #define PG8_STAGE(bufoff, gbase, voff) do { _Pragma("unroll") for (int _i = 0; _i < 2; ++_i) \
;         __builtin_amdgcn_global_load_lds((const unsigned*)((const char*)(gbase) + (voff)[_i]), (LAS unsigned*)(lds + (bufoff) + ldsw + _i * 8192), 16, 0, 0); } while (0)
; #define PG8_LDA(dst, b, h) do { _Pragma("unroll") for (int m = 0; m < 4; ++m) _Pragma("unroll") for (int k = 0; k < 2; ++k) dst[m][k] = *(const LAS bf16x8*)(lds + PG8_SA(b, h) + aoff + m * 2048 + k * 1024); } while (0)
; #define PG8_LDB(dst, b, h) do { _Pragma("unroll") for (int n = 0; n < 2; ++n) _Pragma("unroll") for (int k = 0; k < 2; ++k) dst[n][k] = *(const LAS bf16x8*)(lds + PG8_SB(b, h) + boff + n * 2048 + k * 1024); } while (0)
; #define PG8_MMA(ai, bj, At, Bt) do { __builtin_amdgcn_s_setprio(1); _Pragma("unroll") for (int m = 0; m < 4; ++m) _Pragma("unroll") for (int n = 0; n < 2; ++n) _Pragma("unroll") for (int k = 0; k < 2; ++k) \
;         acc[ai][bj][m][n] = __builtin_amdgcn_mfma_f32_16x16x32_bf16(Bt[n][k], At[m][k], acc[ai][bj][m][n], 0, 0, 0); __builtin_amdgcn_s_setprio(0); } while (0)
; #define PG8_WAIT_V(n) asm volatile("s_waitcnt vmcnt(" #n ")" ::: "memory")
; #define PG8_WAIT_L(n) asm volatile("s_waitcnt lgkmcnt(" #n ")" ::: "memory")
; #define PG8_BAR __builtin_amdgcn_s_barrier()
; #define PG8_SCHED __builtin_amdgcn_sched_barrier(0)
; template <class Epi>
; __device__ __forceinline__ void gemm_phase(LAS unsigned char* lds, const Gemm g, const StaticOrder& S, const Epi& E) {
;     ...
;             PG8_LDB(B0, 0, 0); PG8_SCHED; PG8_LDA(At, 0, 0); PG8_STAGE(PG8_SA(1, 1), a1 + hstepA, voffA);
;             PG8_WAIT_L(8); PG8_BAR; PG8_WAIT_L(0); PG8_MMA(0, 0, At, B0); PG8_BAR; PG8_SCHED;
;             PG8_LDB(B1, 0, 1); PG8_STAGE(PG8_SB(0, 0), b2, voffB);
;     ...
;             PG8_BAR; PG8_WAIT_L(0); PG8_MMA(1, 0, At, B0); PG8_BAR; PG8_SCHED;
;             PG8_STAGE(PG8_SB(1, 1), b3 + hstepB, voffB);
;             PG8_WAIT_V(6); PG8_BAR; PG8_MMA(1, 1, At, B1); PG8_BAR;
	s_waitcnt lgkmcnt(0)
	s_waitcnt lgkmcnt(0)
	v_mfma_f32_16x16x32_bf16 v[28:31], v[146:149], v[174:177], v[28:31]
	v_mfma_f32_16x16x32_bf16 v[24:27], v[158:161], v[174:177], v[24:27]
	v_mfma_f32_16x16x32_bf16 v[20:23], v[146:149], v[182:185], v[20:23]
	v_mfma_f32_16x16x32_bf16 v[16:19], v[158:161], v[182:185], v[16:19]
	v_mfma_f32_16x16x32_bf16 v[12:15], v[146:149], v[190:193], v[12:15]
	v_mfma_f32_16x16x32_bf16 v[8:11], v[158:161], v[190:193], v[8:11]
	v_mfma_f32_16x16x32_bf16 v[4:7], v[146:149], v[198:201], v[4:7]
	v_mfma_f32_16x16x32_bf16 v[0:3], v[158:161], v[198:201], v[0:3]
	v_mfma_f32_16x16x32_bf16 v[28:31], v[154:157], v[178:181], v[28:31]
	v_mfma_f32_16x16x32_bf16 v[24:27], v[162:165], v[178:181], v[24:27]
	v_mfma_f32_16x16x32_bf16 v[20:23], v[154:157], v[186:189], v[20:23]
	v_mfma_f32_16x16x32_bf16 v[16:19], v[162:165], v[186:189], v[16:19]
	v_mfma_f32_16x16x32_bf16 v[12:15], v[154:157], v[194:197], v[12:15]
	v_mfma_f32_16x16x32_bf16 v[8:11], v[162:165], v[194:197], v[8:11]
	v_mfma_f32_16x16x32_bf16 v[4:7], v[154:157], v[202:205], v[4:7]
	v_mfma_f32_16x16x32_bf16 v[0:3], v[162:165], v[202:205], v[0:3]
	s_barrier
	s_add_u32 s22, s22, 0x40080
	s_addc_u32 s23, s23, 0
	s_add_i32 s24, s24, s27
	v_lshl_add_u64 v[146:147], s[22:23], 0, v[132:133]
	s_mov_b32 m0, s24
	s_nop 0
	global_load_lds_dwordx4 v[146:147], off
	v_lshl_add_u64 v[146:147], s[22:23], 0, v[128:129]
	s_add_i32 m0, s24, 0x2000
	s_nop 0
	global_load_lds_dwordx4 v[146:147], off
	s_waitcnt vmcnt(6)
	s_barrier
	v_mfma_f32_16x16x32_bf16 v[92:95], v[206:209], v[174:177], v[92:95]
	v_mfma_f32_16x16x32_bf16 v[88:91], v[214:217], v[174:177], v[88:91]
	v_mfma_f32_16x16x32_bf16 v[84:87], v[206:209], v[182:185], v[84:87]
	v_mfma_f32_16x16x32_bf16 v[80:83], v[214:217], v[182:185], v[80:83]
	v_mfma_f32_16x16x32_bf16 v[72:75], v[206:209], v[190:193], v[72:75]
	v_mfma_f32_16x16x32_bf16 v[68:71], v[214:217], v[190:193], v[68:71]
	v_mfma_f32_16x16x32_bf16 v[52:55], v[206:209], v[198:201], v[52:55]
	v_mfma_f32_16x16x32_bf16 v[44:47], v[214:217], v[198:201], v[44:47]
	v_mfma_f32_16x16x32_bf16 v[92:95], v[210:213], v[178:181], v[92:95]
	v_mfma_f32_16x16x32_bf16 v[88:91], v[218:221], v[178:181], v[88:91]
	v_mfma_f32_16x16x32_bf16 v[84:87], v[210:213], v[186:189], v[84:87]
	v_mfma_f32_16x16x32_bf16 v[80:83], v[218:221], v[186:189], v[80:83]
	v_mfma_f32_16x16x32_bf16 v[72:75], v[210:213], v[194:197], v[72:75]
	v_mfma_f32_16x16x32_bf16 v[68:71], v[218:221], v[194:197], v[68:71]
	v_mfma_f32_16x16x32_bf16 v[52:55], v[210:213], v[202:205], v[52:55]
	v_mfma_f32_16x16x32_bf16 v[44:47], v[218:221], v[202:205], v[44:47]
	s_add_i32 s47, s47, 2
	s_add_u32 s20, s20, 0x100
	s_addc_u32 s21, s21, 0
	s_add_u32 s45, s45, 0x100
	s_addc_u32 s46, s46, 0
	s_cmp_gt_u32 s47, 13
	s_barrier
.LBB0_205:
	ds_read_b128 v[146:149], v170
	ds_read_b128 v[154:157], v170 offset:1024
	ds_read_b128 v[158:161], v170 offset:2048
	ds_read_b128 v[162:165], v170 offset:3072
	s_add_u32 s22, s20, 0xfffc0080
	s_addc_u32 s23, s21, -1
	s_cmp_eq_u32 s47, 12
	s_cselect_b32 s25, s13, s23
	s_cselect_b32 s24, s19, s22
	s_cselect_b32 s23, s11, s46
	s_cselect_b32 s22, s44, s45
	v_lshl_add_u64 v[150:151], s[20:21], 0, v[138:139]
	s_add_i32 m0, s30, 0xc000
	ds_read_b128 v[174:177], v171
	ds_read_b128 v[178:181], v171 offset:1024
	ds_read_b128 v[182:185], v171 offset:2048
	ds_read_b128 v[186:189], v171 offset:3072
	ds_read_b128 v[190:193], v171 offset:4096
	ds_read_b128 v[194:197], v171 offset:5120
	ds_read_b128 v[198:201], v171 offset:6144
	ds_read_b128 v[202:205], v171 offset:7168
	global_load_lds_dwordx4 v[150:151], off
	v_lshl_add_u64 v[150:151], s[20:21], 0, v[140:141]
	s_add_i32 m0, s30, 0xe000
	s_nop 0
	global_load_lds_dwordx4 v[150:151], off
	s_waitcnt lgkmcnt(8)
	s_barrier
	s_waitcnt lgkmcnt(0)
	s_waitcnt lgkmcnt(0)
	v_mfma_f32_16x16x32_bf16 v[76:79], v[146:149], v[174:177], v[76:79]
	v_mfma_f32_16x16x32_bf16 v[64:67], v[158:161], v[174:177], v[64:67]
	v_mfma_f32_16x16x32_bf16 v[60:63], v[146:149], v[182:185], v[60:63]
	v_mfma_f32_16x16x32_bf16 v[56:59], v[158:161], v[182:185], v[56:59]
	v_mfma_f32_16x16x32_bf16 v[48:51], v[146:149], v[190:193], v[48:51]
	v_mfma_f32_16x16x32_bf16 v[40:43], v[158:161], v[190:193], v[40:43]
	v_mfma_f32_16x16x32_bf16 v[36:39], v[146:149], v[198:201], v[36:39]
	v_mfma_f32_16x16x32_bf16 v[32:35], v[158:161], v[198:201], v[32:35]
	v_mfma_f32_16x16x32_bf16 v[76:79], v[154:157], v[178:181], v[76:79]
	v_mfma_f32_16x16x32_bf16 v[64:67], v[162:165], v[178:181], v[64:67]
	v_mfma_f32_16x16x32_bf16 v[60:63], v[154:157], v[186:189], v[60:63]
	v_mfma_f32_16x16x32_bf16 v[56:59], v[162:165], v[186:189], v[56:59]
	v_mfma_f32_16x16x32_bf16 v[48:51], v[154:157], v[194:197], v[48:51]
	v_mfma_f32_16x16x32_bf16 v[40:43], v[162:165], v[194:197], v[40:43]
	v_mfma_f32_16x16x32_bf16 v[36:39], v[154:157], v[202:205], v[36:39]
	v_mfma_f32_16x16x32_bf16 v[32:35], v[162:165], v[202:205], v[32:35]
	s_barrier
	s_add_i32 s48, s39, s27
	v_lshl_add_u64 v[150:151], s[22:23], 0, v[132:133]
	s_mov_b32 m0, s48
	ds_read_b128 v[206:209], v172
	ds_read_b128 v[210:213], v172 offset:1024
	ds_read_b128 v[214:217], v172 offset:2048
	ds_read_b128 v[218:221], v172 offset:3072
	global_load_lds_dwordx4 v[150:151], off
	v_lshl_add_u64 v[166:167], s[22:23], 0, v[128:129]
	s_add_i32 m0, s48, 0x2000
	s_nop 0
	global_load_lds_dwordx4 v[166:167], off
	s_barrier
; #define PG8_STAGE(bufoff, gbase, voff) do { _Pragma("unroll") for (int _i = 0; _i < 2; ++_i) \
;         __builtin_amdgcn_global_load_lds((const unsigned*)((const char*)(gbase) + (voff)[_i]), (LAS unsigned*)(lds + (bufoff) + ldsw + _i * 8192), 16, 0, 0); } while (0)
; #define PG8_LDA(dst, b, h) do { _Pragma("unroll") for (int m = 0; m < 4; ++m) _Pragma("unroll") for (int k = 0; k < 2; ++k) dst[m][k] = *(const LAS bf16x8*)(lds + PG8_SA(b, h) + aoff + m * 2048 + k * 1024); } while (0)
; #define PG8_LDB(dst, b, h) do { _Pragma("unroll") for (int n = 0; n < 2; ++n) _Pragma("unroll") for (int k = 0; k < 2; ++k) dst[n][k] = *(const LAS bf16x8*)(lds + PG8_SB(b, h) + boff + n * 2048 + k * 1024); } while (0)
; #define PG8_MMA(ai, bj, At, Bt) do { __builtin_amdgcn_s_setprio(1); _Pragma("unroll") for (int m = 0; m < 4; ++m) _Pragma("unroll") for (int n = 0; n < 2; ++n) _Pragma("unroll") for (int k = 0; k < 2; ++k) \
;         acc[ai][bj][m][n] = __builtin_amdgcn_mfma_f32_16x16x32_bf16(Bt[n][k], At[m][k], acc[ai][bj][m][n], 0, 0, 0); __builtin_amdgcn_s_setprio(0); } while (0)
; #define PG8_WAIT_V(n) asm volatile("s_waitcnt vmcnt(" #n ")" ::: "memory")
; #define PG8_WAIT_L(n) asm volatile("s_waitcnt lgkmcnt(" #n ")" ::: "memory")
; #define PG8_BAR __builtin_amdgcn_s_barrier()
; #define PG8_SCHED __builtin_amdgcn_sched_barrier(0)
; template <class Epi>
; __device__ __forceinline__ void gemm_phase(LAS unsigned char* lds, const Gemm g, const StaticOrder& S, const Epi& E) {
;     ...
;             PG8_BAR; PG8_WAIT_L(0); PG8_MMA(0, 1, At, B1); PG8_BAR;
;             PG8_LDA(At, 0, 1); PG8_STAGE(PG8_SA(0, 0), a2, voffA);
;             PG8_BAR; PG8_WAIT_L(0); PG8_MMA(1, 0, At, B0); PG8_BAR; PG8_SCHED;
;             PG8_STAGE(PG8_SB(0, 1), b2 + hstepB, voffB);
;             PG8_WAIT_V(6); PG8_BAR; PG8_MMA(1, 1, At, B1); PG8_BAR;
;             PG8_LDB(B0, 1, 0); PG8_SCHED; PG8_LDA(At, 1, 0); PG8_STAGE(PG8_SA(0, 1), a2 + hstepA, voffA);
;             PG8_WAIT_L(8); PG8_BAR; PG8_WAIT_L(0); PG8_MMA(0, 0, At, B0); PG8_BAR; PG8_SCHED;
	s_waitcnt lgkmcnt(0)
	s_waitcnt lgkmcnt(0)
	v_mfma_f32_16x16x32_bf16 v[124:127], v[206:209], v[174:177], v[124:127]
	v_mfma_f32_16x16x32_bf16 v[120:123], v[214:217], v[174:177], v[120:123]
	v_mfma_f32_16x16x32_bf16 v[116:119], v[206:209], v[182:185], v[116:119]
	v_mfma_f32_16x16x32_bf16 v[112:115], v[214:217], v[182:185], v[112:115]
	v_mfma_f32_16x16x32_bf16 v[108:111], v[206:209], v[190:193], v[108:111]
	v_mfma_f32_16x16x32_bf16 v[104:107], v[214:217], v[190:193], v[104:107]
	v_mfma_f32_16x16x32_bf16 v[100:103], v[206:209], v[198:201], v[100:103]
	v_mfma_f32_16x16x32_bf16 v[96:99], v[214:217], v[198:201], v[96:99]
	v_mfma_f32_16x16x32_bf16 v[124:127], v[210:213], v[178:181], v[124:127]
	v_mfma_f32_16x16x32_bf16 v[120:123], v[218:221], v[178:181], v[120:123]
	v_mfma_f32_16x16x32_bf16 v[116:119], v[210:213], v[186:189], v[116:119]
	v_mfma_f32_16x16x32_bf16 v[112:115], v[218:221], v[186:189], v[112:115]
	v_mfma_f32_16x16x32_bf16 v[108:111], v[210:213], v[194:197], v[108:111]
	v_mfma_f32_16x16x32_bf16 v[104:107], v[218:221], v[194:197], v[104:107]
	v_mfma_f32_16x16x32_bf16 v[100:103], v[210:213], v[202:205], v[100:103]
	v_mfma_f32_16x16x32_bf16 v[96:99], v[218:221], v[202:205], v[96:99]
	s_mov_b32 m0, s30
	v_lshl_add_u64 v[222:223], s[24:25], 0, v[134:135]
	s_barrier
	ds_read_b128 v[174:177], v171 offset:16384
	ds_read_b128 v[178:181], v171 offset:17408
	ds_read_b128 v[182:185], v171 offset:18432
	ds_read_b128 v[186:189], v171 offset:19456
	ds_read_b128 v[190:193], v171 offset:20480
	ds_read_b128 v[194:197], v171 offset:21504
	ds_read_b128 v[198:201], v171 offset:22528
	ds_read_b128 v[202:205], v171 offset:23552
	global_load_lds_dwordx4 v[222:223], off
	v_lshl_add_u64 v[224:225], s[24:25], 0, v[130:131]
	s_mov_b32 m0, s31
	s_nop 0
	global_load_lds_dwordx4 v[224:225], off
	s_barrier
	s_waitcnt lgkmcnt(0)
	s_waitcnt lgkmcnt(0)
	v_mfma_f32_16x16x32_bf16 v[28:31], v[146:149], v[174:177], v[28:31]
	v_mfma_f32_16x16x32_bf16 v[24:27], v[158:161], v[174:177], v[24:27]
	v_mfma_f32_16x16x32_bf16 v[20:23], v[146:149], v[182:185], v[20:23]
	v_mfma_f32_16x16x32_bf16 v[16:19], v[158:161], v[182:185], v[16:19]
	v_mfma_f32_16x16x32_bf16 v[12:15], v[146:149], v[190:193], v[12:15]
	v_mfma_f32_16x16x32_bf16 v[8:11], v[158:161], v[190:193], v[8:11]
	v_mfma_f32_16x16x32_bf16 v[4:7], v[146:149], v[198:201], v[4:7]
	v_mfma_f32_16x16x32_bf16 v[0:3], v[158:161], v[198:201], v[0:3]
	v_mfma_f32_16x16x32_bf16 v[28:31], v[154:157], v[178:181], v[28:31]
	v_mfma_f32_16x16x32_bf16 v[24:27], v[162:165], v[178:181], v[24:27]
	v_mfma_f32_16x16x32_bf16 v[20:23], v[154:157], v[186:189], v[20:23]
	v_mfma_f32_16x16x32_bf16 v[16:19], v[162:165], v[186:189], v[16:19]
	v_mfma_f32_16x16x32_bf16 v[12:15], v[154:157], v[194:197], v[12:15]
	v_mfma_f32_16x16x32_bf16 v[8:11], v[162:165], v[194:197], v[8:11]
	v_mfma_f32_16x16x32_bf16 v[4:7], v[154:157], v[202:205], v[4:7]
	v_mfma_f32_16x16x32_bf16 v[0:3], v[162:165], v[202:205], v[0:3]
	s_barrier
	s_add_u32 s48, s22, 0x40000
	s_addc_u32 s49, s23, 0
	s_add_i32 s50, s40, s27
	v_lshl_add_u64 v[146:147], s[48:49], 0, v[132:133]
	s_mov_b32 m0, s50
	s_nop 0
	global_load_lds_dwordx4 v[146:147], off
	v_lshl_add_u64 v[146:147], s[48:49], 0, v[128:129]
	s_add_i32 m0, s50, 0x2000
	s_nop 0
	global_load_lds_dwordx4 v[146:147], off
	s_waitcnt vmcnt(6)
	s_barrier
	v_mfma_f32_16x16x32_bf16 v[92:95], v[206:209], v[174:177], v[92:95]
	v_mfma_f32_16x16x32_bf16 v[88:91], v[214:217], v[174:177], v[88:91]
	v_mfma_f32_16x16x32_bf16 v[84:87], v[206:209], v[182:185], v[84:87]
	v_mfma_f32_16x16x32_bf16 v[80:83], v[214:217], v[182:185], v[80:83]
	v_mfma_f32_16x16x32_bf16 v[72:75], v[206:209], v[190:193], v[72:75]
	v_mfma_f32_16x16x32_bf16 v[68:71], v[214:217], v[190:193], v[68:71]
	v_mfma_f32_16x16x32_bf16 v[52:55], v[206:209], v[198:201], v[52:55]
	v_mfma_f32_16x16x32_bf16 v[44:47], v[214:217], v[198:201], v[44:47]
	v_mfma_f32_16x16x32_bf16 v[92:95], v[210:213], v[178:181], v[92:95]
	v_mfma_f32_16x16x32_bf16 v[88:91], v[218:221], v[178:181], v[88:91]
	v_mfma_f32_16x16x32_bf16 v[84:87], v[210:213], v[186:189], v[84:87]
	v_mfma_f32_16x16x32_bf16 v[80:83], v[218:221], v[186:189], v[80:83]
	v_mfma_f32_16x16x32_bf16 v[72:75], v[210:213], v[194:197], v[72:75]
	v_mfma_f32_16x16x32_bf16 v[68:71], v[218:221], v[194:197], v[68:71]
	v_mfma_f32_16x16x32_bf16 v[52:55], v[210:213], v[202:205], v[52:55]
	v_mfma_f32_16x16x32_bf16 v[44:47], v[218:221], v[202:205], v[44:47]
	s_add_i32 s48, 0, 0x18000
	v_add_u32_e32 v162, s48, v168
	s_barrier
	ds_read_b128 v[146:149], v162
	ds_read_b128 v[154:157], v162 offset:1024
	ds_read_b128 v[158:161], v162 offset:2048
	ds_read_b128 v[162:165], v162 offset:3072
	s_add_u32 s24, s24, 0x40000
	s_addc_u32 s25, s25, 0
	s_mov_b32 m0, s33
	v_lshl_add_u64 v[206:207], s[24:25], 0, v[134:135]
	ds_read_b128 v[174:177], v171 offset:32768
	ds_read_b128 v[178:181], v171 offset:33792
	ds_read_b128 v[182:185], v171 offset:34816
	ds_read_b128 v[186:189], v171 offset:35840
	ds_read_b128 v[190:193], v171 offset:36864
	ds_read_b128 v[194:197], v171 offset:37888
	ds_read_b128 v[198:201], v171 offset:38912
	ds_read_b128 v[202:205], v171 offset:39936
	global_load_lds_dwordx4 v[206:207], off
	v_lshl_add_u64 v[206:207], s[24:25], 0, v[130:131]
	s_mov_b32 m0, s34
	s_nop 0
	global_load_lds_dwordx4 v[206:207], off
	s_waitcnt lgkmcnt(8)
	s_barrier
; #define PG8_STAGE(bufoff, gbase, voff) do { _Pragma("unroll") for (int _i = 0; _i < 2; ++_i) \
;         __builtin_amdgcn_global_load_lds((const unsigned*)((const char*)(gbase) + (voff)[_i]), (LAS unsigned*)(lds + (bufoff) + ldsw + _i * 8192), 16, 0, 0); } while (0)
; #define PG8_LDA(dst, b, h) do { _Pragma("unroll") for (int m = 0; m < 4; ++m) _Pragma("unroll") for (int k = 0; k < 2; ++k) dst[m][k] = *(const LAS bf16x8*)(lds + PG8_SA(b, h) + aoff + m * 2048 + k * 1024); } while (0)
; #define PG8_LDB(dst, b, h) do { _Pragma("unroll") for (int n = 0; n < 2; ++n) _Pragma("unroll") for (int k = 0; k < 2; ++k) dst[n][k] = *(const LAS bf16x8*)(lds + PG8_SB(b, h) + boff + n * 2048 + k * 1024); } while (0)
; #define PG8_MMA(ai, bj, At, Bt) do { __builtin_amdgcn_s_setprio(1); _Pragma("unroll") for (int m = 0; m < 4; ++m) _Pragma("unroll") for (int n = 0; n < 2; ++n) _Pragma("unroll") for (int k = 0; k < 2; ++k) \
;         acc[ai][bj][m][n] = __builtin_amdgcn_mfma_f32_16x16x32_bf16(Bt[n][k], At[m][k], acc[ai][bj][m][n], 0, 0, 0); __builtin_amdgcn_s_setprio(0); } while (0)
; #define PG8_WAIT_V(n) asm volatile("s_waitcnt vmcnt(" #n ")" ::: "memory")
; #define PG8_WAIT_L(n) asm volatile("s_waitcnt lgkmcnt(" #n ")" ::: "memory")
; #define PG8_BAR __builtin_amdgcn_s_barrier()
; #define PG8_SCHED __builtin_amdgcn_sched_barrier(0)
; template <class Epi>
; __device__ __forceinline__ void gemm_phase(LAS unsigned char* lds, const Gemm g, const StaticOrder& S, const Epi& E) {
;     ...
;             PG8_WAIT_L(8); PG8_BAR; PG8_WAIT_L(0); PG8_MMA(0, 0, At, B0); PG8_BAR; PG8_SCHED;
;             PG8_LDB(B1, 1, 1); PG8_STAGE(PG8_SB(1, 0), b3, voffB);
;             PG8_BAR; PG8_WAIT_L(0); PG8_MMA(0, 1, At, B1); PG8_BAR;
;             PG8_LDA(At, 1, 1); PG8_STAGE(PG8_SA(1, 0), a3, voffA);
;             PG8_BAR; PG8_WAIT_L(0); PG8_MMA(1, 0, At, B0); PG8_BAR; PG8_SCHED;
;             PG8_STAGE(PG8_SB(1, 1), b3 + hstepB, voffB);
;             PG8_WAIT_V(6); PG8_BAR; PG8_MMA(1, 1, At, B1); PG8_BAR;
	s_waitcnt lgkmcnt(0)
	s_waitcnt lgkmcnt(0)
	v_mfma_f32_16x16x32_bf16 v[76:79], v[146:149], v[174:177], v[76:79]
	v_mfma_f32_16x16x32_bf16 v[64:67], v[158:161], v[174:177], v[64:67]
	v_mfma_f32_16x16x32_bf16 v[60:63], v[146:149], v[182:185], v[60:63]
	v_mfma_f32_16x16x32_bf16 v[56:59], v[158:161], v[182:185], v[56:59]
	v_mfma_f32_16x16x32_bf16 v[48:51], v[146:149], v[190:193], v[48:51]
	v_mfma_f32_16x16x32_bf16 v[40:43], v[158:161], v[190:193], v[40:43]
	v_mfma_f32_16x16x32_bf16 v[36:39], v[146:149], v[198:201], v[36:39]
	v_mfma_f32_16x16x32_bf16 v[32:35], v[158:161], v[198:201], v[32:35]
	v_mfma_f32_16x16x32_bf16 v[76:79], v[154:157], v[178:181], v[76:79]
	v_mfma_f32_16x16x32_bf16 v[64:67], v[162:165], v[178:181], v[64:67]
	v_mfma_f32_16x16x32_bf16 v[60:63], v[154:157], v[186:189], v[60:63]
	v_mfma_f32_16x16x32_bf16 v[56:59], v[162:165], v[186:189], v[56:59]
	v_mfma_f32_16x16x32_bf16 v[48:51], v[154:157], v[194:197], v[48:51]
	v_mfma_f32_16x16x32_bf16 v[40:43], v[162:165], v[194:197], v[40:43]
	v_mfma_f32_16x16x32_bf16 v[36:39], v[154:157], v[202:205], v[36:39]
	v_mfma_f32_16x16x32_bf16 v[32:35], v[162:165], v[202:205], v[32:35]
	s_barrier
	s_add_i32 s24, 0, 0x1c000
	s_add_i32 s25, s48, s27
	v_add_u32_e32 v218, s24, v168
	v_lshl_add_u64 v[150:151], v[150:151], 0, s[6:7]
	s_mov_b32 m0, s25
	ds_read_b128 v[206:209], v218
	ds_read_b128 v[210:213], v218 offset:1024
	ds_read_b128 v[214:217], v218 offset:2048
	ds_read_b128 v[218:221], v218 offset:3072
	global_load_lds_dwordx4 v[150:151], off
	v_lshl_add_u64 v[150:151], v[166:167], 0, s[6:7]
	s_add_i32 m0, s25, 0x2000
	s_nop 0
	global_load_lds_dwordx4 v[150:151], off
	s_barrier
	s_waitcnt lgkmcnt(0)
	s_waitcnt lgkmcnt(0)
	v_mfma_f32_16x16x32_bf16 v[124:127], v[206:209], v[174:177], v[124:127]
	v_mfma_f32_16x16x32_bf16 v[120:123], v[214:217], v[174:177], v[120:123]
	v_mfma_f32_16x16x32_bf16 v[116:119], v[206:209], v[182:185], v[116:119]
	v_mfma_f32_16x16x32_bf16 v[112:115], v[214:217], v[182:185], v[112:115]
	v_mfma_f32_16x16x32_bf16 v[108:111], v[206:209], v[190:193], v[108:111]
	v_mfma_f32_16x16x32_bf16 v[104:107], v[214:217], v[190:193], v[104:107]
	v_mfma_f32_16x16x32_bf16 v[100:103], v[206:209], v[198:201], v[100:103]
	v_mfma_f32_16x16x32_bf16 v[96:99], v[214:217], v[198:201], v[96:99]
	v_mfma_f32_16x16x32_bf16 v[124:127], v[210:213], v[178:181], v[124:127]
	v_mfma_f32_16x16x32_bf16 v[120:123], v[218:221], v[178:181], v[120:123]
	v_mfma_f32_16x16x32_bf16 v[116:119], v[210:213], v[186:189], v[116:119]
	v_mfma_f32_16x16x32_bf16 v[112:115], v[218:221], v[186:189], v[112:115]
	v_mfma_f32_16x16x32_bf16 v[108:111], v[210:213], v[194:197], v[108:111]
	v_mfma_f32_16x16x32_bf16 v[104:107], v[218:221], v[194:197], v[104:107]
	v_mfma_f32_16x16x32_bf16 v[100:103], v[210:213], v[202:205], v[100:103]
	v_mfma_f32_16x16x32_bf16 v[96:99], v[218:221], v[202:205], v[96:99]
	s_mov_b32 m0, s36
	v_lshl_add_u64 v[150:151], v[222:223], 0, s[6:7]
	s_barrier
	ds_read_b128 v[174:177], v171 offset:49152
	ds_read_b128 v[178:181], v171 offset:50176
	ds_read_b128 v[182:185], v171 offset:51200
	ds_read_b128 v[186:189], v171 offset:52224
	ds_read_b128 v[190:193], v171 offset:53248
	ds_read_b128 v[194:197], v171 offset:54272
	ds_read_b128 v[198:201], v171 offset:55296
	ds_read_b128 v[202:205], v171 offset:56320
	global_load_lds_dwordx4 v[150:151], off
	v_lshl_add_u64 v[150:151], v[224:225], 0, s[6:7]
	s_mov_b32 m0, s37
	s_nop 0
	global_load_lds_dwordx4 v[150:151], off
	s_barrier
	s_waitcnt lgkmcnt(0)
	s_waitcnt lgkmcnt(0)
	v_mfma_f32_16x16x32_bf16 v[28:31], v[146:149], v[174:177], v[28:31]
	v_mfma_f32_16x16x32_bf16 v[24:27], v[158:161], v[174:177], v[24:27]
	v_mfma_f32_16x16x32_bf16 v[20:23], v[146:149], v[182:185], v[20:23]
	v_mfma_f32_16x16x32_bf16 v[16:19], v[158:161], v[182:185], v[16:19]
	v_mfma_f32_16x16x32_bf16 v[12:15], v[146:149], v[190:193], v[12:15]
	v_mfma_f32_16x16x32_bf16 v[8:11], v[158:161], v[190:193], v[8:11]
	v_mfma_f32_16x16x32_bf16 v[4:7], v[146:149], v[198:201], v[4:7]
	v_mfma_f32_16x16x32_bf16 v[0:3], v[158:161], v[198:201], v[0:3]
	v_mfma_f32_16x16x32_bf16 v[28:31], v[154:157], v[178:181], v[28:31]
	v_mfma_f32_16x16x32_bf16 v[24:27], v[162:165], v[178:181], v[24:27]
	v_mfma_f32_16x16x32_bf16 v[20:23], v[154:157], v[186:189], v[20:23]
	v_mfma_f32_16x16x32_bf16 v[16:19], v[162:165], v[186:189], v[16:19]
	v_mfma_f32_16x16x32_bf16 v[12:15], v[154:157], v[194:197], v[12:15]
	v_mfma_f32_16x16x32_bf16 v[8:11], v[162:165], v[194:197], v[8:11]
	v_mfma_f32_16x16x32_bf16 v[4:7], v[154:157], v[202:205], v[4:7]
	v_mfma_f32_16x16x32_bf16 v[0:3], v[162:165], v[202:205], v[0:3]
	s_barrier
	s_add_u32 s22, s22, 0x40080
	s_addc_u32 s23, s23, 0
	s_add_i32 s24, s24, s27
	v_lshl_add_u64 v[146:147], s[22:23], 0, v[132:133]
	s_mov_b32 m0, s24
	s_nop 0
	global_load_lds_dwordx4 v[146:147], off
	v_lshl_add_u64 v[146:147], s[22:23], 0, v[128:129]
	s_add_i32 m0, s24, 0x2000
	s_nop 0
	global_load_lds_dwordx4 v[146:147], off
	s_waitcnt vmcnt(6)
	s_barrier
	v_mfma_f32_16x16x32_bf16 v[92:95], v[206:209], v[174:177], v[92:95]
	v_mfma_f32_16x16x32_bf16 v[88:91], v[214:217], v[174:177], v[88:91]
	v_mfma_f32_16x16x32_bf16 v[84:87], v[206:209], v[182:185], v[84:87]
	v_mfma_f32_16x16x32_bf16 v[80:83], v[214:217], v[182:185], v[80:83]
	v_mfma_f32_16x16x32_bf16 v[72:75], v[206:209], v[190:193], v[72:75]
	v_mfma_f32_16x16x32_bf16 v[68:71], v[214:217], v[190:193], v[68:71]
	v_mfma_f32_16x16x32_bf16 v[52:55], v[206:209], v[198:201], v[52:55]
	v_mfma_f32_16x16x32_bf16 v[44:47], v[214:217], v[198:201], v[44:47]
	v_mfma_f32_16x16x32_bf16 v[92:95], v[210:213], v[178:181], v[92:95]
	v_mfma_f32_16x16x32_bf16 v[88:91], v[218:221], v[178:181], v[88:91]
	v_mfma_f32_16x16x32_bf16 v[84:87], v[210:213], v[186:189], v[84:87]
	v_mfma_f32_16x16x32_bf16 v[80:83], v[218:221], v[186:189], v[80:83]
	v_mfma_f32_16x16x32_bf16 v[72:75], v[210:213], v[194:197], v[72:75]
	v_mfma_f32_16x16x32_bf16 v[68:71], v[218:221], v[194:197], v[68:71]
	v_mfma_f32_16x16x32_bf16 v[52:55], v[210:213], v[202:205], v[52:55]
	v_mfma_f32_16x16x32_bf16 v[44:47], v[218:221], v[202:205], v[44:47]
	s_add_i32 s47, s47, 2
	s_add_u32 s20, s20, 0x100
	s_addc_u32 s21, s21, 0
	s_add_u32 s45, s45, 0x100
	s_addc_u32 s46, s46, 0
	s_cmp_gt_u32 s47, 13
	s_barrier
; __device__ __forceinline__ unsigned pk2(float lo, float hi) { const f32x2 v = (f32x2){lo, hi}; const bf16x2_t b = __builtin_convertvector(v, bf16x2_t); return __builtin_bit_cast(unsigned, b); }
;     __device__ __forceinline__ void operator()(const f32x4 (&acc)[2][2][4][2], const Unit& u, int wr, int wc, int fr, int fq, const float (&)[8]) const {
;     ...
;         const int col0 = u.pn * BM + wc * 32 + 8 * fq;
; #pragma unroll
;         for (int ai = 0; ai < 2; ++ai)
; #pragma unroll
;             for (int m = 0; m < 4; ++m) { const int row = row0 + ai * HALF + m * 16; const float rs = rsqrtf(ep[ai * 4 + m] * (1.0f / 1024.0f) + EPS);
;                 u16* rowp = O + (size_t)row * ldc + col0;
; #pragma unroll
;                 for (int bj = 0; bj < 2; ++bj) { f32x4 v0 = acc[ai][bj][m][0] * rs, v1 = acc[ai][bj][m][1] * rs;
;                     if (ACT == 1) {
; #pragma unroll
;                         for (int j = 0; j < 4; ++j) { const float a0 = fmaxf(v0[j], 0.f), a1 = fmaxf(v1[j], 0.f); v0[j] = a0 * a0; v1[j] = a1 * a1; } }
;                     u32x4 w; w.x = pk2(v0[0], v0[1]); w.y = pk2(v0[2], v0[3]); w.z = pk2(v1[0], v1[1]); w.w = pk2(v1[2], v1[3]);
;                     *(u32x4*)(rowp + bj * HALF) = w; } }
	s_cbranch_scc0 .LBB0_205
	s_bfe_u32 vcc_lo, s18, 0x20003
	s_lshl_b32 vcc_lo, vcc_lo, 10
	s_add_i32 vcc_lo, vcc_lo, 0x20010
	v_lshl_add_u32 v236, v153, 2, vcc_lo
	ds_read_b32 v228, v236
	ds_read_b32 v229, v236 offset:64
	ds_read_b32 v230, v236 offset:128
	ds_read_b32 v231, v236 offset:192
	ds_read_b32 v232, v236 offset:512
	ds_read_b32 v233, v236 offset:576
	ds_read_b32 v234, v236 offset:640
	ds_read_b32 v235, v236 offset:704
	s_waitcnt lgkmcnt(0)
	v_lshl_add_u32 v162, s18, 8, v153
	v_ashrrev_i32_e32 v163, 31, v162
	v_or_b32_e32 v160, 16, v162
	v_or_b32_e32 v158, 32, v162
	v_or_b32_e32 v156, 48, v162
	v_ashrrev_i32_e32 v161, 31, v160
	v_ashrrev_i32_e32 v159, 31, v158
	v_ashrrev_i32_e32 v157, 31, v156
	v_add_u32_e32 v154, 0x80, v162
	v_add_u32_e32 v150, 0x90, v162
	v_add_u32_e32 v148, 0xa0, v162
	v_add_u32_e32 v146, 0xb0, v162
	v_ashrrev_i32_e32 v155, 31, v154
	v_ashrrev_i32_e32 v151, 31, v150
	v_ashrrev_i32_e32 v149, 31, v148
	v_ashrrev_i32_e32 v147, 31, v146
	s_cmp_lg_u32 s43, 20
	s_mov_b64 s[18:19], -1
	s_cbranch_scc0 .LBB0_208
	s_waitcnt vmcnt(8)
	v_lshl_or_b32 v166, s43, 8, v169
	v_ashrrev_i32_e32 v167, 31, v166
	v_lshlrev_b64 v[166:167], 1, v[166:167]
	v_mov_b32_e32 v186, v228
	v_mov_b64_e32 v[164:165], s[96:97]
	v_mad_i64_i32 v[182:183], s[18:19], v162, s42, v[164:165]
	v_lshl_add_u64 v[188:189], v[182:183], 0, v[166:167]
	v_pk_mul_f32 v[184:185], v[78:79], v[186:187] op_sel_hi:[1,0]
	v_pk_mul_f32 v[182:183], v[76:77], v[186:187] op_sel_hi:[1,0]
	v_pk_mul_f32 v[190:191], v[66:67], v[186:187] op_sel_hi:[1,0]
	v_pk_mul_f32 v[192:193], v[64:65], v[186:187] op_sel_hi:[1,0]
	v_cvt_pk_bf16_f32 v182, v182, v183
	v_cvt_pk_bf16_f32 v183, v184, v185
	v_cvt_pk_bf16_f32 v184, v192, v193
	v_cvt_pk_bf16_f32 v185, v190, v191
	v_pk_mul_f32 v[124:125], v[124:125], v[186:187] op_sel_hi:[1,0]
	global_store_dwordx4 v[188:189], v[182:185], off
	v_pk_mul_f32 v[126:127], v[126:127], v[186:187] op_sel_hi:[1,0]
	s_nop 0
	v_pk_mul_f32 v[182:183], v[122:123], v[186:187] op_sel_hi:[1,0]
	v_pk_mul_f32 v[122:123], v[120:121], v[186:187] op_sel_hi:[1,0]
	v_cvt_pk_bf16_f32 v120, v124, v125
	v_cvt_pk_bf16_f32 v121, v126, v127
	v_cvt_pk_bf16_f32 v122, v122, v123
	v_cvt_pk_bf16_f32 v123, v182, v183
	global_store_dwordx4 v[188:189], v[120:123], off offset:256
	s_nop 1
	v_mov_b32_e32 v124, v229
	v_mad_i64_i32 v[120:121], s[18:19], v160, s42, v[164:165]
	v_lshl_add_u64 v[126:127], v[120:121], 0, v[166:167]
	v_pk_mul_f32 v[122:123], v[62:63], v[124:125] op_sel_hi:[1,0]
	v_pk_mul_f32 v[120:121], v[60:61], v[124:125] op_sel_hi:[1,0]
	v_pk_mul_f32 v[182:183], v[58:59], v[124:125] op_sel_hi:[1,0]
	v_pk_mul_f32 v[184:185], v[56:57], v[124:125] op_sel_hi:[1,0]
	v_cvt_pk_bf16_f32 v120, v120, v121
	v_cvt_pk_bf16_f32 v121, v122, v123
	v_cvt_pk_bf16_f32 v122, v184, v185
	v_cvt_pk_bf16_f32 v123, v182, v183
	v_pk_mul_f32 v[116:117], v[116:117], v[124:125] op_sel_hi:[1,0]
	global_store_dwordx4 v[126:127], v[120:123], off
	v_pk_mul_f32 v[118:119], v[118:119], v[124:125] op_sel_hi:[1,0]
	s_nop 0
	v_pk_mul_f32 v[120:121], v[114:115], v[124:125] op_sel_hi:[1,0]
	v_pk_mul_f32 v[114:115], v[112:113], v[124:125] op_sel_hi:[1,0]
	v_cvt_pk_bf16_f32 v112, v116, v117
	v_cvt_pk_bf16_f32 v113, v118, v119
	v_cvt_pk_bf16_f32 v114, v114, v115
	v_cvt_pk_bf16_f32 v115, v120, v121
	global_store_dwordx4 v[126:127], v[112:115], off offset:256
	s_nop 1
	v_mov_b32_e32 v116, v230
	v_mad_i64_i32 v[112:113], s[18:19], v158, s42, v[164:165]
	v_lshl_add_u64 v[118:119], v[112:113], 0, v[166:167]
	v_pk_mul_f32 v[114:115], v[50:51], v[116:117] op_sel_hi:[1,0]
	v_pk_mul_f32 v[112:113], v[48:49], v[116:117] op_sel_hi:[1,0]
	v_pk_mul_f32 v[120:121], v[42:43], v[116:117] op_sel_hi:[1,0]
	v_pk_mul_f32 v[122:123], v[40:41], v[116:117] op_sel_hi:[1,0]
	v_cvt_pk_bf16_f32 v112, v112, v113
	v_cvt_pk_bf16_f32 v113, v114, v115
	v_cvt_pk_bf16_f32 v114, v122, v123
	v_cvt_pk_bf16_f32 v115, v120, v121
	v_pk_mul_f32 v[108:109], v[108:109], v[116:117] op_sel_hi:[1,0]
	global_store_dwordx4 v[118:119], v[112:115], off
	v_pk_mul_f32 v[110:111], v[110:111], v[116:117] op_sel_hi:[1,0]
	s_nop 0
	v_pk_mul_f32 v[112:113], v[106:107], v[116:117] op_sel_hi:[1,0]
	v_pk_mul_f32 v[106:107], v[104:105], v[116:117] op_sel_hi:[1,0]
	v_cvt_pk_bf16_f32 v104, v108, v109
	v_cvt_pk_bf16_f32 v105, v110, v111
	v_cvt_pk_bf16_f32 v106, v106, v107
	v_cvt_pk_bf16_f32 v107, v112, v113
	global_store_dwordx4 v[118:119], v[104:107], off offset:256
	s_nop 1
	v_mov_b32_e32 v108, v231
	v_mad_i64_i32 v[104:105], s[18:19], v156, s42, v[164:165]
	v_lshl_add_u64 v[110:111], v[104:105], 0, v[166:167]
	v_pk_mul_f32 v[106:107], v[38:39], v[108:109] op_sel_hi:[1,0]
	v_pk_mul_f32 v[104:105], v[36:37], v[108:109] op_sel_hi:[1,0]
	v_pk_mul_f32 v[112:113], v[34:35], v[108:109] op_sel_hi:[1,0]
; __device__ __forceinline__ unsigned pk2(float lo, float hi) { const f32x2 v = (f32x2){lo, hi}; const bf16x2_t b = __builtin_convertvector(v, bf16x2_t); return __builtin_bit_cast(unsigned, b); }
;     __device__ __forceinline__ void operator()(const f32x4 (&acc)[2][2][4][2], const Unit& u, int wr, int wc, int fr, int fq, const float (&)[8]) const {
;     ...
;         const int col0 = u.pn * BM + wc * 32 + 8 * fq;
; #pragma unroll
;         for (int ai = 0; ai < 2; ++ai)
; #pragma unroll
;             for (int m = 0; m < 4; ++m) { const int row = row0 + ai * HALF + m * 16; const float rs = rsqrtf(ep[ai * 4 + m] * (1.0f / 1024.0f) + EPS);
;                 u16* rowp = O + (size_t)row * ldc + col0;
; #pragma unroll
;                 for (int bj = 0; bj < 2; ++bj) { f32x4 v0 = acc[ai][bj][m][0] * rs, v1 = acc[ai][bj][m][1] * rs;
;                     if (ACT == 1) {
; #pragma unroll
;                         for (int j = 0; j < 4; ++j) { const float a0 = fmaxf(v0[j], 0.f), a1 = fmaxf(v1[j], 0.f); v0[j] = a0 * a0; v1[j] = a1 * a1; } }
;                     u32x4 w; w.x = pk2(v0[0], v0[1]); w.y = pk2(v0[2], v0[3]); w.z = pk2(v1[0], v1[1]); w.w = pk2(v1[2], v1[3]);
;                     *(u32x4*)(rowp + bj * HALF) = w; } }
	v_pk_mul_f32 v[114:115], v[32:33], v[108:109] op_sel_hi:[1,0]
	v_cvt_pk_bf16_f32 v104, v104, v105
	v_cvt_pk_bf16_f32 v105, v106, v107
	v_cvt_pk_bf16_f32 v106, v114, v115
	v_cvt_pk_bf16_f32 v107, v112, v113
	v_pk_mul_f32 v[100:101], v[100:101], v[108:109] op_sel_hi:[1,0]
	global_store_dwordx4 v[110:111], v[104:107], off
	v_pk_mul_f32 v[102:103], v[102:103], v[108:109] op_sel_hi:[1,0]
	s_nop 0
	v_pk_mul_f32 v[104:105], v[98:99], v[108:109] op_sel_hi:[1,0]
	v_pk_mul_f32 v[98:99], v[96:97], v[108:109] op_sel_hi:[1,0]
	v_cvt_pk_bf16_f32 v96, v100, v101
	v_cvt_pk_bf16_f32 v97, v102, v103
	v_cvt_pk_bf16_f32 v98, v98, v99
	v_cvt_pk_bf16_f32 v99, v104, v105
	global_store_dwordx4 v[110:111], v[96:99], off offset:256
	s_nop 1
	v_mov_b32_e32 v100, v232
	v_mad_i64_i32 v[96:97], s[18:19], v154, s42, v[164:165]
	v_lshl_add_u64 v[102:103], v[96:97], 0, v[166:167]
	v_pk_mul_f32 v[98:99], v[30:31], v[100:101] op_sel_hi:[1,0]
	v_pk_mul_f32 v[96:97], v[28:29], v[100:101] op_sel_hi:[1,0]
	v_pk_mul_f32 v[104:105], v[26:27], v[100:101] op_sel_hi:[1,0]
	v_pk_mul_f32 v[106:107], v[24:25], v[100:101] op_sel_hi:[1,0]
	v_cvt_pk_bf16_f32 v96, v96, v97
	v_cvt_pk_bf16_f32 v97, v98, v99
	v_cvt_pk_bf16_f32 v98, v106, v107
	v_cvt_pk_bf16_f32 v99, v104, v105
	v_pk_mul_f32 v[92:93], v[92:93], v[100:101] op_sel_hi:[1,0]
	global_store_dwordx4 v[102:103], v[96:99], off
	v_pk_mul_f32 v[94:95], v[94:95], v[100:101] op_sel_hi:[1,0]
	s_nop 0
	v_pk_mul_f32 v[96:97], v[90:91], v[100:101] op_sel_hi:[1,0]
	v_pk_mul_f32 v[90:91], v[88:89], v[100:101] op_sel_hi:[1,0]
	v_cvt_pk_bf16_f32 v88, v92, v93
	v_cvt_pk_bf16_f32 v89, v94, v95
	v_cvt_pk_bf16_f32 v90, v90, v91
	v_cvt_pk_bf16_f32 v91, v96, v97
	global_store_dwordx4 v[102:103], v[88:91], off offset:256
	s_nop 1
	v_mov_b32_e32 v92, v233
	v_mad_i64_i32 v[88:89], s[18:19], v150, s42, v[164:165]
	v_lshl_add_u64 v[94:95], v[88:89], 0, v[166:167]
	v_pk_mul_f32 v[90:91], v[22:23], v[92:93] op_sel_hi:[1,0]
	v_pk_mul_f32 v[88:89], v[20:21], v[92:93] op_sel_hi:[1,0]
	v_pk_mul_f32 v[96:97], v[18:19], v[92:93] op_sel_hi:[1,0]
	v_pk_mul_f32 v[98:99], v[16:17], v[92:93] op_sel_hi:[1,0]
	v_cvt_pk_bf16_f32 v88, v88, v89
	v_cvt_pk_bf16_f32 v89, v90, v91
	v_cvt_pk_bf16_f32 v90, v98, v99
	v_cvt_pk_bf16_f32 v91, v96, v97
	v_pk_mul_f32 v[84:85], v[84:85], v[92:93] op_sel_hi:[1,0]
	global_store_dwordx4 v[94:95], v[88:91], off
	v_pk_mul_f32 v[86:87], v[86:87], v[92:93] op_sel_hi:[1,0]
	s_nop 0
	v_pk_mul_f32 v[88:89], v[82:83], v[92:93] op_sel_hi:[1,0]
	v_pk_mul_f32 v[82:83], v[80:81], v[92:93] op_sel_hi:[1,0]
	v_cvt_pk_bf16_f32 v80, v84, v85
	v_cvt_pk_bf16_f32 v81, v86, v87
	v_cvt_pk_bf16_f32 v82, v82, v83
	v_cvt_pk_bf16_f32 v83, v88, v89
	global_store_dwordx4 v[94:95], v[80:83], off offset:256
	s_nop 1
	v_mov_b32_e32 v84, v234
	v_mad_i64_i32 v[80:81], s[18:19], v148, s42, v[164:165]
	v_lshl_add_u64 v[86:87], v[80:81], 0, v[166:167]
	v_pk_mul_f32 v[82:83], v[14:15], v[84:85] op_sel_hi:[1,0]
	v_pk_mul_f32 v[80:81], v[12:13], v[84:85] op_sel_hi:[1,0]
	v_pk_mul_f32 v[88:89], v[10:11], v[84:85] op_sel_hi:[1,0]
	v_pk_mul_f32 v[90:91], v[8:9], v[84:85] op_sel_hi:[1,0]
	v_cvt_pk_bf16_f32 v80, v80, v81
	v_cvt_pk_bf16_f32 v81, v82, v83
	v_cvt_pk_bf16_f32 v82, v90, v91
	v_cvt_pk_bf16_f32 v83, v88, v89
	v_pk_mul_f32 v[72:73], v[72:73], v[84:85] op_sel_hi:[1,0]
	global_store_dwordx4 v[86:87], v[80:83], off
	v_pk_mul_f32 v[74:75], v[74:75], v[84:85] op_sel_hi:[1,0]
	s_nop 0
	v_pk_mul_f32 v[80:81], v[70:71], v[84:85] op_sel_hi:[1,0]
	v_pk_mul_f32 v[70:71], v[68:69], v[84:85] op_sel_hi:[1,0]
	v_cvt_pk_bf16_f32 v68, v72, v73
	v_cvt_pk_bf16_f32 v69, v74, v75
	v_cvt_pk_bf16_f32 v70, v70, v71
	v_cvt_pk_bf16_f32 v71, v80, v81
	global_store_dwordx4 v[86:87], v[68:71], off offset:256
	s_nop 1
	v_mov_b32_e32 v72, v235
	v_mad_i64_i32 v[68:69], s[18:19], v146, s42, v[164:165]
	v_lshl_add_u64 v[74:75], v[68:69], 0, v[166:167]
	v_pk_mul_f32 v[70:71], v[6:7], v[72:73] op_sel_hi:[1,0]
	v_pk_mul_f32 v[68:69], v[4:5], v[72:73] op_sel_hi:[1,0]
	v_pk_mul_f32 v[80:81], v[2:3], v[72:73] op_sel_hi:[1,0]
	v_pk_mul_f32 v[82:83], v[0:1], v[72:73] op_sel_hi:[1,0]
	v_cvt_pk_bf16_f32 v68, v68, v69
	v_cvt_pk_bf16_f32 v69, v70, v71
	v_cvt_pk_bf16_f32 v70, v82, v83
	v_cvt_pk_bf16_f32 v71, v80, v81
	global_store_dwordx4 v[74:75], v[68:71], off
	v_pk_mul_f32 v[54:55], v[54:55], v[72:73] op_sel_hi:[1,0]
	v_pk_mul_f32 v[52:53], v[52:53], v[72:73] op_sel_hi:[1,0]
	v_pk_mul_f32 v[68:69], v[46:47], v[72:73] op_sel_hi:[1,0]
	v_pk_mul_f32 v[46:47], v[44:45], v[72:73] op_sel_hi:[1,0]
	v_cvt_pk_bf16_f32 v44, v52, v53
	v_cvt_pk_bf16_f32 v45, v54, v55
	v_cvt_pk_bf16_f32 v46, v46, v47
	v_cvt_pk_bf16_f32 v47, v68, v69
	global_store_dwordx4 v[74:75], v[44:47], off offset:256
	s_mov_b64 s[18:19], 0

; #define PG8_STAGE(bufoff, gbase, voff) do { _Pragma("unroll") for (int _i = 0; _i < 2; ++_i) \
;         __builtin_amdgcn_global_load_lds((const unsigned*)((const char*)(gbase) + (voff)[_i]), (LAS unsigned*)(lds + (bufoff) + ldsw + _i * 8192), 16, 0, 0); } while (0)
; #define PG8_LDA(dst, b, h) do { _Pragma("unroll") for (int m = 0; m < 4; ++m) _Pragma("unroll") for (int k = 0; k < 2; ++k) dst[m][k] = *(const LAS bf16x8*)(lds + PG8_SA(b, h) + aoff + m * 2048 + k * 1024); } while (0)
; #define PG8_LDB(dst, b, h) do { _Pragma("unroll") for (int n = 0; n < 2; ++n) _Pragma("unroll") for (int k = 0; k < 2; ++k) dst[n][k] = *(const LAS bf16x8*)(lds + PG8_SB(b, h) + boff + n * 2048 + k * 1024); } while (0)
; #define PG8_MMA(ai, bj, At, Bt) do { __builtin_amdgcn_s_setprio(1); _Pragma("unroll") for (int m = 0; m < 4; ++m) _Pragma("unroll") for (int n = 0; n < 2; ++n) _Pragma("unroll") for (int k = 0; k < 2; ++k) \
;         acc[ai][bj][m][n] = __builtin_amdgcn_mfma_f32_16x16x32_bf16(Bt[n][k], At[m][k], acc[ai][bj][m][n], 0, 0, 0); __builtin_amdgcn_s_setprio(0); } while (0)
; #define PG8_WAIT_L(n) asm volatile("s_waitcnt lgkmcnt(" #n ")" ::: "memory")
; #define PG8_BAR __builtin_amdgcn_s_barrier()
; #define PG8_SCHED __builtin_amdgcn_sched_barrier(0)
; template <class Epi>
; __device__ __forceinline__ void gemm_phase(LAS unsigned char* lds, const Gemm g, const StaticOrder& S, const Epi& E) {
;     ...
;             PG8_LDB(B0, 0, 0); PG8_SCHED; PG8_LDA(At, 0, 0); PG8_STAGE(PG8_SA(1, 1), a1 + hstepA, voffA);
;             PG8_WAIT_L(8); PG8_BAR; PG8_WAIT_L(0); PG8_MMA(0, 0, At, B0); PG8_BAR; PG8_SCHED;
;             PG8_LDB(B1, 0, 1); PG8_STAGE(PG8_SB(0, 0), b2, voffB);
;             PG8_BAR; PG8_WAIT_L(0); PG8_MMA(0, 1, At, B1); PG8_BAR;
;             PG8_LDA(At, 0, 1); PG8_STAGE(PG8_SA(0, 0), a2, voffA);
;             PG8_BAR; PG8_WAIT_L(0); PG8_MMA(1, 0, At, B0); PG8_BAR; PG8_SCHED;
.LBB0_683:
	s_ashr_i32 s17, s16, 31
	s_lshl_b64 s[20:21], s[16:17], 20
	s_add_u32 s20, s29, s20
	s_addc_u32 s21, s30, s21
	s_and_b64 s[4:5], s[4:5], exec
	s_cselect_b32 s17, s21, s23
	s_cselect_b32 s45, s20, s22
	s_add_u32 s4, s24, 0x140080
	s_addc_u32 s5, s25, 0
	s_add_u32 s46, s22, 0x100
	s_addc_u32 s47, s23, 0
	s_mov_b32 s48, -2
	s_waitcnt lgkmcnt(0)
	ds_read_b128 v[128:131], v191
	ds_read_b128 v[132:135], v191 offset:1024
	ds_read_b128 v[136:139], v191 offset:2048
	ds_read_b128 v[140:143], v191 offset:3072
	s_add_u32 s22, s4, 0xffec0080
	s_addc_u32 s23, s5, -1
	s_cmp_eq_u32 s48, 28
	s_cselect_b32 s25, s19, s23
	s_cselect_b32 s24, s18, s22
	s_cselect_b32 s23, s17, s47
	s_cselect_b32 s22, s45, s46
	v_lshl_add_u64 v[186:187], s[4:5], 0, v[162:163]
	s_add_i32 m0, s11, 0xc000
	ds_read_b128 v[144:147], v192
	ds_read_b128 v[148:151], v192 offset:1024
	ds_read_b128 v[170:173], v192 offset:2048
	ds_read_b128 v[174:177], v192 offset:3072
	ds_read_b128 v[178:181], v192 offset:4096
	ds_read_b128 v[182:185], v192 offset:5120
	ds_read_b128 v[196:199], v192 offset:6144
	ds_read_b128 v[200:203], v192 offset:7168
	global_load_lds_dwordx4 v[186:187], off
	v_lshl_add_u64 v[186:187], s[4:5], 0, v[164:165]
	s_add_i32 m0, s11, 0xe000
	s_nop 0
	global_load_lds_dwordx4 v[186:187], off
	s_waitcnt lgkmcnt(8)
	s_barrier
	s_waitcnt lgkmcnt(0)
	s_waitcnt lgkmcnt(0)
	v_mfma_f32_16x16x32_bf16 v[124:127], v[128:131], v[144:147], 0
	v_mfma_f32_16x16x32_bf16 v[120:123], v[136:139], v[144:147], 0
	v_mfma_f32_16x16x32_bf16 v[108:111], v[128:131], v[170:173], 0
	v_mfma_f32_16x16x32_bf16 v[104:107], v[136:139], v[170:173], 0
	v_mfma_f32_16x16x32_bf16 v[92:95], v[128:131], v[178:181], 0
	v_mfma_f32_16x16x32_bf16 v[88:91], v[136:139], v[178:181], 0
	v_mfma_f32_16x16x32_bf16 v[76:79], v[128:131], v[196:199], 0
	v_mfma_f32_16x16x32_bf16 v[72:75], v[136:139], v[196:199], 0
	v_mfma_f32_16x16x32_bf16 v[124:127], v[132:135], v[148:151], v[124:127]
	v_mfma_f32_16x16x32_bf16 v[120:123], v[140:143], v[148:151], v[120:123]
	v_mfma_f32_16x16x32_bf16 v[108:111], v[132:135], v[174:177], v[108:111]
	v_mfma_f32_16x16x32_bf16 v[104:107], v[140:143], v[174:177], v[104:107]
	v_mfma_f32_16x16x32_bf16 v[92:95], v[132:135], v[182:185], v[92:95]
	v_mfma_f32_16x16x32_bf16 v[88:91], v[140:143], v[182:185], v[88:91]
	v_mfma_f32_16x16x32_bf16 v[76:79], v[132:135], v[200:203], v[76:79]
	v_mfma_f32_16x16x32_bf16 v[72:75], v[140:143], v[200:203], v[72:75]
	s_barrier
	s_add_i32 s49, s42, s31
	v_lshl_add_u64 v[186:187], s[22:23], 0, v[156:157]
	s_mov_b32 m0, s49
	ds_read_b128 v[204:207], v193
	ds_read_b128 v[208:211], v193 offset:1024
	ds_read_b128 v[212:215], v193 offset:2048
	ds_read_b128 v[216:219], v193 offset:3072
	global_load_lds_dwordx4 v[186:187], off
	v_lshl_add_u64 v[220:221], s[22:23], 0, v[160:161]
	s_add_i32 m0, s49, 0x2000
	s_nop 0
	global_load_lds_dwordx4 v[220:221], off
	s_barrier
	s_waitcnt lgkmcnt(0)
	s_waitcnt lgkmcnt(0)
	v_mfma_f32_16x16x32_bf16 v[116:119], v[204:207], v[144:147], 0
	v_mfma_f32_16x16x32_bf16 v[112:115], v[212:215], v[144:147], 0
	v_mfma_f32_16x16x32_bf16 v[100:103], v[204:207], v[170:173], 0
	v_mfma_f32_16x16x32_bf16 v[96:99], v[212:215], v[170:173], 0
	v_mfma_f32_16x16x32_bf16 v[84:87], v[204:207], v[178:181], 0
	v_mfma_f32_16x16x32_bf16 v[80:83], v[212:215], v[178:181], 0
	v_mfma_f32_16x16x32_bf16 v[68:71], v[204:207], v[196:199], 0
	v_mfma_f32_16x16x32_bf16 v[64:67], v[212:215], v[196:199], 0
	v_mfma_f32_16x16x32_bf16 v[116:119], v[208:211], v[148:151], v[116:119]
	v_mfma_f32_16x16x32_bf16 v[112:115], v[216:219], v[148:151], v[112:115]
	v_mfma_f32_16x16x32_bf16 v[100:103], v[208:211], v[174:177], v[100:103]
	v_mfma_f32_16x16x32_bf16 v[96:99], v[216:219], v[174:177], v[96:99]
	v_mfma_f32_16x16x32_bf16 v[84:87], v[208:211], v[182:185], v[84:87]
	v_mfma_f32_16x16x32_bf16 v[80:83], v[216:219], v[182:185], v[80:83]
	v_mfma_f32_16x16x32_bf16 v[68:71], v[208:211], v[200:203], v[68:71]
	v_mfma_f32_16x16x32_bf16 v[64:67], v[216:219], v[200:203], v[64:67]
	s_mov_b32 m0, s11
	v_lshl_add_u64 v[222:223], s[24:25], 0, v[154:155]
	s_barrier
	ds_read_b128 v[144:147], v192 offset:16384
	ds_read_b128 v[148:151], v192 offset:17408
	ds_read_b128 v[170:173], v192 offset:18432
	ds_read_b128 v[174:177], v192 offset:19456
	ds_read_b128 v[178:181], v192 offset:20480
	ds_read_b128 v[182:185], v192 offset:21504
	ds_read_b128 v[196:199], v192 offset:22528
	ds_read_b128 v[200:203], v192 offset:23552
	global_load_lds_dwordx4 v[222:223], off
	v_lshl_add_u64 v[224:225], s[24:25], 0, v[158:159]
	s_mov_b32 m0, s34
	s_nop 0
	global_load_lds_dwordx4 v[224:225], off
	s_barrier
	s_waitcnt lgkmcnt(0)
	s_waitcnt lgkmcnt(0)
	v_mfma_f32_16x16x32_bf16 v[60:63], v[128:131], v[144:147], 0
	v_mfma_f32_16x16x32_bf16 v[56:59], v[136:139], v[144:147], 0
	v_mfma_f32_16x16x32_bf16 v[44:47], v[128:131], v[170:173], 0
	v_mfma_f32_16x16x32_bf16 v[40:43], v[136:139], v[170:173], 0
	v_mfma_f32_16x16x32_bf16 v[28:31], v[128:131], v[178:181], 0
	v_mfma_f32_16x16x32_bf16 v[24:27], v[136:139], v[178:181], 0
	v_mfma_f32_16x16x32_bf16 v[12:15], v[128:131], v[196:199], 0
	v_mfma_f32_16x16x32_bf16 v[8:11], v[136:139], v[196:199], 0
	v_mfma_f32_16x16x32_bf16 v[60:63], v[132:135], v[148:151], v[60:63]
	v_mfma_f32_16x16x32_bf16 v[56:59], v[140:143], v[148:151], v[56:59]
	v_mfma_f32_16x16x32_bf16 v[44:47], v[132:135], v[174:177], v[44:47]
	v_mfma_f32_16x16x32_bf16 v[40:43], v[140:143], v[174:177], v[40:43]
	v_mfma_f32_16x16x32_bf16 v[28:31], v[132:135], v[182:185], v[28:31]
	v_mfma_f32_16x16x32_bf16 v[24:27], v[140:143], v[182:185], v[24:27]
	v_mfma_f32_16x16x32_bf16 v[12:15], v[132:135], v[200:203], v[12:15]
	v_mfma_f32_16x16x32_bf16 v[8:11], v[140:143], v[200:203], v[8:11]
	s_barrier
; #define PG8_STAGE(bufoff, gbase, voff) do { _Pragma("unroll") for (int _i = 0; _i < 2; ++_i) \
;         __builtin_amdgcn_global_load_lds((const unsigned*)((const char*)(gbase) + (voff)[_i]), (LAS unsigned*)(lds + (bufoff) + ldsw + _i * 8192), 16, 0, 0); } while (0)
; #define PG8_LDA(dst, b, h) do { _Pragma("unroll") for (int m = 0; m < 4; ++m) _Pragma("unroll") for (int k = 0; k < 2; ++k) dst[m][k] = *(const LAS bf16x8*)(lds + PG8_SA(b, h) + aoff + m * 2048 + k * 1024); } while (0)
; #define PG8_LDB(dst, b, h) do { _Pragma("unroll") for (int n = 0; n < 2; ++n) _Pragma("unroll") for (int k = 0; k < 2; ++k) dst[n][k] = *(const LAS bf16x8*)(lds + PG8_SB(b, h) + boff + n * 2048 + k * 1024); } while (0)
; #define PG8_MMA(ai, bj, At, Bt) do { __builtin_amdgcn_s_setprio(1); _Pragma("unroll") for (int m = 0; m < 4; ++m) _Pragma("unroll") for (int n = 0; n < 2; ++n) _Pragma("unroll") for (int k = 0; k < 2; ++k) \
;         acc[ai][bj][m][n] = __builtin_amdgcn_mfma_f32_16x16x32_bf16(Bt[n][k], At[m][k], acc[ai][bj][m][n], 0, 0, 0); __builtin_amdgcn_s_setprio(0); } while (0)
; #define PG8_WAIT_V(n) asm volatile("s_waitcnt vmcnt(" #n ")" ::: "memory")
; #define PG8_WAIT_L(n) asm volatile("s_waitcnt lgkmcnt(" #n ")" ::: "memory")
; #define PG8_BAR __builtin_amdgcn_s_barrier()
; #define PG8_SCHED __builtin_amdgcn_sched_barrier(0)
; template <class Epi>
; __device__ __forceinline__ void gemm_phase(LAS unsigned char* lds, const Gemm g, const StaticOrder& S, const Epi& E) {
;     ...
;             PG8_STAGE(PG8_SB(0, 1), b2 + hstepB, voffB);
;             PG8_WAIT_V(6); PG8_BAR; PG8_MMA(1, 1, At, B1); PG8_BAR;
;             PG8_LDB(B0, 1, 0); PG8_SCHED; PG8_LDA(At, 1, 0); PG8_STAGE(PG8_SA(0, 1), a2 + hstepA, voffA);
;             PG8_WAIT_L(8); PG8_BAR; PG8_WAIT_L(0); PG8_MMA(0, 0, At, B0); PG8_BAR; PG8_SCHED;
;             PG8_LDB(B1, 1, 1); PG8_STAGE(PG8_SB(1, 0), b3, voffB);
;             PG8_BAR; PG8_WAIT_L(0); PG8_MMA(0, 1, At, B1); PG8_BAR;
;             PG8_LDA(At, 1, 1); PG8_STAGE(PG8_SA(1, 0), a3, voffA);
	s_add_u32 s50, s22, 0x80000
	s_addc_u32 s51, s23, 0
	s_add_i32 s49, s43, s31
	v_lshl_add_u64 v[128:129], s[50:51], 0, v[156:157]
	s_mov_b32 m0, s49
	s_nop 0
	global_load_lds_dwordx4 v[128:129], off
	v_lshl_add_u64 v[128:129], s[50:51], 0, v[160:161]
	s_add_i32 m0, s49, 0x2000
	s_nop 0
	global_load_lds_dwordx4 v[128:129], off
	s_waitcnt vmcnt(6)
	s_barrier
	v_mfma_f32_16x16x32_bf16 v[52:55], v[204:207], v[144:147], 0
	v_mfma_f32_16x16x32_bf16 v[48:51], v[212:215], v[144:147], 0
	v_mfma_f32_16x16x32_bf16 v[36:39], v[204:207], v[170:173], 0
	v_mfma_f32_16x16x32_bf16 v[32:35], v[212:215], v[170:173], 0
	v_mfma_f32_16x16x32_bf16 v[20:23], v[204:207], v[178:181], 0
	v_mfma_f32_16x16x32_bf16 v[16:19], v[212:215], v[178:181], 0
	v_mfma_f32_16x16x32_bf16 v[4:7], v[204:207], v[196:199], 0
	v_mfma_f32_16x16x32_bf16 v[0:3], v[212:215], v[196:199], 0
	v_mfma_f32_16x16x32_bf16 v[52:55], v[208:211], v[148:151], v[52:55]
	v_mfma_f32_16x16x32_bf16 v[48:51], v[216:219], v[148:151], v[48:51]
	v_mfma_f32_16x16x32_bf16 v[36:39], v[208:211], v[174:177], v[36:39]
	v_mfma_f32_16x16x32_bf16 v[32:35], v[216:219], v[174:177], v[32:35]
	v_mfma_f32_16x16x32_bf16 v[20:23], v[208:211], v[182:185], v[20:23]
	v_mfma_f32_16x16x32_bf16 v[16:19], v[216:219], v[182:185], v[16:19]
	v_mfma_f32_16x16x32_bf16 v[4:7], v[208:211], v[200:203], v[4:7]
	v_mfma_f32_16x16x32_bf16 v[0:3], v[216:219], v[200:203], v[0:3]
	s_add_i32 s49, 0, 0x18000
	v_add_u32_e32 v140, s49, v189
	s_barrier
	ds_read_b128 v[128:131], v140
	ds_read_b128 v[132:135], v140 offset:1024
	ds_read_b128 v[136:139], v140 offset:2048
	ds_read_b128 v[140:143], v140 offset:3072
	s_add_u32 s24, s24, 0x140000
	s_addc_u32 s25, s25, 0
	s_mov_b32 m0, s35
	v_lshl_add_u64 v[204:205], s[24:25], 0, v[154:155]
	ds_read_b128 v[144:147], v192 offset:32768
	ds_read_b128 v[148:151], v192 offset:33792
	ds_read_b128 v[170:173], v192 offset:34816
	ds_read_b128 v[174:177], v192 offset:35840
	ds_read_b128 v[178:181], v192 offset:36864
	ds_read_b128 v[182:185], v192 offset:37888
	ds_read_b128 v[196:199], v192 offset:38912
	ds_read_b128 v[200:203], v192 offset:39936
	global_load_lds_dwordx4 v[204:205], off
	v_lshl_add_u64 v[204:205], s[24:25], 0, v[158:159]
	s_mov_b32 m0, s36
	s_nop 0
	global_load_lds_dwordx4 v[204:205], off
	s_waitcnt lgkmcnt(8)
	s_barrier
	s_waitcnt lgkmcnt(0)
	s_waitcnt lgkmcnt(0)
	v_mfma_f32_16x16x32_bf16 v[124:127], v[128:131], v[144:147], v[124:127]
	v_mfma_f32_16x16x32_bf16 v[120:123], v[136:139], v[144:147], v[120:123]
	v_mfma_f32_16x16x32_bf16 v[108:111], v[128:131], v[170:173], v[108:111]
	v_mfma_f32_16x16x32_bf16 v[104:107], v[136:139], v[170:173], v[104:107]
	v_mfma_f32_16x16x32_bf16 v[92:95], v[128:131], v[178:181], v[92:95]
	v_mfma_f32_16x16x32_bf16 v[88:91], v[136:139], v[178:181], v[88:91]
	v_mfma_f32_16x16x32_bf16 v[76:79], v[128:131], v[196:199], v[76:79]
	v_mfma_f32_16x16x32_bf16 v[72:75], v[136:139], v[196:199], v[72:75]
	v_mfma_f32_16x16x32_bf16 v[124:127], v[132:135], v[148:151], v[124:127]
	v_mfma_f32_16x16x32_bf16 v[120:123], v[140:143], v[148:151], v[120:123]
	v_mfma_f32_16x16x32_bf16 v[108:111], v[132:135], v[174:177], v[108:111]
	v_mfma_f32_16x16x32_bf16 v[104:107], v[140:143], v[174:177], v[104:107]
	v_mfma_f32_16x16x32_bf16 v[92:95], v[132:135], v[182:185], v[92:95]
	v_mfma_f32_16x16x32_bf16 v[88:91], v[140:143], v[182:185], v[88:91]
	v_mfma_f32_16x16x32_bf16 v[76:79], v[132:135], v[200:203], v[76:79]
	v_mfma_f32_16x16x32_bf16 v[72:75], v[140:143], v[200:203], v[72:75]
	s_barrier
	s_add_i32 s24, 0, 0x1c000
	s_add_i32 s25, s49, s31
	v_add_u32_e32 v195, s24, v189
	v_lshl_add_u64 v[186:187], v[186:187], 0, s[14:15]
	s_mov_b32 m0, s25
	ds_read_b128 v[204:207], v195
	ds_read_b128 v[208:211], v195 offset:1024
	ds_read_b128 v[212:215], v195 offset:2048
	ds_read_b128 v[216:219], v195 offset:3072
	global_load_lds_dwordx4 v[186:187], off
	v_lshl_add_u64 v[186:187], v[220:221], 0, s[14:15]
	s_add_i32 m0, s25, 0x2000
	s_nop 0
	global_load_lds_dwordx4 v[186:187], off
	s_barrier
	s_waitcnt lgkmcnt(0)
	s_waitcnt lgkmcnt(0)
	v_mfma_f32_16x16x32_bf16 v[116:119], v[204:207], v[144:147], v[116:119]
	v_mfma_f32_16x16x32_bf16 v[112:115], v[212:215], v[144:147], v[112:115]
	v_mfma_f32_16x16x32_bf16 v[100:103], v[204:207], v[170:173], v[100:103]
	v_mfma_f32_16x16x32_bf16 v[96:99], v[212:215], v[170:173], v[96:99]
	v_mfma_f32_16x16x32_bf16 v[84:87], v[204:207], v[178:181], v[84:87]
	v_mfma_f32_16x16x32_bf16 v[80:83], v[212:215], v[178:181], v[80:83]
	v_mfma_f32_16x16x32_bf16 v[68:71], v[204:207], v[196:199], v[68:71]
	v_mfma_f32_16x16x32_bf16 v[64:67], v[212:215], v[196:199], v[64:67]
	v_mfma_f32_16x16x32_bf16 v[116:119], v[208:211], v[148:151], v[116:119]
	v_mfma_f32_16x16x32_bf16 v[112:115], v[216:219], v[148:151], v[112:115]
	v_mfma_f32_16x16x32_bf16 v[100:103], v[208:211], v[174:177], v[100:103]
	v_mfma_f32_16x16x32_bf16 v[96:99], v[216:219], v[174:177], v[96:99]
	v_mfma_f32_16x16x32_bf16 v[84:87], v[208:211], v[182:185], v[84:87]
	v_mfma_f32_16x16x32_bf16 v[80:83], v[216:219], v[182:185], v[80:83]
	v_mfma_f32_16x16x32_bf16 v[68:71], v[208:211], v[200:203], v[68:71]
	v_mfma_f32_16x16x32_bf16 v[64:67], v[216:219], v[200:203], v[64:67]
	s_mov_b32 m0, s38
	v_lshl_add_u64 v[186:187], v[222:223], 0, s[14:15]
	s_barrier
	ds_read_b128 v[144:147], v192 offset:49152
	ds_read_b128 v[148:151], v192 offset:50176
	ds_read_b128 v[170:173], v192 offset:51200
	ds_read_b128 v[174:177], v192 offset:52224
	ds_read_b128 v[178:181], v192 offset:53248
	ds_read_b128 v[182:185], v192 offset:54272
	ds_read_b128 v[196:199], v192 offset:55296
	ds_read_b128 v[200:203], v192 offset:56320
	global_load_lds_dwordx4 v[186:187], off
	v_lshl_add_u64 v[186:187], v[224:225], 0, s[14:15]
	s_mov_b32 m0, s39
	s_nop 0
	global_load_lds_dwordx4 v[186:187], off
	s_barrier
; #define PG8_STAGE(bufoff, gbase, voff) do { _Pragma("unroll") for (int _i = 0; _i < 2; ++_i) \
;         __builtin_amdgcn_global_load_lds((const unsigned*)((const char*)(gbase) + (voff)[_i]), (LAS unsigned*)(lds + (bufoff) + ldsw + _i * 8192), 16, 0, 0); } while (0)
; #define PG8_LDA(dst, b, h) do { _Pragma("unroll") for (int m = 0; m < 4; ++m) _Pragma("unroll") for (int k = 0; k < 2; ++k) dst[m][k] = *(const LAS bf16x8*)(lds + PG8_SA(b, h) + aoff + m * 2048 + k * 1024); } while (0)
; #define PG8_LDB(dst, b, h) do { _Pragma("unroll") for (int n = 0; n < 2; ++n) _Pragma("unroll") for (int k = 0; k < 2; ++k) dst[n][k] = *(const LAS bf16x8*)(lds + PG8_SB(b, h) + boff + n * 2048 + k * 1024); } while (0)
; #define PG8_MMA(ai, bj, At, Bt) do { __builtin_amdgcn_s_setprio(1); _Pragma("unroll") for (int m = 0; m < 4; ++m) _Pragma("unroll") for (int n = 0; n < 2; ++n) _Pragma("unroll") for (int k = 0; k < 2; ++k) \
;         acc[ai][bj][m][n] = __builtin_amdgcn_mfma_f32_16x16x32_bf16(Bt[n][k], At[m][k], acc[ai][bj][m][n], 0, 0, 0); __builtin_amdgcn_s_setprio(0); } while (0)
; #define PG8_WAIT_V(n) asm volatile("s_waitcnt vmcnt(" #n ")" ::: "memory")
; #define PG8_WAIT_L(n) asm volatile("s_waitcnt lgkmcnt(" #n ")" ::: "memory")
; #define PG8_BAR __builtin_amdgcn_s_barrier()
; #define PG8_SCHED __builtin_amdgcn_sched_barrier(0)
; template <class Epi>
; __device__ __forceinline__ void gemm_phase(LAS unsigned char* lds, const Gemm g, const StaticOrder& S, const Epi& E) {
;     ...
;             PG8_LDB(B0, 0, 0); PG8_SCHED; PG8_LDA(At, 0, 0); PG8_STAGE(PG8_SA(1, 1), a1 + hstepA, voffA);
;             PG8_WAIT_L(8); PG8_BAR; PG8_WAIT_L(0); PG8_MMA(0, 0, At, B0); PG8_BAR; PG8_SCHED;
;             PG8_LDB(B1, 0, 1); PG8_STAGE(PG8_SB(0, 0), b2, voffB);
;     ...
;             PG8_BAR; PG8_WAIT_L(0); PG8_MMA(1, 0, At, B0); PG8_BAR; PG8_SCHED;
;             PG8_STAGE(PG8_SB(1, 1), b3 + hstepB, voffB);
;             PG8_WAIT_V(6); PG8_BAR; PG8_MMA(1, 1, At, B1); PG8_BAR;
	s_waitcnt lgkmcnt(0)
	s_waitcnt lgkmcnt(0)
	v_mfma_f32_16x16x32_bf16 v[60:63], v[128:131], v[144:147], v[60:63]
	v_mfma_f32_16x16x32_bf16 v[56:59], v[136:139], v[144:147], v[56:59]
	v_mfma_f32_16x16x32_bf16 v[44:47], v[128:131], v[170:173], v[44:47]
	v_mfma_f32_16x16x32_bf16 v[40:43], v[136:139], v[170:173], v[40:43]
	v_mfma_f32_16x16x32_bf16 v[28:31], v[128:131], v[178:181], v[28:31]
	v_mfma_f32_16x16x32_bf16 v[24:27], v[136:139], v[178:181], v[24:27]
	v_mfma_f32_16x16x32_bf16 v[12:15], v[128:131], v[196:199], v[12:15]
	v_mfma_f32_16x16x32_bf16 v[8:11], v[136:139], v[196:199], v[8:11]
	v_mfma_f32_16x16x32_bf16 v[60:63], v[132:135], v[148:151], v[60:63]
	v_mfma_f32_16x16x32_bf16 v[56:59], v[140:143], v[148:151], v[56:59]
	v_mfma_f32_16x16x32_bf16 v[44:47], v[132:135], v[174:177], v[44:47]
	v_mfma_f32_16x16x32_bf16 v[40:43], v[140:143], v[174:177], v[40:43]
	v_mfma_f32_16x16x32_bf16 v[28:31], v[132:135], v[182:185], v[28:31]
	v_mfma_f32_16x16x32_bf16 v[24:27], v[140:143], v[182:185], v[24:27]
	v_mfma_f32_16x16x32_bf16 v[12:15], v[132:135], v[200:203], v[12:15]
	v_mfma_f32_16x16x32_bf16 v[8:11], v[140:143], v[200:203], v[8:11]
	s_barrier
	s_add_u32 s22, s22, 0x80080
	s_addc_u32 s23, s23, 0
	s_add_i32 s24, s24, s31
	v_lshl_add_u64 v[128:129], s[22:23], 0, v[156:157]
	s_mov_b32 m0, s24
	s_nop 0
	global_load_lds_dwordx4 v[128:129], off
	v_lshl_add_u64 v[128:129], s[22:23], 0, v[160:161]
	s_add_i32 m0, s24, 0x2000
	s_nop 0
	global_load_lds_dwordx4 v[128:129], off
	s_waitcnt vmcnt(6)
	s_barrier
	v_mfma_f32_16x16x32_bf16 v[52:55], v[204:207], v[144:147], v[52:55]
	v_mfma_f32_16x16x32_bf16 v[48:51], v[212:215], v[144:147], v[48:51]
	v_mfma_f32_16x16x32_bf16 v[36:39], v[204:207], v[170:173], v[36:39]
	v_mfma_f32_16x16x32_bf16 v[32:35], v[212:215], v[170:173], v[32:35]
	v_mfma_f32_16x16x32_bf16 v[20:23], v[204:207], v[178:181], v[20:23]
	v_mfma_f32_16x16x32_bf16 v[16:19], v[212:215], v[178:181], v[16:19]
	v_mfma_f32_16x16x32_bf16 v[4:7], v[204:207], v[196:199], v[4:7]
	v_mfma_f32_16x16x32_bf16 v[0:3], v[212:215], v[196:199], v[0:3]
	v_mfma_f32_16x16x32_bf16 v[52:55], v[208:211], v[148:151], v[52:55]
	v_mfma_f32_16x16x32_bf16 v[48:51], v[216:219], v[148:151], v[48:51]
	v_mfma_f32_16x16x32_bf16 v[36:39], v[208:211], v[174:177], v[36:39]
	v_mfma_f32_16x16x32_bf16 v[32:35], v[216:219], v[174:177], v[32:35]
	v_mfma_f32_16x16x32_bf16 v[20:23], v[208:211], v[182:185], v[20:23]
	v_mfma_f32_16x16x32_bf16 v[16:19], v[216:219], v[182:185], v[16:19]
	v_mfma_f32_16x16x32_bf16 v[4:7], v[208:211], v[200:203], v[4:7]
	v_mfma_f32_16x16x32_bf16 v[0:3], v[216:219], v[200:203], v[0:3]
	s_add_i32 s48, s48, 2
	s_add_u32 s4, s4, 0x100
	s_addc_u32 s5, s5, 0
	s_add_u32 s46, s46, 0x100
	s_addc_u32 s47, s47, 0
	s_cmp_gt_u32 s48, 29
	s_barrier
.LBB0_684:
	ds_read_b128 v[128:131], v191
	ds_read_b128 v[132:135], v191 offset:1024
	ds_read_b128 v[136:139], v191 offset:2048
	ds_read_b128 v[140:143], v191 offset:3072
	s_add_u32 s22, s4, 0xffec0080
	s_addc_u32 s23, s5, -1
	s_cmp_eq_u32 s48, 28
	s_cselect_b32 s25, s19, s23
	s_cselect_b32 s24, s18, s22
	s_cselect_b32 s23, s17, s47
	s_cselect_b32 s22, s45, s46
	v_lshl_add_u64 v[186:187], s[4:5], 0, v[162:163]
	s_add_i32 m0, s11, 0xc000
	ds_read_b128 v[144:147], v192
	ds_read_b128 v[148:151], v192 offset:1024
	ds_read_b128 v[170:173], v192 offset:2048
	ds_read_b128 v[174:177], v192 offset:3072
	ds_read_b128 v[178:181], v192 offset:4096
	ds_read_b128 v[182:185], v192 offset:5120
	ds_read_b128 v[196:199], v192 offset:6144
	ds_read_b128 v[200:203], v192 offset:7168
	global_load_lds_dwordx4 v[186:187], off
	v_lshl_add_u64 v[186:187], s[4:5], 0, v[164:165]
	s_add_i32 m0, s11, 0xe000
	s_nop 0
	global_load_lds_dwordx4 v[186:187], off
	s_waitcnt lgkmcnt(8)
	s_barrier
	s_waitcnt lgkmcnt(0)
	s_waitcnt lgkmcnt(0)
	v_mfma_f32_16x16x32_bf16 v[124:127], v[128:131], v[144:147], v[124:127]
	v_mfma_f32_16x16x32_bf16 v[120:123], v[136:139], v[144:147], v[120:123]
	v_mfma_f32_16x16x32_bf16 v[108:111], v[128:131], v[170:173], v[108:111]
	v_mfma_f32_16x16x32_bf16 v[104:107], v[136:139], v[170:173], v[104:107]
	v_mfma_f32_16x16x32_bf16 v[92:95], v[128:131], v[178:181], v[92:95]
	v_mfma_f32_16x16x32_bf16 v[88:91], v[136:139], v[178:181], v[88:91]
	v_mfma_f32_16x16x32_bf16 v[76:79], v[128:131], v[196:199], v[76:79]
	v_mfma_f32_16x16x32_bf16 v[72:75], v[136:139], v[196:199], v[72:75]
	v_mfma_f32_16x16x32_bf16 v[124:127], v[132:135], v[148:151], v[124:127]
	v_mfma_f32_16x16x32_bf16 v[120:123], v[140:143], v[148:151], v[120:123]
	v_mfma_f32_16x16x32_bf16 v[108:111], v[132:135], v[174:177], v[108:111]
	v_mfma_f32_16x16x32_bf16 v[104:107], v[140:143], v[174:177], v[104:107]
	v_mfma_f32_16x16x32_bf16 v[92:95], v[132:135], v[182:185], v[92:95]
	v_mfma_f32_16x16x32_bf16 v[88:91], v[140:143], v[182:185], v[88:91]
	v_mfma_f32_16x16x32_bf16 v[76:79], v[132:135], v[200:203], v[76:79]
	v_mfma_f32_16x16x32_bf16 v[72:75], v[140:143], v[200:203], v[72:75]
	s_barrier
	s_add_i32 s49, s42, s31
	v_lshl_add_u64 v[186:187], s[22:23], 0, v[156:157]
	s_mov_b32 m0, s49
	ds_read_b128 v[204:207], v193
	ds_read_b128 v[208:211], v193 offset:1024
	ds_read_b128 v[212:215], v193 offset:2048
	ds_read_b128 v[216:219], v193 offset:3072
	global_load_lds_dwordx4 v[186:187], off
	v_lshl_add_u64 v[220:221], s[22:23], 0, v[160:161]
	s_add_i32 m0, s49, 0x2000
	s_nop 0
	global_load_lds_dwordx4 v[220:221], off
	s_barrier
; #define PG8_STAGE(bufoff, gbase, voff) do { _Pragma("unroll") for (int _i = 0; _i < 2; ++_i) \
;         __builtin_amdgcn_global_load_lds((const unsigned*)((const char*)(gbase) + (voff)[_i]), (LAS unsigned*)(lds + (bufoff) + ldsw + _i * 8192), 16, 0, 0); } while (0)
; #define PG8_LDA(dst, b, h) do { _Pragma("unroll") for (int m = 0; m < 4; ++m) _Pragma("unroll") for (int k = 0; k < 2; ++k) dst[m][k] = *(const LAS bf16x8*)(lds + PG8_SA(b, h) + aoff + m * 2048 + k * 1024); } while (0)
; #define PG8_LDB(dst, b, h) do { _Pragma("unroll") for (int n = 0; n < 2; ++n) _Pragma("unroll") for (int k = 0; k < 2; ++k) dst[n][k] = *(const LAS bf16x8*)(lds + PG8_SB(b, h) + boff + n * 2048 + k * 1024); } while (0)
; #define PG8_MMA(ai, bj, At, Bt) do { __builtin_amdgcn_s_setprio(1); _Pragma("unroll") for (int m = 0; m < 4; ++m) _Pragma("unroll") for (int n = 0; n < 2; ++n) _Pragma("unroll") for (int k = 0; k < 2; ++k) \
;         acc[ai][bj][m][n] = __builtin_amdgcn_mfma_f32_16x16x32_bf16(Bt[n][k], At[m][k], acc[ai][bj][m][n], 0, 0, 0); __builtin_amdgcn_s_setprio(0); } while (0)
; #define PG8_WAIT_V(n) asm volatile("s_waitcnt vmcnt(" #n ")" ::: "memory")
; #define PG8_WAIT_L(n) asm volatile("s_waitcnt lgkmcnt(" #n ")" ::: "memory")
; #define PG8_BAR __builtin_amdgcn_s_barrier()
; #define PG8_SCHED __builtin_amdgcn_sched_barrier(0)
; template <class Epi>
; __device__ __forceinline__ void gemm_phase(LAS unsigned char* lds, const Gemm g, const StaticOrder& S, const Epi& E) {
;     ...
;             PG8_BAR; PG8_WAIT_L(0); PG8_MMA(0, 1, At, B1); PG8_BAR;
;             PG8_LDA(At, 0, 1); PG8_STAGE(PG8_SA(0, 0), a2, voffA);
;             PG8_BAR; PG8_WAIT_L(0); PG8_MMA(1, 0, At, B0); PG8_BAR; PG8_SCHED;
;             PG8_STAGE(PG8_SB(0, 1), b2 + hstepB, voffB);
;             PG8_WAIT_V(6); PG8_BAR; PG8_MMA(1, 1, At, B1); PG8_BAR;
;             PG8_LDB(B0, 1, 0); PG8_SCHED; PG8_LDA(At, 1, 0); PG8_STAGE(PG8_SA(0, 1), a2 + hstepA, voffA);
	s_waitcnt lgkmcnt(0)
	s_waitcnt lgkmcnt(0)
	v_mfma_f32_16x16x32_bf16 v[116:119], v[204:207], v[144:147], v[116:119]
	v_mfma_f32_16x16x32_bf16 v[112:115], v[212:215], v[144:147], v[112:115]
	v_mfma_f32_16x16x32_bf16 v[100:103], v[204:207], v[170:173], v[100:103]
	v_mfma_f32_16x16x32_bf16 v[96:99], v[212:215], v[170:173], v[96:99]
	v_mfma_f32_16x16x32_bf16 v[84:87], v[204:207], v[178:181], v[84:87]
	v_mfma_f32_16x16x32_bf16 v[80:83], v[212:215], v[178:181], v[80:83]
	v_mfma_f32_16x16x32_bf16 v[68:71], v[204:207], v[196:199], v[68:71]
	v_mfma_f32_16x16x32_bf16 v[64:67], v[212:215], v[196:199], v[64:67]
	v_mfma_f32_16x16x32_bf16 v[116:119], v[208:211], v[148:151], v[116:119]
	v_mfma_f32_16x16x32_bf16 v[112:115], v[216:219], v[148:151], v[112:115]
	v_mfma_f32_16x16x32_bf16 v[100:103], v[208:211], v[174:177], v[100:103]
	v_mfma_f32_16x16x32_bf16 v[96:99], v[216:219], v[174:177], v[96:99]
	v_mfma_f32_16x16x32_bf16 v[84:87], v[208:211], v[182:185], v[84:87]
	v_mfma_f32_16x16x32_bf16 v[80:83], v[216:219], v[182:185], v[80:83]
	v_mfma_f32_16x16x32_bf16 v[68:71], v[208:211], v[200:203], v[68:71]
	v_mfma_f32_16x16x32_bf16 v[64:67], v[216:219], v[200:203], v[64:67]
	s_mov_b32 m0, s11
	v_lshl_add_u64 v[222:223], s[24:25], 0, v[154:155]
	s_barrier
	ds_read_b128 v[144:147], v192 offset:16384
	ds_read_b128 v[148:151], v192 offset:17408
	ds_read_b128 v[170:173], v192 offset:18432
	ds_read_b128 v[174:177], v192 offset:19456
	ds_read_b128 v[178:181], v192 offset:20480
	ds_read_b128 v[182:185], v192 offset:21504
	ds_read_b128 v[196:199], v192 offset:22528
	ds_read_b128 v[200:203], v192 offset:23552
	global_load_lds_dwordx4 v[222:223], off
	v_lshl_add_u64 v[224:225], s[24:25], 0, v[158:159]
	s_mov_b32 m0, s34
	s_nop 0
	global_load_lds_dwordx4 v[224:225], off
	s_barrier
	s_waitcnt lgkmcnt(0)
	s_waitcnt lgkmcnt(0)
	v_mfma_f32_16x16x32_bf16 v[60:63], v[128:131], v[144:147], v[60:63]
	v_mfma_f32_16x16x32_bf16 v[56:59], v[136:139], v[144:147], v[56:59]
	v_mfma_f32_16x16x32_bf16 v[44:47], v[128:131], v[170:173], v[44:47]
	v_mfma_f32_16x16x32_bf16 v[40:43], v[136:139], v[170:173], v[40:43]
	v_mfma_f32_16x16x32_bf16 v[28:31], v[128:131], v[178:181], v[28:31]
	v_mfma_f32_16x16x32_bf16 v[24:27], v[136:139], v[178:181], v[24:27]
	v_mfma_f32_16x16x32_bf16 v[12:15], v[128:131], v[196:199], v[12:15]
	v_mfma_f32_16x16x32_bf16 v[8:11], v[136:139], v[196:199], v[8:11]
	v_mfma_f32_16x16x32_bf16 v[60:63], v[132:135], v[148:151], v[60:63]
	v_mfma_f32_16x16x32_bf16 v[56:59], v[140:143], v[148:151], v[56:59]
	v_mfma_f32_16x16x32_bf16 v[44:47], v[132:135], v[174:177], v[44:47]
	v_mfma_f32_16x16x32_bf16 v[40:43], v[140:143], v[174:177], v[40:43]
	v_mfma_f32_16x16x32_bf16 v[28:31], v[132:135], v[182:185], v[28:31]
	v_mfma_f32_16x16x32_bf16 v[24:27], v[140:143], v[182:185], v[24:27]
	v_mfma_f32_16x16x32_bf16 v[12:15], v[132:135], v[200:203], v[12:15]
	v_mfma_f32_16x16x32_bf16 v[8:11], v[140:143], v[200:203], v[8:11]
	s_barrier
	s_add_u32 s50, s22, 0x80000
	s_addc_u32 s51, s23, 0
	s_add_i32 s49, s43, s31
	v_lshl_add_u64 v[128:129], s[50:51], 0, v[156:157]
	s_mov_b32 m0, s49
	s_nop 0
	global_load_lds_dwordx4 v[128:129], off
	v_lshl_add_u64 v[128:129], s[50:51], 0, v[160:161]
	s_add_i32 m0, s49, 0x2000
	s_nop 0
	global_load_lds_dwordx4 v[128:129], off
	s_waitcnt vmcnt(6)
	s_barrier
	v_mfma_f32_16x16x32_bf16 v[52:55], v[204:207], v[144:147], v[52:55]
	v_mfma_f32_16x16x32_bf16 v[48:51], v[212:215], v[144:147], v[48:51]
	v_mfma_f32_16x16x32_bf16 v[36:39], v[204:207], v[170:173], v[36:39]
	v_mfma_f32_16x16x32_bf16 v[32:35], v[212:215], v[170:173], v[32:35]
	v_mfma_f32_16x16x32_bf16 v[20:23], v[204:207], v[178:181], v[20:23]
	v_mfma_f32_16x16x32_bf16 v[16:19], v[212:215], v[178:181], v[16:19]
	v_mfma_f32_16x16x32_bf16 v[4:7], v[204:207], v[196:199], v[4:7]
	v_mfma_f32_16x16x32_bf16 v[0:3], v[212:215], v[196:199], v[0:3]
	v_mfma_f32_16x16x32_bf16 v[52:55], v[208:211], v[148:151], v[52:55]
	v_mfma_f32_16x16x32_bf16 v[48:51], v[216:219], v[148:151], v[48:51]
	v_mfma_f32_16x16x32_bf16 v[36:39], v[208:211], v[174:177], v[36:39]
	v_mfma_f32_16x16x32_bf16 v[32:35], v[216:219], v[174:177], v[32:35]
	v_mfma_f32_16x16x32_bf16 v[20:23], v[208:211], v[182:185], v[20:23]
	v_mfma_f32_16x16x32_bf16 v[16:19], v[216:219], v[182:185], v[16:19]
	v_mfma_f32_16x16x32_bf16 v[4:7], v[208:211], v[200:203], v[4:7]
	v_mfma_f32_16x16x32_bf16 v[0:3], v[216:219], v[200:203], v[0:3]
	s_add_i32 s49, 0, 0x18000
	v_add_u32_e32 v140, s49, v189
	s_barrier
	ds_read_b128 v[128:131], v140
	ds_read_b128 v[132:135], v140 offset:1024
	ds_read_b128 v[136:139], v140 offset:2048
	ds_read_b128 v[140:143], v140 offset:3072
	s_add_u32 s24, s24, 0x140000
	s_addc_u32 s25, s25, 0
	s_mov_b32 m0, s35
	v_lshl_add_u64 v[204:205], s[24:25], 0, v[154:155]
	ds_read_b128 v[144:147], v192 offset:32768
	ds_read_b128 v[148:151], v192 offset:33792
	ds_read_b128 v[170:173], v192 offset:34816
	ds_read_b128 v[174:177], v192 offset:35840
	ds_read_b128 v[178:181], v192 offset:36864
	ds_read_b128 v[182:185], v192 offset:37888
	ds_read_b128 v[196:199], v192 offset:38912
	ds_read_b128 v[200:203], v192 offset:39936
	global_load_lds_dwordx4 v[204:205], off
	v_lshl_add_u64 v[204:205], s[24:25], 0, v[158:159]
	s_mov_b32 m0, s36
	s_nop 0
	global_load_lds_dwordx4 v[204:205], off
	s_waitcnt lgkmcnt(8)
	s_barrier
; #define PG8_STAGE(bufoff, gbase, voff) do { _Pragma("unroll") for (int _i = 0; _i < 2; ++_i) \
;         __builtin_amdgcn_global_load_lds((const unsigned*)((const char*)(gbase) + (voff)[_i]), (LAS unsigned*)(lds + (bufoff) + ldsw + _i * 8192), 16, 0, 0); } while (0)
; #define PG8_LDA(dst, b, h) do { _Pragma("unroll") for (int m = 0; m < 4; ++m) _Pragma("unroll") for (int k = 0; k < 2; ++k) dst[m][k] = *(const LAS bf16x8*)(lds + PG8_SA(b, h) + aoff + m * 2048 + k * 1024); } while (0)
; #define PG8_LDB(dst, b, h) do { _Pragma("unroll") for (int n = 0; n < 2; ++n) _Pragma("unroll") for (int k = 0; k < 2; ++k) dst[n][k] = *(const LAS bf16x8*)(lds + PG8_SB(b, h) + boff + n * 2048 + k * 1024); } while (0)
; #define PG8_MMA(ai, bj, At, Bt) do { __builtin_amdgcn_s_setprio(1); _Pragma("unroll") for (int m = 0; m < 4; ++m) _Pragma("unroll") for (int n = 0; n < 2; ++n) _Pragma("unroll") for (int k = 0; k < 2; ++k) \
;         acc[ai][bj][m][n] = __builtin_amdgcn_mfma_f32_16x16x32_bf16(Bt[n][k], At[m][k], acc[ai][bj][m][n], 0, 0, 0); __builtin_amdgcn_s_setprio(0); } while (0)
; #define PG8_WAIT_V(n) asm volatile("s_waitcnt vmcnt(" #n ")" ::: "memory")
; #define PG8_WAIT_L(n) asm volatile("s_waitcnt lgkmcnt(" #n ")" ::: "memory")
; #define PG8_BAR __builtin_amdgcn_s_barrier()
; #define PG8_SCHED __builtin_amdgcn_sched_barrier(0)
; template <class Epi>
; __device__ __forceinline__ void gemm_phase(LAS unsigned char* lds, const Gemm g, const StaticOrder& S, const Epi& E) {
;     ...
;             PG8_WAIT_L(8); PG8_BAR; PG8_WAIT_L(0); PG8_MMA(0, 0, At, B0); PG8_BAR; PG8_SCHED;
;             PG8_LDB(B1, 1, 1); PG8_STAGE(PG8_SB(1, 0), b3, voffB);
;             PG8_BAR; PG8_WAIT_L(0); PG8_MMA(0, 1, At, B1); PG8_BAR;
;             PG8_LDA(At, 1, 1); PG8_STAGE(PG8_SA(1, 0), a3, voffA);
;             PG8_BAR; PG8_WAIT_L(0); PG8_MMA(1, 0, At, B0); PG8_BAR; PG8_SCHED;
;             PG8_STAGE(PG8_SB(1, 1), b3 + hstepB, voffB);
;             PG8_WAIT_V(6); PG8_BAR; PG8_MMA(1, 1, At, B1); PG8_BAR;
	s_waitcnt lgkmcnt(0)
	s_waitcnt lgkmcnt(0)
	v_mfma_f32_16x16x32_bf16 v[124:127], v[128:131], v[144:147], v[124:127]
	v_mfma_f32_16x16x32_bf16 v[120:123], v[136:139], v[144:147], v[120:123]
	v_mfma_f32_16x16x32_bf16 v[108:111], v[128:131], v[170:173], v[108:111]
	v_mfma_f32_16x16x32_bf16 v[104:107], v[136:139], v[170:173], v[104:107]
	v_mfma_f32_16x16x32_bf16 v[92:95], v[128:131], v[178:181], v[92:95]
	v_mfma_f32_16x16x32_bf16 v[88:91], v[136:139], v[178:181], v[88:91]
	v_mfma_f32_16x16x32_bf16 v[76:79], v[128:131], v[196:199], v[76:79]
	v_mfma_f32_16x16x32_bf16 v[72:75], v[136:139], v[196:199], v[72:75]
	v_mfma_f32_16x16x32_bf16 v[124:127], v[132:135], v[148:151], v[124:127]
	v_mfma_f32_16x16x32_bf16 v[120:123], v[140:143], v[148:151], v[120:123]
	v_mfma_f32_16x16x32_bf16 v[108:111], v[132:135], v[174:177], v[108:111]
	v_mfma_f32_16x16x32_bf16 v[104:107], v[140:143], v[174:177], v[104:107]
	v_mfma_f32_16x16x32_bf16 v[92:95], v[132:135], v[182:185], v[92:95]
	v_mfma_f32_16x16x32_bf16 v[88:91], v[140:143], v[182:185], v[88:91]
	v_mfma_f32_16x16x32_bf16 v[76:79], v[132:135], v[200:203], v[76:79]
	v_mfma_f32_16x16x32_bf16 v[72:75], v[140:143], v[200:203], v[72:75]
	s_barrier
	s_add_i32 s24, 0, 0x1c000
	s_add_i32 s25, s49, s31
	v_add_u32_e32 v195, s24, v189
	v_lshl_add_u64 v[186:187], v[186:187], 0, s[14:15]
	s_mov_b32 m0, s25
	ds_read_b128 v[204:207], v195
	ds_read_b128 v[208:211], v195 offset:1024
	ds_read_b128 v[212:215], v195 offset:2048
	ds_read_b128 v[216:219], v195 offset:3072
	global_load_lds_dwordx4 v[186:187], off
	v_lshl_add_u64 v[186:187], v[220:221], 0, s[14:15]
	s_add_i32 m0, s25, 0x2000
	s_nop 0
	global_load_lds_dwordx4 v[186:187], off
	s_barrier
	s_waitcnt lgkmcnt(0)
	s_waitcnt lgkmcnt(0)
	v_mfma_f32_16x16x32_bf16 v[116:119], v[204:207], v[144:147], v[116:119]
	v_mfma_f32_16x16x32_bf16 v[112:115], v[212:215], v[144:147], v[112:115]
	v_mfma_f32_16x16x32_bf16 v[100:103], v[204:207], v[170:173], v[100:103]
	v_mfma_f32_16x16x32_bf16 v[96:99], v[212:215], v[170:173], v[96:99]
	v_mfma_f32_16x16x32_bf16 v[84:87], v[204:207], v[178:181], v[84:87]
	v_mfma_f32_16x16x32_bf16 v[80:83], v[212:215], v[178:181], v[80:83]
	v_mfma_f32_16x16x32_bf16 v[68:71], v[204:207], v[196:199], v[68:71]
	v_mfma_f32_16x16x32_bf16 v[64:67], v[212:215], v[196:199], v[64:67]
	v_mfma_f32_16x16x32_bf16 v[116:119], v[208:211], v[148:151], v[116:119]
	v_mfma_f32_16x16x32_bf16 v[112:115], v[216:219], v[148:151], v[112:115]
	v_mfma_f32_16x16x32_bf16 v[100:103], v[208:211], v[174:177], v[100:103]
	v_mfma_f32_16x16x32_bf16 v[96:99], v[216:219], v[174:177], v[96:99]
	v_mfma_f32_16x16x32_bf16 v[84:87], v[208:211], v[182:185], v[84:87]
	v_mfma_f32_16x16x32_bf16 v[80:83], v[216:219], v[182:185], v[80:83]
	v_mfma_f32_16x16x32_bf16 v[68:71], v[208:211], v[200:203], v[68:71]
	v_mfma_f32_16x16x32_bf16 v[64:67], v[216:219], v[200:203], v[64:67]
	s_mov_b32 m0, s38
	v_lshl_add_u64 v[186:187], v[222:223], 0, s[14:15]
	s_barrier
	ds_read_b128 v[144:147], v192 offset:49152
	ds_read_b128 v[148:151], v192 offset:50176
	ds_read_b128 v[170:173], v192 offset:51200
	ds_read_b128 v[174:177], v192 offset:52224
	ds_read_b128 v[178:181], v192 offset:53248
	ds_read_b128 v[182:185], v192 offset:54272
	ds_read_b128 v[196:199], v192 offset:55296
	ds_read_b128 v[200:203], v192 offset:56320
	global_load_lds_dwordx4 v[186:187], off
	v_lshl_add_u64 v[186:187], v[224:225], 0, s[14:15]
	s_mov_b32 m0, s39
	s_nop 0
	global_load_lds_dwordx4 v[186:187], off
	s_barrier
	s_waitcnt lgkmcnt(0)
	s_waitcnt lgkmcnt(0)
	v_mfma_f32_16x16x32_bf16 v[60:63], v[128:131], v[144:147], v[60:63]
	v_mfma_f32_16x16x32_bf16 v[56:59], v[136:139], v[144:147], v[56:59]
	v_mfma_f32_16x16x32_bf16 v[44:47], v[128:131], v[170:173], v[44:47]
	v_mfma_f32_16x16x32_bf16 v[40:43], v[136:139], v[170:173], v[40:43]
	v_mfma_f32_16x16x32_bf16 v[28:31], v[128:131], v[178:181], v[28:31]
	v_mfma_f32_16x16x32_bf16 v[24:27], v[136:139], v[178:181], v[24:27]
	v_mfma_f32_16x16x32_bf16 v[12:15], v[128:131], v[196:199], v[12:15]
	v_mfma_f32_16x16x32_bf16 v[8:11], v[136:139], v[196:199], v[8:11]
	v_mfma_f32_16x16x32_bf16 v[60:63], v[132:135], v[148:151], v[60:63]
	v_mfma_f32_16x16x32_bf16 v[56:59], v[140:143], v[148:151], v[56:59]
	v_mfma_f32_16x16x32_bf16 v[44:47], v[132:135], v[174:177], v[44:47]
	v_mfma_f32_16x16x32_bf16 v[40:43], v[140:143], v[174:177], v[40:43]
	v_mfma_f32_16x16x32_bf16 v[28:31], v[132:135], v[182:185], v[28:31]
	v_mfma_f32_16x16x32_bf16 v[24:27], v[140:143], v[182:185], v[24:27]
	v_mfma_f32_16x16x32_bf16 v[12:15], v[132:135], v[200:203], v[12:15]
	v_mfma_f32_16x16x32_bf16 v[8:11], v[140:143], v[200:203], v[8:11]
	s_barrier
	s_add_u32 s22, s22, 0x80080
	s_addc_u32 s23, s23, 0
	s_add_i32 s24, s24, s31
	v_lshl_add_u64 v[128:129], s[22:23], 0, v[156:157]
	s_mov_b32 m0, s24
	s_nop 0
	global_load_lds_dwordx4 v[128:129], off
	v_lshl_add_u64 v[128:129], s[22:23], 0, v[160:161]
	s_add_i32 m0, s24, 0x2000
	s_nop 0
	global_load_lds_dwordx4 v[128:129], off
	s_waitcnt vmcnt(6)
	s_barrier
	v_mfma_f32_16x16x32_bf16 v[52:55], v[204:207], v[144:147], v[52:55]
	v_mfma_f32_16x16x32_bf16 v[48:51], v[212:215], v[144:147], v[48:51]
	v_mfma_f32_16x16x32_bf16 v[36:39], v[204:207], v[170:173], v[36:39]
	v_mfma_f32_16x16x32_bf16 v[32:35], v[212:215], v[170:173], v[32:35]
	v_mfma_f32_16x16x32_bf16 v[20:23], v[204:207], v[178:181], v[20:23]
	v_mfma_f32_16x16x32_bf16 v[16:19], v[212:215], v[178:181], v[16:19]
	v_mfma_f32_16x16x32_bf16 v[4:7], v[204:207], v[196:199], v[4:7]
	v_mfma_f32_16x16x32_bf16 v[0:3], v[212:215], v[196:199], v[0:3]
	v_mfma_f32_16x16x32_bf16 v[52:55], v[208:211], v[148:151], v[52:55]
	v_mfma_f32_16x16x32_bf16 v[48:51], v[216:219], v[148:151], v[48:51]
	v_mfma_f32_16x16x32_bf16 v[36:39], v[208:211], v[174:177], v[36:39]
	v_mfma_f32_16x16x32_bf16 v[32:35], v[216:219], v[174:177], v[32:35]
	v_mfma_f32_16x16x32_bf16 v[20:23], v[208:211], v[182:185], v[20:23]
	v_mfma_f32_16x16x32_bf16 v[16:19], v[216:219], v[182:185], v[16:19]
	v_mfma_f32_16x16x32_bf16 v[4:7], v[208:211], v[200:203], v[4:7]
	v_mfma_f32_16x16x32_bf16 v[0:3], v[216:219], v[200:203], v[0:3]
	s_add_i32 s48, s48, 2
	s_add_u32 s4, s4, 0x100
	s_addc_u32 s5, s5, 0
	s_add_u32 s46, s46, 0x100
	s_addc_u32 s47, s47, 0
	s_cmp_gt_u32 s48, 29
	s_barrier
; __device__ __forceinline__ unsigned pk2(float lo, float hi) { const f32x2 v = (f32x2){lo, hi}; const bf16x2_t b = __builtin_convertvector(v, bf16x2_t); return __builtin_bit_cast(unsigned, b); }
; __device__ __forceinline__ void unpack8(const u32x4 v, float* f) { f[0] = bf_lo(v.x); f[1] = bf_hi(v.x); f[2] = bf_lo(v.y); f[3] = bf_hi(v.y); f[4] = bf_lo(v.z); f[5] = bf_hi(v.z); f[6] = bf_lo(v.w); f[7] = bf_hi(v.w); }
;     __device__ __forceinline__ void operator()(const f32x4 (&acc)[2][2][4][2], const Unit& u, int wr, int wc, int fr, int fq, const float (&)[8]) const {
;         const int row0 = u.pm * BM + wr * 64 + fr, col0 = u.pn * BM + wc * 32 + 8 * fq;
; #pragma unroll
;         for (int ai = 0; ai < 2; ++ai) {
;             u32x4 bv[4][2];
; #pragma unroll
;             for (int m = 0; m < 4; ++m)
; #pragma unroll
;                 for (int bj = 0; bj < 2; ++bj) bv[m][bj] = *(const u32x4*)(xb + (size_t)(row0 + ai * HALF + m * 16) * DM + col0 + bj * HALF);
; #pragma unroll
;             for (int m = 0; m < 4; ++m) { const int row = row0 + ai * HALF + m * 16; const size_t ro = (size_t)row * DM + col0; float s = 0.f;
; #pragma unroll
;                 for (int bj = 0; bj < 2; ++bj) { float b8[8]; unpack8(bv[m][bj], b8);
;                     const f32x4 v0 = (f32x4){b8[0], b8[1], b8[2], b8[3]} + acc[ai][bj][m][0], v1 = (f32x4){b8[4], b8[5], b8[6], b8[7]} + acc[ai][bj][m][1];
;                     s += v0[0] * v0[0] + v0[1] * v0[1] + v0[2] * v0[2] + v0[3] * v0[3] + v1[0] * v1[0] + v1[1] * v1[1] + v1[2] * v1[2] + v1[3] * v1[3];
;                     if (LAST) { *(f32x4*)(out + ro + bj * HALF) = v0; *(f32x4*)(out + ro + bj * HALF + 4) = v1; }
;                     else { u32x4 w; w.x = pk2(v0[0], v0[1]); w.y = pk2(v0[2], v0[3]); w.z = pk2(v1[0], v1[1]); w.w = pk2(v1[2], v1[3]); *(u32x4*)(xb + ro + bj * HALF) = w; } }
;                 s += __shfl_xor(s, 16); s += __shfl_xor(s, 32);
;                 if (fq == 0) ss[(size_t)row * 16 + u.pn * 4 + wc] = s; }
	s_cbranch_scc0 .LBB0_684
	v_lshl_or_b32 v170, s10, 8, v190
	v_lshl_add_u32 v172, s12, 8, v188
	v_ashrrev_i32_e32 v171, 31, v170
	v_lshlrev_b64 v[206:207], 1, v[170:171]
	v_ashrrev_i32_e32 v173, 31, v172
	v_lshl_add_u64 v[174:175], s[76:77], 0, v[206:207]
	v_lshlrev_b64 v[208:209], 11, v[172:173]
	v_lshl_add_u64 v[128:129], v[174:175], 0, v[208:209]
	global_load_dwordx4 v[198:201], v[128:129], off
	global_load_dwordx4 v[202:205], v[128:129], off offset:256
	v_or_b32_e32 v184, 16, v172
	v_or_b32_e32 v180, 32, v172
	v_or_b32_e32 v176, 48, v172
	v_ashrrev_i32_e32 v185, 31, v184
	v_ashrrev_i32_e32 v181, 31, v180
	v_ashrrev_i32_e32 v177, 31, v176
	v_lshlrev_b64 v[186:187], 11, v[184:185]
	v_lshlrev_b64 v[182:183], 11, v[180:181]
	v_lshlrev_b64 v[178:179], 11, v[176:177]
	v_lshl_add_u64 v[128:129], v[174:175], 0, v[186:187]
	v_lshl_add_u64 v[130:131], v[174:175], 0, v[182:183]
	v_lshl_add_u64 v[196:197], v[174:175], 0, v[178:179]
	global_load_dwordx4 v[148:151], v[128:129], off
	global_load_dwordx4 v[144:147], v[128:129], off offset:256
	global_load_dwordx4 v[140:143], v[130:131], off
	global_load_dwordx4 v[136:139], v[130:131], off offset:256
	global_load_dwordx4 v[132:135], v[196:197], off
	s_nop 0
	global_load_dwordx4 v[128:131], v[196:197], off offset:256
	v_add_u32_e32 v218, 0x80, v172
	v_ashrrev_i32_e32 v219, 31, v218
	v_lshlrev_b64 v[218:219], 11, v[218:219]
	v_lshl_add_u64 v[218:219], v[174:175], 0, v[218:219]
	global_load_dwordx4 v[220:223], v[218:219], off
	global_load_dwordx4 v[224:227], v[218:219], off offset:256
	v_add_u32_e32 v218, 0x90, v172
	v_ashrrev_i32_e32 v219, 31, v218
	v_lshlrev_b64 v[218:219], 11, v[218:219]
	v_lshl_add_u64 v[218:219], v[174:175], 0, v[218:219]
	global_load_dwordx4 v[228:231], v[218:219], off
	global_load_dwordx4 v[232:235], v[218:219], off offset:256
	v_add_u32_e32 v218, 0xa0, v172
	v_ashrrev_i32_e32 v219, 31, v218
	v_lshlrev_b64 v[218:219], 11, v[218:219]
	v_lshl_add_u64 v[218:219], v[174:175], 0, v[218:219]
	global_load_dwordx4 v[236:239], v[218:219], off
	global_load_dwordx4 v[240:243], v[218:219], off offset:256
	v_add_u32_e32 v218, 0xb0, v172
	v_ashrrev_i32_e32 v219, 31, v218
	v_lshlrev_b64 v[218:219], 11, v[218:219]
	v_lshl_add_u64 v[218:219], v[174:175], 0, v[218:219]
	global_load_dwordx4 v[244:247], v[218:219], off
	global_load_dwordx4 v[252:255], v[218:219], off offset:256
	v_and_b32_e32 v196, 64, v194
	v_xor_b32_e32 v195, 16, v194
	v_add_u32_e32 v196, 64, v196
	v_xor_b32_e32 v197, 32, v194
	v_cmp_lt_i32_e32 vcc, v195, v196
	s_waitcnt vmcnt(15)
	v_lshlrev_b32_e32 v210, 16, v198
	v_cndmask_b32_e32 v195, v194, v195, vcc
	v_cmp_lt_i32_e32 vcc, v197, v196
	v_and_b32_e32 v211, 0xffff0000, v198
	s_waitcnt vmcnt(14)
	v_lshlrev_b32_e32 v214, 16, v202
	v_and_b32_e32 v215, 0xffff0000, v202
	v_cndmask_b32_e32 v197, v194, v197, vcc
	v_lshlrev_b32_e32 v212, 16, v200
	v_and_b32_e32 v213, 0xffff0000, v200
	v_lshlrev_b32_e32 v200, 16, v201
	v_and_b32_e32 v201, 0xffff0000, v201
	v_lshlrev_b32_e32 v216, 16, v204
	v_and_b32_e32 v217, 0xffff0000, v204
	v_pk_add_f32 v[124:125], v[124:125], v[210:211]
	v_pk_add_f32 v[116:117], v[116:117], v[214:215]
	v_lshlrev_b32_e32 v196, 2, v195
	v_lshlrev_b32_e32 v195, 2, v197
	v_lshlrev_b32_e32 v198, 16, v199
	v_and_b32_e32 v199, 0xffff0000, v199
	v_lshlrev_b32_e32 v202, 16, v203
	v_and_b32_e32 v203, 0xffff0000, v203
	v_pk_add_f32 v[122:123], v[122:123], v[200:201]
	v_pk_add_f32 v[200:201], v[112:113], v[216:217]
	v_mul_f32_e32 v197, v125, v125
	v_cvt_pk_bf16_f32 v112, v124, v125
	v_mul_f32_e32 v125, v117, v117
	v_pk_add_f32 v[126:127], v[126:127], v[198:199]
	v_pk_add_f32 v[118:119], v[118:119], v[202:203]
	v_fmac_f32_e32 v197, v124, v124
	v_fmac_f32_e32 v125, v116, v116
	v_fmac_f32_e32 v197, v126, v126
	v_fmac_f32_e32 v125, v118, v118
	v_pk_add_f32 v[120:121], v[120:121], v[212:213]
	v_fmac_f32_e32 v197, v127, v127
	v_fmac_f32_e32 v125, v119, v119
	v_lshlrev_b32_e32 v204, 16, v205
	v_and_b32_e32 v205, 0xffff0000, v205
	v_fmac_f32_e32 v197, v120, v120
	v_fmac_f32_e32 v125, v200, v200
	v_pk_add_f32 v[198:199], v[114:115], v[204:205]
	v_fmac_f32_e32 v197, v121, v121
	v_fmac_f32_e32 v125, v201, v201
	v_fmac_f32_e32 v197, v122, v122
	v_fmac_f32_e32 v125, v198, v198
	v_fmac_f32_e32 v197, v123, v123
	v_fmac_f32_e32 v125, v199, v199
	v_cvt_pk_bf16_f32 v115, v122, v123
	v_add_f32_e32 v122, v197, v125
	ds_bpermute_b32 v123, v196, v122
	v_cvt_pk_bf16_f32 v114, v120, v121
	v_lshl_add_u64 v[120:121], s[76:77], 0, v[208:209]
	v_cvt_pk_bf16_f32 v113, v126, v127
	v_lshl_add_u64 v[120:121], v[120:121], 0, v[206:207]
	global_store_dwordx4 v[120:121], v[112:115], off
	s_waitcnt lgkmcnt(0)
	s_nop 0
	v_add_f32_e32 v112, v122, v123
	ds_bpermute_b32 v113, v195, v112
	v_cvt_pk_bf16_f32 v114, v116, v117
	v_cvt_pk_bf16_f32 v115, v118, v119
	v_cvt_pk_bf16_f32 v116, v200, v201
	v_cvt_pk_bf16_f32 v117, v198, v199
	global_store_dwordx4 v[120:121], v[114:117], off offset:256
	s_and_saveexec_b64 s[4:5], s[0:1]
	s_cbranch_execz .LBB0_687
	s_waitcnt lgkmcnt(0)
	v_add_f32_e32 v114, v112, v113
	s_lshl_b32 s22, s10, 2
	v_lshlrev_b64 v[112:113], 6, v[172:173]
	s_ashr_i32 s23, s22, 31
	v_lshl_add_u64 v[112:113], s[6:7], 0, v[112:113]
	v_lshl_add_u64 v[112:113], s[22:23], 2, v[112:113]
	s_lshl_b32 s12, s37, 2
	v_lshl_add_u64 v[112:113], v[112:113], 0, s[12:13]
	global_store_dword v[112:113], v114, off

; #define PG8_STAGE(bufoff, gbase, voff) do { _Pragma("unroll") for (int _i = 0; _i < 2; ++_i) \
;         __builtin_amdgcn_global_load_lds((const unsigned*)((const char*)(gbase) + (voff)[_i]), (LAS unsigned*)(lds + (bufoff) + ldsw + _i * 8192), 16, 0, 0); } while (0)
; #define PG8_LDA(dst, b, h) do { _Pragma("unroll") for (int m = 0; m < 4; ++m) _Pragma("unroll") for (int k = 0; k < 2; ++k) dst[m][k] = *(const LAS bf16x8*)(lds + PG8_SA(b, h) + aoff + m * 2048 + k * 1024); } while (0)
; #define PG8_LDB(dst, b, h) do { _Pragma("unroll") for (int n = 0; n < 2; ++n) _Pragma("unroll") for (int k = 0; k < 2; ++k) dst[n][k] = *(const LAS bf16x8*)(lds + PG8_SB(b, h) + boff + n * 2048 + k * 1024); } while (0)
; #define PG8_MMA(ai, bj, At, Bt) do { __builtin_amdgcn_s_setprio(1); _Pragma("unroll") for (int m = 0; m < 4; ++m) _Pragma("unroll") for (int n = 0; n < 2; ++n) _Pragma("unroll") for (int k = 0; k < 2; ++k) \
;         acc[ai][bj][m][n] = __builtin_amdgcn_mfma_f32_16x16x32_bf16(Bt[n][k], At[m][k], acc[ai][bj][m][n], 0, 0, 0); __builtin_amdgcn_s_setprio(0); } while (0)
; #define PG8_WAIT_L(n) asm volatile("s_waitcnt lgkmcnt(" #n ")" ::: "memory")
; #define PG8_BAR __builtin_amdgcn_s_barrier()
; #define PG8_SCHED __builtin_amdgcn_sched_barrier(0)
; template <class Epi>
; __device__ __forceinline__ void gemm_phase(LAS unsigned char* lds, const Gemm g, const StaticOrder& S, const Epi& E) {
;     ...
;             PG8_LDB(B0, 0, 0); PG8_SCHED; PG8_LDA(At, 0, 0); PG8_STAGE(PG8_SA(1, 1), a1 + hstepA, voffA);
;             PG8_WAIT_L(8); PG8_BAR; PG8_WAIT_L(0); PG8_MMA(0, 0, At, B0); PG8_BAR; PG8_SCHED;
;             PG8_LDB(B1, 0, 1); PG8_STAGE(PG8_SB(0, 0), b2, voffB);
;             PG8_BAR; PG8_WAIT_L(0); PG8_MMA(0, 1, At, B1); PG8_BAR;
;             PG8_LDA(At, 0, 1); PG8_STAGE(PG8_SA(0, 0), a2, voffA);
;             PG8_BAR; PG8_WAIT_L(0); PG8_MMA(1, 0, At, B0); PG8_BAR; PG8_SCHED;
.LBB0_769:
	s_ashr_i32 s13, s12, 31
	v_cmp_lt_i64_e32 vcc, s[14:15], v[142:143]
	s_lshl_b64 s[14:15], s[12:13], 19
	s_add_u32 s14, s76, s14
	s_addc_u32 s15, s77, s15
	s_and_b64 s[16:17], vcc, exec
	s_cselect_b32 s13, s15, s21
	s_cselect_b32 s41, s14, s20
	s_ashr_i32 s11, s10, 31
	s_lshl_b64 s[16:17], s[10:11], 19
	s_add_u32 s16, s27, s16
	s_addc_u32 s17, s28, s17
	s_and_b64 s[24:25], vcc, exec
	s_cselect_b32 s11, s17, s23
	s_cselect_b32 s42, s16, s22
	s_add_u32 s20, s20, 0x40080
	s_addc_u32 s21, s21, 0
	s_add_u32 s43, s22, 0x100
	s_addc_u32 s44, s23, 0
	s_mov_b32 s45, -2
	ds_read_b128 v[146:149], v177
	ds_read_b128 v[154:157], v177 offset:1024
	ds_read_b128 v[158:161], v177 offset:2048
	ds_read_b128 v[162:165], v177 offset:3072
	s_add_u32 s22, s20, 0xfffc0080
	s_addc_u32 s23, s21, -1
	s_cmp_eq_u32 s45, 12
	s_cselect_b32 s25, s13, s23
	s_cselect_b32 s24, s41, s22
	s_cselect_b32 s23, s11, s44
	s_cselect_b32 s22, s42, s43
	v_lshl_add_u64 v[150:151], s[20:21], 0, v[138:139]
	s_add_i32 m0, s19, 0xc000
	ds_read_b128 v[166:169], v178
	ds_read_b128 v[170:173], v178 offset:1024
	ds_read_b128 v[182:185], v178 offset:2048
	ds_read_b128 v[186:189], v178 offset:3072
	ds_read_b128 v[190:193], v178 offset:4096
	ds_read_b128 v[194:197], v178 offset:5120
	ds_read_b128 v[198:201], v178 offset:6144
	ds_read_b128 v[202:205], v178 offset:7168
	global_load_lds_dwordx4 v[150:151], off
	v_lshl_add_u64 v[150:151], s[20:21], 0, v[140:141]
	s_add_i32 m0, s19, 0xe000
	s_nop 0
	global_load_lds_dwordx4 v[150:151], off
	s_waitcnt lgkmcnt(8)
	s_barrier
	s_waitcnt lgkmcnt(0)
	s_waitcnt lgkmcnt(0)
	v_mfma_f32_16x16x32_bf16 v[124:127], v[146:149], v[166:169], 0
	v_mfma_f32_16x16x32_bf16 v[120:123], v[158:161], v[166:169], 0
	v_mfma_f32_16x16x32_bf16 v[108:111], v[146:149], v[182:185], 0
	v_mfma_f32_16x16x32_bf16 v[104:107], v[158:161], v[182:185], 0
	v_mfma_f32_16x16x32_bf16 v[92:95], v[146:149], v[190:193], 0
	v_mfma_f32_16x16x32_bf16 v[88:91], v[158:161], v[190:193], 0
	v_mfma_f32_16x16x32_bf16 v[76:79], v[146:149], v[198:201], 0
	v_mfma_f32_16x16x32_bf16 v[72:75], v[158:161], v[198:201], 0
	v_mfma_f32_16x16x32_bf16 v[124:127], v[154:157], v[170:173], v[124:127]
	v_mfma_f32_16x16x32_bf16 v[120:123], v[162:165], v[170:173], v[120:123]
	v_mfma_f32_16x16x32_bf16 v[108:111], v[154:157], v[186:189], v[108:111]
	v_mfma_f32_16x16x32_bf16 v[104:107], v[162:165], v[186:189], v[104:107]
	v_mfma_f32_16x16x32_bf16 v[92:95], v[154:157], v[194:197], v[92:95]
	v_mfma_f32_16x16x32_bf16 v[88:91], v[162:165], v[194:197], v[88:91]
	v_mfma_f32_16x16x32_bf16 v[76:79], v[154:157], v[202:205], v[76:79]
	v_mfma_f32_16x16x32_bf16 v[72:75], v[162:165], v[202:205], v[72:75]
	s_barrier
	s_add_i32 s46, s7, s29
	v_lshl_add_u64 v[150:151], s[22:23], 0, v[130:131]
	s_mov_b32 m0, s46
	ds_read_b128 v[206:209], v179
	ds_read_b128 v[210:213], v179 offset:1024
	ds_read_b128 v[214:217], v179 offset:2048
	ds_read_b128 v[218:221], v179 offset:3072
	global_load_lds_dwordx4 v[150:151], off
	v_lshl_add_u64 v[222:223], s[22:23], 0, v[134:135]
	s_add_i32 m0, s46, 0x2000
	s_nop 0
	global_load_lds_dwordx4 v[222:223], off
	s_barrier
	s_waitcnt lgkmcnt(0)
	s_waitcnt lgkmcnt(0)
	v_mfma_f32_16x16x32_bf16 v[116:119], v[206:209], v[166:169], 0
	v_mfma_f32_16x16x32_bf16 v[112:115], v[214:217], v[166:169], 0
	v_mfma_f32_16x16x32_bf16 v[100:103], v[206:209], v[182:185], 0
	v_mfma_f32_16x16x32_bf16 v[96:99], v[214:217], v[182:185], 0
	v_mfma_f32_16x16x32_bf16 v[84:87], v[206:209], v[190:193], 0
	v_mfma_f32_16x16x32_bf16 v[80:83], v[214:217], v[190:193], 0
	v_mfma_f32_16x16x32_bf16 v[68:71], v[206:209], v[198:201], 0
	v_mfma_f32_16x16x32_bf16 v[64:67], v[214:217], v[198:201], 0
	v_mfma_f32_16x16x32_bf16 v[116:119], v[210:213], v[170:173], v[116:119]
	v_mfma_f32_16x16x32_bf16 v[112:115], v[218:221], v[170:173], v[112:115]
	v_mfma_f32_16x16x32_bf16 v[100:103], v[210:213], v[186:189], v[100:103]
	v_mfma_f32_16x16x32_bf16 v[96:99], v[218:221], v[186:189], v[96:99]
	v_mfma_f32_16x16x32_bf16 v[84:87], v[210:213], v[194:197], v[84:87]
	v_mfma_f32_16x16x32_bf16 v[80:83], v[218:221], v[194:197], v[80:83]
	v_mfma_f32_16x16x32_bf16 v[68:71], v[210:213], v[202:205], v[68:71]
	v_mfma_f32_16x16x32_bf16 v[64:67], v[218:221], v[202:205], v[64:67]
	s_mov_b32 m0, s19
	v_lshl_add_u64 v[224:225], s[24:25], 0, v[128:129]
	s_barrier
	ds_read_b128 v[166:169], v178 offset:16384
	ds_read_b128 v[170:173], v178 offset:17408
	ds_read_b128 v[182:185], v178 offset:18432
	ds_read_b128 v[186:189], v178 offset:19456
	ds_read_b128 v[190:193], v178 offset:20480
	ds_read_b128 v[194:197], v178 offset:21504
	ds_read_b128 v[198:201], v178 offset:22528
	ds_read_b128 v[202:205], v178 offset:23552
	global_load_lds_dwordx4 v[224:225], off
	v_lshl_add_u64 v[226:227], s[24:25], 0, v[132:133]
	s_mov_b32 m0, s30
	s_nop 0
	global_load_lds_dwordx4 v[226:227], off
	s_barrier
	s_waitcnt lgkmcnt(0)
	s_waitcnt lgkmcnt(0)
	v_mfma_f32_16x16x32_bf16 v[60:63], v[146:149], v[166:169], 0
	v_mfma_f32_16x16x32_bf16 v[56:59], v[158:161], v[166:169], 0
	v_mfma_f32_16x16x32_bf16 v[44:47], v[146:149], v[182:185], 0
	v_mfma_f32_16x16x32_bf16 v[40:43], v[158:161], v[182:185], 0
	v_mfma_f32_16x16x32_bf16 v[28:31], v[146:149], v[190:193], 0
	v_mfma_f32_16x16x32_bf16 v[24:27], v[158:161], v[190:193], 0
	v_mfma_f32_16x16x32_bf16 v[12:15], v[146:149], v[198:201], 0
	v_mfma_f32_16x16x32_bf16 v[8:11], v[158:161], v[198:201], 0
	v_mfma_f32_16x16x32_bf16 v[60:63], v[154:157], v[170:173], v[60:63]
	v_mfma_f32_16x16x32_bf16 v[56:59], v[162:165], v[170:173], v[56:59]
	v_mfma_f32_16x16x32_bf16 v[44:47], v[154:157], v[186:189], v[44:47]
	v_mfma_f32_16x16x32_bf16 v[40:43], v[162:165], v[186:189], v[40:43]
	v_mfma_f32_16x16x32_bf16 v[28:31], v[154:157], v[194:197], v[28:31]
	v_mfma_f32_16x16x32_bf16 v[24:27], v[162:165], v[194:197], v[24:27]
	v_mfma_f32_16x16x32_bf16 v[12:15], v[154:157], v[202:205], v[12:15]
	v_mfma_f32_16x16x32_bf16 v[8:11], v[162:165], v[202:205], v[8:11]
	s_barrier
; #define PG8_STAGE(bufoff, gbase, voff) do { _Pragma("unroll") for (int _i = 0; _i < 2; ++_i) \
;         __builtin_amdgcn_global_load_lds((const unsigned*)((const char*)(gbase) + (voff)[_i]), (LAS unsigned*)(lds + (bufoff) + ldsw + _i * 8192), 16, 0, 0); } while (0)
; #define PG8_LDA(dst, b, h) do { _Pragma("unroll") for (int m = 0; m < 4; ++m) _Pragma("unroll") for (int k = 0; k < 2; ++k) dst[m][k] = *(const LAS bf16x8*)(lds + PG8_SA(b, h) + aoff + m * 2048 + k * 1024); } while (0)
; #define PG8_LDB(dst, b, h) do { _Pragma("unroll") for (int n = 0; n < 2; ++n) _Pragma("unroll") for (int k = 0; k < 2; ++k) dst[n][k] = *(const LAS bf16x8*)(lds + PG8_SB(b, h) + boff + n * 2048 + k * 1024); } while (0)
; #define PG8_MMA(ai, bj, At, Bt) do { __builtin_amdgcn_s_setprio(1); _Pragma("unroll") for (int m = 0; m < 4; ++m) _Pragma("unroll") for (int n = 0; n < 2; ++n) _Pragma("unroll") for (int k = 0; k < 2; ++k) \
;         acc[ai][bj][m][n] = __builtin_amdgcn_mfma_f32_16x16x32_bf16(Bt[n][k], At[m][k], acc[ai][bj][m][n], 0, 0, 0); __builtin_amdgcn_s_setprio(0); } while (0)
; #define PG8_WAIT_V(n) asm volatile("s_waitcnt vmcnt(" #n ")" ::: "memory")
; #define PG8_WAIT_L(n) asm volatile("s_waitcnt lgkmcnt(" #n ")" ::: "memory")
; #define PG8_BAR __builtin_amdgcn_s_barrier()
; #define PG8_SCHED __builtin_amdgcn_sched_barrier(0)
; template <class Epi>
; __device__ __forceinline__ void gemm_phase(LAS unsigned char* lds, const Gemm g, const StaticOrder& S, const Epi& E) {
;     ...
;             PG8_STAGE(PG8_SB(0, 1), b2 + hstepB, voffB);
;             PG8_WAIT_V(6); PG8_BAR; PG8_MMA(1, 1, At, B1); PG8_BAR;
;             PG8_LDB(B0, 1, 0); PG8_SCHED; PG8_LDA(At, 1, 0); PG8_STAGE(PG8_SA(0, 1), a2 + hstepA, voffA);
;             PG8_WAIT_L(8); PG8_BAR; PG8_WAIT_L(0); PG8_MMA(0, 0, At, B0); PG8_BAR; PG8_SCHED;
;             PG8_LDB(B1, 1, 1); PG8_STAGE(PG8_SB(1, 0), b3, voffB);
;             PG8_BAR; PG8_WAIT_L(0); PG8_MMA(0, 1, At, B1); PG8_BAR;
;             PG8_LDA(At, 1, 1); PG8_STAGE(PG8_SA(1, 0), a3, voffA);
	s_add_u32 s46, s22, 0x40000
	s_addc_u32 s47, s23, 0
	s_add_i32 s48, s38, s29
	v_lshl_add_u64 v[146:147], s[46:47], 0, v[130:131]
	s_mov_b32 m0, s48
	s_nop 0
	global_load_lds_dwordx4 v[146:147], off
	v_lshl_add_u64 v[146:147], s[46:47], 0, v[134:135]
	s_add_i32 m0, s48, 0x2000
	s_nop 0
	global_load_lds_dwordx4 v[146:147], off
	s_waitcnt vmcnt(6)
	s_barrier
	v_mfma_f32_16x16x32_bf16 v[52:55], v[206:209], v[166:169], 0
	v_mfma_f32_16x16x32_bf16 v[48:51], v[214:217], v[166:169], 0
	v_mfma_f32_16x16x32_bf16 v[36:39], v[206:209], v[182:185], 0
	v_mfma_f32_16x16x32_bf16 v[32:35], v[214:217], v[182:185], 0
	v_mfma_f32_16x16x32_bf16 v[20:23], v[206:209], v[190:193], 0
	v_mfma_f32_16x16x32_bf16 v[16:19], v[214:217], v[190:193], 0
	v_mfma_f32_16x16x32_bf16 v[4:7], v[206:209], v[198:201], 0
	v_mfma_f32_16x16x32_bf16 v[0:3], v[214:217], v[198:201], 0
	v_mfma_f32_16x16x32_bf16 v[52:55], v[210:213], v[170:173], v[52:55]
	v_mfma_f32_16x16x32_bf16 v[48:51], v[218:221], v[170:173], v[48:51]
	v_mfma_f32_16x16x32_bf16 v[36:39], v[210:213], v[186:189], v[36:39]
	v_mfma_f32_16x16x32_bf16 v[32:35], v[218:221], v[186:189], v[32:35]
	v_mfma_f32_16x16x32_bf16 v[20:23], v[210:213], v[194:197], v[20:23]
	v_mfma_f32_16x16x32_bf16 v[16:19], v[218:221], v[194:197], v[16:19]
	v_mfma_f32_16x16x32_bf16 v[4:7], v[210:213], v[202:205], v[4:7]
	v_mfma_f32_16x16x32_bf16 v[0:3], v[218:221], v[202:205], v[0:3]
	s_add_i32 s46, 0, 0x18000
	v_add_u32_e32 v162, s46, v175
	s_barrier
	ds_read_b128 v[146:149], v162
	ds_read_b128 v[154:157], v162 offset:1024
	ds_read_b128 v[158:161], v162 offset:2048
	ds_read_b128 v[162:165], v162 offset:3072
	s_add_u32 s24, s24, 0x40000
	s_addc_u32 s25, s25, 0
	s_mov_b32 m0, s31
	v_lshl_add_u64 v[206:207], s[24:25], 0, v[128:129]
	ds_read_b128 v[166:169], v178 offset:32768
	ds_read_b128 v[170:173], v178 offset:33792
	ds_read_b128 v[182:185], v178 offset:34816
	ds_read_b128 v[186:189], v178 offset:35840
	ds_read_b128 v[190:193], v178 offset:36864
	ds_read_b128 v[194:197], v178 offset:37888
	ds_read_b128 v[198:201], v178 offset:38912
	ds_read_b128 v[202:205], v178 offset:39936
	global_load_lds_dwordx4 v[206:207], off
	v_lshl_add_u64 v[206:207], s[24:25], 0, v[132:133]
	s_mov_b32 m0, s33
	s_nop 0
	global_load_lds_dwordx4 v[206:207], off
	s_waitcnt lgkmcnt(8)
	s_barrier
	s_waitcnt lgkmcnt(0)
	s_waitcnt lgkmcnt(0)
	v_mfma_f32_16x16x32_bf16 v[124:127], v[146:149], v[166:169], v[124:127]
	v_mfma_f32_16x16x32_bf16 v[120:123], v[158:161], v[166:169], v[120:123]
	v_mfma_f32_16x16x32_bf16 v[108:111], v[146:149], v[182:185], v[108:111]
	v_mfma_f32_16x16x32_bf16 v[104:107], v[158:161], v[182:185], v[104:107]
	v_mfma_f32_16x16x32_bf16 v[92:95], v[146:149], v[190:193], v[92:95]
	v_mfma_f32_16x16x32_bf16 v[88:91], v[158:161], v[190:193], v[88:91]
	v_mfma_f32_16x16x32_bf16 v[76:79], v[146:149], v[198:201], v[76:79]
	v_mfma_f32_16x16x32_bf16 v[72:75], v[158:161], v[198:201], v[72:75]
	v_mfma_f32_16x16x32_bf16 v[124:127], v[154:157], v[170:173], v[124:127]
	v_mfma_f32_16x16x32_bf16 v[120:123], v[162:165], v[170:173], v[120:123]
	v_mfma_f32_16x16x32_bf16 v[108:111], v[154:157], v[186:189], v[108:111]
	v_mfma_f32_16x16x32_bf16 v[104:107], v[162:165], v[186:189], v[104:107]
	v_mfma_f32_16x16x32_bf16 v[92:95], v[154:157], v[194:197], v[92:95]
	v_mfma_f32_16x16x32_bf16 v[88:91], v[162:165], v[194:197], v[88:91]
	v_mfma_f32_16x16x32_bf16 v[76:79], v[154:157], v[202:205], v[76:79]
	v_mfma_f32_16x16x32_bf16 v[72:75], v[162:165], v[202:205], v[72:75]
	s_barrier
	s_add_i32 s24, 0, 0x1c000
	s_add_i32 s25, s46, s29
	v_add_u32_e32 v181, s24, v175
	v_lshl_add_u64 v[150:151], v[150:151], 0, s[4:5]
	s_mov_b32 m0, s25
	ds_read_b128 v[206:209], v181
	ds_read_b128 v[210:213], v181 offset:1024
	ds_read_b128 v[214:217], v181 offset:2048
	ds_read_b128 v[218:221], v181 offset:3072
	global_load_lds_dwordx4 v[150:151], off
	v_lshl_add_u64 v[150:151], v[222:223], 0, s[4:5]
	s_add_i32 m0, s25, 0x2000
	s_nop 0
	global_load_lds_dwordx4 v[150:151], off
	s_barrier
	s_waitcnt lgkmcnt(0)
	s_waitcnt lgkmcnt(0)
	v_mfma_f32_16x16x32_bf16 v[116:119], v[206:209], v[166:169], v[116:119]
	v_mfma_f32_16x16x32_bf16 v[112:115], v[214:217], v[166:169], v[112:115]
	v_mfma_f32_16x16x32_bf16 v[100:103], v[206:209], v[182:185], v[100:103]
	v_mfma_f32_16x16x32_bf16 v[96:99], v[214:217], v[182:185], v[96:99]
	v_mfma_f32_16x16x32_bf16 v[84:87], v[206:209], v[190:193], v[84:87]
	v_mfma_f32_16x16x32_bf16 v[80:83], v[214:217], v[190:193], v[80:83]
	v_mfma_f32_16x16x32_bf16 v[68:71], v[206:209], v[198:201], v[68:71]
	v_mfma_f32_16x16x32_bf16 v[64:67], v[214:217], v[198:201], v[64:67]
	v_mfma_f32_16x16x32_bf16 v[116:119], v[210:213], v[170:173], v[116:119]
	v_mfma_f32_16x16x32_bf16 v[112:115], v[218:221], v[170:173], v[112:115]
	v_mfma_f32_16x16x32_bf16 v[100:103], v[210:213], v[186:189], v[100:103]
	v_mfma_f32_16x16x32_bf16 v[96:99], v[218:221], v[186:189], v[96:99]
	v_mfma_f32_16x16x32_bf16 v[84:87], v[210:213], v[194:197], v[84:87]
	v_mfma_f32_16x16x32_bf16 v[80:83], v[218:221], v[194:197], v[80:83]
	v_mfma_f32_16x16x32_bf16 v[68:71], v[210:213], v[202:205], v[68:71]
	v_mfma_f32_16x16x32_bf16 v[64:67], v[218:221], v[202:205], v[64:67]
	s_mov_b32 m0, s35
	v_lshl_add_u64 v[150:151], v[224:225], 0, s[4:5]
	s_barrier
	ds_read_b128 v[166:169], v178 offset:49152
	ds_read_b128 v[170:173], v178 offset:50176
	ds_read_b128 v[182:185], v178 offset:51200
	ds_read_b128 v[186:189], v178 offset:52224
	ds_read_b128 v[190:193], v178 offset:53248
	ds_read_b128 v[194:197], v178 offset:54272
	ds_read_b128 v[198:201], v178 offset:55296
	ds_read_b128 v[202:205], v178 offset:56320
	global_load_lds_dwordx4 v[150:151], off
	v_lshl_add_u64 v[150:151], v[226:227], 0, s[4:5]
	s_mov_b32 m0, s36
	s_nop 0
	global_load_lds_dwordx4 v[150:151], off
	s_barrier
; #define PG8_STAGE(bufoff, gbase, voff) do { _Pragma("unroll") for (int _i = 0; _i < 2; ++_i) \
;         __builtin_amdgcn_global_load_lds((const unsigned*)((const char*)(gbase) + (voff)[_i]), (LAS unsigned*)(lds + (bufoff) + ldsw + _i * 8192), 16, 0, 0); } while (0)
; #define PG8_LDA(dst, b, h) do { _Pragma("unroll") for (int m = 0; m < 4; ++m) _Pragma("unroll") for (int k = 0; k < 2; ++k) dst[m][k] = *(const LAS bf16x8*)(lds + PG8_SA(b, h) + aoff + m * 2048 + k * 1024); } while (0)
; #define PG8_LDB(dst, b, h) do { _Pragma("unroll") for (int n = 0; n < 2; ++n) _Pragma("unroll") for (int k = 0; k < 2; ++k) dst[n][k] = *(const LAS bf16x8*)(lds + PG8_SB(b, h) + boff + n * 2048 + k * 1024); } while (0)
; #define PG8_MMA(ai, bj, At, Bt) do { __builtin_amdgcn_s_setprio(1); _Pragma("unroll") for (int m = 0; m < 4; ++m) _Pragma("unroll") for (int n = 0; n < 2; ++n) _Pragma("unroll") for (int k = 0; k < 2; ++k) \
;         acc[ai][bj][m][n] = __builtin_amdgcn_mfma_f32_16x16x32_bf16(Bt[n][k], At[m][k], acc[ai][bj][m][n], 0, 0, 0); __builtin_amdgcn_s_setprio(0); } while (0)
; #define PG8_WAIT_V(n) asm volatile("s_waitcnt vmcnt(" #n ")" ::: "memory")
; #define PG8_WAIT_L(n) asm volatile("s_waitcnt lgkmcnt(" #n ")" ::: "memory")
; #define PG8_BAR __builtin_amdgcn_s_barrier()
; #define PG8_SCHED __builtin_amdgcn_sched_barrier(0)
; template <class Epi>
; __device__ __forceinline__ void gemm_phase(LAS unsigned char* lds, const Gemm g, const StaticOrder& S, const Epi& E) {
;     ...
;             PG8_LDB(B0, 0, 0); PG8_SCHED; PG8_LDA(At, 0, 0); PG8_STAGE(PG8_SA(1, 1), a1 + hstepA, voffA);
;             PG8_WAIT_L(8); PG8_BAR; PG8_WAIT_L(0); PG8_MMA(0, 0, At, B0); PG8_BAR; PG8_SCHED;
;             PG8_LDB(B1, 0, 1); PG8_STAGE(PG8_SB(0, 0), b2, voffB);
;     ...
;             PG8_BAR; PG8_WAIT_L(0); PG8_MMA(1, 0, At, B0); PG8_BAR; PG8_SCHED;
;             PG8_STAGE(PG8_SB(1, 1), b3 + hstepB, voffB);
;             PG8_WAIT_V(6); PG8_BAR; PG8_MMA(1, 1, At, B1); PG8_BAR;
	s_waitcnt lgkmcnt(0)
	s_waitcnt lgkmcnt(0)
	v_mfma_f32_16x16x32_bf16 v[60:63], v[146:149], v[166:169], v[60:63]
	v_mfma_f32_16x16x32_bf16 v[56:59], v[158:161], v[166:169], v[56:59]
	v_mfma_f32_16x16x32_bf16 v[44:47], v[146:149], v[182:185], v[44:47]
	v_mfma_f32_16x16x32_bf16 v[40:43], v[158:161], v[182:185], v[40:43]
	v_mfma_f32_16x16x32_bf16 v[28:31], v[146:149], v[190:193], v[28:31]
	v_mfma_f32_16x16x32_bf16 v[24:27], v[158:161], v[190:193], v[24:27]
	v_mfma_f32_16x16x32_bf16 v[12:15], v[146:149], v[198:201], v[12:15]
	v_mfma_f32_16x16x32_bf16 v[8:11], v[158:161], v[198:201], v[8:11]
	v_mfma_f32_16x16x32_bf16 v[60:63], v[154:157], v[170:173], v[60:63]
	v_mfma_f32_16x16x32_bf16 v[56:59], v[162:165], v[170:173], v[56:59]
	v_mfma_f32_16x16x32_bf16 v[44:47], v[154:157], v[186:189], v[44:47]
	v_mfma_f32_16x16x32_bf16 v[40:43], v[162:165], v[186:189], v[40:43]
	v_mfma_f32_16x16x32_bf16 v[28:31], v[154:157], v[194:197], v[28:31]
	v_mfma_f32_16x16x32_bf16 v[24:27], v[162:165], v[194:197], v[24:27]
	v_mfma_f32_16x16x32_bf16 v[12:15], v[154:157], v[202:205], v[12:15]
	v_mfma_f32_16x16x32_bf16 v[8:11], v[162:165], v[202:205], v[8:11]
	s_barrier
	s_add_u32 s22, s22, 0x40080
	s_addc_u32 s23, s23, 0
	s_add_i32 s24, s24, s29
	v_lshl_add_u64 v[146:147], s[22:23], 0, v[130:131]
	s_mov_b32 m0, s24
	s_nop 0
	global_load_lds_dwordx4 v[146:147], off
	v_lshl_add_u64 v[146:147], s[22:23], 0, v[134:135]
	s_add_i32 m0, s24, 0x2000
	s_nop 0
	global_load_lds_dwordx4 v[146:147], off
	s_waitcnt vmcnt(6)
	s_barrier
	v_mfma_f32_16x16x32_bf16 v[52:55], v[206:209], v[166:169], v[52:55]
	v_mfma_f32_16x16x32_bf16 v[48:51], v[214:217], v[166:169], v[48:51]
	v_mfma_f32_16x16x32_bf16 v[36:39], v[206:209], v[182:185], v[36:39]
	v_mfma_f32_16x16x32_bf16 v[32:35], v[214:217], v[182:185], v[32:35]
	v_mfma_f32_16x16x32_bf16 v[20:23], v[206:209], v[190:193], v[20:23]
	v_mfma_f32_16x16x32_bf16 v[16:19], v[214:217], v[190:193], v[16:19]
	v_mfma_f32_16x16x32_bf16 v[4:7], v[206:209], v[198:201], v[4:7]
	v_mfma_f32_16x16x32_bf16 v[0:3], v[214:217], v[198:201], v[0:3]
	v_mfma_f32_16x16x32_bf16 v[52:55], v[210:213], v[170:173], v[52:55]
	v_mfma_f32_16x16x32_bf16 v[48:51], v[218:221], v[170:173], v[48:51]
	v_mfma_f32_16x16x32_bf16 v[36:39], v[210:213], v[186:189], v[36:39]
	v_mfma_f32_16x16x32_bf16 v[32:35], v[218:221], v[186:189], v[32:35]
	v_mfma_f32_16x16x32_bf16 v[20:23], v[210:213], v[194:197], v[20:23]
	v_mfma_f32_16x16x32_bf16 v[16:19], v[218:221], v[194:197], v[16:19]
	v_mfma_f32_16x16x32_bf16 v[4:7], v[210:213], v[202:205], v[4:7]
	v_mfma_f32_16x16x32_bf16 v[0:3], v[218:221], v[202:205], v[0:3]
	s_add_i32 s45, s45, 2
	s_add_u32 s20, s20, 0x100
	s_addc_u32 s21, s21, 0
	s_add_u32 s43, s43, 0x100
	s_addc_u32 s44, s44, 0
	s_cmp_gt_u32 s45, 13
	s_barrier
.LBB0_770:
	ds_read_b128 v[146:149], v177
	ds_read_b128 v[154:157], v177 offset:1024
	ds_read_b128 v[158:161], v177 offset:2048
	ds_read_b128 v[162:165], v177 offset:3072
	s_add_u32 s22, s20, 0xfffc0080
	s_addc_u32 s23, s21, -1
	s_cmp_eq_u32 s45, 12
	s_cselect_b32 s25, s13, s23
	s_cselect_b32 s24, s41, s22
	s_cselect_b32 s23, s11, s44
	s_cselect_b32 s22, s42, s43
	v_lshl_add_u64 v[150:151], s[20:21], 0, v[138:139]
	s_add_i32 m0, s19, 0xc000
	ds_read_b128 v[166:169], v178
	ds_read_b128 v[170:173], v178 offset:1024
	ds_read_b128 v[182:185], v178 offset:2048
	ds_read_b128 v[186:189], v178 offset:3072
	ds_read_b128 v[190:193], v178 offset:4096
	ds_read_b128 v[194:197], v178 offset:5120
	ds_read_b128 v[198:201], v178 offset:6144
	ds_read_b128 v[202:205], v178 offset:7168
	global_load_lds_dwordx4 v[150:151], off
	v_lshl_add_u64 v[150:151], s[20:21], 0, v[140:141]
	s_add_i32 m0, s19, 0xe000
	s_nop 0
	global_load_lds_dwordx4 v[150:151], off
	s_waitcnt lgkmcnt(8)
	s_barrier
	s_waitcnt lgkmcnt(0)
	s_waitcnt lgkmcnt(0)
	v_mfma_f32_16x16x32_bf16 v[124:127], v[146:149], v[166:169], v[124:127]
	v_mfma_f32_16x16x32_bf16 v[120:123], v[158:161], v[166:169], v[120:123]
	v_mfma_f32_16x16x32_bf16 v[108:111], v[146:149], v[182:185], v[108:111]
	v_mfma_f32_16x16x32_bf16 v[104:107], v[158:161], v[182:185], v[104:107]
	v_mfma_f32_16x16x32_bf16 v[92:95], v[146:149], v[190:193], v[92:95]
	v_mfma_f32_16x16x32_bf16 v[88:91], v[158:161], v[190:193], v[88:91]
	v_mfma_f32_16x16x32_bf16 v[76:79], v[146:149], v[198:201], v[76:79]
	v_mfma_f32_16x16x32_bf16 v[72:75], v[158:161], v[198:201], v[72:75]
	v_mfma_f32_16x16x32_bf16 v[124:127], v[154:157], v[170:173], v[124:127]
	v_mfma_f32_16x16x32_bf16 v[120:123], v[162:165], v[170:173], v[120:123]
	v_mfma_f32_16x16x32_bf16 v[108:111], v[154:157], v[186:189], v[108:111]
	v_mfma_f32_16x16x32_bf16 v[104:107], v[162:165], v[186:189], v[104:107]
	v_mfma_f32_16x16x32_bf16 v[92:95], v[154:157], v[194:197], v[92:95]
	v_mfma_f32_16x16x32_bf16 v[88:91], v[162:165], v[194:197], v[88:91]
	v_mfma_f32_16x16x32_bf16 v[76:79], v[154:157], v[202:205], v[76:79]
	v_mfma_f32_16x16x32_bf16 v[72:75], v[162:165], v[202:205], v[72:75]
	s_barrier
	s_add_i32 s46, s7, s29
	v_lshl_add_u64 v[150:151], s[22:23], 0, v[130:131]
	s_mov_b32 m0, s46
	ds_read_b128 v[206:209], v179
	ds_read_b128 v[210:213], v179 offset:1024
	ds_read_b128 v[214:217], v179 offset:2048
	ds_read_b128 v[218:221], v179 offset:3072
	global_load_lds_dwordx4 v[150:151], off
	v_lshl_add_u64 v[222:223], s[22:23], 0, v[134:135]
	s_add_i32 m0, s46, 0x2000
	s_nop 0
	global_load_lds_dwordx4 v[222:223], off
	s_barrier
; #define PG8_STAGE(bufoff, gbase, voff) do { _Pragma("unroll") for (int _i = 0; _i < 2; ++_i) \
;         __builtin_amdgcn_global_load_lds((const unsigned*)((const char*)(gbase) + (voff)[_i]), (LAS unsigned*)(lds + (bufoff) + ldsw + _i * 8192), 16, 0, 0); } while (0)
; #define PG8_LDA(dst, b, h) do { _Pragma("unroll") for (int m = 0; m < 4; ++m) _Pragma("unroll") for (int k = 0; k < 2; ++k) dst[m][k] = *(const LAS bf16x8*)(lds + PG8_SA(b, h) + aoff + m * 2048 + k * 1024); } while (0)
; #define PG8_LDB(dst, b, h) do { _Pragma("unroll") for (int n = 0; n < 2; ++n) _Pragma("unroll") for (int k = 0; k < 2; ++k) dst[n][k] = *(const LAS bf16x8*)(lds + PG8_SB(b, h) + boff + n * 2048 + k * 1024); } while (0)
; #define PG8_MMA(ai, bj, At, Bt) do { __builtin_amdgcn_s_setprio(1); _Pragma("unroll") for (int m = 0; m < 4; ++m) _Pragma("unroll") for (int n = 0; n < 2; ++n) _Pragma("unroll") for (int k = 0; k < 2; ++k) \
;         acc[ai][bj][m][n] = __builtin_amdgcn_mfma_f32_16x16x32_bf16(Bt[n][k], At[m][k], acc[ai][bj][m][n], 0, 0, 0); __builtin_amdgcn_s_setprio(0); } while (0)
; #define PG8_WAIT_V(n) asm volatile("s_waitcnt vmcnt(" #n ")" ::: "memory")
; #define PG8_WAIT_L(n) asm volatile("s_waitcnt lgkmcnt(" #n ")" ::: "memory")
; #define PG8_BAR __builtin_amdgcn_s_barrier()
; #define PG8_SCHED __builtin_amdgcn_sched_barrier(0)
; template <class Epi>
; __device__ __forceinline__ void gemm_phase(LAS unsigned char* lds, const Gemm g, const StaticOrder& S, const Epi& E) {
;     ...
;             PG8_BAR; PG8_WAIT_L(0); PG8_MMA(0, 1, At, B1); PG8_BAR;
;             PG8_LDA(At, 0, 1); PG8_STAGE(PG8_SA(0, 0), a2, voffA);
;             PG8_BAR; PG8_WAIT_L(0); PG8_MMA(1, 0, At, B0); PG8_BAR; PG8_SCHED;
;             PG8_STAGE(PG8_SB(0, 1), b2 + hstepB, voffB);
;             PG8_WAIT_V(6); PG8_BAR; PG8_MMA(1, 1, At, B1); PG8_BAR;
;             PG8_LDB(B0, 1, 0); PG8_SCHED; PG8_LDA(At, 1, 0); PG8_STAGE(PG8_SA(0, 1), a2 + hstepA, voffA);
	s_waitcnt lgkmcnt(0)
	s_waitcnt lgkmcnt(0)
	v_mfma_f32_16x16x32_bf16 v[116:119], v[206:209], v[166:169], v[116:119]
	v_mfma_f32_16x16x32_bf16 v[112:115], v[214:217], v[166:169], v[112:115]
	v_mfma_f32_16x16x32_bf16 v[100:103], v[206:209], v[182:185], v[100:103]
	v_mfma_f32_16x16x32_bf16 v[96:99], v[214:217], v[182:185], v[96:99]
	v_mfma_f32_16x16x32_bf16 v[84:87], v[206:209], v[190:193], v[84:87]
	v_mfma_f32_16x16x32_bf16 v[80:83], v[214:217], v[190:193], v[80:83]
	v_mfma_f32_16x16x32_bf16 v[68:71], v[206:209], v[198:201], v[68:71]
	v_mfma_f32_16x16x32_bf16 v[64:67], v[214:217], v[198:201], v[64:67]
	v_mfma_f32_16x16x32_bf16 v[116:119], v[210:213], v[170:173], v[116:119]
	v_mfma_f32_16x16x32_bf16 v[112:115], v[218:221], v[170:173], v[112:115]
	v_mfma_f32_16x16x32_bf16 v[100:103], v[210:213], v[186:189], v[100:103]
	v_mfma_f32_16x16x32_bf16 v[96:99], v[218:221], v[186:189], v[96:99]
	v_mfma_f32_16x16x32_bf16 v[84:87], v[210:213], v[194:197], v[84:87]
	v_mfma_f32_16x16x32_bf16 v[80:83], v[218:221], v[194:197], v[80:83]
	v_mfma_f32_16x16x32_bf16 v[68:71], v[210:213], v[202:205], v[68:71]
	v_mfma_f32_16x16x32_bf16 v[64:67], v[218:221], v[202:205], v[64:67]
	s_mov_b32 m0, s19
	v_lshl_add_u64 v[224:225], s[24:25], 0, v[128:129]
	s_barrier
	ds_read_b128 v[166:169], v178 offset:16384
	ds_read_b128 v[170:173], v178 offset:17408
	ds_read_b128 v[182:185], v178 offset:18432
	ds_read_b128 v[186:189], v178 offset:19456
	ds_read_b128 v[190:193], v178 offset:20480
	ds_read_b128 v[194:197], v178 offset:21504
	ds_read_b128 v[198:201], v178 offset:22528
	ds_read_b128 v[202:205], v178 offset:23552
	global_load_lds_dwordx4 v[224:225], off
	v_lshl_add_u64 v[226:227], s[24:25], 0, v[132:133]
	s_mov_b32 m0, s30
	s_nop 0
	global_load_lds_dwordx4 v[226:227], off
	s_barrier
	s_waitcnt lgkmcnt(0)
	s_waitcnt lgkmcnt(0)
	v_mfma_f32_16x16x32_bf16 v[60:63], v[146:149], v[166:169], v[60:63]
	v_mfma_f32_16x16x32_bf16 v[56:59], v[158:161], v[166:169], v[56:59]
	v_mfma_f32_16x16x32_bf16 v[44:47], v[146:149], v[182:185], v[44:47]
	v_mfma_f32_16x16x32_bf16 v[40:43], v[158:161], v[182:185], v[40:43]
	v_mfma_f32_16x16x32_bf16 v[28:31], v[146:149], v[190:193], v[28:31]
	v_mfma_f32_16x16x32_bf16 v[24:27], v[158:161], v[190:193], v[24:27]
	v_mfma_f32_16x16x32_bf16 v[12:15], v[146:149], v[198:201], v[12:15]
	v_mfma_f32_16x16x32_bf16 v[8:11], v[158:161], v[198:201], v[8:11]
	v_mfma_f32_16x16x32_bf16 v[60:63], v[154:157], v[170:173], v[60:63]
	v_mfma_f32_16x16x32_bf16 v[56:59], v[162:165], v[170:173], v[56:59]
	v_mfma_f32_16x16x32_bf16 v[44:47], v[154:157], v[186:189], v[44:47]
	v_mfma_f32_16x16x32_bf16 v[40:43], v[162:165], v[186:189], v[40:43]
	v_mfma_f32_16x16x32_bf16 v[28:31], v[154:157], v[194:197], v[28:31]
	v_mfma_f32_16x16x32_bf16 v[24:27], v[162:165], v[194:197], v[24:27]
	v_mfma_f32_16x16x32_bf16 v[12:15], v[154:157], v[202:205], v[12:15]
	v_mfma_f32_16x16x32_bf16 v[8:11], v[162:165], v[202:205], v[8:11]
	s_barrier
	s_add_u32 s46, s22, 0x40000
	s_addc_u32 s47, s23, 0
	s_add_i32 s48, s38, s29
	v_lshl_add_u64 v[146:147], s[46:47], 0, v[130:131]
	s_mov_b32 m0, s48
	s_nop 0
	global_load_lds_dwordx4 v[146:147], off
	v_lshl_add_u64 v[146:147], s[46:47], 0, v[134:135]
	s_add_i32 m0, s48, 0x2000
	s_nop 0
	global_load_lds_dwordx4 v[146:147], off
	s_waitcnt vmcnt(6)
	s_barrier
	v_mfma_f32_16x16x32_bf16 v[52:55], v[206:209], v[166:169], v[52:55]
	v_mfma_f32_16x16x32_bf16 v[48:51], v[214:217], v[166:169], v[48:51]
	v_mfma_f32_16x16x32_bf16 v[36:39], v[206:209], v[182:185], v[36:39]
	v_mfma_f32_16x16x32_bf16 v[32:35], v[214:217], v[182:185], v[32:35]
	v_mfma_f32_16x16x32_bf16 v[20:23], v[206:209], v[190:193], v[20:23]
	v_mfma_f32_16x16x32_bf16 v[16:19], v[214:217], v[190:193], v[16:19]
	v_mfma_f32_16x16x32_bf16 v[4:7], v[206:209], v[198:201], v[4:7]
	v_mfma_f32_16x16x32_bf16 v[0:3], v[214:217], v[198:201], v[0:3]
	v_mfma_f32_16x16x32_bf16 v[52:55], v[210:213], v[170:173], v[52:55]
	v_mfma_f32_16x16x32_bf16 v[48:51], v[218:221], v[170:173], v[48:51]
	v_mfma_f32_16x16x32_bf16 v[36:39], v[210:213], v[186:189], v[36:39]
	v_mfma_f32_16x16x32_bf16 v[32:35], v[218:221], v[186:189], v[32:35]
	v_mfma_f32_16x16x32_bf16 v[20:23], v[210:213], v[194:197], v[20:23]
	v_mfma_f32_16x16x32_bf16 v[16:19], v[218:221], v[194:197], v[16:19]
	v_mfma_f32_16x16x32_bf16 v[4:7], v[210:213], v[202:205], v[4:7]
	v_mfma_f32_16x16x32_bf16 v[0:3], v[218:221], v[202:205], v[0:3]
	s_add_i32 s46, 0, 0x18000
	v_add_u32_e32 v162, s46, v175
	s_barrier
	ds_read_b128 v[146:149], v162
	ds_read_b128 v[154:157], v162 offset:1024
	ds_read_b128 v[158:161], v162 offset:2048
	ds_read_b128 v[162:165], v162 offset:3072
	s_add_u32 s24, s24, 0x40000
	s_addc_u32 s25, s25, 0
	s_mov_b32 m0, s31
	v_lshl_add_u64 v[206:207], s[24:25], 0, v[128:129]
	ds_read_b128 v[166:169], v178 offset:32768
	ds_read_b128 v[170:173], v178 offset:33792
	ds_read_b128 v[182:185], v178 offset:34816
	ds_read_b128 v[186:189], v178 offset:35840
	ds_read_b128 v[190:193], v178 offset:36864
	ds_read_b128 v[194:197], v178 offset:37888
	ds_read_b128 v[198:201], v178 offset:38912
	ds_read_b128 v[202:205], v178 offset:39936
	global_load_lds_dwordx4 v[206:207], off
	v_lshl_add_u64 v[206:207], s[24:25], 0, v[132:133]
	s_mov_b32 m0, s33
	s_nop 0
	global_load_lds_dwordx4 v[206:207], off
	s_waitcnt lgkmcnt(8)
	s_barrier
; #define PG8_STAGE(bufoff, gbase, voff) do { _Pragma("unroll") for (int _i = 0; _i < 2; ++_i) \
;         __builtin_amdgcn_global_load_lds((const unsigned*)((const char*)(gbase) + (voff)[_i]), (LAS unsigned*)(lds + (bufoff) + ldsw + _i * 8192), 16, 0, 0); } while (0)
; #define PG8_LDA(dst, b, h) do { _Pragma("unroll") for (int m = 0; m < 4; ++m) _Pragma("unroll") for (int k = 0; k < 2; ++k) dst[m][k] = *(const LAS bf16x8*)(lds + PG8_SA(b, h) + aoff + m * 2048 + k * 1024); } while (0)
; #define PG8_LDB(dst, b, h) do { _Pragma("unroll") for (int n = 0; n < 2; ++n) _Pragma("unroll") for (int k = 0; k < 2; ++k) dst[n][k] = *(const LAS bf16x8*)(lds + PG8_SB(b, h) + boff + n * 2048 + k * 1024); } while (0)
; #define PG8_MMA(ai, bj, At, Bt) do { __builtin_amdgcn_s_setprio(1); _Pragma("unroll") for (int m = 0; m < 4; ++m) _Pragma("unroll") for (int n = 0; n < 2; ++n) _Pragma("unroll") for (int k = 0; k < 2; ++k) \
;         acc[ai][bj][m][n] = __builtin_amdgcn_mfma_f32_16x16x32_bf16(Bt[n][k], At[m][k], acc[ai][bj][m][n], 0, 0, 0); __builtin_amdgcn_s_setprio(0); } while (0)
; #define PG8_WAIT_V(n) asm volatile("s_waitcnt vmcnt(" #n ")" ::: "memory")
; #define PG8_WAIT_L(n) asm volatile("s_waitcnt lgkmcnt(" #n ")" ::: "memory")
; #define PG8_BAR __builtin_amdgcn_s_barrier()
; #define PG8_SCHED __builtin_amdgcn_sched_barrier(0)
; template <class Epi>
; __device__ __forceinline__ void gemm_phase(LAS unsigned char* lds, const Gemm g, const StaticOrder& S, const Epi& E) {
;     ...
;             PG8_WAIT_L(8); PG8_BAR; PG8_WAIT_L(0); PG8_MMA(0, 0, At, B0); PG8_BAR; PG8_SCHED;
;             PG8_LDB(B1, 1, 1); PG8_STAGE(PG8_SB(1, 0), b3, voffB);
;             PG8_BAR; PG8_WAIT_L(0); PG8_MMA(0, 1, At, B1); PG8_BAR;
;             PG8_LDA(At, 1, 1); PG8_STAGE(PG8_SA(1, 0), a3, voffA);
;             PG8_BAR; PG8_WAIT_L(0); PG8_MMA(1, 0, At, B0); PG8_BAR; PG8_SCHED;
;             PG8_STAGE(PG8_SB(1, 1), b3 + hstepB, voffB);
;             PG8_WAIT_V(6); PG8_BAR; PG8_MMA(1, 1, At, B1); PG8_BAR;
	s_waitcnt lgkmcnt(0)
	s_waitcnt lgkmcnt(0)
	v_mfma_f32_16x16x32_bf16 v[124:127], v[146:149], v[166:169], v[124:127]
	v_mfma_f32_16x16x32_bf16 v[120:123], v[158:161], v[166:169], v[120:123]
	v_mfma_f32_16x16x32_bf16 v[108:111], v[146:149], v[182:185], v[108:111]
	v_mfma_f32_16x16x32_bf16 v[104:107], v[158:161], v[182:185], v[104:107]
	v_mfma_f32_16x16x32_bf16 v[92:95], v[146:149], v[190:193], v[92:95]
	v_mfma_f32_16x16x32_bf16 v[88:91], v[158:161], v[190:193], v[88:91]
	v_mfma_f32_16x16x32_bf16 v[76:79], v[146:149], v[198:201], v[76:79]
	v_mfma_f32_16x16x32_bf16 v[72:75], v[158:161], v[198:201], v[72:75]
	v_mfma_f32_16x16x32_bf16 v[124:127], v[154:157], v[170:173], v[124:127]
	v_mfma_f32_16x16x32_bf16 v[120:123], v[162:165], v[170:173], v[120:123]
	v_mfma_f32_16x16x32_bf16 v[108:111], v[154:157], v[186:189], v[108:111]
	v_mfma_f32_16x16x32_bf16 v[104:107], v[162:165], v[186:189], v[104:107]
	v_mfma_f32_16x16x32_bf16 v[92:95], v[154:157], v[194:197], v[92:95]
	v_mfma_f32_16x16x32_bf16 v[88:91], v[162:165], v[194:197], v[88:91]
	v_mfma_f32_16x16x32_bf16 v[76:79], v[154:157], v[202:205], v[76:79]
	v_mfma_f32_16x16x32_bf16 v[72:75], v[162:165], v[202:205], v[72:75]
	s_barrier
	s_add_i32 s24, 0, 0x1c000
	s_add_i32 s25, s46, s29
	v_add_u32_e32 v181, s24, v175
	v_lshl_add_u64 v[150:151], v[150:151], 0, s[4:5]
	s_mov_b32 m0, s25
	ds_read_b128 v[206:209], v181
	ds_read_b128 v[210:213], v181 offset:1024
	ds_read_b128 v[214:217], v181 offset:2048
	ds_read_b128 v[218:221], v181 offset:3072
	global_load_lds_dwordx4 v[150:151], off
	v_lshl_add_u64 v[150:151], v[222:223], 0, s[4:5]
	s_add_i32 m0, s25, 0x2000
	s_nop 0
	global_load_lds_dwordx4 v[150:151], off
	s_barrier
	s_waitcnt lgkmcnt(0)
	s_waitcnt lgkmcnt(0)
	v_mfma_f32_16x16x32_bf16 v[116:119], v[206:209], v[166:169], v[116:119]
	v_mfma_f32_16x16x32_bf16 v[112:115], v[214:217], v[166:169], v[112:115]
	v_mfma_f32_16x16x32_bf16 v[100:103], v[206:209], v[182:185], v[100:103]
	v_mfma_f32_16x16x32_bf16 v[96:99], v[214:217], v[182:185], v[96:99]
	v_mfma_f32_16x16x32_bf16 v[84:87], v[206:209], v[190:193], v[84:87]
	v_mfma_f32_16x16x32_bf16 v[80:83], v[214:217], v[190:193], v[80:83]
	v_mfma_f32_16x16x32_bf16 v[68:71], v[206:209], v[198:201], v[68:71]
	v_mfma_f32_16x16x32_bf16 v[64:67], v[214:217], v[198:201], v[64:67]
	v_mfma_f32_16x16x32_bf16 v[116:119], v[210:213], v[170:173], v[116:119]
	v_mfma_f32_16x16x32_bf16 v[112:115], v[218:221], v[170:173], v[112:115]
	v_mfma_f32_16x16x32_bf16 v[100:103], v[210:213], v[186:189], v[100:103]
	v_mfma_f32_16x16x32_bf16 v[96:99], v[218:221], v[186:189], v[96:99]
	v_mfma_f32_16x16x32_bf16 v[84:87], v[210:213], v[194:197], v[84:87]
	v_mfma_f32_16x16x32_bf16 v[80:83], v[218:221], v[194:197], v[80:83]
	v_mfma_f32_16x16x32_bf16 v[68:71], v[210:213], v[202:205], v[68:71]
	v_mfma_f32_16x16x32_bf16 v[64:67], v[218:221], v[202:205], v[64:67]
	s_mov_b32 m0, s35
	v_lshl_add_u64 v[150:151], v[224:225], 0, s[4:5]
	s_barrier
	ds_read_b128 v[166:169], v178 offset:49152
	ds_read_b128 v[170:173], v178 offset:50176
	ds_read_b128 v[182:185], v178 offset:51200
	ds_read_b128 v[186:189], v178 offset:52224
	ds_read_b128 v[190:193], v178 offset:53248
	ds_read_b128 v[194:197], v178 offset:54272
	ds_read_b128 v[198:201], v178 offset:55296
	ds_read_b128 v[202:205], v178 offset:56320
	global_load_lds_dwordx4 v[150:151], off
	v_lshl_add_u64 v[150:151], v[226:227], 0, s[4:5]
	s_mov_b32 m0, s36
	s_nop 0
	global_load_lds_dwordx4 v[150:151], off
	s_barrier
	s_waitcnt lgkmcnt(0)
	s_waitcnt lgkmcnt(0)
	v_mfma_f32_16x16x32_bf16 v[60:63], v[146:149], v[166:169], v[60:63]
	v_mfma_f32_16x16x32_bf16 v[56:59], v[158:161], v[166:169], v[56:59]
	v_mfma_f32_16x16x32_bf16 v[44:47], v[146:149], v[182:185], v[44:47]
	v_mfma_f32_16x16x32_bf16 v[40:43], v[158:161], v[182:185], v[40:43]
	v_mfma_f32_16x16x32_bf16 v[28:31], v[146:149], v[190:193], v[28:31]
	v_mfma_f32_16x16x32_bf16 v[24:27], v[158:161], v[190:193], v[24:27]
	v_mfma_f32_16x16x32_bf16 v[12:15], v[146:149], v[198:201], v[12:15]
	v_mfma_f32_16x16x32_bf16 v[8:11], v[158:161], v[198:201], v[8:11]
	v_mfma_f32_16x16x32_bf16 v[60:63], v[154:157], v[170:173], v[60:63]
	v_mfma_f32_16x16x32_bf16 v[56:59], v[162:165], v[170:173], v[56:59]
	v_mfma_f32_16x16x32_bf16 v[44:47], v[154:157], v[186:189], v[44:47]
	v_mfma_f32_16x16x32_bf16 v[40:43], v[162:165], v[186:189], v[40:43]
	v_mfma_f32_16x16x32_bf16 v[28:31], v[154:157], v[194:197], v[28:31]
	v_mfma_f32_16x16x32_bf16 v[24:27], v[162:165], v[194:197], v[24:27]
	v_mfma_f32_16x16x32_bf16 v[12:15], v[154:157], v[202:205], v[12:15]
	v_mfma_f32_16x16x32_bf16 v[8:11], v[162:165], v[202:205], v[8:11]
	s_barrier
	s_add_u32 s22, s22, 0x40080
	s_addc_u32 s23, s23, 0
	s_add_i32 s24, s24, s29
	v_lshl_add_u64 v[146:147], s[22:23], 0, v[130:131]
	s_mov_b32 m0, s24
	s_nop 0
	global_load_lds_dwordx4 v[146:147], off
	v_lshl_add_u64 v[146:147], s[22:23], 0, v[134:135]
	s_add_i32 m0, s24, 0x2000
	s_nop 0
	global_load_lds_dwordx4 v[146:147], off
	s_waitcnt vmcnt(6)
	s_barrier
	v_mfma_f32_16x16x32_bf16 v[52:55], v[206:209], v[166:169], v[52:55]
	v_mfma_f32_16x16x32_bf16 v[48:51], v[214:217], v[166:169], v[48:51]
	v_mfma_f32_16x16x32_bf16 v[36:39], v[206:209], v[182:185], v[36:39]
	v_mfma_f32_16x16x32_bf16 v[32:35], v[214:217], v[182:185], v[32:35]
	v_mfma_f32_16x16x32_bf16 v[20:23], v[206:209], v[190:193], v[20:23]
	v_mfma_f32_16x16x32_bf16 v[16:19], v[214:217], v[190:193], v[16:19]
	v_mfma_f32_16x16x32_bf16 v[4:7], v[206:209], v[198:201], v[4:7]
	v_mfma_f32_16x16x32_bf16 v[0:3], v[214:217], v[198:201], v[0:3]
	v_mfma_f32_16x16x32_bf16 v[52:55], v[210:213], v[170:173], v[52:55]
	v_mfma_f32_16x16x32_bf16 v[48:51], v[218:221], v[170:173], v[48:51]
	v_mfma_f32_16x16x32_bf16 v[36:39], v[210:213], v[186:189], v[36:39]
	v_mfma_f32_16x16x32_bf16 v[32:35], v[218:221], v[186:189], v[32:35]
	v_mfma_f32_16x16x32_bf16 v[20:23], v[210:213], v[194:197], v[20:23]
	v_mfma_f32_16x16x32_bf16 v[16:19], v[218:221], v[194:197], v[16:19]
	v_mfma_f32_16x16x32_bf16 v[4:7], v[210:213], v[202:205], v[4:7]
	v_mfma_f32_16x16x32_bf16 v[0:3], v[218:221], v[202:205], v[0:3]
	s_add_i32 s45, s45, 2
	s_add_u32 s20, s20, 0x100
	s_addc_u32 s21, s21, 0
	s_add_u32 s43, s43, 0x100
	s_addc_u32 s44, s44, 0
	s_cmp_gt_u32 s45, 13
	s_barrier
; __device__ __forceinline__ unsigned pk2(float lo, float hi) { const f32x2 v = (f32x2){lo, hi}; const bf16x2_t b = __builtin_convertvector(v, bf16x2_t); return __builtin_bit_cast(unsigned, b); }
;     __device__ __forceinline__ void operator()(const f32x4 (&acc)[2][2][4][2], const Unit& u, int wr, int wc, int fr, int fq, const float (&)[8]) const {
;     ...
;             for (int m = 0; m < 4; ++m) { const int row = row0 + ai * HALF + m * 16; const float rs = rsqrtf(ep[ai * 4 + m] * (1.0f / 1024.0f) + EPS);
;                 u16* rowp = O + (size_t)row * ldc + col0;
; #pragma unroll
;                 for (int bj = 0; bj < 2; ++bj) { f32x4 v0 = acc[ai][bj][m][0] * rs, v1 = acc[ai][bj][m][1] * rs;
;                     if (ACT == 1) {
; #pragma unroll
;                         for (int j = 0; j < 4; ++j) { const float a0 = fmaxf(v0[j], 0.f), a1 = fmaxf(v1[j], 0.f); v0[j] = a0 * a0; v1[j] = a1 * a1; } }
;                     u32x4 w; w.x = pk2(v0[0], v0[1]); w.y = pk2(v0[2], v0[3]); w.z = pk2(v1[0], v1[1]); w.w = pk2(v1[2], v1[3]);
;                     *(u32x4*)(rowp + bj * HALF) = w; } }
	s_cbranch_scc0 .LBB0_770
	s_bfe_u32 vcc_lo, s18, 0x20003
	s_lshl_b32 vcc_lo, vcc_lo, 10
	s_add_i32 vcc_lo, vcc_lo, 0x20010
	v_lshl_add_u32 v236, v174, 2, vcc_lo
	ds_read_b32 v228, v236
	ds_read_b32 v229, v236 offset:64
	ds_read_b32 v230, v236 offset:128
	ds_read_b32 v231, v236 offset:192
	ds_read_b32 v232, v236 offset:512
	ds_read_b32 v233, v236 offset:576
	ds_read_b32 v234, v236 offset:640
	ds_read_b32 v235, v236 offset:704
	s_waitcnt lgkmcnt(0)
	v_lshl_add_u32 v148, s18, 8, v174
	v_ashrrev_i32_e32 v149, 31, v148
	v_or_b32_e32 v172, 16, v148
	v_ashrrev_i32_e32 v173, 31, v172
	v_or_b32_e32 v168, 32, v148
	v_or_b32_e32 v164, 48, v148
	v_ashrrev_i32_e32 v169, 31, v168
	v_ashrrev_i32_e32 v165, 31, v164
	v_add_u32_e32 v162, 0x80, v148
	v_add_u32_e32 v156, 0x90, v148
	v_ashrrev_i32_e32 v163, 31, v162
	v_ashrrev_i32_e32 v157, 31, v156
	v_add_u32_e32 v150, 0xa0, v148
	v_ashrrev_i32_e32 v151, 31, v150
	v_add_u32_e32 v146, 0xb0, v148
	v_ashrrev_i32_e32 v147, 31, v146
	v_lshl_or_b32 v166, s40, 8, v176
	v_ashrrev_i32_e32 v167, 31, v166
	v_lshlrev_b64 v[170:171], 13, v[148:149]
	v_lshlrev_b64 v[148:149], 1, v[166:167]
	v_lshl_add_u64 v[166:167], s[96:97], 0, v[170:171]
	v_lshl_add_u64 v[212:213], v[166:167], 0, v[148:149]
	s_mov_b32 s40, s10
	s_mov_b32 s18, s12
	s_mov_b64 s[22:23], s[16:17]
	s_mov_b64 s[20:21], s[14:15]
	s_waitcnt vmcnt(8)
	s_waitcnt lgkmcnt(0)
	s_waitcnt lgkmcnt(0)
	v_mov_b32_e32 v184, v228
	v_pk_mul_f32 v[120:121], v[120:121], v[184:185] op_sel_hi:[1,0]
	v_pk_mul_f32 v[126:127], v[126:127], v[184:185] op_sel_hi:[1,0]
	v_pk_mul_f32 v[124:125], v[124:125], v[184:185] op_sel_hi:[1,0]
	v_pk_mul_f32 v[122:123], v[122:123], v[184:185] op_sel_hi:[1,0]
	v_max_f32_e32 v120, 0, v120
	v_max_f32_e32 v121, 0, v121
	v_max_f32_e32 v124, 0, v124
	v_max_f32_e32 v125, 0, v125
	v_pk_mul_f32 v[190:191], v[120:121], v[120:121]
	v_max_f32_e32 v120, 0, v126
	v_max_f32_e32 v122, 0, v122
	v_max_f32_e32 v121, 0, v127
	v_max_f32_e32 v123, 0, v123
	v_pk_mul_f32 v[124:125], v[124:125], v[124:125]
	v_pk_mul_f32 v[126:127], v[120:121], v[120:121]
	v_pk_mul_f32 v[194:195], v[122:123], v[122:123]
	v_pk_mul_f32 v[114:115], v[114:115], v[184:185] op_sel_hi:[1,0]
	v_cvt_pk_bf16_f32 v120, v124, v125
	v_cvt_pk_bf16_f32 v121, v126, v127
	v_cvt_pk_bf16_f32 v122, v190, v191
	v_cvt_pk_bf16_f32 v123, v194, v195
	v_pk_mul_f32 v[116:117], v[116:117], v[184:185] op_sel_hi:[1,0]
	v_pk_mul_f32 v[112:113], v[112:113], v[184:185] op_sel_hi:[1,0]
	v_max_f32_e32 v114, 0, v114
	v_max_f32_e32 v115, 0, v115
	global_store_dwordx4 v[212:213], v[120:123], off
	v_pk_mul_f32 v[118:119], v[118:119], v[184:185] op_sel_hi:[1,0]
	v_max_f32_e32 v116, 0, v116
	v_max_f32_e32 v112, 0, v112
	v_max_f32_e32 v117, 0, v117
	v_max_f32_e32 v113, 0, v113
	v_pk_mul_f32 v[122:123], v[114:115], v[114:115]
	v_pk_mul_f32 v[116:117], v[116:117], v[116:117]
	v_pk_mul_f32 v[120:121], v[112:113], v[112:113]
	v_max_f32_e32 v112, 0, v118
	v_max_f32_e32 v113, 0, v119
	v_pk_mul_f32 v[118:119], v[112:113], v[112:113]
	v_cvt_pk_bf16_f32 v112, v116, v117
	v_cvt_pk_bf16_f32 v113, v118, v119
	v_cvt_pk_bf16_f32 v114, v120, v121
	v_cvt_pk_bf16_f32 v115, v122, v123
	global_store_dwordx4 v[212:213], v[112:115], off offset:256
	s_nop 1
	v_mov_b32_e32 v112, v229
	v_pk_mul_f32 v[104:105], v[104:105], v[112:113] op_sel_hi:[1,0]
	v_pk_mul_f32 v[110:111], v[110:111], v[112:113] op_sel_hi:[1,0]
	v_pk_mul_f32 v[108:109], v[108:109], v[112:113] op_sel_hi:[1,0]
	v_pk_mul_f32 v[106:107], v[106:107], v[112:113] op_sel_hi:[1,0]
	v_max_f32_e32 v104, 0, v104
	v_max_f32_e32 v105, 0, v105
	v_lshlrev_b64 v[114:115], 13, v[172:173]
	v_max_f32_e32 v108, 0, v108
	v_max_f32_e32 v109, 0, v109
	v_pk_mul_f32 v[116:117], v[104:105], v[104:105]
	v_max_f32_e32 v104, 0, v110
	v_max_f32_e32 v106, 0, v106
	v_max_f32_e32 v105, 0, v111
	v_max_f32_e32 v107, 0, v107
	v_lshl_add_u64 v[114:115], s[96:97], 0, v[114:115]
	v_pk_mul_f32 v[108:109], v[108:109], v[108:109]
	v_pk_mul_f32 v[110:111], v[104:105], v[104:105]
	v_pk_mul_f32 v[118:119], v[106:107], v[106:107]
	v_pk_mul_f32 v[96:97], v[96:97], v[112:113] op_sel_hi:[1,0]
	v_lshl_add_u64 v[114:115], v[114:115], 0, v[148:149]
	v_cvt_pk_bf16_f32 v104, v108, v109
	v_cvt_pk_bf16_f32 v105, v110, v111
	v_cvt_pk_bf16_f32 v106, v116, v117
	v_cvt_pk_bf16_f32 v107, v118, v119
	v_pk_mul_f32 v[102:103], v[102:103], v[112:113] op_sel_hi:[1,0]
	v_max_f32_e32 v96, 0, v96
	v_max_f32_e32 v97, 0, v97
	global_store_dwordx4 v[114:115], v[104:107], off
	v_pk_mul_f32 v[100:101], v[100:101], v[112:113] op_sel_hi:[1,0]
	v_pk_mul_f32 v[98:99], v[98:99], v[112:113] op_sel_hi:[1,0]
	v_pk_mul_f32 v[104:105], v[96:97], v[96:97]
	v_max_f32_e32 v96, 0, v102
	v_max_f32_e32 v97, 0, v103
	v_max_f32_e32 v100, 0, v100
	v_max_f32_e32 v101, 0, v101
	v_pk_mul_f32 v[100:101], v[100:101], v[100:101]
	v_pk_mul_f32 v[108:109], v[96:97], v[96:97]
	v_cvt_pk_bf16_f32 v96, v100, v101
	s_waitcnt lgkmcnt(0)
	v_max_f32_e32 v98, 0, v98
	v_max_f32_e32 v99, 0, v99
	v_pk_mul_f32 v[110:111], v[98:99], v[98:99]
	v_cvt_pk_bf16_f32 v97, v108, v109
	v_cvt_pk_bf16_f32 v98, v104, v105
	v_cvt_pk_bf16_f32 v99, v110, v111
	global_store_dwordx4 v[114:115], v[96:99], off offset:256
	s_waitcnt lgkmcnt(0)
; __device__ __forceinline__ unsigned pk2(float lo, float hi) { const f32x2 v = (f32x2){lo, hi}; const bf16x2_t b = __builtin_convertvector(v, bf16x2_t); return __builtin_bit_cast(unsigned, b); }
;     __device__ __forceinline__ void operator()(const f32x4 (&acc)[2][2][4][2], const Unit& u, int wr, int wc, int fr, int fq, const float (&)[8]) const {
;     ...
;             for (int m = 0; m < 4; ++m) { const int row = row0 + ai * HALF + m * 16; const float rs = rsqrtf(ep[ai * 4 + m] * (1.0f / 1024.0f) + EPS);
;                 u16* rowp = O + (size_t)row * ldc + col0;
; #pragma unroll
;                 for (int bj = 0; bj < 2; ++bj) { f32x4 v0 = acc[ai][bj][m][0] * rs, v1 = acc[ai][bj][m][1] * rs;
;                     if (ACT == 1) {
; #pragma unroll
;                         for (int j = 0; j < 4; ++j) { const float a0 = fmaxf(v0[j], 0.f), a1 = fmaxf(v1[j], 0.f); v0[j] = a0 * a0; v1[j] = a1 * a1; } }
;                     u32x4 w; w.x = pk2(v0[0], v0[1]); w.y = pk2(v0[2], v0[3]); w.z = pk2(v1[0], v1[1]); w.w = pk2(v1[2], v1[3]);
;                     *(u32x4*)(rowp + bj * HALF) = w; } }
	s_nop 0
	s_nop 0
	s_nop 0
	s_nop 1
	v_lshlrev_b64 v[98:99], 13, v[168:169]
	v_lshl_add_u64 v[98:99], s[96:97], 0, v[98:99]
	v_lshl_add_u64 v[98:99], v[98:99], 0, v[148:149]
	v_mov_b32_e32 v100, v230
	v_pk_mul_f32 v[88:89], v[88:89], v[100:101] op_sel_hi:[1,0]
	v_pk_mul_f32 v[94:95], v[94:95], v[100:101] op_sel_hi:[1,0]
	v_pk_mul_f32 v[92:93], v[92:93], v[100:101] op_sel_hi:[1,0]
	v_pk_mul_f32 v[90:91], v[90:91], v[100:101] op_sel_hi:[1,0]
	v_max_f32_e32 v88, 0, v88
	v_max_f32_e32 v89, 0, v89
	v_max_f32_e32 v92, 0, v92
	v_max_f32_e32 v93, 0, v93
	v_pk_mul_f32 v[102:103], v[88:89], v[88:89]
	v_max_f32_e32 v88, 0, v94
	v_max_f32_e32 v90, 0, v90
	v_max_f32_e32 v89, 0, v95
	v_max_f32_e32 v91, 0, v91
	v_pk_mul_f32 v[92:93], v[92:93], v[92:93]
	v_pk_mul_f32 v[94:95], v[88:89], v[88:89]
	v_pk_mul_f32 v[104:105], v[90:91], v[90:91]
	v_pk_mul_f32 v[82:83], v[82:83], v[100:101] op_sel_hi:[1,0]
	v_cvt_pk_bf16_f32 v88, v92, v93
	v_cvt_pk_bf16_f32 v89, v94, v95
	v_cvt_pk_bf16_f32 v90, v102, v103
	v_cvt_pk_bf16_f32 v91, v104, v105
	v_pk_mul_f32 v[84:85], v[84:85], v[100:101] op_sel_hi:[1,0]
	v_pk_mul_f32 v[80:81], v[80:81], v[100:101] op_sel_hi:[1,0]
	v_max_f32_e32 v82, 0, v82
	v_max_f32_e32 v83, 0, v83
	global_store_dwordx4 v[98:99], v[88:91], off
	v_pk_mul_f32 v[86:87], v[86:87], v[100:101] op_sel_hi:[1,0]
	v_max_f32_e32 v84, 0, v84
	v_max_f32_e32 v80, 0, v80
	v_max_f32_e32 v85, 0, v85
	v_max_f32_e32 v81, 0, v81
	v_pk_mul_f32 v[90:91], v[82:83], v[82:83]
	v_pk_mul_f32 v[84:85], v[84:85], v[84:85]
	v_pk_mul_f32 v[88:89], v[80:81], v[80:81]
	v_max_f32_e32 v80, 0, v86
	v_max_f32_e32 v81, 0, v87
	v_pk_mul_f32 v[86:87], v[80:81], v[80:81]
	v_cvt_pk_bf16_f32 v80, v84, v85
	v_cvt_pk_bf16_f32 v81, v86, v87
	v_cvt_pk_bf16_f32 v82, v88, v89
	v_cvt_pk_bf16_f32 v83, v90, v91
	global_store_dwordx4 v[98:99], v[80:83], off offset:256
	s_nop 1
	v_mov_b32_e32 v80, v231
	v_pk_mul_f32 v[72:73], v[72:73], v[80:81] op_sel_hi:[1,0]
	v_pk_mul_f32 v[78:79], v[78:79], v[80:81] op_sel_hi:[1,0]
	v_pk_mul_f32 v[76:77], v[76:77], v[80:81] op_sel_hi:[1,0]
	v_pk_mul_f32 v[74:75], v[74:75], v[80:81] op_sel_hi:[1,0]
	v_max_f32_e32 v72, 0, v72
	v_max_f32_e32 v73, 0, v73
	v_lshlrev_b64 v[82:83], 13, v[164:165]
	v_max_f32_e32 v76, 0, v76
	v_max_f32_e32 v77, 0, v77
	v_pk_mul_f32 v[84:85], v[72:73], v[72:73]
	v_max_f32_e32 v72, 0, v78
	v_max_f32_e32 v74, 0, v74
	v_max_f32_e32 v73, 0, v79
	v_max_f32_e32 v75, 0, v75
	v_lshl_add_u64 v[82:83], s[96:97], 0, v[82:83]
	v_pk_mul_f32 v[76:77], v[76:77], v[76:77]
	v_pk_mul_f32 v[78:79], v[72:73], v[72:73]
	v_pk_mul_f32 v[86:87], v[74:75], v[74:75]
	v_pk_mul_f32 v[64:65], v[64:65], v[80:81] op_sel_hi:[1,0]
	v_lshl_add_u64 v[82:83], v[82:83], 0, v[148:149]
	v_cvt_pk_bf16_f32 v72, v76, v77
	v_cvt_pk_bf16_f32 v73, v78, v79
	v_cvt_pk_bf16_f32 v74, v84, v85
	v_cvt_pk_bf16_f32 v75, v86, v87
	v_pk_mul_f32 v[70:71], v[70:71], v[80:81] op_sel_hi:[1,0]
	v_max_f32_e32 v64, 0, v64
	v_max_f32_e32 v65, 0, v65
	global_store_dwordx4 v[82:83], v[72:75], off
	v_pk_mul_f32 v[68:69], v[68:69], v[80:81] op_sel_hi:[1,0]
	v_pk_mul_f32 v[66:67], v[66:67], v[80:81] op_sel_hi:[1,0]
	v_pk_mul_f32 v[72:73], v[64:65], v[64:65]
	v_max_f32_e32 v64, 0, v70
	v_max_f32_e32 v65, 0, v71
	v_max_f32_e32 v68, 0, v68
	v_max_f32_e32 v69, 0, v69
	v_pk_mul_f32 v[68:69], v[68:69], v[68:69]
	v_pk_mul_f32 v[76:77], v[64:65], v[64:65]
	v_cvt_pk_bf16_f32 v64, v68, v69
	s_waitcnt lgkmcnt(0)
	v_max_f32_e32 v66, 0, v66
	v_max_f32_e32 v67, 0, v67
	v_pk_mul_f32 v[78:79], v[66:67], v[66:67]
	v_cvt_pk_bf16_f32 v65, v76, v77
	v_cvt_pk_bf16_f32 v66, v72, v73
	v_cvt_pk_bf16_f32 v67, v78, v79
	global_store_dwordx4 v[82:83], v[64:67], off offset:256
	s_waitcnt lgkmcnt(0)
	s_nop 0
	s_nop 0
	s_nop 0
	s_nop 1
	v_lshlrev_b64 v[66:67], 13, v[162:163]
	v_lshl_add_u64 v[66:67], s[96:97], 0, v[66:67]
	v_lshl_add_u64 v[66:67], v[66:67], 0, v[148:149]
	v_mov_b32_e32 v68, v232
	v_pk_mul_f32 v[56:57], v[56:57], v[68:69] op_sel_hi:[1,0]
	v_pk_mul_f32 v[62:63], v[62:63], v[68:69] op_sel_hi:[1,0]
	v_pk_mul_f32 v[60:61], v[60:61], v[68:69] op_sel_hi:[1,0]
	v_pk_mul_f32 v[58:59], v[58:59], v[68:69] op_sel_hi:[1,0]
	v_max_f32_e32 v56, 0, v56
	v_max_f32_e32 v57, 0, v57
	v_max_f32_e32 v60, 0, v60
	v_max_f32_e32 v61, 0, v61
	v_pk_mul_f32 v[70:71], v[56:57], v[56:57]
	v_max_f32_e32 v56, 0, v62
	v_max_f32_e32 v58, 0, v58
	v_max_f32_e32 v57, 0, v63
	v_max_f32_e32 v59, 0, v59
	v_pk_mul_f32 v[60:61], v[60:61], v[60:61]
	v_pk_mul_f32 v[62:63], v[56:57], v[56:57]
	v_pk_mul_f32 v[72:73], v[58:59], v[58:59]
	v_pk_mul_f32 v[50:51], v[50:51], v[68:69] op_sel_hi:[1,0]
	v_cvt_pk_bf16_f32 v56, v60, v61
	v_cvt_pk_bf16_f32 v57, v62, v63
	v_cvt_pk_bf16_f32 v58, v70, v71
	v_cvt_pk_bf16_f32 v59, v72, v73
	v_pk_mul_f32 v[52:53], v[52:53], v[68:69] op_sel_hi:[1,0]
	v_pk_mul_f32 v[48:49], v[48:49], v[68:69] op_sel_hi:[1,0]
	v_max_f32_e32 v50, 0, v50
	v_max_f32_e32 v51, 0, v51
	global_store_dwordx4 v[66:67], v[56:59], off
	v_pk_mul_f32 v[54:55], v[54:55], v[68:69] op_sel_hi:[1,0]
	v_max_f32_e32 v52, 0, v52
	v_max_f32_e32 v48, 0, v48
	v_max_f32_e32 v53, 0, v53
	v_max_f32_e32 v49, 0, v49
	v_pk_mul_f32 v[58:59], v[50:51], v[50:51]
	v_pk_mul_f32 v[52:53], v[52:53], v[52:53]
	v_pk_mul_f32 v[56:57], v[48:49], v[48:49]
	v_max_f32_e32 v48, 0, v54
	v_max_f32_e32 v49, 0, v55
	v_pk_mul_f32 v[54:55], v[48:49], v[48:49]
	v_cvt_pk_bf16_f32 v48, v52, v53
	v_cvt_pk_bf16_f32 v49, v54, v55
	v_cvt_pk_bf16_f32 v50, v56, v57
	v_cvt_pk_bf16_f32 v51, v58, v59
	global_store_dwordx4 v[66:67], v[48:51], off offset:256
	s_nop 1
	v_mov_b32_e32 v48, v233
	v_pk_mul_f32 v[40:41], v[40:41], v[48:49] op_sel_hi:[1,0]
	v_pk_mul_f32 v[46:47], v[46:47], v[48:49] op_sel_hi:[1,0]
	v_pk_mul_f32 v[44:45], v[44:45], v[48:49] op_sel_hi:[1,0]
	v_pk_mul_f32 v[42:43], v[42:43], v[48:49] op_sel_hi:[1,0]
	v_max_f32_e32 v40, 0, v40
	v_max_f32_e32 v41, 0, v41
	v_lshlrev_b64 v[50:51], 13, v[156:157]
	v_max_f32_e32 v44, 0, v44
	v_max_f32_e32 v45, 0, v45
	v_pk_mul_f32 v[52:53], v[40:41], v[40:41]
	v_max_f32_e32 v40, 0, v46
	v_max_f32_e32 v42, 0, v42
	v_max_f32_e32 v41, 0, v47
	v_max_f32_e32 v43, 0, v43
	v_lshl_add_u64 v[50:51], s[96:97], 0, v[50:51]
	v_pk_mul_f32 v[44:45], v[44:45], v[44:45]
	v_pk_mul_f32 v[46:47], v[40:41], v[40:41]
	v_pk_mul_f32 v[54:55], v[42:43], v[42:43]
	v_pk_mul_f32 v[32:33], v[32:33], v[48:49] op_sel_hi:[1,0]
	v_lshl_add_u64 v[50:51], v[50:51], 0, v[148:149]
	v_cvt_pk_bf16_f32 v40, v44, v45
	v_cvt_pk_bf16_f32 v41, v46, v47
	v_cvt_pk_bf16_f32 v42, v52, v53
	v_cvt_pk_bf16_f32 v43, v54, v55
	v_pk_mul_f32 v[38:39], v[38:39], v[48:49] op_sel_hi:[1,0]
	v_max_f32_e32 v32, 0, v32
	v_max_f32_e32 v33, 0, v33
	global_store_dwordx4 v[50:51], v[40:43], off
	v_pk_mul_f32 v[36:37], v[36:37], v[48:49] op_sel_hi:[1,0]
	v_pk_mul_f32 v[34:35], v[34:35], v[48:49] op_sel_hi:[1,0]
	v_pk_mul_f32 v[40:41], v[32:33], v[32:33]
	v_max_f32_e32 v32, 0, v38
	v_max_f32_e32 v33, 0, v39
	v_max_f32_e32 v36, 0, v36
	v_max_f32_e32 v37, 0, v37
	v_pk_mul_f32 v[36:37], v[36:37], v[36:37]
	v_pk_mul_f32 v[44:45], v[32:33], v[32:33]
	v_cvt_pk_bf16_f32 v32, v36, v37
	s_waitcnt lgkmcnt(0)
; __device__ __forceinline__ unsigned pk2(float lo, float hi) { const f32x2 v = (f32x2){lo, hi}; const bf16x2_t b = __builtin_convertvector(v, bf16x2_t); return __builtin_bit_cast(unsigned, b); }
; #define PG8_WAIT_V(n) asm volatile("s_waitcnt vmcnt(" #n ")" ::: "memory")
; #define PG8_BAR __builtin_amdgcn_s_barrier()
;     __device__ __forceinline__ void operator()(const f32x4 (&acc)[2][2][4][2], const Unit& u, int wr, int wc, int fr, int fq, const float (&)[8]) const {
;     ...
;             for (int m = 0; m < 4; ++m) { const int row = row0 + ai * HALF + m * 16; const float rs = rsqrtf(ep[ai * 4 + m] * (1.0f / 1024.0f) + EPS);
;                 u16* rowp = O + (size_t)row * ldc + col0;
; #pragma unroll
;                 for (int bj = 0; bj < 2; ++bj) { f32x4 v0 = acc[ai][bj][m][0] * rs, v1 = acc[ai][bj][m][1] * rs;
;                     if (ACT == 1) {
; #pragma unroll
;                         for (int j = 0; j < 4; ++j) { const float a0 = fmaxf(v0[j], 0.f), a1 = fmaxf(v1[j], 0.f); v0[j] = a0 * a0; v1[j] = a1 * a1; } }
;                     u32x4 w; w.x = pk2(v0[0], v0[1]); w.y = pk2(v0[2], v0[3]); w.z = pk2(v1[0], v1[1]); w.w = pk2(v1[2], v1[3]);
;                     *(u32x4*)(rowp + bj * HALF) = w; } }
; template <class Epi>
; __device__ __forceinline__ void gemm_phase(LAS unsigned char* lds, const Gemm g, const StaticOrder& S, const Epi& E) {
;     ...
;         if (!has_next) break;
; #pragma unroll
;         for (int a = 0; a < 2; ++a)
; #pragma unroll
;             for (int b = 0; b < 2; ++b)
; #pragma unroll
;                 for (int m = 0; m < 4; ++m)
; #pragma unroll
;                     for (int n = 0; n < 2; ++n) acc[a][b][m][n] = (f32x4){0.f, 0.f, 0.f, 0.f};
;         cur = nxt; cA = nA; cB = nB; ++ui;
;     }
;     PG8_WAIT_V(0);
;     if (wr == 0) PG8_BAR;
;     PG8_BAR;
	v_max_f32_e32 v34, 0, v34
	v_max_f32_e32 v35, 0, v35
	v_pk_mul_f32 v[46:47], v[34:35], v[34:35]
	v_cvt_pk_bf16_f32 v33, v44, v45
	v_cvt_pk_bf16_f32 v34, v40, v41
	v_cvt_pk_bf16_f32 v35, v46, v47
	global_store_dwordx4 v[50:51], v[32:35], off offset:256
	s_waitcnt lgkmcnt(0)
	s_nop 0
	s_nop 0
	s_nop 0
	s_nop 1
	v_lshlrev_b64 v[34:35], 13, v[150:151]
	v_lshl_add_u64 v[34:35], s[96:97], 0, v[34:35]
	v_lshl_add_u64 v[34:35], v[34:35], 0, v[148:149]
	v_mov_b32_e32 v36, v234
	v_pk_mul_f32 v[24:25], v[24:25], v[36:37] op_sel_hi:[1,0]
	v_pk_mul_f32 v[30:31], v[30:31], v[36:37] op_sel_hi:[1,0]
	v_pk_mul_f32 v[28:29], v[28:29], v[36:37] op_sel_hi:[1,0]
	v_pk_mul_f32 v[26:27], v[26:27], v[36:37] op_sel_hi:[1,0]
	v_max_f32_e32 v24, 0, v24
	v_max_f32_e32 v25, 0, v25
	v_max_f32_e32 v28, 0, v28
	v_max_f32_e32 v29, 0, v29
	v_pk_mul_f32 v[38:39], v[24:25], v[24:25]
	v_max_f32_e32 v24, 0, v30
	v_max_f32_e32 v26, 0, v26
	v_max_f32_e32 v25, 0, v31
	v_max_f32_e32 v27, 0, v27
	v_pk_mul_f32 v[28:29], v[28:29], v[28:29]
	v_pk_mul_f32 v[30:31], v[24:25], v[24:25]
	v_pk_mul_f32 v[40:41], v[26:27], v[26:27]
	v_pk_mul_f32 v[18:19], v[18:19], v[36:37] op_sel_hi:[1,0]
	v_cvt_pk_bf16_f32 v24, v28, v29
	v_cvt_pk_bf16_f32 v25, v30, v31
	v_cvt_pk_bf16_f32 v26, v38, v39
	v_cvt_pk_bf16_f32 v27, v40, v41
	v_pk_mul_f32 v[20:21], v[20:21], v[36:37] op_sel_hi:[1,0]
	v_pk_mul_f32 v[16:17], v[16:17], v[36:37] op_sel_hi:[1,0]
	v_max_f32_e32 v18, 0, v18
	v_max_f32_e32 v19, 0, v19
	global_store_dwordx4 v[34:35], v[24:27], off
	v_pk_mul_f32 v[22:23], v[22:23], v[36:37] op_sel_hi:[1,0]
	v_max_f32_e32 v20, 0, v20
	v_max_f32_e32 v16, 0, v16
	v_max_f32_e32 v21, 0, v21
	v_max_f32_e32 v17, 0, v17
	v_pk_mul_f32 v[26:27], v[18:19], v[18:19]
	v_pk_mul_f32 v[20:21], v[20:21], v[20:21]
	v_pk_mul_f32 v[24:25], v[16:17], v[16:17]
	v_max_f32_e32 v16, 0, v22
	v_max_f32_e32 v17, 0, v23
	v_pk_mul_f32 v[22:23], v[16:17], v[16:17]
	v_cvt_pk_bf16_f32 v16, v20, v21
	v_cvt_pk_bf16_f32 v17, v22, v23
	v_cvt_pk_bf16_f32 v18, v24, v25
	v_cvt_pk_bf16_f32 v19, v26, v27
	global_store_dwordx4 v[34:35], v[16:19], off offset:256
	s_nop 1
	v_mov_b32_e32 v16, v235
	v_pk_mul_f32 v[8:9], v[8:9], v[16:17] op_sel_hi:[1,0]
	v_pk_mul_f32 v[14:15], v[14:15], v[16:17] op_sel_hi:[1,0]
	v_pk_mul_f32 v[12:13], v[12:13], v[16:17] op_sel_hi:[1,0]
	v_pk_mul_f32 v[10:11], v[10:11], v[16:17] op_sel_hi:[1,0]
	v_max_f32_e32 v8, 0, v8
	v_max_f32_e32 v9, 0, v9
	v_lshlrev_b64 v[18:19], 13, v[146:147]
	v_max_f32_e32 v12, 0, v12
	v_max_f32_e32 v13, 0, v13
	v_pk_mul_f32 v[20:21], v[8:9], v[8:9]
	v_max_f32_e32 v8, 0, v14
	v_max_f32_e32 v10, 0, v10
	v_max_f32_e32 v9, 0, v15
	v_max_f32_e32 v11, 0, v11
	v_lshl_add_u64 v[18:19], s[96:97], 0, v[18:19]
	v_pk_mul_f32 v[12:13], v[12:13], v[12:13]
	v_pk_mul_f32 v[14:15], v[8:9], v[8:9]
	v_pk_mul_f32 v[22:23], v[10:11], v[10:11]
	v_pk_mul_f32 v[0:1], v[0:1], v[16:17] op_sel_hi:[1,0]
	v_lshl_add_u64 v[18:19], v[18:19], 0, v[148:149]
	v_cvt_pk_bf16_f32 v8, v12, v13
	v_cvt_pk_bf16_f32 v9, v14, v15
	v_cvt_pk_bf16_f32 v10, v20, v21
	v_cvt_pk_bf16_f32 v11, v22, v23
	v_pk_mul_f32 v[6:7], v[6:7], v[16:17] op_sel_hi:[1,0]
	v_pk_mul_f32 v[4:5], v[4:5], v[16:17] op_sel_hi:[1,0]
	v_pk_mul_f32 v[2:3], v[2:3], v[16:17] op_sel_hi:[1,0]
	v_max_f32_e32 v0, 0, v0
	v_max_f32_e32 v1, 0, v1
	global_store_dwordx4 v[18:19], v[8:11], off
	v_max_f32_e32 v4, 0, v4
	v_max_f32_e32 v5, 0, v5
	v_pk_mul_f32 v[8:9], v[0:1], v[0:1]
	v_max_f32_e32 v0, 0, v6
	v_max_f32_e32 v2, 0, v2
	v_max_f32_e32 v1, 0, v7
	v_max_f32_e32 v3, 0, v3
	v_pk_mul_f32 v[4:5], v[4:5], v[4:5]
	v_pk_mul_f32 v[6:7], v[0:1], v[0:1]
	v_pk_mul_f32 v[10:11], v[2:3], v[2:3]
	v_cvt_pk_bf16_f32 v0, v4, v5
	v_cvt_pk_bf16_f32 v1, v6, v7
	v_cvt_pk_bf16_f32 v2, v8, v9
	v_cvt_pk_bf16_f32 v3, v10, v11
	s_and_b64 vcc, exec, s[0:1]
	global_store_dwordx4 v[18:19], v[0:3], off offset:256
	s_cbranch_vccz .LBB0_763
	s_waitcnt vmcnt(0)
	s_cmpk_gt_u32 s9, 0xff
	s_cbranch_scc1 .LBB0_774
	s_barrier

; #define PG8_STAGE(bufoff, gbase, voff) do { _Pragma("unroll") for (int _i = 0; _i < 2; ++_i) \
;         __builtin_amdgcn_global_load_lds((const unsigned*)((const char*)(gbase) + (voff)[_i]), (LAS unsigned*)(lds + (bufoff) + ldsw + _i * 8192), 16, 0, 0); } while (0)
; #define PG8_LDA(dst, b, h) do { _Pragma("unroll") for (int m = 0; m < 4; ++m) _Pragma("unroll") for (int k = 0; k < 2; ++k) dst[m][k] = *(const LAS bf16x8*)(lds + PG8_SA(b, h) + aoff + m * 2048 + k * 1024); } while (0)
; #define PG8_LDB(dst, b, h) do { _Pragma("unroll") for (int n = 0; n < 2; ++n) _Pragma("unroll") for (int k = 0; k < 2; ++k) dst[n][k] = *(const LAS bf16x8*)(lds + PG8_SB(b, h) + boff + n * 2048 + k * 1024); } while (0)
; #define PG8_MMA(ai, bj, At, Bt) do { __builtin_amdgcn_s_setprio(1); _Pragma("unroll") for (int m = 0; m < 4; ++m) _Pragma("unroll") for (int n = 0; n < 2; ++n) _Pragma("unroll") for (int k = 0; k < 2; ++k) \
;         acc[ai][bj][m][n] = __builtin_amdgcn_mfma_f32_16x16x32_bf16(Bt[n][k], At[m][k], acc[ai][bj][m][n], 0, 0, 0); __builtin_amdgcn_s_setprio(0); } while (0)
; #define PG8_WAIT_L(n) asm volatile("s_waitcnt lgkmcnt(" #n ")" ::: "memory")
; #define PG8_BAR __builtin_amdgcn_s_barrier()
; #define PG8_SCHED __builtin_amdgcn_sched_barrier(0)
; template <class Epi>
; __device__ __forceinline__ void gemm_phase(LAS unsigned char* lds, const Gemm g, const StaticOrder& S, const Epi& E) {
;     ...
;             PG8_LDB(B0, 0, 0); PG8_SCHED; PG8_LDA(At, 0, 0); PG8_STAGE(PG8_SA(1, 1), a1 + hstepA, voffA);
;             PG8_WAIT_L(8); PG8_BAR; PG8_WAIT_L(0); PG8_MMA(0, 0, At, B0); PG8_BAR; PG8_SCHED;
;             PG8_LDB(B1, 0, 1); PG8_STAGE(PG8_SB(0, 0), b2, voffB);
;             PG8_BAR; PG8_WAIT_L(0); PG8_MMA(0, 1, At, B1); PG8_BAR;
;             PG8_LDA(At, 0, 1); PG8_STAGE(PG8_SA(0, 0), a2, voffA);
;             PG8_BAR; PG8_WAIT_L(0); PG8_MMA(1, 0, At, B0); PG8_BAR; PG8_SCHED;
.LBB0_843:
	s_ashr_i32 s17, s16, 31
	v_cmp_lt_i64_e32 vcc, s[18:19], v[166:167]
	s_lshl_b64 s[18:19], s[16:17], 21
	s_add_u32 s18, s96, s18
	s_addc_u32 s19, s97, s19
	s_and_b64 s[20:21], vcc, exec
	s_cselect_b32 s17, s19, s23
	s_cselect_b32 s44, s18, s22
	s_ashr_i32 s15, s14, 31
	s_lshl_b64 s[20:21], s[14:15], 21
	s_add_u32 s20, s29, s20
	s_addc_u32 s21, s30, s21
	s_and_b64 s[26:27], vcc, exec
	s_cselect_b32 s15, s21, s25
	s_cselect_b32 s45, s20, s24
	s_add_u32 s22, s22, 0x100080
	s_addc_u32 s23, s23, 0
	s_add_u32 s46, s24, 0x100
	s_addc_u32 s47, s25, 0
	s_mov_b32 s48, -2
	s_waitcnt lgkmcnt(0)
	ds_read_b128 v[128:131], v191
	ds_read_b128 v[132:135], v191 offset:1024
	ds_read_b128 v[136:139], v191 offset:2048
	ds_read_b128 v[140:143], v191 offset:3072
	s_add_u32 s24, s22, 0xfff00080
	s_addc_u32 s25, s23, -1
	s_cmp_eq_u32 s48, 60
	s_cselect_b32 s27, s17, s25
	s_cselect_b32 s26, s44, s24
	s_cselect_b32 s25, s15, s47
	s_cselect_b32 s24, s45, s46
	v_lshl_add_u64 v[186:187], s[22:23], 0, v[162:163]
	s_add_i32 m0, s7, 0xc000
	ds_read_b128 v[144:147], v192
	ds_read_b128 v[148:151], v192 offset:1024
	ds_read_b128 v[170:173], v192 offset:2048
	ds_read_b128 v[174:177], v192 offset:3072
	ds_read_b128 v[178:181], v192 offset:4096
	ds_read_b128 v[182:185], v192 offset:5120
	ds_read_b128 v[196:199], v192 offset:6144
	ds_read_b128 v[200:203], v192 offset:7168
	global_load_lds_dwordx4 v[186:187], off
	v_lshl_add_u64 v[186:187], s[22:23], 0, v[164:165]
	s_add_i32 m0, s7, 0xe000
	s_nop 0
	global_load_lds_dwordx4 v[186:187], off
	s_waitcnt lgkmcnt(8)
	s_barrier
	s_waitcnt lgkmcnt(0)
	s_waitcnt lgkmcnt(0)
	v_mfma_f32_16x16x32_bf16 v[124:127], v[128:131], v[144:147], 0
	v_mfma_f32_16x16x32_bf16 v[120:123], v[136:139], v[144:147], 0
	v_mfma_f32_16x16x32_bf16 v[108:111], v[128:131], v[170:173], 0
	v_mfma_f32_16x16x32_bf16 v[104:107], v[136:139], v[170:173], 0
	v_mfma_f32_16x16x32_bf16 v[92:95], v[128:131], v[178:181], 0
	v_mfma_f32_16x16x32_bf16 v[88:91], v[136:139], v[178:181], 0
	v_mfma_f32_16x16x32_bf16 v[76:79], v[128:131], v[196:199], 0
	v_mfma_f32_16x16x32_bf16 v[72:75], v[136:139], v[196:199], 0
	v_mfma_f32_16x16x32_bf16 v[124:127], v[132:135], v[148:151], v[124:127]
	v_mfma_f32_16x16x32_bf16 v[120:123], v[140:143], v[148:151], v[120:123]
	v_mfma_f32_16x16x32_bf16 v[108:111], v[132:135], v[174:177], v[108:111]
	v_mfma_f32_16x16x32_bf16 v[104:107], v[140:143], v[174:177], v[104:107]
	v_mfma_f32_16x16x32_bf16 v[92:95], v[132:135], v[182:185], v[92:95]
	v_mfma_f32_16x16x32_bf16 v[88:91], v[140:143], v[182:185], v[88:91]
	v_mfma_f32_16x16x32_bf16 v[76:79], v[132:135], v[200:203], v[76:79]
	v_mfma_f32_16x16x32_bf16 v[72:75], v[140:143], v[200:203], v[72:75]
	s_barrier
	s_add_i32 s49, s42, s31
	v_lshl_add_u64 v[186:187], s[24:25], 0, v[156:157]
	s_mov_b32 m0, s49
	ds_read_b128 v[204:207], v193
	ds_read_b128 v[208:211], v193 offset:1024
	ds_read_b128 v[212:215], v193 offset:2048
	ds_read_b128 v[216:219], v193 offset:3072
	global_load_lds_dwordx4 v[186:187], off
	v_lshl_add_u64 v[220:221], s[24:25], 0, v[160:161]
	s_add_i32 m0, s49, 0x2000
	s_nop 0
	global_load_lds_dwordx4 v[220:221], off
	s_barrier
	s_waitcnt lgkmcnt(0)
	s_waitcnt lgkmcnt(0)
	v_mfma_f32_16x16x32_bf16 v[116:119], v[204:207], v[144:147], 0
	v_mfma_f32_16x16x32_bf16 v[112:115], v[212:215], v[144:147], 0
	v_mfma_f32_16x16x32_bf16 v[100:103], v[204:207], v[170:173], 0
	v_mfma_f32_16x16x32_bf16 v[96:99], v[212:215], v[170:173], 0
	v_mfma_f32_16x16x32_bf16 v[84:87], v[204:207], v[178:181], 0
	v_mfma_f32_16x16x32_bf16 v[80:83], v[212:215], v[178:181], 0
	v_mfma_f32_16x16x32_bf16 v[68:71], v[204:207], v[196:199], 0
	v_mfma_f32_16x16x32_bf16 v[64:67], v[212:215], v[196:199], 0
	v_mfma_f32_16x16x32_bf16 v[116:119], v[208:211], v[148:151], v[116:119]
	v_mfma_f32_16x16x32_bf16 v[112:115], v[216:219], v[148:151], v[112:115]
	v_mfma_f32_16x16x32_bf16 v[100:103], v[208:211], v[174:177], v[100:103]
	v_mfma_f32_16x16x32_bf16 v[96:99], v[216:219], v[174:177], v[96:99]
	v_mfma_f32_16x16x32_bf16 v[84:87], v[208:211], v[182:185], v[84:87]
	v_mfma_f32_16x16x32_bf16 v[80:83], v[216:219], v[182:185], v[80:83]
	v_mfma_f32_16x16x32_bf16 v[68:71], v[208:211], v[200:203], v[68:71]
	v_mfma_f32_16x16x32_bf16 v[64:67], v[216:219], v[200:203], v[64:67]
	s_mov_b32 m0, s7
	v_lshl_add_u64 v[222:223], s[26:27], 0, v[154:155]
	s_barrier
	ds_read_b128 v[144:147], v192 offset:16384
	ds_read_b128 v[148:151], v192 offset:17408
	ds_read_b128 v[170:173], v192 offset:18432
	ds_read_b128 v[174:177], v192 offset:19456
	ds_read_b128 v[178:181], v192 offset:20480
	ds_read_b128 v[182:185], v192 offset:21504
	ds_read_b128 v[196:199], v192 offset:22528
	ds_read_b128 v[200:203], v192 offset:23552
	global_load_lds_dwordx4 v[222:223], off
	v_lshl_add_u64 v[224:225], s[26:27], 0, v[158:159]
	s_mov_b32 m0, s34
	s_nop 0
	global_load_lds_dwordx4 v[224:225], off
	s_barrier
	s_waitcnt lgkmcnt(0)
	s_waitcnt lgkmcnt(0)
	v_mfma_f32_16x16x32_bf16 v[60:63], v[128:131], v[144:147], 0
	v_mfma_f32_16x16x32_bf16 v[56:59], v[136:139], v[144:147], 0
	v_mfma_f32_16x16x32_bf16 v[44:47], v[128:131], v[170:173], 0
	v_mfma_f32_16x16x32_bf16 v[40:43], v[136:139], v[170:173], 0
	v_mfma_f32_16x16x32_bf16 v[28:31], v[128:131], v[178:181], 0
	v_mfma_f32_16x16x32_bf16 v[24:27], v[136:139], v[178:181], 0
	v_mfma_f32_16x16x32_bf16 v[12:15], v[128:131], v[196:199], 0
	v_mfma_f32_16x16x32_bf16 v[8:11], v[136:139], v[196:199], 0
	v_mfma_f32_16x16x32_bf16 v[60:63], v[132:135], v[148:151], v[60:63]
	v_mfma_f32_16x16x32_bf16 v[56:59], v[140:143], v[148:151], v[56:59]
	v_mfma_f32_16x16x32_bf16 v[44:47], v[132:135], v[174:177], v[44:47]
	v_mfma_f32_16x16x32_bf16 v[40:43], v[140:143], v[174:177], v[40:43]
	v_mfma_f32_16x16x32_bf16 v[28:31], v[132:135], v[182:185], v[28:31]
	v_mfma_f32_16x16x32_bf16 v[24:27], v[140:143], v[182:185], v[24:27]
	v_mfma_f32_16x16x32_bf16 v[12:15], v[132:135], v[200:203], v[12:15]
	v_mfma_f32_16x16x32_bf16 v[8:11], v[140:143], v[200:203], v[8:11]
	s_barrier
; #define PG8_STAGE(bufoff, gbase, voff) do { _Pragma("unroll") for (int _i = 0; _i < 2; ++_i) \
;         __builtin_amdgcn_global_load_lds((const unsigned*)((const char*)(gbase) + (voff)[_i]), (LAS unsigned*)(lds + (bufoff) + ldsw + _i * 8192), 16, 0, 0); } while (0)
; #define PG8_LDA(dst, b, h) do { _Pragma("unroll") for (int m = 0; m < 4; ++m) _Pragma("unroll") for (int k = 0; k < 2; ++k) dst[m][k] = *(const LAS bf16x8*)(lds + PG8_SA(b, h) + aoff + m * 2048 + k * 1024); } while (0)
; #define PG8_LDB(dst, b, h) do { _Pragma("unroll") for (int n = 0; n < 2; ++n) _Pragma("unroll") for (int k = 0; k < 2; ++k) dst[n][k] = *(const LAS bf16x8*)(lds + PG8_SB(b, h) + boff + n * 2048 + k * 1024); } while (0)
; #define PG8_MMA(ai, bj, At, Bt) do { __builtin_amdgcn_s_setprio(1); _Pragma("unroll") for (int m = 0; m < 4; ++m) _Pragma("unroll") for (int n = 0; n < 2; ++n) _Pragma("unroll") for (int k = 0; k < 2; ++k) \
;         acc[ai][bj][m][n] = __builtin_amdgcn_mfma_f32_16x16x32_bf16(Bt[n][k], At[m][k], acc[ai][bj][m][n], 0, 0, 0); __builtin_amdgcn_s_setprio(0); } while (0)
; #define PG8_WAIT_V(n) asm volatile("s_waitcnt vmcnt(" #n ")" ::: "memory")
; #define PG8_WAIT_L(n) asm volatile("s_waitcnt lgkmcnt(" #n ")" ::: "memory")
; #define PG8_BAR __builtin_amdgcn_s_barrier()
; #define PG8_SCHED __builtin_amdgcn_sched_barrier(0)
; template <class Epi>
; __device__ __forceinline__ void gemm_phase(LAS unsigned char* lds, const Gemm g, const StaticOrder& S, const Epi& E) {
;     ...
;             PG8_STAGE(PG8_SB(0, 1), b2 + hstepB, voffB);
;             PG8_WAIT_V(6); PG8_BAR; PG8_MMA(1, 1, At, B1); PG8_BAR;
;             PG8_LDB(B0, 1, 0); PG8_SCHED; PG8_LDA(At, 1, 0); PG8_STAGE(PG8_SA(0, 1), a2 + hstepA, voffA);
;             PG8_WAIT_L(8); PG8_BAR; PG8_WAIT_L(0); PG8_MMA(0, 0, At, B0); PG8_BAR; PG8_SCHED;
;             PG8_LDB(B1, 1, 1); PG8_STAGE(PG8_SB(1, 0), b3, voffB);
;             PG8_BAR; PG8_WAIT_L(0); PG8_MMA(0, 1, At, B1); PG8_BAR;
;             PG8_LDA(At, 1, 1); PG8_STAGE(PG8_SA(1, 0), a3, voffA);
	s_add_u32 s50, s24, 0x100000
	s_addc_u32 s51, s25, 0
	s_add_i32 s49, s43, s31
	v_lshl_add_u64 v[128:129], s[50:51], 0, v[156:157]
	s_mov_b32 m0, s49
	s_nop 0
	global_load_lds_dwordx4 v[128:129], off
	v_lshl_add_u64 v[128:129], s[50:51], 0, v[160:161]
	s_add_i32 m0, s49, 0x2000
	s_nop 0
	global_load_lds_dwordx4 v[128:129], off
	s_waitcnt vmcnt(6)
	s_barrier
	v_mfma_f32_16x16x32_bf16 v[52:55], v[204:207], v[144:147], 0
	v_mfma_f32_16x16x32_bf16 v[48:51], v[212:215], v[144:147], 0
	v_mfma_f32_16x16x32_bf16 v[36:39], v[204:207], v[170:173], 0
	v_mfma_f32_16x16x32_bf16 v[32:35], v[212:215], v[170:173], 0
	v_mfma_f32_16x16x32_bf16 v[20:23], v[204:207], v[178:181], 0
	v_mfma_f32_16x16x32_bf16 v[16:19], v[212:215], v[178:181], 0
	v_mfma_f32_16x16x32_bf16 v[4:7], v[204:207], v[196:199], 0
	v_mfma_f32_16x16x32_bf16 v[0:3], v[212:215], v[196:199], 0
	v_mfma_f32_16x16x32_bf16 v[52:55], v[208:211], v[148:151], v[52:55]
	v_mfma_f32_16x16x32_bf16 v[48:51], v[216:219], v[148:151], v[48:51]
	v_mfma_f32_16x16x32_bf16 v[36:39], v[208:211], v[174:177], v[36:39]
	v_mfma_f32_16x16x32_bf16 v[32:35], v[216:219], v[174:177], v[32:35]
	v_mfma_f32_16x16x32_bf16 v[20:23], v[208:211], v[182:185], v[20:23]
	v_mfma_f32_16x16x32_bf16 v[16:19], v[216:219], v[182:185], v[16:19]
	v_mfma_f32_16x16x32_bf16 v[4:7], v[208:211], v[200:203], v[4:7]
	v_mfma_f32_16x16x32_bf16 v[0:3], v[216:219], v[200:203], v[0:3]
	s_add_i32 s49, 0, 0x18000
	v_add_u32_e32 v140, s49, v189
	s_barrier
	ds_read_b128 v[128:131], v140
	ds_read_b128 v[132:135], v140 offset:1024
	ds_read_b128 v[136:139], v140 offset:2048
	ds_read_b128 v[140:143], v140 offset:3072
	s_add_u32 s26, s26, 0x100000
	s_addc_u32 s27, s27, 0
	s_mov_b32 m0, s35
	v_lshl_add_u64 v[204:205], s[26:27], 0, v[154:155]
	ds_read_b128 v[144:147], v192 offset:32768
	ds_read_b128 v[148:151], v192 offset:33792
	ds_read_b128 v[170:173], v192 offset:34816
	ds_read_b128 v[174:177], v192 offset:35840
	ds_read_b128 v[178:181], v192 offset:36864
	ds_read_b128 v[182:185], v192 offset:37888
	ds_read_b128 v[196:199], v192 offset:38912
	ds_read_b128 v[200:203], v192 offset:39936
	global_load_lds_dwordx4 v[204:205], off
	v_lshl_add_u64 v[204:205], s[26:27], 0, v[158:159]
	s_mov_b32 m0, s36
	s_nop 0
	global_load_lds_dwordx4 v[204:205], off
	s_waitcnt lgkmcnt(8)
	s_barrier
	s_waitcnt lgkmcnt(0)
	s_waitcnt lgkmcnt(0)
	v_mfma_f32_16x16x32_bf16 v[124:127], v[128:131], v[144:147], v[124:127]
	v_mfma_f32_16x16x32_bf16 v[120:123], v[136:139], v[144:147], v[120:123]
	v_mfma_f32_16x16x32_bf16 v[108:111], v[128:131], v[170:173], v[108:111]
	v_mfma_f32_16x16x32_bf16 v[104:107], v[136:139], v[170:173], v[104:107]
	v_mfma_f32_16x16x32_bf16 v[92:95], v[128:131], v[178:181], v[92:95]
	v_mfma_f32_16x16x32_bf16 v[88:91], v[136:139], v[178:181], v[88:91]
	v_mfma_f32_16x16x32_bf16 v[76:79], v[128:131], v[196:199], v[76:79]
	v_mfma_f32_16x16x32_bf16 v[72:75], v[136:139], v[196:199], v[72:75]
	v_mfma_f32_16x16x32_bf16 v[124:127], v[132:135], v[148:151], v[124:127]
	v_mfma_f32_16x16x32_bf16 v[120:123], v[140:143], v[148:151], v[120:123]
	v_mfma_f32_16x16x32_bf16 v[108:111], v[132:135], v[174:177], v[108:111]
	v_mfma_f32_16x16x32_bf16 v[104:107], v[140:143], v[174:177], v[104:107]
	v_mfma_f32_16x16x32_bf16 v[92:95], v[132:135], v[182:185], v[92:95]
	v_mfma_f32_16x16x32_bf16 v[88:91], v[140:143], v[182:185], v[88:91]
	v_mfma_f32_16x16x32_bf16 v[76:79], v[132:135], v[200:203], v[76:79]
	v_mfma_f32_16x16x32_bf16 v[72:75], v[140:143], v[200:203], v[72:75]
	s_barrier
	s_add_i32 s26, 0, 0x1c000
	s_add_i32 s27, s49, s31
	v_add_u32_e32 v195, s26, v189
	v_lshl_add_u64 v[186:187], v[186:187], 0, s[12:13]
	s_mov_b32 m0, s27
	ds_read_b128 v[204:207], v195
	ds_read_b128 v[208:211], v195 offset:1024
	ds_read_b128 v[212:215], v195 offset:2048
	ds_read_b128 v[216:219], v195 offset:3072
	global_load_lds_dwordx4 v[186:187], off
	v_lshl_add_u64 v[186:187], v[220:221], 0, s[12:13]
	s_add_i32 m0, s27, 0x2000
	s_nop 0
	global_load_lds_dwordx4 v[186:187], off
	s_barrier
	s_waitcnt lgkmcnt(0)
	s_waitcnt lgkmcnt(0)
	v_mfma_f32_16x16x32_bf16 v[116:119], v[204:207], v[144:147], v[116:119]
	v_mfma_f32_16x16x32_bf16 v[112:115], v[212:215], v[144:147], v[112:115]
	v_mfma_f32_16x16x32_bf16 v[100:103], v[204:207], v[170:173], v[100:103]
	v_mfma_f32_16x16x32_bf16 v[96:99], v[212:215], v[170:173], v[96:99]
	v_mfma_f32_16x16x32_bf16 v[84:87], v[204:207], v[178:181], v[84:87]
	v_mfma_f32_16x16x32_bf16 v[80:83], v[212:215], v[178:181], v[80:83]
	v_mfma_f32_16x16x32_bf16 v[68:71], v[204:207], v[196:199], v[68:71]
	v_mfma_f32_16x16x32_bf16 v[64:67], v[212:215], v[196:199], v[64:67]
	v_mfma_f32_16x16x32_bf16 v[116:119], v[208:211], v[148:151], v[116:119]
	v_mfma_f32_16x16x32_bf16 v[112:115], v[216:219], v[148:151], v[112:115]
	v_mfma_f32_16x16x32_bf16 v[100:103], v[208:211], v[174:177], v[100:103]
	v_mfma_f32_16x16x32_bf16 v[96:99], v[216:219], v[174:177], v[96:99]
	v_mfma_f32_16x16x32_bf16 v[84:87], v[208:211], v[182:185], v[84:87]
	v_mfma_f32_16x16x32_bf16 v[80:83], v[216:219], v[182:185], v[80:83]
	v_mfma_f32_16x16x32_bf16 v[68:71], v[208:211], v[200:203], v[68:71]
	v_mfma_f32_16x16x32_bf16 v[64:67], v[216:219], v[200:203], v[64:67]
	s_mov_b32 m0, s38
	v_lshl_add_u64 v[186:187], v[222:223], 0, s[12:13]
	s_barrier
	ds_read_b128 v[144:147], v192 offset:49152
	ds_read_b128 v[148:151], v192 offset:50176
	ds_read_b128 v[170:173], v192 offset:51200
	ds_read_b128 v[174:177], v192 offset:52224
	ds_read_b128 v[178:181], v192 offset:53248
	ds_read_b128 v[182:185], v192 offset:54272
	ds_read_b128 v[196:199], v192 offset:55296
	ds_read_b128 v[200:203], v192 offset:56320
	global_load_lds_dwordx4 v[186:187], off
	v_lshl_add_u64 v[186:187], v[224:225], 0, s[12:13]
	s_mov_b32 m0, s39
	s_nop 0
	global_load_lds_dwordx4 v[186:187], off
	s_barrier
; #define PG8_STAGE(bufoff, gbase, voff) do { _Pragma("unroll") for (int _i = 0; _i < 2; ++_i) \
;         __builtin_amdgcn_global_load_lds((const unsigned*)((const char*)(gbase) + (voff)[_i]), (LAS unsigned*)(lds + (bufoff) + ldsw + _i * 8192), 16, 0, 0); } while (0)
; #define PG8_LDA(dst, b, h) do { _Pragma("unroll") for (int m = 0; m < 4; ++m) _Pragma("unroll") for (int k = 0; k < 2; ++k) dst[m][k] = *(const LAS bf16x8*)(lds + PG8_SA(b, h) + aoff + m * 2048 + k * 1024); } while (0)
; #define PG8_LDB(dst, b, h) do { _Pragma("unroll") for (int n = 0; n < 2; ++n) _Pragma("unroll") for (int k = 0; k < 2; ++k) dst[n][k] = *(const LAS bf16x8*)(lds + PG8_SB(b, h) + boff + n * 2048 + k * 1024); } while (0)
; #define PG8_MMA(ai, bj, At, Bt) do { __builtin_amdgcn_s_setprio(1); _Pragma("unroll") for (int m = 0; m < 4; ++m) _Pragma("unroll") for (int n = 0; n < 2; ++n) _Pragma("unroll") for (int k = 0; k < 2; ++k) \
;         acc[ai][bj][m][n] = __builtin_amdgcn_mfma_f32_16x16x32_bf16(Bt[n][k], At[m][k], acc[ai][bj][m][n], 0, 0, 0); __builtin_amdgcn_s_setprio(0); } while (0)
; #define PG8_WAIT_V(n) asm volatile("s_waitcnt vmcnt(" #n ")" ::: "memory")
; #define PG8_WAIT_L(n) asm volatile("s_waitcnt lgkmcnt(" #n ")" ::: "memory")
; #define PG8_BAR __builtin_amdgcn_s_barrier()
; #define PG8_SCHED __builtin_amdgcn_sched_barrier(0)
; template <class Epi>
; __device__ __forceinline__ void gemm_phase(LAS unsigned char* lds, const Gemm g, const StaticOrder& S, const Epi& E) {
;     ...
;             PG8_LDB(B0, 0, 0); PG8_SCHED; PG8_LDA(At, 0, 0); PG8_STAGE(PG8_SA(1, 1), a1 + hstepA, voffA);
;             PG8_WAIT_L(8); PG8_BAR; PG8_WAIT_L(0); PG8_MMA(0, 0, At, B0); PG8_BAR; PG8_SCHED;
;             PG8_LDB(B1, 0, 1); PG8_STAGE(PG8_SB(0, 0), b2, voffB);
;     ...
;             PG8_BAR; PG8_WAIT_L(0); PG8_MMA(1, 0, At, B0); PG8_BAR; PG8_SCHED;
;             PG8_STAGE(PG8_SB(1, 1), b3 + hstepB, voffB);
;             PG8_WAIT_V(6); PG8_BAR; PG8_MMA(1, 1, At, B1); PG8_BAR;
	s_waitcnt lgkmcnt(0)
	s_waitcnt lgkmcnt(0)
	v_mfma_f32_16x16x32_bf16 v[60:63], v[128:131], v[144:147], v[60:63]
	v_mfma_f32_16x16x32_bf16 v[56:59], v[136:139], v[144:147], v[56:59]
	v_mfma_f32_16x16x32_bf16 v[44:47], v[128:131], v[170:173], v[44:47]
	v_mfma_f32_16x16x32_bf16 v[40:43], v[136:139], v[170:173], v[40:43]
	v_mfma_f32_16x16x32_bf16 v[28:31], v[128:131], v[178:181], v[28:31]
	v_mfma_f32_16x16x32_bf16 v[24:27], v[136:139], v[178:181], v[24:27]
	v_mfma_f32_16x16x32_bf16 v[12:15], v[128:131], v[196:199], v[12:15]
	v_mfma_f32_16x16x32_bf16 v[8:11], v[136:139], v[196:199], v[8:11]
	v_mfma_f32_16x16x32_bf16 v[60:63], v[132:135], v[148:151], v[60:63]
	v_mfma_f32_16x16x32_bf16 v[56:59], v[140:143], v[148:151], v[56:59]
	v_mfma_f32_16x16x32_bf16 v[44:47], v[132:135], v[174:177], v[44:47]
	v_mfma_f32_16x16x32_bf16 v[40:43], v[140:143], v[174:177], v[40:43]
	v_mfma_f32_16x16x32_bf16 v[28:31], v[132:135], v[182:185], v[28:31]
	v_mfma_f32_16x16x32_bf16 v[24:27], v[140:143], v[182:185], v[24:27]
	v_mfma_f32_16x16x32_bf16 v[12:15], v[132:135], v[200:203], v[12:15]
	v_mfma_f32_16x16x32_bf16 v[8:11], v[140:143], v[200:203], v[8:11]
	s_barrier
	s_add_u32 s24, s24, 0x100080
	s_addc_u32 s25, s25, 0
	s_add_i32 s26, s26, s31
	v_lshl_add_u64 v[128:129], s[24:25], 0, v[156:157]
	s_mov_b32 m0, s26
	s_nop 0
	global_load_lds_dwordx4 v[128:129], off
	v_lshl_add_u64 v[128:129], s[24:25], 0, v[160:161]
	s_add_i32 m0, s26, 0x2000
	s_nop 0
	global_load_lds_dwordx4 v[128:129], off
	s_waitcnt vmcnt(6)
	s_barrier
	v_mfma_f32_16x16x32_bf16 v[52:55], v[204:207], v[144:147], v[52:55]
	v_mfma_f32_16x16x32_bf16 v[48:51], v[212:215], v[144:147], v[48:51]
	v_mfma_f32_16x16x32_bf16 v[36:39], v[204:207], v[170:173], v[36:39]
	v_mfma_f32_16x16x32_bf16 v[32:35], v[212:215], v[170:173], v[32:35]
	v_mfma_f32_16x16x32_bf16 v[20:23], v[204:207], v[178:181], v[20:23]
	v_mfma_f32_16x16x32_bf16 v[16:19], v[212:215], v[178:181], v[16:19]
	v_mfma_f32_16x16x32_bf16 v[4:7], v[204:207], v[196:199], v[4:7]
	v_mfma_f32_16x16x32_bf16 v[0:3], v[212:215], v[196:199], v[0:3]
	v_mfma_f32_16x16x32_bf16 v[52:55], v[208:211], v[148:151], v[52:55]
	v_mfma_f32_16x16x32_bf16 v[48:51], v[216:219], v[148:151], v[48:51]
	v_mfma_f32_16x16x32_bf16 v[36:39], v[208:211], v[174:177], v[36:39]
	v_mfma_f32_16x16x32_bf16 v[32:35], v[216:219], v[174:177], v[32:35]
	v_mfma_f32_16x16x32_bf16 v[20:23], v[208:211], v[182:185], v[20:23]
	v_mfma_f32_16x16x32_bf16 v[16:19], v[216:219], v[182:185], v[16:19]
	v_mfma_f32_16x16x32_bf16 v[4:7], v[208:211], v[200:203], v[4:7]
	v_mfma_f32_16x16x32_bf16 v[0:3], v[216:219], v[200:203], v[0:3]
	s_add_i32 s48, s48, 2
	s_add_u32 s22, s22, 0x100
	s_addc_u32 s23, s23, 0
	s_add_u32 s46, s46, 0x100
	s_addc_u32 s47, s47, 0
	s_cmp_gt_u32 s48, 61
	s_barrier
.LBB0_844:
	ds_read_b128 v[128:131], v191
	ds_read_b128 v[132:135], v191 offset:1024
	ds_read_b128 v[136:139], v191 offset:2048
	ds_read_b128 v[140:143], v191 offset:3072
	s_add_u32 s24, s22, 0xfff00080
	s_addc_u32 s25, s23, -1
	s_cmp_eq_u32 s48, 60
	s_cselect_b32 s27, s17, s25
	s_cselect_b32 s26, s44, s24
	s_cselect_b32 s25, s15, s47
	s_cselect_b32 s24, s45, s46
	v_lshl_add_u64 v[186:187], s[22:23], 0, v[162:163]
	s_add_i32 m0, s7, 0xc000
	ds_read_b128 v[144:147], v192
	ds_read_b128 v[148:151], v192 offset:1024
	ds_read_b128 v[170:173], v192 offset:2048
	ds_read_b128 v[174:177], v192 offset:3072
	ds_read_b128 v[178:181], v192 offset:4096
	ds_read_b128 v[182:185], v192 offset:5120
	ds_read_b128 v[196:199], v192 offset:6144
	ds_read_b128 v[200:203], v192 offset:7168
	global_load_lds_dwordx4 v[186:187], off
	v_lshl_add_u64 v[186:187], s[22:23], 0, v[164:165]
	s_add_i32 m0, s7, 0xe000
	s_nop 0
	global_load_lds_dwordx4 v[186:187], off
	s_waitcnt lgkmcnt(8)
	s_barrier
	s_waitcnt lgkmcnt(0)
	s_waitcnt lgkmcnt(0)
	v_mfma_f32_16x16x32_bf16 v[124:127], v[128:131], v[144:147], v[124:127]
	v_mfma_f32_16x16x32_bf16 v[120:123], v[136:139], v[144:147], v[120:123]
	v_mfma_f32_16x16x32_bf16 v[108:111], v[128:131], v[170:173], v[108:111]
	v_mfma_f32_16x16x32_bf16 v[104:107], v[136:139], v[170:173], v[104:107]
	v_mfma_f32_16x16x32_bf16 v[92:95], v[128:131], v[178:181], v[92:95]
	v_mfma_f32_16x16x32_bf16 v[88:91], v[136:139], v[178:181], v[88:91]
	v_mfma_f32_16x16x32_bf16 v[76:79], v[128:131], v[196:199], v[76:79]
	v_mfma_f32_16x16x32_bf16 v[72:75], v[136:139], v[196:199], v[72:75]
	v_mfma_f32_16x16x32_bf16 v[124:127], v[132:135], v[148:151], v[124:127]
	v_mfma_f32_16x16x32_bf16 v[120:123], v[140:143], v[148:151], v[120:123]
	v_mfma_f32_16x16x32_bf16 v[108:111], v[132:135], v[174:177], v[108:111]
	v_mfma_f32_16x16x32_bf16 v[104:107], v[140:143], v[174:177], v[104:107]
	v_mfma_f32_16x16x32_bf16 v[92:95], v[132:135], v[182:185], v[92:95]
	v_mfma_f32_16x16x32_bf16 v[88:91], v[140:143], v[182:185], v[88:91]
	v_mfma_f32_16x16x32_bf16 v[76:79], v[132:135], v[200:203], v[76:79]
	v_mfma_f32_16x16x32_bf16 v[72:75], v[140:143], v[200:203], v[72:75]
	s_barrier
	s_add_i32 s49, s42, s31
	v_lshl_add_u64 v[186:187], s[24:25], 0, v[156:157]
	s_mov_b32 m0, s49
	ds_read_b128 v[204:207], v193
	ds_read_b128 v[208:211], v193 offset:1024
	ds_read_b128 v[212:215], v193 offset:2048
	ds_read_b128 v[216:219], v193 offset:3072
	global_load_lds_dwordx4 v[186:187], off
	v_lshl_add_u64 v[220:221], s[24:25], 0, v[160:161]
	s_add_i32 m0, s49, 0x2000
	s_nop 0
	global_load_lds_dwordx4 v[220:221], off
	s_barrier
; #define PG8_STAGE(bufoff, gbase, voff) do { _Pragma("unroll") for (int _i = 0; _i < 2; ++_i) \
;         __builtin_amdgcn_global_load_lds((const unsigned*)((const char*)(gbase) + (voff)[_i]), (LAS unsigned*)(lds + (bufoff) + ldsw + _i * 8192), 16, 0, 0); } while (0)
; #define PG8_LDA(dst, b, h) do { _Pragma("unroll") for (int m = 0; m < 4; ++m) _Pragma("unroll") for (int k = 0; k < 2; ++k) dst[m][k] = *(const LAS bf16x8*)(lds + PG8_SA(b, h) + aoff + m * 2048 + k * 1024); } while (0)
; #define PG8_LDB(dst, b, h) do { _Pragma("unroll") for (int n = 0; n < 2; ++n) _Pragma("unroll") for (int k = 0; k < 2; ++k) dst[n][k] = *(const LAS bf16x8*)(lds + PG8_SB(b, h) + boff + n * 2048 + k * 1024); } while (0)
; #define PG8_MMA(ai, bj, At, Bt) do { __builtin_amdgcn_s_setprio(1); _Pragma("unroll") for (int m = 0; m < 4; ++m) _Pragma("unroll") for (int n = 0; n < 2; ++n) _Pragma("unroll") for (int k = 0; k < 2; ++k) \
;         acc[ai][bj][m][n] = __builtin_amdgcn_mfma_f32_16x16x32_bf16(Bt[n][k], At[m][k], acc[ai][bj][m][n], 0, 0, 0); __builtin_amdgcn_s_setprio(0); } while (0)
; #define PG8_WAIT_V(n) asm volatile("s_waitcnt vmcnt(" #n ")" ::: "memory")
; #define PG8_WAIT_L(n) asm volatile("s_waitcnt lgkmcnt(" #n ")" ::: "memory")
; #define PG8_BAR __builtin_amdgcn_s_barrier()
; #define PG8_SCHED __builtin_amdgcn_sched_barrier(0)
; template <class Epi>
; __device__ __forceinline__ void gemm_phase(LAS unsigned char* lds, const Gemm g, const StaticOrder& S, const Epi& E) {
;     ...
;             PG8_BAR; PG8_WAIT_L(0); PG8_MMA(0, 1, At, B1); PG8_BAR;
;             PG8_LDA(At, 0, 1); PG8_STAGE(PG8_SA(0, 0), a2, voffA);
;             PG8_BAR; PG8_WAIT_L(0); PG8_MMA(1, 0, At, B0); PG8_BAR; PG8_SCHED;
;             PG8_STAGE(PG8_SB(0, 1), b2 + hstepB, voffB);
;             PG8_WAIT_V(6); PG8_BAR; PG8_MMA(1, 1, At, B1); PG8_BAR;
;             PG8_LDB(B0, 1, 0); PG8_SCHED; PG8_LDA(At, 1, 0); PG8_STAGE(PG8_SA(0, 1), a2 + hstepA, voffA);
	s_waitcnt lgkmcnt(0)
	s_waitcnt lgkmcnt(0)
	v_mfma_f32_16x16x32_bf16 v[116:119], v[204:207], v[144:147], v[116:119]
	v_mfma_f32_16x16x32_bf16 v[112:115], v[212:215], v[144:147], v[112:115]
	v_mfma_f32_16x16x32_bf16 v[100:103], v[204:207], v[170:173], v[100:103]
	v_mfma_f32_16x16x32_bf16 v[96:99], v[212:215], v[170:173], v[96:99]
	v_mfma_f32_16x16x32_bf16 v[84:87], v[204:207], v[178:181], v[84:87]
	v_mfma_f32_16x16x32_bf16 v[80:83], v[212:215], v[178:181], v[80:83]
	v_mfma_f32_16x16x32_bf16 v[68:71], v[204:207], v[196:199], v[68:71]
	v_mfma_f32_16x16x32_bf16 v[64:67], v[212:215], v[196:199], v[64:67]
	v_mfma_f32_16x16x32_bf16 v[116:119], v[208:211], v[148:151], v[116:119]
	v_mfma_f32_16x16x32_bf16 v[112:115], v[216:219], v[148:151], v[112:115]
	v_mfma_f32_16x16x32_bf16 v[100:103], v[208:211], v[174:177], v[100:103]
	v_mfma_f32_16x16x32_bf16 v[96:99], v[216:219], v[174:177], v[96:99]
	v_mfma_f32_16x16x32_bf16 v[84:87], v[208:211], v[182:185], v[84:87]
	v_mfma_f32_16x16x32_bf16 v[80:83], v[216:219], v[182:185], v[80:83]
	v_mfma_f32_16x16x32_bf16 v[68:71], v[208:211], v[200:203], v[68:71]
	v_mfma_f32_16x16x32_bf16 v[64:67], v[216:219], v[200:203], v[64:67]
	s_mov_b32 m0, s7
	v_lshl_add_u64 v[222:223], s[26:27], 0, v[154:155]
	s_barrier
	ds_read_b128 v[144:147], v192 offset:16384
	ds_read_b128 v[148:151], v192 offset:17408
	ds_read_b128 v[170:173], v192 offset:18432
	ds_read_b128 v[174:177], v192 offset:19456
	ds_read_b128 v[178:181], v192 offset:20480
	ds_read_b128 v[182:185], v192 offset:21504
	ds_read_b128 v[196:199], v192 offset:22528
	ds_read_b128 v[200:203], v192 offset:23552
	global_load_lds_dwordx4 v[222:223], off
	v_lshl_add_u64 v[224:225], s[26:27], 0, v[158:159]
	s_mov_b32 m0, s34
	s_nop 0
	global_load_lds_dwordx4 v[224:225], off
	s_barrier
	s_waitcnt lgkmcnt(0)
	s_waitcnt lgkmcnt(0)
	v_mfma_f32_16x16x32_bf16 v[60:63], v[128:131], v[144:147], v[60:63]
	v_mfma_f32_16x16x32_bf16 v[56:59], v[136:139], v[144:147], v[56:59]
	v_mfma_f32_16x16x32_bf16 v[44:47], v[128:131], v[170:173], v[44:47]
	v_mfma_f32_16x16x32_bf16 v[40:43], v[136:139], v[170:173], v[40:43]
	v_mfma_f32_16x16x32_bf16 v[28:31], v[128:131], v[178:181], v[28:31]
	v_mfma_f32_16x16x32_bf16 v[24:27], v[136:139], v[178:181], v[24:27]
	v_mfma_f32_16x16x32_bf16 v[12:15], v[128:131], v[196:199], v[12:15]
	v_mfma_f32_16x16x32_bf16 v[8:11], v[136:139], v[196:199], v[8:11]
	v_mfma_f32_16x16x32_bf16 v[60:63], v[132:135], v[148:151], v[60:63]
	v_mfma_f32_16x16x32_bf16 v[56:59], v[140:143], v[148:151], v[56:59]
	v_mfma_f32_16x16x32_bf16 v[44:47], v[132:135], v[174:177], v[44:47]
	v_mfma_f32_16x16x32_bf16 v[40:43], v[140:143], v[174:177], v[40:43]
	v_mfma_f32_16x16x32_bf16 v[28:31], v[132:135], v[182:185], v[28:31]
	v_mfma_f32_16x16x32_bf16 v[24:27], v[140:143], v[182:185], v[24:27]
	v_mfma_f32_16x16x32_bf16 v[12:15], v[132:135], v[200:203], v[12:15]
	v_mfma_f32_16x16x32_bf16 v[8:11], v[140:143], v[200:203], v[8:11]
	s_barrier
	s_add_u32 s50, s24, 0x100000
	s_addc_u32 s51, s25, 0
	s_add_i32 s49, s43, s31
	v_lshl_add_u64 v[128:129], s[50:51], 0, v[156:157]
	s_mov_b32 m0, s49
	s_nop 0
	global_load_lds_dwordx4 v[128:129], off
	v_lshl_add_u64 v[128:129], s[50:51], 0, v[160:161]
	s_add_i32 m0, s49, 0x2000
	s_nop 0
	global_load_lds_dwordx4 v[128:129], off
	s_waitcnt vmcnt(6)
	s_barrier
	v_mfma_f32_16x16x32_bf16 v[52:55], v[204:207], v[144:147], v[52:55]
	v_mfma_f32_16x16x32_bf16 v[48:51], v[212:215], v[144:147], v[48:51]
	v_mfma_f32_16x16x32_bf16 v[36:39], v[204:207], v[170:173], v[36:39]
	v_mfma_f32_16x16x32_bf16 v[32:35], v[212:215], v[170:173], v[32:35]
	v_mfma_f32_16x16x32_bf16 v[20:23], v[204:207], v[178:181], v[20:23]
	v_mfma_f32_16x16x32_bf16 v[16:19], v[212:215], v[178:181], v[16:19]
	v_mfma_f32_16x16x32_bf16 v[4:7], v[204:207], v[196:199], v[4:7]
	v_mfma_f32_16x16x32_bf16 v[0:3], v[212:215], v[196:199], v[0:3]
	v_mfma_f32_16x16x32_bf16 v[52:55], v[208:211], v[148:151], v[52:55]
	v_mfma_f32_16x16x32_bf16 v[48:51], v[216:219], v[148:151], v[48:51]
	v_mfma_f32_16x16x32_bf16 v[36:39], v[208:211], v[174:177], v[36:39]
	v_mfma_f32_16x16x32_bf16 v[32:35], v[216:219], v[174:177], v[32:35]
	v_mfma_f32_16x16x32_bf16 v[20:23], v[208:211], v[182:185], v[20:23]
	v_mfma_f32_16x16x32_bf16 v[16:19], v[216:219], v[182:185], v[16:19]
	v_mfma_f32_16x16x32_bf16 v[4:7], v[208:211], v[200:203], v[4:7]
	v_mfma_f32_16x16x32_bf16 v[0:3], v[216:219], v[200:203], v[0:3]
	s_add_i32 s49, 0, 0x18000
	v_add_u32_e32 v140, s49, v189
	s_barrier
	ds_read_b128 v[128:131], v140
	ds_read_b128 v[132:135], v140 offset:1024
	ds_read_b128 v[136:139], v140 offset:2048
	ds_read_b128 v[140:143], v140 offset:3072
	s_add_u32 s26, s26, 0x100000
	s_addc_u32 s27, s27, 0
	s_mov_b32 m0, s35
	v_lshl_add_u64 v[204:205], s[26:27], 0, v[154:155]
	ds_read_b128 v[144:147], v192 offset:32768
	ds_read_b128 v[148:151], v192 offset:33792
	ds_read_b128 v[170:173], v192 offset:34816
	ds_read_b128 v[174:177], v192 offset:35840
	ds_read_b128 v[178:181], v192 offset:36864
	ds_read_b128 v[182:185], v192 offset:37888
	ds_read_b128 v[196:199], v192 offset:38912
	ds_read_b128 v[200:203], v192 offset:39936
	global_load_lds_dwordx4 v[204:205], off
	v_lshl_add_u64 v[204:205], s[26:27], 0, v[158:159]
	s_mov_b32 m0, s36
	s_nop 0
	global_load_lds_dwordx4 v[204:205], off
	s_waitcnt lgkmcnt(8)
	s_barrier
; #define PG8_STAGE(bufoff, gbase, voff) do { _Pragma("unroll") for (int _i = 0; _i < 2; ++_i) \
;         __builtin_amdgcn_global_load_lds((const unsigned*)((const char*)(gbase) + (voff)[_i]), (LAS unsigned*)(lds + (bufoff) + ldsw + _i * 8192), 16, 0, 0); } while (0)
; #define PG8_LDA(dst, b, h) do { _Pragma("unroll") for (int m = 0; m < 4; ++m) _Pragma("unroll") for (int k = 0; k < 2; ++k) dst[m][k] = *(const LAS bf16x8*)(lds + PG8_SA(b, h) + aoff + m * 2048 + k * 1024); } while (0)
; #define PG8_LDB(dst, b, h) do { _Pragma("unroll") for (int n = 0; n < 2; ++n) _Pragma("unroll") for (int k = 0; k < 2; ++k) dst[n][k] = *(const LAS bf16x8*)(lds + PG8_SB(b, h) + boff + n * 2048 + k * 1024); } while (0)
; #define PG8_MMA(ai, bj, At, Bt) do { __builtin_amdgcn_s_setprio(1); _Pragma("unroll") for (int m = 0; m < 4; ++m) _Pragma("unroll") for (int n = 0; n < 2; ++n) _Pragma("unroll") for (int k = 0; k < 2; ++k) \
;         acc[ai][bj][m][n] = __builtin_amdgcn_mfma_f32_16x16x32_bf16(Bt[n][k], At[m][k], acc[ai][bj][m][n], 0, 0, 0); __builtin_amdgcn_s_setprio(0); } while (0)
; #define PG8_WAIT_V(n) asm volatile("s_waitcnt vmcnt(" #n ")" ::: "memory")
; #define PG8_WAIT_L(n) asm volatile("s_waitcnt lgkmcnt(" #n ")" ::: "memory")
; #define PG8_BAR __builtin_amdgcn_s_barrier()
; #define PG8_SCHED __builtin_amdgcn_sched_barrier(0)
; template <class Epi>
; __device__ __forceinline__ void gemm_phase(LAS unsigned char* lds, const Gemm g, const StaticOrder& S, const Epi& E) {
;     ...
;             PG8_WAIT_L(8); PG8_BAR; PG8_WAIT_L(0); PG8_MMA(0, 0, At, B0); PG8_BAR; PG8_SCHED;
;             PG8_LDB(B1, 1, 1); PG8_STAGE(PG8_SB(1, 0), b3, voffB);
;             PG8_BAR; PG8_WAIT_L(0); PG8_MMA(0, 1, At, B1); PG8_BAR;
;             PG8_LDA(At, 1, 1); PG8_STAGE(PG8_SA(1, 0), a3, voffA);
;             PG8_BAR; PG8_WAIT_L(0); PG8_MMA(1, 0, At, B0); PG8_BAR; PG8_SCHED;
;             PG8_STAGE(PG8_SB(1, 1), b3 + hstepB, voffB);
;             PG8_WAIT_V(6); PG8_BAR; PG8_MMA(1, 1, At, B1); PG8_BAR;
	s_waitcnt lgkmcnt(0)
	s_waitcnt lgkmcnt(0)
	v_mfma_f32_16x16x32_bf16 v[124:127], v[128:131], v[144:147], v[124:127]
	v_mfma_f32_16x16x32_bf16 v[120:123], v[136:139], v[144:147], v[120:123]
	v_mfma_f32_16x16x32_bf16 v[108:111], v[128:131], v[170:173], v[108:111]
	v_mfma_f32_16x16x32_bf16 v[104:107], v[136:139], v[170:173], v[104:107]
	v_mfma_f32_16x16x32_bf16 v[92:95], v[128:131], v[178:181], v[92:95]
	v_mfma_f32_16x16x32_bf16 v[88:91], v[136:139], v[178:181], v[88:91]
	v_mfma_f32_16x16x32_bf16 v[76:79], v[128:131], v[196:199], v[76:79]
	v_mfma_f32_16x16x32_bf16 v[72:75], v[136:139], v[196:199], v[72:75]
	v_mfma_f32_16x16x32_bf16 v[124:127], v[132:135], v[148:151], v[124:127]
	v_mfma_f32_16x16x32_bf16 v[120:123], v[140:143], v[148:151], v[120:123]
	v_mfma_f32_16x16x32_bf16 v[108:111], v[132:135], v[174:177], v[108:111]
	v_mfma_f32_16x16x32_bf16 v[104:107], v[140:143], v[174:177], v[104:107]
	v_mfma_f32_16x16x32_bf16 v[92:95], v[132:135], v[182:185], v[92:95]
	v_mfma_f32_16x16x32_bf16 v[88:91], v[140:143], v[182:185], v[88:91]
	v_mfma_f32_16x16x32_bf16 v[76:79], v[132:135], v[200:203], v[76:79]
	v_mfma_f32_16x16x32_bf16 v[72:75], v[140:143], v[200:203], v[72:75]
	s_barrier
	s_add_i32 s26, 0, 0x1c000
	s_add_i32 s27, s49, s31
	v_add_u32_e32 v195, s26, v189
	v_lshl_add_u64 v[186:187], v[186:187], 0, s[12:13]
	s_mov_b32 m0, s27
	ds_read_b128 v[204:207], v195
	ds_read_b128 v[208:211], v195 offset:1024
	ds_read_b128 v[212:215], v195 offset:2048
	ds_read_b128 v[216:219], v195 offset:3072
	global_load_lds_dwordx4 v[186:187], off
	v_lshl_add_u64 v[186:187], v[220:221], 0, s[12:13]
	s_add_i32 m0, s27, 0x2000
	s_nop 0
	global_load_lds_dwordx4 v[186:187], off
	s_barrier
	s_waitcnt lgkmcnt(0)
	s_waitcnt lgkmcnt(0)
	v_mfma_f32_16x16x32_bf16 v[116:119], v[204:207], v[144:147], v[116:119]
	v_mfma_f32_16x16x32_bf16 v[112:115], v[212:215], v[144:147], v[112:115]
	v_mfma_f32_16x16x32_bf16 v[100:103], v[204:207], v[170:173], v[100:103]
	v_mfma_f32_16x16x32_bf16 v[96:99], v[212:215], v[170:173], v[96:99]
	v_mfma_f32_16x16x32_bf16 v[84:87], v[204:207], v[178:181], v[84:87]
	v_mfma_f32_16x16x32_bf16 v[80:83], v[212:215], v[178:181], v[80:83]
	v_mfma_f32_16x16x32_bf16 v[68:71], v[204:207], v[196:199], v[68:71]
	v_mfma_f32_16x16x32_bf16 v[64:67], v[212:215], v[196:199], v[64:67]
	v_mfma_f32_16x16x32_bf16 v[116:119], v[208:211], v[148:151], v[116:119]
	v_mfma_f32_16x16x32_bf16 v[112:115], v[216:219], v[148:151], v[112:115]
	v_mfma_f32_16x16x32_bf16 v[100:103], v[208:211], v[174:177], v[100:103]
	v_mfma_f32_16x16x32_bf16 v[96:99], v[216:219], v[174:177], v[96:99]
	v_mfma_f32_16x16x32_bf16 v[84:87], v[208:211], v[182:185], v[84:87]
	v_mfma_f32_16x16x32_bf16 v[80:83], v[216:219], v[182:185], v[80:83]
	v_mfma_f32_16x16x32_bf16 v[68:71], v[208:211], v[200:203], v[68:71]
	v_mfma_f32_16x16x32_bf16 v[64:67], v[216:219], v[200:203], v[64:67]
	s_mov_b32 m0, s38
	v_lshl_add_u64 v[186:187], v[222:223], 0, s[12:13]
	s_barrier
	ds_read_b128 v[144:147], v192 offset:49152
	ds_read_b128 v[148:151], v192 offset:50176
	ds_read_b128 v[170:173], v192 offset:51200
	ds_read_b128 v[174:177], v192 offset:52224
	ds_read_b128 v[178:181], v192 offset:53248
	ds_read_b128 v[182:185], v192 offset:54272
	ds_read_b128 v[196:199], v192 offset:55296
	ds_read_b128 v[200:203], v192 offset:56320
	global_load_lds_dwordx4 v[186:187], off
	v_lshl_add_u64 v[186:187], v[224:225], 0, s[12:13]
	s_mov_b32 m0, s39
	s_nop 0
	global_load_lds_dwordx4 v[186:187], off
	s_barrier
	s_waitcnt lgkmcnt(0)
	s_waitcnt lgkmcnt(0)
	v_mfma_f32_16x16x32_bf16 v[60:63], v[128:131], v[144:147], v[60:63]
	v_mfma_f32_16x16x32_bf16 v[56:59], v[136:139], v[144:147], v[56:59]
	v_mfma_f32_16x16x32_bf16 v[44:47], v[128:131], v[170:173], v[44:47]
	v_mfma_f32_16x16x32_bf16 v[40:43], v[136:139], v[170:173], v[40:43]
	v_mfma_f32_16x16x32_bf16 v[28:31], v[128:131], v[178:181], v[28:31]
	v_mfma_f32_16x16x32_bf16 v[24:27], v[136:139], v[178:181], v[24:27]
	v_mfma_f32_16x16x32_bf16 v[12:15], v[128:131], v[196:199], v[12:15]
	v_mfma_f32_16x16x32_bf16 v[8:11], v[136:139], v[196:199], v[8:11]
	v_mfma_f32_16x16x32_bf16 v[60:63], v[132:135], v[148:151], v[60:63]
	v_mfma_f32_16x16x32_bf16 v[56:59], v[140:143], v[148:151], v[56:59]
	v_mfma_f32_16x16x32_bf16 v[44:47], v[132:135], v[174:177], v[44:47]
	v_mfma_f32_16x16x32_bf16 v[40:43], v[140:143], v[174:177], v[40:43]
	v_mfma_f32_16x16x32_bf16 v[28:31], v[132:135], v[182:185], v[28:31]
	v_mfma_f32_16x16x32_bf16 v[24:27], v[140:143], v[182:185], v[24:27]
	v_mfma_f32_16x16x32_bf16 v[12:15], v[132:135], v[200:203], v[12:15]
	v_mfma_f32_16x16x32_bf16 v[8:11], v[140:143], v[200:203], v[8:11]
	s_barrier
	s_add_u32 s24, s24, 0x100080
	s_addc_u32 s25, s25, 0
	s_add_i32 s26, s26, s31
	v_lshl_add_u64 v[128:129], s[24:25], 0, v[156:157]
	s_mov_b32 m0, s26
	s_nop 0
	global_load_lds_dwordx4 v[128:129], off
	v_lshl_add_u64 v[128:129], s[24:25], 0, v[160:161]
	s_add_i32 m0, s26, 0x2000
	s_nop 0
	global_load_lds_dwordx4 v[128:129], off
	s_waitcnt vmcnt(6)
	s_barrier
	v_mfma_f32_16x16x32_bf16 v[52:55], v[204:207], v[144:147], v[52:55]
	v_mfma_f32_16x16x32_bf16 v[48:51], v[212:215], v[144:147], v[48:51]
	v_mfma_f32_16x16x32_bf16 v[36:39], v[204:207], v[170:173], v[36:39]
	v_mfma_f32_16x16x32_bf16 v[32:35], v[212:215], v[170:173], v[32:35]
	v_mfma_f32_16x16x32_bf16 v[20:23], v[204:207], v[178:181], v[20:23]
	v_mfma_f32_16x16x32_bf16 v[16:19], v[212:215], v[178:181], v[16:19]
	v_mfma_f32_16x16x32_bf16 v[4:7], v[204:207], v[196:199], v[4:7]
	v_mfma_f32_16x16x32_bf16 v[0:3], v[212:215], v[196:199], v[0:3]
	v_mfma_f32_16x16x32_bf16 v[52:55], v[208:211], v[148:151], v[52:55]
	v_mfma_f32_16x16x32_bf16 v[48:51], v[216:219], v[148:151], v[48:51]
	v_mfma_f32_16x16x32_bf16 v[36:39], v[208:211], v[174:177], v[36:39]
	v_mfma_f32_16x16x32_bf16 v[32:35], v[216:219], v[174:177], v[32:35]
	v_mfma_f32_16x16x32_bf16 v[20:23], v[208:211], v[182:185], v[20:23]
	v_mfma_f32_16x16x32_bf16 v[16:19], v[216:219], v[182:185], v[16:19]
	v_mfma_f32_16x16x32_bf16 v[4:7], v[208:211], v[200:203], v[4:7]
	v_mfma_f32_16x16x32_bf16 v[0:3], v[216:219], v[200:203], v[0:3]
	s_add_i32 s48, s48, 2
	s_add_u32 s22, s22, 0x100
	s_addc_u32 s23, s23, 0
	s_add_u32 s46, s46, 0x100
	s_addc_u32 s47, s47, 0
	s_cmp_gt_u32 s48, 61
	s_barrier
; __device__ __forceinline__ unsigned pk2(float lo, float hi) { const f32x2 v = (f32x2){lo, hi}; const bf16x2_t b = __builtin_convertvector(v, bf16x2_t); return __builtin_bit_cast(unsigned, b); }
; __device__ __forceinline__ void unpack8(const u32x4 v, float* f) { f[0] = bf_lo(v.x); f[1] = bf_hi(v.x); f[2] = bf_lo(v.y); f[3] = bf_hi(v.y); f[4] = bf_lo(v.z); f[5] = bf_hi(v.z); f[6] = bf_lo(v.w); f[7] = bf_hi(v.w); }
;     __device__ __forceinline__ void operator()(const f32x4 (&acc)[2][2][4][2], const Unit& u, int wr, int wc, int fr, int fq, const float (&)[8]) const {
;         const int row0 = u.pm * BM + wr * 64 + fr, col0 = u.pn * BM + wc * 32 + 8 * fq;
; #pragma unroll
;         for (int ai = 0; ai < 2; ++ai) {
;             u32x4 bv[4][2];
; #pragma unroll
;             for (int m = 0; m < 4; ++m)
; #pragma unroll
;                 for (int bj = 0; bj < 2; ++bj) bv[m][bj] = *(const u32x4*)(xb + (size_t)(row0 + ai * HALF + m * 16) * DM + col0 + bj * HALF);
; #pragma unroll
;             for (int m = 0; m < 4; ++m) { const int row = row0 + ai * HALF + m * 16; const size_t ro = (size_t)row * DM + col0; float s = 0.f;
; #pragma unroll
;                 for (int bj = 0; bj < 2; ++bj) { float b8[8]; unpack8(bv[m][bj], b8);
;                     const f32x4 v0 = (f32x4){b8[0], b8[1], b8[2], b8[3]} + acc[ai][bj][m][0], v1 = (f32x4){b8[4], b8[5], b8[6], b8[7]} + acc[ai][bj][m][1];
;                     s += v0[0] * v0[0] + v0[1] * v0[1] + v0[2] * v0[2] + v0[3] * v0[3] + v1[0] * v1[0] + v1[1] * v1[1] + v1[2] * v1[2] + v1[3] * v1[3];
;                     if (LAST) { *(f32x4*)(out + ro + bj * HALF) = v0; *(f32x4*)(out + ro + bj * HALF + 4) = v1; }
;                     else { u32x4 w; w.x = pk2(v0[0], v0[1]); w.y = pk2(v0[2], v0[3]); w.z = pk2(v1[0], v1[1]); w.w = pk2(v1[2], v1[3]); *(u32x4*)(xb + ro + bj * HALF) = w; } }
;                 s += __shfl_xor(s, 16); s += __shfl_xor(s, 32);
;                 if (fq == 0) ss[(size_t)row * 16 + u.pn * 4 + wc] = s; }
	s_cbranch_scc0 .LBB0_844
	v_lshl_or_b32 v170, s6, 8, v190
	v_lshl_add_u32 v172, s8, 8, v188
	v_ashrrev_i32_e32 v171, 31, v170
	v_lshlrev_b64 v[206:207], 1, v[170:171]
	v_ashrrev_i32_e32 v173, 31, v172
	v_lshl_add_u64 v[174:175], s[76:77], 0, v[206:207]
	v_lshlrev_b64 v[208:209], 11, v[172:173]
	v_lshl_add_u64 v[128:129], v[174:175], 0, v[208:209]
	global_load_dwordx4 v[198:201], v[128:129], off
	global_load_dwordx4 v[202:205], v[128:129], off offset:256
	v_or_b32_e32 v184, 16, v172
	v_or_b32_e32 v180, 32, v172
	v_or_b32_e32 v176, 48, v172
	v_ashrrev_i32_e32 v185, 31, v184
	v_ashrrev_i32_e32 v181, 31, v180
	v_ashrrev_i32_e32 v177, 31, v176
	v_lshlrev_b64 v[186:187], 11, v[184:185]
	v_lshlrev_b64 v[182:183], 11, v[180:181]
	v_lshlrev_b64 v[178:179], 11, v[176:177]
	v_lshl_add_u64 v[128:129], v[174:175], 0, v[186:187]
	v_lshl_add_u64 v[130:131], v[174:175], 0, v[182:183]
	v_lshl_add_u64 v[196:197], v[174:175], 0, v[178:179]
	global_load_dwordx4 v[148:151], v[128:129], off
	global_load_dwordx4 v[144:147], v[128:129], off offset:256
	global_load_dwordx4 v[140:143], v[130:131], off
	global_load_dwordx4 v[136:139], v[130:131], off offset:256
	global_load_dwordx4 v[132:135], v[196:197], off
	s_nop 0
	global_load_dwordx4 v[128:131], v[196:197], off offset:256
	v_add_u32_e32 v218, 0x80, v172
	v_ashrrev_i32_e32 v219, 31, v218
	v_lshlrev_b64 v[218:219], 11, v[218:219]
	v_lshl_add_u64 v[218:219], v[174:175], 0, v[218:219]
	global_load_dwordx4 v[220:223], v[218:219], off
	global_load_dwordx4 v[224:227], v[218:219], off offset:256
	v_add_u32_e32 v218, 0x90, v172
	v_ashrrev_i32_e32 v219, 31, v218
	v_lshlrev_b64 v[218:219], 11, v[218:219]
	v_lshl_add_u64 v[218:219], v[174:175], 0, v[218:219]
	global_load_dwordx4 v[228:231], v[218:219], off
	global_load_dwordx4 v[232:235], v[218:219], off offset:256
	v_add_u32_e32 v218, 0xa0, v172
	v_ashrrev_i32_e32 v219, 31, v218
	v_lshlrev_b64 v[218:219], 11, v[218:219]
	v_lshl_add_u64 v[218:219], v[174:175], 0, v[218:219]
	global_load_dwordx4 v[236:239], v[218:219], off
	global_load_dwordx4 v[240:243], v[218:219], off offset:256
	v_add_u32_e32 v218, 0xb0, v172
	v_ashrrev_i32_e32 v219, 31, v218
	v_lshlrev_b64 v[218:219], 11, v[218:219]
	v_lshl_add_u64 v[218:219], v[174:175], 0, v[218:219]
	global_load_dwordx4 v[244:247], v[218:219], off
	global_load_dwordx4 v[252:255], v[218:219], off offset:256
	v_and_b32_e32 v196, 64, v194
	v_xor_b32_e32 v195, 16, v194
	v_add_u32_e32 v196, 64, v196
	v_xor_b32_e32 v197, 32, v194
	v_cmp_lt_i32_e32 vcc, v195, v196
	s_waitcnt vmcnt(15)
	v_lshlrev_b32_e32 v210, 16, v198
	v_cndmask_b32_e32 v195, v194, v195, vcc
	v_cmp_lt_i32_e32 vcc, v197, v196
	v_and_b32_e32 v211, 0xffff0000, v198
	s_waitcnt vmcnt(14)
	v_lshlrev_b32_e32 v214, 16, v202
	v_and_b32_e32 v215, 0xffff0000, v202
	v_cndmask_b32_e32 v197, v194, v197, vcc
	v_lshlrev_b32_e32 v212, 16, v200
	v_and_b32_e32 v213, 0xffff0000, v200
	v_lshlrev_b32_e32 v200, 16, v201
	v_and_b32_e32 v201, 0xffff0000, v201
	v_lshlrev_b32_e32 v216, 16, v204
	v_and_b32_e32 v217, 0xffff0000, v204
	v_pk_add_f32 v[124:125], v[124:125], v[210:211]
	v_pk_add_f32 v[116:117], v[116:117], v[214:215]
	v_lshlrev_b32_e32 v196, 2, v195
	v_lshlrev_b32_e32 v195, 2, v197
	v_lshlrev_b32_e32 v198, 16, v199
	v_and_b32_e32 v199, 0xffff0000, v199
	v_lshlrev_b32_e32 v202, 16, v203
	v_and_b32_e32 v203, 0xffff0000, v203
	v_pk_add_f32 v[122:123], v[122:123], v[200:201]
	v_pk_add_f32 v[200:201], v[112:113], v[216:217]
	v_mul_f32_e32 v197, v125, v125
	v_cvt_pk_bf16_f32 v112, v124, v125
	v_mul_f32_e32 v125, v117, v117
	v_pk_add_f32 v[126:127], v[126:127], v[198:199]
	v_pk_add_f32 v[118:119], v[118:119], v[202:203]
	v_fmac_f32_e32 v197, v124, v124
	v_fmac_f32_e32 v125, v116, v116
	v_fmac_f32_e32 v197, v126, v126
	v_fmac_f32_e32 v125, v118, v118
	v_pk_add_f32 v[120:121], v[120:121], v[212:213]
	v_fmac_f32_e32 v197, v127, v127
	v_fmac_f32_e32 v125, v119, v119
	v_lshlrev_b32_e32 v204, 16, v205
	v_and_b32_e32 v205, 0xffff0000, v205
	v_fmac_f32_e32 v197, v120, v120
	v_fmac_f32_e32 v125, v200, v200
	v_pk_add_f32 v[198:199], v[114:115], v[204:205]
	v_fmac_f32_e32 v197, v121, v121
	v_fmac_f32_e32 v125, v201, v201
	v_fmac_f32_e32 v197, v122, v122
	v_fmac_f32_e32 v125, v198, v198
	v_fmac_f32_e32 v197, v123, v123
	v_fmac_f32_e32 v125, v199, v199
	v_cvt_pk_bf16_f32 v115, v122, v123
	v_add_f32_e32 v122, v197, v125
	ds_bpermute_b32 v123, v196, v122
	v_cvt_pk_bf16_f32 v114, v120, v121
	v_lshl_add_u64 v[120:121], s[76:77], 0, v[208:209]
	v_cvt_pk_bf16_f32 v113, v126, v127
	v_lshl_add_u64 v[120:121], v[120:121], 0, v[206:207]
	global_store_dwordx4 v[120:121], v[112:115], off
	s_waitcnt lgkmcnt(0)
	s_nop 0
	v_add_f32_e32 v112, v122, v123
	ds_bpermute_b32 v113, v195, v112
	v_cvt_pk_bf16_f32 v114, v116, v117
	v_cvt_pk_bf16_f32 v115, v118, v119
	v_cvt_pk_bf16_f32 v116, v200, v201
	v_cvt_pk_bf16_f32 v117, v198, v199
	global_store_dwordx4 v[120:121], v[114:117], off offset:256
	s_and_saveexec_b64 s[22:23], s[0:1]
	s_cbranch_execz .LBB0_847
	s_waitcnt lgkmcnt(0)
	v_add_f32_e32 v114, v112, v113
	s_lshl_b32 s24, s6, 2
	v_lshlrev_b64 v[112:113], 6, v[172:173]
	s_ashr_i32 s25, s24, 31
	v_lshl_add_u64 v[112:113], s[10:11], 0, v[112:113]
	v_lshl_add_u64 v[112:113], s[24:25], 2, v[112:113]
	s_lshl_b32 s8, s37, 2
	v_lshl_add_u64 v[112:113], v[112:113], 0, s[8:9]
	global_store_dword v[112:113], v114, off

; #define PG8_STAGE(bufoff, gbase, voff) do { _Pragma("unroll") for (int _i = 0; _i < 2; ++_i) \
;         __builtin_amdgcn_global_load_lds((const unsigned*)((const char*)(gbase) + (voff)[_i]), (LAS unsigned*)(lds + (bufoff) + ldsw + _i * 8192), 16, 0, 0); } while (0)
; #define PG8_LDA(dst, b, h) do { _Pragma("unroll") for (int m = 0; m < 4; ++m) _Pragma("unroll") for (int k = 0; k < 2; ++k) dst[m][k] = *(const LAS bf16x8*)(lds + PG8_SA(b, h) + aoff + m * 2048 + k * 1024); } while (0)
; #define PG8_LDB(dst, b, h) do { _Pragma("unroll") for (int n = 0; n < 2; ++n) _Pragma("unroll") for (int k = 0; k < 2; ++k) dst[n][k] = *(const LAS bf16x8*)(lds + PG8_SB(b, h) + boff + n * 2048 + k * 1024); } while (0)
; #define PG8_WAIT_V(n) asm volatile("s_waitcnt vmcnt(" #n ")" ::: "memory")
; #define PG8_WAIT_L(n) asm volatile("s_waitcnt lgkmcnt(" #n ")" ::: "memory")
; #define PG8_BAR __builtin_amdgcn_s_barrier()
; #define PG8_SCHED __builtin_amdgcn_sched_barrier(0)
; template <class Epi>
; __device__ __forceinline__ void gemm_phase(LAS unsigned char* lds, const Gemm g, const StaticOrder& S, const Epi& E) {
;     ...
;         const bool has_next = S.next(ui + 1, nxt);
;         const char* nA = has_next ? (const char*)g.A + (size_t)nxt.pm * tstepA : cA; const char* nB = has_next ? (const char*)g.Bt + (size_t)nxt.pn * tstepB : cB;
;         for (int t = 0; t < nt; t += 2) {
;             const bool last = (t == nt - 2);
;             const char* a1 = cA + (size_t)(t + 1) * kstep;
;             const char* a2 = last ? nA : cA + (size_t)(t + 2) * kstep; const char* b2 = last ? nB : cB + (size_t)(t + 2) * kstep;
;             const char* a3 = a2 + kstep; const char* b3 = b2 + kstep;
;             if (last) E.pre(cur, wr, fr, epre);
;             PG8_LDB(B0, 0, 0); PG8_SCHED; PG8_LDA(At, 0, 0); PG8_STAGE(PG8_SA(1, 1), a1 + hstepA, voffA);
;             PG8_WAIT_L(8); PG8_BAR; PG8_WAIT_L(0); PG8_MMA(0, 0, At, B0); PG8_BAR; PG8_SCHED;
;             PG8_LDB(B1, 0, 1); PG8_STAGE(PG8_SB(0, 0), b2, voffB);
;             PG8_BAR; PG8_WAIT_L(0); PG8_MMA(0, 1, At, B1); PG8_BAR;
;             PG8_LDA(At, 0, 1); PG8_STAGE(PG8_SA(0, 0), a2, voffA);
;             PG8_BAR; PG8_WAIT_L(0); PG8_MMA(1, 0, At, B0); PG8_BAR; PG8_SCHED;
;             PG8_STAGE(PG8_SB(0, 1), b2 + hstepB, voffB);
;             PG8_WAIT_V(6); PG8_BAR; PG8_MMA(1, 1, At, B1); PG8_BAR;
.LBB0_921:
	s_ashr_i32 s13, s12, 31
	v_cmp_lt_i64_e32 vcc, s[14:15], v[142:143]
	s_lshl_b64 s[14:15], s[12:13], 19
	s_add_u32 s14, s76, s14
	s_addc_u32 s15, s77, s15
	s_and_b64 s[16:17], vcc, exec
	s_cselect_b32 s13, s15, s21
	s_cselect_b32 s43, s14, s20
	s_ashr_i32 s11, s10, 31
	s_lshl_b64 s[16:17], s[10:11], 19
	s_add_u32 s16, s9, s16
	s_addc_u32 s17, s26, s17
	s_and_b64 s[24:25], vcc, exec
	s_cselect_b32 s11, s17, s23
	s_cselect_b32 s44, s16, s22
	s_add_u32 s20, s20, 0x40080
	s_addc_u32 s21, s21, 0
	s_add_u32 s45, s22, 0x100
	s_addc_u32 s46, s23, 0
	s_mov_b32 s47, -2
	ds_read_b128 v[146:149], v173
	ds_read_b128 v[154:157], v173 offset:1024
	ds_read_b128 v[158:161], v173 offset:2048
	ds_read_b128 v[162:165], v173 offset:3072
	s_add_u32 s22, s20, 0xfffc0080
	s_addc_u32 s23, s21, -1
	s_cmp_eq_u32 s47, 12
	s_cselect_b32 s25, s13, s23
	s_cselect_b32 s24, s43, s22
	s_cselect_b32 s23, s11, s46
	s_cselect_b32 s22, s44, s45
	v_lshl_add_u64 v[150:151], s[20:21], 0, v[138:139]
	s_add_i32 m0, s19, 0xc000
	ds_read_b128 v[166:169], v174
	ds_read_b128 v[178:181], v174 offset:1024
	ds_read_b128 v[182:185], v174 offset:2048
	ds_read_b128 v[186:189], v174 offset:3072
	ds_read_b128 v[190:193], v174 offset:4096
	ds_read_b128 v[194:197], v174 offset:5120
	ds_read_b128 v[198:201], v174 offset:6144
	ds_read_b128 v[202:205], v174 offset:7168
	global_load_lds_dwordx4 v[150:151], off
	v_lshl_add_u64 v[150:151], s[20:21], 0, v[140:141]
	s_add_i32 m0, s19, 0xe000
	s_nop 0
	global_load_lds_dwordx4 v[150:151], off
	s_waitcnt lgkmcnt(8)
	s_barrier
	s_waitcnt lgkmcnt(0)
	s_waitcnt lgkmcnt(0)
	v_mfma_f32_16x16x32_bf16 v[124:127], v[146:149], v[166:169], 0
	v_mfma_f32_16x16x32_bf16 v[120:123], v[158:161], v[166:169], 0
	v_mfma_f32_16x16x32_bf16 v[112:115], v[146:149], v[182:185], 0
	v_mfma_f32_16x16x32_bf16 v[104:107], v[158:161], v[182:185], 0
	v_mfma_f32_16x16x32_bf16 v[92:95], v[146:149], v[190:193], 0
	v_mfma_f32_16x16x32_bf16 v[88:91], v[158:161], v[190:193], 0
	v_mfma_f32_16x16x32_bf16 v[80:83], v[146:149], v[198:201], 0
	v_mfma_f32_16x16x32_bf16 v[72:75], v[158:161], v[198:201], 0
	v_mfma_f32_16x16x32_bf16 v[124:127], v[154:157], v[178:181], v[124:127]
	v_mfma_f32_16x16x32_bf16 v[120:123], v[162:165], v[178:181], v[120:123]
	v_mfma_f32_16x16x32_bf16 v[112:115], v[154:157], v[186:189], v[112:115]
	v_mfma_f32_16x16x32_bf16 v[104:107], v[162:165], v[186:189], v[104:107]
	v_mfma_f32_16x16x32_bf16 v[92:95], v[154:157], v[194:197], v[92:95]
	v_mfma_f32_16x16x32_bf16 v[88:91], v[162:165], v[194:197], v[88:91]
	v_mfma_f32_16x16x32_bf16 v[80:83], v[154:157], v[202:205], v[80:83]
	v_mfma_f32_16x16x32_bf16 v[72:75], v[162:165], v[202:205], v[72:75]
	s_barrier
	s_add_i32 s48, s38, s27
	v_lshl_add_u64 v[150:151], s[22:23], 0, v[132:133]
	s_mov_b32 m0, s48
	ds_read_b128 v[206:209], v175
	ds_read_b128 v[210:213], v175 offset:1024
	ds_read_b128 v[214:217], v175 offset:2048
	ds_read_b128 v[218:221], v175 offset:3072
	global_load_lds_dwordx4 v[150:151], off
	v_lshl_add_u64 v[222:223], s[22:23], 0, v[128:129]
	s_add_i32 m0, s48, 0x2000
	s_nop 0
	global_load_lds_dwordx4 v[222:223], off
	s_barrier
	s_waitcnt lgkmcnt(0)
	s_waitcnt lgkmcnt(0)
	v_mfma_f32_16x16x32_bf16 v[116:119], v[206:209], v[166:169], 0
	v_mfma_f32_16x16x32_bf16 v[108:111], v[214:217], v[166:169], 0
	v_mfma_f32_16x16x32_bf16 v[100:103], v[206:209], v[182:185], 0
	v_mfma_f32_16x16x32_bf16 v[96:99], v[214:217], v[182:185], 0
	v_mfma_f32_16x16x32_bf16 v[84:87], v[206:209], v[190:193], 0
	v_mfma_f32_16x16x32_bf16 v[76:79], v[214:217], v[190:193], 0
	v_mfma_f32_16x16x32_bf16 v[68:71], v[206:209], v[198:201], 0
	v_mfma_f32_16x16x32_bf16 v[64:67], v[214:217], v[198:201], 0
	v_mfma_f32_16x16x32_bf16 v[116:119], v[210:213], v[178:181], v[116:119]
	v_mfma_f32_16x16x32_bf16 v[108:111], v[218:221], v[178:181], v[108:111]
	v_mfma_f32_16x16x32_bf16 v[100:103], v[210:213], v[186:189], v[100:103]
	v_mfma_f32_16x16x32_bf16 v[96:99], v[218:221], v[186:189], v[96:99]
	v_mfma_f32_16x16x32_bf16 v[84:87], v[210:213], v[194:197], v[84:87]
	v_mfma_f32_16x16x32_bf16 v[76:79], v[218:221], v[194:197], v[76:79]
	v_mfma_f32_16x16x32_bf16 v[68:71], v[210:213], v[202:205], v[68:71]
	v_mfma_f32_16x16x32_bf16 v[64:67], v[218:221], v[202:205], v[64:67]
	s_mov_b32 m0, s19
	v_lshl_add_u64 v[224:225], s[24:25], 0, v[134:135]
	s_barrier
	ds_read_b128 v[166:169], v174 offset:16384
	ds_read_b128 v[178:181], v174 offset:17408
	ds_read_b128 v[182:185], v174 offset:18432
	ds_read_b128 v[186:189], v174 offset:19456
	ds_read_b128 v[190:193], v174 offset:20480
	ds_read_b128 v[194:197], v174 offset:21504
	ds_read_b128 v[198:201], v174 offset:22528
	ds_read_b128 v[202:205], v174 offset:23552
	global_load_lds_dwordx4 v[224:225], off
	v_lshl_add_u64 v[226:227], s[24:25], 0, v[130:131]
	s_mov_b32 m0, s30
	s_nop 0
	global_load_lds_dwordx4 v[226:227], off
	s_barrier
	s_waitcnt lgkmcnt(0)
	s_waitcnt lgkmcnt(0)
	v_mfma_f32_16x16x32_bf16 v[60:63], v[146:149], v[166:169], 0
	v_mfma_f32_16x16x32_bf16 v[56:59], v[158:161], v[166:169], 0
	v_mfma_f32_16x16x32_bf16 v[48:51], v[146:149], v[182:185], 0
	v_mfma_f32_16x16x32_bf16 v[40:43], v[158:161], v[182:185], 0
	v_mfma_f32_16x16x32_bf16 v[32:35], v[146:149], v[190:193], 0
	v_mfma_f32_16x16x32_bf16 v[24:27], v[158:161], v[190:193], 0
	v_mfma_f32_16x16x32_bf16 v[16:19], v[146:149], v[198:201], 0
	v_mfma_f32_16x16x32_bf16 v[8:11], v[158:161], v[198:201], 0
	v_mfma_f32_16x16x32_bf16 v[60:63], v[154:157], v[178:181], v[60:63]
	v_mfma_f32_16x16x32_bf16 v[56:59], v[162:165], v[178:181], v[56:59]
	v_mfma_f32_16x16x32_bf16 v[48:51], v[154:157], v[186:189], v[48:51]
	v_mfma_f32_16x16x32_bf16 v[40:43], v[162:165], v[186:189], v[40:43]
	v_mfma_f32_16x16x32_bf16 v[32:35], v[154:157], v[194:197], v[32:35]
	v_mfma_f32_16x16x32_bf16 v[24:27], v[162:165], v[194:197], v[24:27]
	v_mfma_f32_16x16x32_bf16 v[16:19], v[154:157], v[202:205], v[16:19]
	v_mfma_f32_16x16x32_bf16 v[8:11], v[162:165], v[202:205], v[8:11]
	s_barrier
; #define PG8_STAGE(bufoff, gbase, voff) do { _Pragma("unroll") for (int _i = 0; _i < 2; ++_i) \
;         __builtin_amdgcn_global_load_lds((const unsigned*)((const char*)(gbase) + (voff)[_i]), (LAS unsigned*)(lds + (bufoff) + ldsw + _i * 8192), 16, 0, 0); } while (0)
; #define PG8_LDA(dst, b, h) do { _Pragma("unroll") for (int m = 0; m < 4; ++m) _Pragma("unroll") for (int k = 0; k < 2; ++k) dst[m][k] = *(const LAS bf16x8*)(lds + PG8_SA(b, h) + aoff + m * 2048 + k * 1024); } while (0)
; #define PG8_LDB(dst, b, h) do { _Pragma("unroll") for (int n = 0; n < 2; ++n) _Pragma("unroll") for (int k = 0; k < 2; ++k) dst[n][k] = *(const LAS bf16x8*)(lds + PG8_SB(b, h) + boff + n * 2048 + k * 1024); } while (0)
; #define PG8_MMA(ai, bj, At, Bt) do { __builtin_amdgcn_s_setprio(1); _Pragma("unroll") for (int m = 0; m < 4; ++m) _Pragma("unroll") for (int n = 0; n < 2; ++n) _Pragma("unroll") for (int k = 0; k < 2; ++k) \
;         acc[ai][bj][m][n] = __builtin_amdgcn_mfma_f32_16x16x32_bf16(Bt[n][k], At[m][k], acc[ai][bj][m][n], 0, 0, 0); __builtin_amdgcn_s_setprio(0); } while (0)
; #define PG8_WAIT_V(n) asm volatile("s_waitcnt vmcnt(" #n ")" ::: "memory")
; #define PG8_WAIT_L(n) asm volatile("s_waitcnt lgkmcnt(" #n ")" ::: "memory")
; #define PG8_BAR __builtin_amdgcn_s_barrier()
; #define PG8_SCHED __builtin_amdgcn_sched_barrier(0)
; template <class Epi>
; __device__ __forceinline__ void gemm_phase(LAS unsigned char* lds, const Gemm g, const StaticOrder& S, const Epi& E) {
;     ...
;             PG8_BAR; PG8_WAIT_L(0); PG8_MMA(1, 0, At, B0); PG8_BAR; PG8_SCHED;
;             PG8_STAGE(PG8_SB(0, 1), b2 + hstepB, voffB);
;             PG8_WAIT_V(6); PG8_BAR; PG8_MMA(1, 1, At, B1); PG8_BAR;
;             PG8_LDB(B0, 1, 0); PG8_SCHED; PG8_LDA(At, 1, 0); PG8_STAGE(PG8_SA(0, 1), a2 + hstepA, voffA);
;             PG8_WAIT_L(8); PG8_BAR; PG8_WAIT_L(0); PG8_MMA(0, 0, At, B0); PG8_BAR; PG8_SCHED;
;             PG8_LDB(B1, 1, 1); PG8_STAGE(PG8_SB(1, 0), b3, voffB);
;             PG8_BAR; PG8_WAIT_L(0); PG8_MMA(0, 1, At, B1); PG8_BAR;
;             PG8_LDA(At, 1, 1); PG8_STAGE(PG8_SA(1, 0), a3, voffA);
;             PG8_BAR; PG8_WAIT_L(0); PG8_MMA(1, 0, At, B0); PG8_BAR; PG8_SCHED;
	s_add_u32 s48, s22, 0x40000
	s_addc_u32 s49, s23, 0
	s_add_i32 s50, s39, s27
	v_lshl_add_u64 v[146:147], s[48:49], 0, v[132:133]
	s_mov_b32 m0, s50
	s_nop 0
	global_load_lds_dwordx4 v[146:147], off
	v_lshl_add_u64 v[146:147], s[48:49], 0, v[128:129]
	s_add_i32 m0, s50, 0x2000
	s_nop 0
	global_load_lds_dwordx4 v[146:147], off
	s_waitcnt vmcnt(6)
	s_barrier
	v_mfma_f32_16x16x32_bf16 v[52:55], v[206:209], v[166:169], 0
	v_mfma_f32_16x16x32_bf16 v[44:47], v[214:217], v[166:169], 0
	v_mfma_f32_16x16x32_bf16 v[36:39], v[206:209], v[182:185], 0
	v_mfma_f32_16x16x32_bf16 v[28:31], v[214:217], v[182:185], 0
	v_mfma_f32_16x16x32_bf16 v[20:23], v[206:209], v[190:193], 0
	v_mfma_f32_16x16x32_bf16 v[12:15], v[214:217], v[190:193], 0
	v_mfma_f32_16x16x32_bf16 v[4:7], v[206:209], v[198:201], 0
	v_mfma_f32_16x16x32_bf16 v[0:3], v[214:217], v[198:201], 0
	v_mfma_f32_16x16x32_bf16 v[52:55], v[210:213], v[178:181], v[52:55]
	v_mfma_f32_16x16x32_bf16 v[44:47], v[218:221], v[178:181], v[44:47]
	v_mfma_f32_16x16x32_bf16 v[36:39], v[210:213], v[186:189], v[36:39]
	v_mfma_f32_16x16x32_bf16 v[28:31], v[218:221], v[186:189], v[28:31]
	v_mfma_f32_16x16x32_bf16 v[20:23], v[210:213], v[194:197], v[20:23]
	v_mfma_f32_16x16x32_bf16 v[12:15], v[218:221], v[194:197], v[12:15]
	v_mfma_f32_16x16x32_bf16 v[4:7], v[210:213], v[202:205], v[4:7]
	v_mfma_f32_16x16x32_bf16 v[0:3], v[218:221], v[202:205], v[0:3]
	s_add_i32 s48, 0, 0x18000
	v_add_u32_e32 v162, s48, v171
	s_barrier
	ds_read_b128 v[146:149], v162
	ds_read_b128 v[154:157], v162 offset:1024
	ds_read_b128 v[158:161], v162 offset:2048
	ds_read_b128 v[162:165], v162 offset:3072
	s_add_u32 s24, s24, 0x40000
	s_addc_u32 s25, s25, 0
	s_mov_b32 m0, s31
	v_lshl_add_u64 v[206:207], s[24:25], 0, v[134:135]
	ds_read_b128 v[166:169], v174 offset:32768
	ds_read_b128 v[178:181], v174 offset:33792
	ds_read_b128 v[182:185], v174 offset:34816
	ds_read_b128 v[186:189], v174 offset:35840
	ds_read_b128 v[190:193], v174 offset:36864
	ds_read_b128 v[194:197], v174 offset:37888
	ds_read_b128 v[198:201], v174 offset:38912
	ds_read_b128 v[202:205], v174 offset:39936
	global_load_lds_dwordx4 v[206:207], off
	v_lshl_add_u64 v[206:207], s[24:25], 0, v[130:131]
	s_mov_b32 m0, s33
	s_nop 0
	global_load_lds_dwordx4 v[206:207], off
	s_waitcnt lgkmcnt(8)
	s_barrier
	s_waitcnt lgkmcnt(0)
	s_waitcnt lgkmcnt(0)
	v_mfma_f32_16x16x32_bf16 v[124:127], v[146:149], v[166:169], v[124:127]
	v_mfma_f32_16x16x32_bf16 v[120:123], v[158:161], v[166:169], v[120:123]
	v_mfma_f32_16x16x32_bf16 v[112:115], v[146:149], v[182:185], v[112:115]
	v_mfma_f32_16x16x32_bf16 v[104:107], v[158:161], v[182:185], v[104:107]
	v_mfma_f32_16x16x32_bf16 v[92:95], v[146:149], v[190:193], v[92:95]
	v_mfma_f32_16x16x32_bf16 v[88:91], v[158:161], v[190:193], v[88:91]
	v_mfma_f32_16x16x32_bf16 v[80:83], v[146:149], v[198:201], v[80:83]
	v_mfma_f32_16x16x32_bf16 v[72:75], v[158:161], v[198:201], v[72:75]
	v_mfma_f32_16x16x32_bf16 v[124:127], v[154:157], v[178:181], v[124:127]
	v_mfma_f32_16x16x32_bf16 v[120:123], v[162:165], v[178:181], v[120:123]
	v_mfma_f32_16x16x32_bf16 v[112:115], v[154:157], v[186:189], v[112:115]
	v_mfma_f32_16x16x32_bf16 v[104:107], v[162:165], v[186:189], v[104:107]
	v_mfma_f32_16x16x32_bf16 v[92:95], v[154:157], v[194:197], v[92:95]
	v_mfma_f32_16x16x32_bf16 v[88:91], v[162:165], v[194:197], v[88:91]
	v_mfma_f32_16x16x32_bf16 v[80:83], v[154:157], v[202:205], v[80:83]
	v_mfma_f32_16x16x32_bf16 v[72:75], v[162:165], v[202:205], v[72:75]
	s_barrier
	s_add_i32 s24, 0, 0x1c000
	s_add_i32 s25, s48, s27
	v_add_u32_e32 v177, s24, v171
	v_lshl_add_u64 v[150:151], v[150:151], 0, s[4:5]
	s_mov_b32 m0, s25
	ds_read_b128 v[206:209], v177
	ds_read_b128 v[210:213], v177 offset:1024
	ds_read_b128 v[214:217], v177 offset:2048
	ds_read_b128 v[218:221], v177 offset:3072
	global_load_lds_dwordx4 v[150:151], off
	v_lshl_add_u64 v[150:151], v[222:223], 0, s[4:5]
	s_add_i32 m0, s25, 0x2000
	s_nop 0
	global_load_lds_dwordx4 v[150:151], off
	s_barrier
	s_waitcnt lgkmcnt(0)
	s_waitcnt lgkmcnt(0)
	v_mfma_f32_16x16x32_bf16 v[116:119], v[206:209], v[166:169], v[116:119]
	v_mfma_f32_16x16x32_bf16 v[108:111], v[214:217], v[166:169], v[108:111]
	v_mfma_f32_16x16x32_bf16 v[100:103], v[206:209], v[182:185], v[100:103]
	v_mfma_f32_16x16x32_bf16 v[96:99], v[214:217], v[182:185], v[96:99]
	v_mfma_f32_16x16x32_bf16 v[84:87], v[206:209], v[190:193], v[84:87]
	v_mfma_f32_16x16x32_bf16 v[76:79], v[214:217], v[190:193], v[76:79]
	v_mfma_f32_16x16x32_bf16 v[68:71], v[206:209], v[198:201], v[68:71]
	v_mfma_f32_16x16x32_bf16 v[64:67], v[214:217], v[198:201], v[64:67]
	v_mfma_f32_16x16x32_bf16 v[116:119], v[210:213], v[178:181], v[116:119]
	v_mfma_f32_16x16x32_bf16 v[108:111], v[218:221], v[178:181], v[108:111]
	v_mfma_f32_16x16x32_bf16 v[100:103], v[210:213], v[186:189], v[100:103]
	v_mfma_f32_16x16x32_bf16 v[96:99], v[218:221], v[186:189], v[96:99]
	v_mfma_f32_16x16x32_bf16 v[84:87], v[210:213], v[194:197], v[84:87]
	v_mfma_f32_16x16x32_bf16 v[76:79], v[218:221], v[194:197], v[76:79]
	v_mfma_f32_16x16x32_bf16 v[68:71], v[210:213], v[202:205], v[68:71]
	v_mfma_f32_16x16x32_bf16 v[64:67], v[218:221], v[202:205], v[64:67]
	s_mov_b32 m0, s35
	v_lshl_add_u64 v[150:151], v[224:225], 0, s[4:5]
	s_barrier
	ds_read_b128 v[166:169], v174 offset:49152
	ds_read_b128 v[178:181], v174 offset:50176
	ds_read_b128 v[182:185], v174 offset:51200
	ds_read_b128 v[186:189], v174 offset:52224
	ds_read_b128 v[190:193], v174 offset:53248
	ds_read_b128 v[194:197], v174 offset:54272
	ds_read_b128 v[198:201], v174 offset:55296
	ds_read_b128 v[202:205], v174 offset:56320
	global_load_lds_dwordx4 v[150:151], off
	v_lshl_add_u64 v[150:151], v[226:227], 0, s[4:5]
	s_mov_b32 m0, s36
	s_nop 0
	global_load_lds_dwordx4 v[150:151], off
	s_barrier
; #define PG8_STAGE(bufoff, gbase, voff) do { _Pragma("unroll") for (int _i = 0; _i < 2; ++_i) \
;         __builtin_amdgcn_global_load_lds((const unsigned*)((const char*)(gbase) + (voff)[_i]), (LAS unsigned*)(lds + (bufoff) + ldsw + _i * 8192), 16, 0, 0); } while (0)
; #define PG8_LDA(dst, b, h) do { _Pragma("unroll") for (int m = 0; m < 4; ++m) _Pragma("unroll") for (int k = 0; k < 2; ++k) dst[m][k] = *(const LAS bf16x8*)(lds + PG8_SA(b, h) + aoff + m * 2048 + k * 1024); } while (0)
; #define PG8_LDB(dst, b, h) do { _Pragma("unroll") for (int n = 0; n < 2; ++n) _Pragma("unroll") for (int k = 0; k < 2; ++k) dst[n][k] = *(const LAS bf16x8*)(lds + PG8_SB(b, h) + boff + n * 2048 + k * 1024); } while (0)
; #define PG8_MMA(ai, bj, At, Bt) do { __builtin_amdgcn_s_setprio(1); _Pragma("unroll") for (int m = 0; m < 4; ++m) _Pragma("unroll") for (int n = 0; n < 2; ++n) _Pragma("unroll") for (int k = 0; k < 2; ++k) \
;         acc[ai][bj][m][n] = __builtin_amdgcn_mfma_f32_16x16x32_bf16(Bt[n][k], At[m][k], acc[ai][bj][m][n], 0, 0, 0); __builtin_amdgcn_s_setprio(0); } while (0)
; #define PG8_WAIT_V(n) asm volatile("s_waitcnt vmcnt(" #n ")" ::: "memory")
; #define PG8_BAR __builtin_amdgcn_s_barrier()
; template <class Epi>
; __device__ __forceinline__ void gemm_phase(LAS unsigned char* lds, const Gemm g, const StaticOrder& S, const Epi& E) {
;     ...
;             PG8_LDB(B0, 0, 0); PG8_SCHED; PG8_LDA(At, 0, 0); PG8_STAGE(PG8_SA(1, 1), a1 + hstepA, voffA);
;             PG8_WAIT_L(8); PG8_BAR; PG8_WAIT_L(0); PG8_MMA(0, 0, At, B0); PG8_BAR; PG8_SCHED;
;             PG8_LDB(B1, 0, 1); PG8_STAGE(PG8_SB(0, 0), b2, voffB);
;             PG8_BAR; PG8_WAIT_L(0); PG8_MMA(0, 1, At, B1); PG8_BAR;
;     ...
;             PG8_WAIT_V(6); PG8_BAR; PG8_MMA(1, 1, At, B1); PG8_BAR;
;             PG8_LDB(B0, 1, 0); PG8_SCHED; PG8_LDA(At, 1, 0); PG8_STAGE(PG8_SA(0, 1), a2 + hstepA, voffA);
;             PG8_WAIT_L(8); PG8_BAR; PG8_WAIT_L(0); PG8_MMA(0, 0, At, B0); PG8_BAR; PG8_SCHED;
;             PG8_LDB(B1, 1, 1); PG8_STAGE(PG8_SB(1, 0), b3, voffB);
;             PG8_BAR; PG8_WAIT_L(0); PG8_MMA(0, 1, At, B1); PG8_BAR;
;             PG8_LDA(At, 1, 1); PG8_STAGE(PG8_SA(1, 0), a3, voffA);
;             PG8_BAR; PG8_WAIT_L(0); PG8_MMA(1, 0, At, B0); PG8_BAR; PG8_SCHED;
;             PG8_STAGE(PG8_SB(1, 1), b3 + hstepB, voffB);
;             PG8_WAIT_V(6); PG8_BAR; PG8_MMA(1, 1, At, B1); PG8_BAR;
	s_waitcnt lgkmcnt(0)
	s_waitcnt lgkmcnt(0)
	v_mfma_f32_16x16x32_bf16 v[60:63], v[146:149], v[166:169], v[60:63]
	v_mfma_f32_16x16x32_bf16 v[56:59], v[158:161], v[166:169], v[56:59]
	v_mfma_f32_16x16x32_bf16 v[48:51], v[146:149], v[182:185], v[48:51]
	v_mfma_f32_16x16x32_bf16 v[40:43], v[158:161], v[182:185], v[40:43]
	v_mfma_f32_16x16x32_bf16 v[32:35], v[146:149], v[190:193], v[32:35]
	v_mfma_f32_16x16x32_bf16 v[24:27], v[158:161], v[190:193], v[24:27]
	v_mfma_f32_16x16x32_bf16 v[16:19], v[146:149], v[198:201], v[16:19]
	v_mfma_f32_16x16x32_bf16 v[8:11], v[158:161], v[198:201], v[8:11]
	v_mfma_f32_16x16x32_bf16 v[60:63], v[154:157], v[178:181], v[60:63]
	v_mfma_f32_16x16x32_bf16 v[56:59], v[162:165], v[178:181], v[56:59]
	v_mfma_f32_16x16x32_bf16 v[48:51], v[154:157], v[186:189], v[48:51]
	v_mfma_f32_16x16x32_bf16 v[40:43], v[162:165], v[186:189], v[40:43]
	v_mfma_f32_16x16x32_bf16 v[32:35], v[154:157], v[194:197], v[32:35]
	v_mfma_f32_16x16x32_bf16 v[24:27], v[162:165], v[194:197], v[24:27]
	v_mfma_f32_16x16x32_bf16 v[16:19], v[154:157], v[202:205], v[16:19]
	v_mfma_f32_16x16x32_bf16 v[8:11], v[162:165], v[202:205], v[8:11]
	s_barrier
	s_add_u32 s22, s22, 0x40080
	s_addc_u32 s23, s23, 0
	s_add_i32 s24, s24, s27
	v_lshl_add_u64 v[146:147], s[22:23], 0, v[132:133]
	s_mov_b32 m0, s24
	s_nop 0
	global_load_lds_dwordx4 v[146:147], off
	v_lshl_add_u64 v[146:147], s[22:23], 0, v[128:129]
	s_add_i32 m0, s24, 0x2000
	s_nop 0
	global_load_lds_dwordx4 v[146:147], off
	s_waitcnt vmcnt(6)
	s_barrier
	v_mfma_f32_16x16x32_bf16 v[52:55], v[206:209], v[166:169], v[52:55]
	v_mfma_f32_16x16x32_bf16 v[44:47], v[214:217], v[166:169], v[44:47]
	v_mfma_f32_16x16x32_bf16 v[36:39], v[206:209], v[182:185], v[36:39]
	v_mfma_f32_16x16x32_bf16 v[28:31], v[214:217], v[182:185], v[28:31]
	v_mfma_f32_16x16x32_bf16 v[20:23], v[206:209], v[190:193], v[20:23]
	v_mfma_f32_16x16x32_bf16 v[12:15], v[214:217], v[190:193], v[12:15]
	v_mfma_f32_16x16x32_bf16 v[4:7], v[206:209], v[198:201], v[4:7]
	v_mfma_f32_16x16x32_bf16 v[0:3], v[214:217], v[198:201], v[0:3]
	v_mfma_f32_16x16x32_bf16 v[52:55], v[210:213], v[178:181], v[52:55]
	v_mfma_f32_16x16x32_bf16 v[44:47], v[218:221], v[178:181], v[44:47]
	v_mfma_f32_16x16x32_bf16 v[36:39], v[210:213], v[186:189], v[36:39]
	v_mfma_f32_16x16x32_bf16 v[28:31], v[218:221], v[186:189], v[28:31]
	v_mfma_f32_16x16x32_bf16 v[20:23], v[210:213], v[194:197], v[20:23]
	v_mfma_f32_16x16x32_bf16 v[12:15], v[218:221], v[194:197], v[12:15]
	v_mfma_f32_16x16x32_bf16 v[4:7], v[210:213], v[202:205], v[4:7]
	v_mfma_f32_16x16x32_bf16 v[0:3], v[218:221], v[202:205], v[0:3]
	s_add_i32 s47, s47, 2
	s_add_u32 s20, s20, 0x100
	s_addc_u32 s21, s21, 0
	s_add_u32 s45, s45, 0x100
	s_addc_u32 s46, s46, 0
	s_cmp_gt_u32 s47, 13
	s_barrier
.LBB0_922:
	ds_read_b128 v[146:149], v173
	ds_read_b128 v[154:157], v173 offset:1024
	ds_read_b128 v[158:161], v173 offset:2048
	ds_read_b128 v[162:165], v173 offset:3072
	s_add_u32 s22, s20, 0xfffc0080
	s_addc_u32 s23, s21, -1
	s_cmp_eq_u32 s47, 12
	s_cselect_b32 s25, s13, s23
	s_cselect_b32 s24, s43, s22
	s_cselect_b32 s23, s11, s46
	s_cselect_b32 s22, s44, s45
	v_lshl_add_u64 v[150:151], s[20:21], 0, v[138:139]
	s_add_i32 m0, s19, 0xc000
	ds_read_b128 v[166:169], v174
	ds_read_b128 v[178:181], v174 offset:1024
	ds_read_b128 v[182:185], v174 offset:2048
	ds_read_b128 v[186:189], v174 offset:3072
	ds_read_b128 v[190:193], v174 offset:4096
	ds_read_b128 v[194:197], v174 offset:5120
	ds_read_b128 v[198:201], v174 offset:6144
	ds_read_b128 v[202:205], v174 offset:7168
	global_load_lds_dwordx4 v[150:151], off
	v_lshl_add_u64 v[150:151], s[20:21], 0, v[140:141]
	s_add_i32 m0, s19, 0xe000
	s_nop 0
	global_load_lds_dwordx4 v[150:151], off
	s_waitcnt lgkmcnt(8)
	s_barrier
	s_waitcnt lgkmcnt(0)
	s_waitcnt lgkmcnt(0)
	v_mfma_f32_16x16x32_bf16 v[124:127], v[146:149], v[166:169], v[124:127]
	v_mfma_f32_16x16x32_bf16 v[120:123], v[158:161], v[166:169], v[120:123]
	v_mfma_f32_16x16x32_bf16 v[112:115], v[146:149], v[182:185], v[112:115]
	v_mfma_f32_16x16x32_bf16 v[104:107], v[158:161], v[182:185], v[104:107]
	v_mfma_f32_16x16x32_bf16 v[92:95], v[146:149], v[190:193], v[92:95]
	v_mfma_f32_16x16x32_bf16 v[88:91], v[158:161], v[190:193], v[88:91]
	v_mfma_f32_16x16x32_bf16 v[80:83], v[146:149], v[198:201], v[80:83]
	v_mfma_f32_16x16x32_bf16 v[72:75], v[158:161], v[198:201], v[72:75]
	v_mfma_f32_16x16x32_bf16 v[124:127], v[154:157], v[178:181], v[124:127]
	v_mfma_f32_16x16x32_bf16 v[120:123], v[162:165], v[178:181], v[120:123]
	v_mfma_f32_16x16x32_bf16 v[112:115], v[154:157], v[186:189], v[112:115]
	v_mfma_f32_16x16x32_bf16 v[104:107], v[162:165], v[186:189], v[104:107]
	v_mfma_f32_16x16x32_bf16 v[92:95], v[154:157], v[194:197], v[92:95]
	v_mfma_f32_16x16x32_bf16 v[88:91], v[162:165], v[194:197], v[88:91]
	v_mfma_f32_16x16x32_bf16 v[80:83], v[154:157], v[202:205], v[80:83]
	v_mfma_f32_16x16x32_bf16 v[72:75], v[162:165], v[202:205], v[72:75]
	s_barrier
	s_add_i32 s48, s38, s27
	v_lshl_add_u64 v[150:151], s[22:23], 0, v[132:133]
	s_mov_b32 m0, s48
	ds_read_b128 v[206:209], v175
	ds_read_b128 v[210:213], v175 offset:1024
	ds_read_b128 v[214:217], v175 offset:2048
	ds_read_b128 v[218:221], v175 offset:3072
	global_load_lds_dwordx4 v[150:151], off
	v_lshl_add_u64 v[222:223], s[22:23], 0, v[128:129]
	s_add_i32 m0, s48, 0x2000
	s_nop 0
	global_load_lds_dwordx4 v[222:223], off
	s_barrier
; #define PG8_STAGE(bufoff, gbase, voff) do { _Pragma("unroll") for (int _i = 0; _i < 2; ++_i) \
;         __builtin_amdgcn_global_load_lds((const unsigned*)((const char*)(gbase) + (voff)[_i]), (LAS unsigned*)(lds + (bufoff) + ldsw + _i * 8192), 16, 0, 0); } while (0)
; #define PG8_LDA(dst, b, h) do { _Pragma("unroll") for (int m = 0; m < 4; ++m) _Pragma("unroll") for (int k = 0; k < 2; ++k) dst[m][k] = *(const LAS bf16x8*)(lds + PG8_SA(b, h) + aoff + m * 2048 + k * 1024); } while (0)
; #define PG8_LDB(dst, b, h) do { _Pragma("unroll") for (int n = 0; n < 2; ++n) _Pragma("unroll") for (int k = 0; k < 2; ++k) dst[n][k] = *(const LAS bf16x8*)(lds + PG8_SB(b, h) + boff + n * 2048 + k * 1024); } while (0)
; #define PG8_MMA(ai, bj, At, Bt) do { __builtin_amdgcn_s_setprio(1); _Pragma("unroll") for (int m = 0; m < 4; ++m) _Pragma("unroll") for (int n = 0; n < 2; ++n) _Pragma("unroll") for (int k = 0; k < 2; ++k) \
;         acc[ai][bj][m][n] = __builtin_amdgcn_mfma_f32_16x16x32_bf16(Bt[n][k], At[m][k], acc[ai][bj][m][n], 0, 0, 0); __builtin_amdgcn_s_setprio(0); } while (0)
; #define PG8_WAIT_V(n) asm volatile("s_waitcnt vmcnt(" #n ")" ::: "memory")
; #define PG8_WAIT_L(n) asm volatile("s_waitcnt lgkmcnt(" #n ")" ::: "memory")
; #define PG8_BAR __builtin_amdgcn_s_barrier()
; #define PG8_SCHED __builtin_amdgcn_sched_barrier(0)
; template <class Epi>
; __device__ __forceinline__ void gemm_phase(LAS unsigned char* lds, const Gemm g, const StaticOrder& S, const Epi& E) {
;     ...
;             PG8_LDB(B1, 0, 1); PG8_STAGE(PG8_SB(0, 0), b2, voffB);
;             PG8_BAR; PG8_WAIT_L(0); PG8_MMA(0, 1, At, B1); PG8_BAR;
;             PG8_LDA(At, 0, 1); PG8_STAGE(PG8_SA(0, 0), a2, voffA);
;             PG8_BAR; PG8_WAIT_L(0); PG8_MMA(1, 0, At, B0); PG8_BAR; PG8_SCHED;
;             PG8_STAGE(PG8_SB(0, 1), b2 + hstepB, voffB);
;             PG8_WAIT_V(6); PG8_BAR; PG8_MMA(1, 1, At, B1); PG8_BAR;
;             PG8_LDB(B0, 1, 0); PG8_SCHED; PG8_LDA(At, 1, 0); PG8_STAGE(PG8_SA(0, 1), a2 + hstepA, voffA);
;             PG8_WAIT_L(8); PG8_BAR; PG8_WAIT_L(0); PG8_MMA(0, 0, At, B0); PG8_BAR; PG8_SCHED;
;             PG8_LDB(B1, 1, 1); PG8_STAGE(PG8_SB(1, 0), b3, voffB);
;             PG8_BAR; PG8_WAIT_L(0); PG8_MMA(0, 1, At, B1); PG8_BAR;
;             PG8_LDA(At, 1, 1); PG8_STAGE(PG8_SA(1, 0), a3, voffA);
	s_waitcnt lgkmcnt(0)
	s_waitcnt lgkmcnt(0)
	v_mfma_f32_16x16x32_bf16 v[116:119], v[206:209], v[166:169], v[116:119]
	v_mfma_f32_16x16x32_bf16 v[108:111], v[214:217], v[166:169], v[108:111]
	v_mfma_f32_16x16x32_bf16 v[100:103], v[206:209], v[182:185], v[100:103]
	v_mfma_f32_16x16x32_bf16 v[96:99], v[214:217], v[182:185], v[96:99]
	v_mfma_f32_16x16x32_bf16 v[84:87], v[206:209], v[190:193], v[84:87]
	v_mfma_f32_16x16x32_bf16 v[76:79], v[214:217], v[190:193], v[76:79]
	v_mfma_f32_16x16x32_bf16 v[68:71], v[206:209], v[198:201], v[68:71]
	v_mfma_f32_16x16x32_bf16 v[64:67], v[214:217], v[198:201], v[64:67]
	v_mfma_f32_16x16x32_bf16 v[116:119], v[210:213], v[178:181], v[116:119]
	v_mfma_f32_16x16x32_bf16 v[108:111], v[218:221], v[178:181], v[108:111]
	v_mfma_f32_16x16x32_bf16 v[100:103], v[210:213], v[186:189], v[100:103]
	v_mfma_f32_16x16x32_bf16 v[96:99], v[218:221], v[186:189], v[96:99]
	v_mfma_f32_16x16x32_bf16 v[84:87], v[210:213], v[194:197], v[84:87]
	v_mfma_f32_16x16x32_bf16 v[76:79], v[218:221], v[194:197], v[76:79]
	v_mfma_f32_16x16x32_bf16 v[68:71], v[210:213], v[202:205], v[68:71]
	v_mfma_f32_16x16x32_bf16 v[64:67], v[218:221], v[202:205], v[64:67]
	s_mov_b32 m0, s19
	v_lshl_add_u64 v[224:225], s[24:25], 0, v[134:135]
	s_barrier
	ds_read_b128 v[166:169], v174 offset:16384
	ds_read_b128 v[178:181], v174 offset:17408
	ds_read_b128 v[182:185], v174 offset:18432
	ds_read_b128 v[186:189], v174 offset:19456
	ds_read_b128 v[190:193], v174 offset:20480
	ds_read_b128 v[194:197], v174 offset:21504
	ds_read_b128 v[198:201], v174 offset:22528
	ds_read_b128 v[202:205], v174 offset:23552
	global_load_lds_dwordx4 v[224:225], off
	v_lshl_add_u64 v[226:227], s[24:25], 0, v[130:131]
	s_mov_b32 m0, s30
	s_nop 0
	global_load_lds_dwordx4 v[226:227], off
	s_barrier
	s_waitcnt lgkmcnt(0)
	s_waitcnt lgkmcnt(0)
	v_mfma_f32_16x16x32_bf16 v[60:63], v[146:149], v[166:169], v[60:63]
	v_mfma_f32_16x16x32_bf16 v[56:59], v[158:161], v[166:169], v[56:59]
	v_mfma_f32_16x16x32_bf16 v[48:51], v[146:149], v[182:185], v[48:51]
	v_mfma_f32_16x16x32_bf16 v[40:43], v[158:161], v[182:185], v[40:43]
	v_mfma_f32_16x16x32_bf16 v[32:35], v[146:149], v[190:193], v[32:35]
	v_mfma_f32_16x16x32_bf16 v[24:27], v[158:161], v[190:193], v[24:27]
	v_mfma_f32_16x16x32_bf16 v[16:19], v[146:149], v[198:201], v[16:19]
	v_mfma_f32_16x16x32_bf16 v[8:11], v[158:161], v[198:201], v[8:11]
	v_mfma_f32_16x16x32_bf16 v[60:63], v[154:157], v[178:181], v[60:63]
	v_mfma_f32_16x16x32_bf16 v[56:59], v[162:165], v[178:181], v[56:59]
	v_mfma_f32_16x16x32_bf16 v[48:51], v[154:157], v[186:189], v[48:51]
	v_mfma_f32_16x16x32_bf16 v[40:43], v[162:165], v[186:189], v[40:43]
	v_mfma_f32_16x16x32_bf16 v[32:35], v[154:157], v[194:197], v[32:35]
	v_mfma_f32_16x16x32_bf16 v[24:27], v[162:165], v[194:197], v[24:27]
	v_mfma_f32_16x16x32_bf16 v[16:19], v[154:157], v[202:205], v[16:19]
	v_mfma_f32_16x16x32_bf16 v[8:11], v[162:165], v[202:205], v[8:11]
	s_barrier
	s_add_u32 s48, s22, 0x40000
	s_addc_u32 s49, s23, 0
	s_add_i32 s50, s39, s27
	v_lshl_add_u64 v[146:147], s[48:49], 0, v[132:133]
	s_mov_b32 m0, s50
	s_nop 0
	global_load_lds_dwordx4 v[146:147], off
	v_lshl_add_u64 v[146:147], s[48:49], 0, v[128:129]
	s_add_i32 m0, s50, 0x2000
	s_nop 0
	global_load_lds_dwordx4 v[146:147], off
	s_waitcnt vmcnt(6)
	s_barrier
	v_mfma_f32_16x16x32_bf16 v[52:55], v[206:209], v[166:169], v[52:55]
	v_mfma_f32_16x16x32_bf16 v[44:47], v[214:217], v[166:169], v[44:47]
	v_mfma_f32_16x16x32_bf16 v[36:39], v[206:209], v[182:185], v[36:39]
	v_mfma_f32_16x16x32_bf16 v[28:31], v[214:217], v[182:185], v[28:31]
	v_mfma_f32_16x16x32_bf16 v[20:23], v[206:209], v[190:193], v[20:23]
	v_mfma_f32_16x16x32_bf16 v[12:15], v[214:217], v[190:193], v[12:15]
	v_mfma_f32_16x16x32_bf16 v[4:7], v[206:209], v[198:201], v[4:7]
	v_mfma_f32_16x16x32_bf16 v[0:3], v[214:217], v[198:201], v[0:3]
	v_mfma_f32_16x16x32_bf16 v[52:55], v[210:213], v[178:181], v[52:55]
	v_mfma_f32_16x16x32_bf16 v[44:47], v[218:221], v[178:181], v[44:47]
	v_mfma_f32_16x16x32_bf16 v[36:39], v[210:213], v[186:189], v[36:39]
	v_mfma_f32_16x16x32_bf16 v[28:31], v[218:221], v[186:189], v[28:31]
	v_mfma_f32_16x16x32_bf16 v[20:23], v[210:213], v[194:197], v[20:23]
	v_mfma_f32_16x16x32_bf16 v[12:15], v[218:221], v[194:197], v[12:15]
	v_mfma_f32_16x16x32_bf16 v[4:7], v[210:213], v[202:205], v[4:7]
	v_mfma_f32_16x16x32_bf16 v[0:3], v[218:221], v[202:205], v[0:3]
	s_add_i32 s48, 0, 0x18000
	v_add_u32_e32 v162, s48, v171
	s_barrier
	ds_read_b128 v[146:149], v162
	ds_read_b128 v[154:157], v162 offset:1024
	ds_read_b128 v[158:161], v162 offset:2048
	ds_read_b128 v[162:165], v162 offset:3072
	s_add_u32 s24, s24, 0x40000
	s_addc_u32 s25, s25, 0
	s_mov_b32 m0, s31
	v_lshl_add_u64 v[206:207], s[24:25], 0, v[134:135]
	ds_read_b128 v[166:169], v174 offset:32768
	ds_read_b128 v[178:181], v174 offset:33792
	ds_read_b128 v[182:185], v174 offset:34816
	ds_read_b128 v[186:189], v174 offset:35840
	ds_read_b128 v[190:193], v174 offset:36864
	ds_read_b128 v[194:197], v174 offset:37888
	ds_read_b128 v[198:201], v174 offset:38912
	ds_read_b128 v[202:205], v174 offset:39936
	global_load_lds_dwordx4 v[206:207], off
	v_lshl_add_u64 v[206:207], s[24:25], 0, v[130:131]
	s_mov_b32 m0, s33
	s_nop 0
	global_load_lds_dwordx4 v[206:207], off
	s_waitcnt lgkmcnt(8)
	s_barrier
; #define PG8_STAGE(bufoff, gbase, voff) do { _Pragma("unroll") for (int _i = 0; _i < 2; ++_i) \
;         __builtin_amdgcn_global_load_lds((const unsigned*)((const char*)(gbase) + (voff)[_i]), (LAS unsigned*)(lds + (bufoff) + ldsw + _i * 8192), 16, 0, 0); } while (0)
; #define PG8_LDA(dst, b, h) do { _Pragma("unroll") for (int m = 0; m < 4; ++m) _Pragma("unroll") for (int k = 0; k < 2; ++k) dst[m][k] = *(const LAS bf16x8*)(lds + PG8_SA(b, h) + aoff + m * 2048 + k * 1024); } while (0)
; #define PG8_LDB(dst, b, h) do { _Pragma("unroll") for (int n = 0; n < 2; ++n) _Pragma("unroll") for (int k = 0; k < 2; ++k) dst[n][k] = *(const LAS bf16x8*)(lds + PG8_SB(b, h) + boff + n * 2048 + k * 1024); } while (0)
; #define PG8_MMA(ai, bj, At, Bt) do { __builtin_amdgcn_s_setprio(1); _Pragma("unroll") for (int m = 0; m < 4; ++m) _Pragma("unroll") for (int n = 0; n < 2; ++n) _Pragma("unroll") for (int k = 0; k < 2; ++k) \
;         acc[ai][bj][m][n] = __builtin_amdgcn_mfma_f32_16x16x32_bf16(Bt[n][k], At[m][k], acc[ai][bj][m][n], 0, 0, 0); __builtin_amdgcn_s_setprio(0); } while (0)
; #define PG8_WAIT_V(n) asm volatile("s_waitcnt vmcnt(" #n ")" ::: "memory")
; #define PG8_WAIT_L(n) asm volatile("s_waitcnt lgkmcnt(" #n ")" ::: "memory")
; #define PG8_BAR __builtin_amdgcn_s_barrier()
; #define PG8_SCHED __builtin_amdgcn_sched_barrier(0)
; template <class Epi>
; __device__ __forceinline__ void gemm_phase(LAS unsigned char* lds, const Gemm g, const StaticOrder& S, const Epi& E) {
;     ...
;             PG8_WAIT_L(8); PG8_BAR; PG8_WAIT_L(0); PG8_MMA(0, 0, At, B0); PG8_BAR; PG8_SCHED;
;             PG8_LDB(B1, 1, 1); PG8_STAGE(PG8_SB(1, 0), b3, voffB);
;             PG8_BAR; PG8_WAIT_L(0); PG8_MMA(0, 1, At, B1); PG8_BAR;
;             PG8_LDA(At, 1, 1); PG8_STAGE(PG8_SA(1, 0), a3, voffA);
;             PG8_BAR; PG8_WAIT_L(0); PG8_MMA(1, 0, At, B0); PG8_BAR; PG8_SCHED;
;             PG8_STAGE(PG8_SB(1, 1), b3 + hstepB, voffB);
;             PG8_WAIT_V(6); PG8_BAR; PG8_MMA(1, 1, At, B1); PG8_BAR;
	s_waitcnt lgkmcnt(0)
	s_waitcnt lgkmcnt(0)
	v_mfma_f32_16x16x32_bf16 v[124:127], v[146:149], v[166:169], v[124:127]
	v_mfma_f32_16x16x32_bf16 v[120:123], v[158:161], v[166:169], v[120:123]
	v_mfma_f32_16x16x32_bf16 v[112:115], v[146:149], v[182:185], v[112:115]
	v_mfma_f32_16x16x32_bf16 v[104:107], v[158:161], v[182:185], v[104:107]
	v_mfma_f32_16x16x32_bf16 v[92:95], v[146:149], v[190:193], v[92:95]
	v_mfma_f32_16x16x32_bf16 v[88:91], v[158:161], v[190:193], v[88:91]
	v_mfma_f32_16x16x32_bf16 v[80:83], v[146:149], v[198:201], v[80:83]
	v_mfma_f32_16x16x32_bf16 v[72:75], v[158:161], v[198:201], v[72:75]
	v_mfma_f32_16x16x32_bf16 v[124:127], v[154:157], v[178:181], v[124:127]
	v_mfma_f32_16x16x32_bf16 v[120:123], v[162:165], v[178:181], v[120:123]
	v_mfma_f32_16x16x32_bf16 v[112:115], v[154:157], v[186:189], v[112:115]
	v_mfma_f32_16x16x32_bf16 v[104:107], v[162:165], v[186:189], v[104:107]
	v_mfma_f32_16x16x32_bf16 v[92:95], v[154:157], v[194:197], v[92:95]
	v_mfma_f32_16x16x32_bf16 v[88:91], v[162:165], v[194:197], v[88:91]
	v_mfma_f32_16x16x32_bf16 v[80:83], v[154:157], v[202:205], v[80:83]
	v_mfma_f32_16x16x32_bf16 v[72:75], v[162:165], v[202:205], v[72:75]
	s_barrier
	s_add_i32 s24, 0, 0x1c000
	s_add_i32 s25, s48, s27
	v_add_u32_e32 v177, s24, v171
	v_lshl_add_u64 v[150:151], v[150:151], 0, s[4:5]
	s_mov_b32 m0, s25
	ds_read_b128 v[206:209], v177
	ds_read_b128 v[210:213], v177 offset:1024
	ds_read_b128 v[214:217], v177 offset:2048
	ds_read_b128 v[218:221], v177 offset:3072
	global_load_lds_dwordx4 v[150:151], off
	v_lshl_add_u64 v[150:151], v[222:223], 0, s[4:5]
	s_add_i32 m0, s25, 0x2000
	s_nop 0
	global_load_lds_dwordx4 v[150:151], off
	s_barrier
	s_waitcnt lgkmcnt(0)
	s_waitcnt lgkmcnt(0)
	v_mfma_f32_16x16x32_bf16 v[116:119], v[206:209], v[166:169], v[116:119]
	v_mfma_f32_16x16x32_bf16 v[108:111], v[214:217], v[166:169], v[108:111]
	v_mfma_f32_16x16x32_bf16 v[100:103], v[206:209], v[182:185], v[100:103]
	v_mfma_f32_16x16x32_bf16 v[96:99], v[214:217], v[182:185], v[96:99]
	v_mfma_f32_16x16x32_bf16 v[84:87], v[206:209], v[190:193], v[84:87]
	v_mfma_f32_16x16x32_bf16 v[76:79], v[214:217], v[190:193], v[76:79]
	v_mfma_f32_16x16x32_bf16 v[68:71], v[206:209], v[198:201], v[68:71]
	v_mfma_f32_16x16x32_bf16 v[64:67], v[214:217], v[198:201], v[64:67]
	v_mfma_f32_16x16x32_bf16 v[116:119], v[210:213], v[178:181], v[116:119]
	v_mfma_f32_16x16x32_bf16 v[108:111], v[218:221], v[178:181], v[108:111]
	v_mfma_f32_16x16x32_bf16 v[100:103], v[210:213], v[186:189], v[100:103]
	v_mfma_f32_16x16x32_bf16 v[96:99], v[218:221], v[186:189], v[96:99]
	v_mfma_f32_16x16x32_bf16 v[84:87], v[210:213], v[194:197], v[84:87]
	v_mfma_f32_16x16x32_bf16 v[76:79], v[218:221], v[194:197], v[76:79]
	v_mfma_f32_16x16x32_bf16 v[68:71], v[210:213], v[202:205], v[68:71]
	v_mfma_f32_16x16x32_bf16 v[64:67], v[218:221], v[202:205], v[64:67]
	s_mov_b32 m0, s35
	v_lshl_add_u64 v[150:151], v[224:225], 0, s[4:5]
	s_barrier
	ds_read_b128 v[166:169], v174 offset:49152
	ds_read_b128 v[178:181], v174 offset:50176
	ds_read_b128 v[182:185], v174 offset:51200
	ds_read_b128 v[186:189], v174 offset:52224
	ds_read_b128 v[190:193], v174 offset:53248
	ds_read_b128 v[194:197], v174 offset:54272
	ds_read_b128 v[198:201], v174 offset:55296
	ds_read_b128 v[202:205], v174 offset:56320
	global_load_lds_dwordx4 v[150:151], off
	v_lshl_add_u64 v[150:151], v[226:227], 0, s[4:5]
	s_mov_b32 m0, s36
	s_nop 0
	global_load_lds_dwordx4 v[150:151], off
	s_barrier
	s_waitcnt lgkmcnt(0)
	s_waitcnt lgkmcnt(0)
	v_mfma_f32_16x16x32_bf16 v[60:63], v[146:149], v[166:169], v[60:63]
	v_mfma_f32_16x16x32_bf16 v[56:59], v[158:161], v[166:169], v[56:59]
	v_mfma_f32_16x16x32_bf16 v[48:51], v[146:149], v[182:185], v[48:51]
	v_mfma_f32_16x16x32_bf16 v[40:43], v[158:161], v[182:185], v[40:43]
	v_mfma_f32_16x16x32_bf16 v[32:35], v[146:149], v[190:193], v[32:35]
	v_mfma_f32_16x16x32_bf16 v[24:27], v[158:161], v[190:193], v[24:27]
	v_mfma_f32_16x16x32_bf16 v[16:19], v[146:149], v[198:201], v[16:19]
	v_mfma_f32_16x16x32_bf16 v[8:11], v[158:161], v[198:201], v[8:11]
	v_mfma_f32_16x16x32_bf16 v[60:63], v[154:157], v[178:181], v[60:63]
	v_mfma_f32_16x16x32_bf16 v[56:59], v[162:165], v[178:181], v[56:59]
	v_mfma_f32_16x16x32_bf16 v[48:51], v[154:157], v[186:189], v[48:51]
	v_mfma_f32_16x16x32_bf16 v[40:43], v[162:165], v[186:189], v[40:43]
	v_mfma_f32_16x16x32_bf16 v[32:35], v[154:157], v[194:197], v[32:35]
	v_mfma_f32_16x16x32_bf16 v[24:27], v[162:165], v[194:197], v[24:27]
	v_mfma_f32_16x16x32_bf16 v[16:19], v[154:157], v[202:205], v[16:19]
	v_mfma_f32_16x16x32_bf16 v[8:11], v[162:165], v[202:205], v[8:11]
	s_barrier
	s_add_u32 s22, s22, 0x40080
	s_addc_u32 s23, s23, 0
	s_add_i32 s24, s24, s27
	v_lshl_add_u64 v[146:147], s[22:23], 0, v[132:133]
	s_mov_b32 m0, s24
	s_nop 0
	global_load_lds_dwordx4 v[146:147], off
	v_lshl_add_u64 v[146:147], s[22:23], 0, v[128:129]
	s_add_i32 m0, s24, 0x2000
	s_nop 0
	global_load_lds_dwordx4 v[146:147], off
	s_waitcnt vmcnt(6)
	s_barrier
	v_mfma_f32_16x16x32_bf16 v[52:55], v[206:209], v[166:169], v[52:55]
	v_mfma_f32_16x16x32_bf16 v[44:47], v[214:217], v[166:169], v[44:47]
	v_mfma_f32_16x16x32_bf16 v[36:39], v[206:209], v[182:185], v[36:39]
	v_mfma_f32_16x16x32_bf16 v[28:31], v[214:217], v[182:185], v[28:31]
	v_mfma_f32_16x16x32_bf16 v[20:23], v[206:209], v[190:193], v[20:23]
	v_mfma_f32_16x16x32_bf16 v[12:15], v[214:217], v[190:193], v[12:15]
	v_mfma_f32_16x16x32_bf16 v[4:7], v[206:209], v[198:201], v[4:7]
	v_mfma_f32_16x16x32_bf16 v[0:3], v[214:217], v[198:201], v[0:3]
	v_mfma_f32_16x16x32_bf16 v[52:55], v[210:213], v[178:181], v[52:55]
	v_mfma_f32_16x16x32_bf16 v[44:47], v[218:221], v[178:181], v[44:47]
	v_mfma_f32_16x16x32_bf16 v[36:39], v[210:213], v[186:189], v[36:39]
	v_mfma_f32_16x16x32_bf16 v[28:31], v[218:221], v[186:189], v[28:31]
	v_mfma_f32_16x16x32_bf16 v[20:23], v[210:213], v[194:197], v[20:23]
	v_mfma_f32_16x16x32_bf16 v[12:15], v[218:221], v[194:197], v[12:15]
	v_mfma_f32_16x16x32_bf16 v[4:7], v[210:213], v[202:205], v[4:7]
	v_mfma_f32_16x16x32_bf16 v[0:3], v[218:221], v[202:205], v[0:3]
	s_add_i32 s47, s47, 2
	s_add_u32 s20, s20, 0x100
	s_addc_u32 s21, s21, 0
	s_add_u32 s45, s45, 0x100
	s_addc_u32 s46, s46, 0
	s_cmp_gt_u32 s47, 13
	s_barrier
; __device__ __forceinline__ unsigned pk2(float lo, float hi) { const f32x2 v = (f32x2){lo, hi}; const bf16x2_t b = __builtin_convertvector(v, bf16x2_t); return __builtin_bit_cast(unsigned, b); }
;     __device__ __forceinline__ void operator()(const f32x4 (&acc)[2][2][4][2], const Unit& u, int wr, int wc, int fr, int fq, const float (&)[8]) const {
;     ...
;         const int col0 = u.pn * BM + wc * 32 + 8 * fq;
; #pragma unroll
;         for (int ai = 0; ai < 2; ++ai)
; #pragma unroll
;             for (int m = 0; m < 4; ++m) { const int row = row0 + ai * HALF + m * 16; const float rs = rsqrtf(ep[ai * 4 + m] * (1.0f / 1024.0f) + EPS);
;                 u16* rowp = O + (size_t)row * ldc + col0;
; #pragma unroll
;                 for (int bj = 0; bj < 2; ++bj) { f32x4 v0 = acc[ai][bj][m][0] * rs, v1 = acc[ai][bj][m][1] * rs;
;                     if (ACT == 1) {
; #pragma unroll
;                         for (int j = 0; j < 4; ++j) { const float a0 = fmaxf(v0[j], 0.f), a1 = fmaxf(v1[j], 0.f); v0[j] = a0 * a0; v1[j] = a1 * a1; } }
;                     u32x4 w; w.x = pk2(v0[0], v0[1]); w.y = pk2(v0[2], v0[3]); w.z = pk2(v1[0], v1[1]); w.w = pk2(v1[2], v1[3]);
;                     *(u32x4*)(rowp + bj * HALF) = w; } }
	s_cbranch_scc0 .LBB0_922
	s_bfe_u32 vcc_lo, s18, 0x20003
	s_lshl_b32 vcc_lo, vcc_lo, 10
	s_add_i32 vcc_lo, vcc_lo, 0x20010
	v_lshl_add_u32 v236, v170, 2, vcc_lo
	ds_read_b32 v228, v236
	ds_read_b32 v229, v236 offset:64
	ds_read_b32 v230, v236 offset:128
	ds_read_b32 v231, v236 offset:192
	ds_read_b32 v232, v236 offset:512
	ds_read_b32 v233, v236 offset:576
	ds_read_b32 v234, v236 offset:640
	ds_read_b32 v235, v236 offset:704
	s_waitcnt lgkmcnt(0)
	v_lshl_add_u32 v154, s18, 8, v170
	v_or_b32_e32 v206, 16, v154
	v_or_b32_e32 v168, 32, v154
	v_or_b32_e32 v162, 48, v154
	v_add_u32_e32 v160, 0x80, v154
	v_add_u32_e32 v156, 0x90, v154
	v_add_u32_e32 v150, 0xa0, v154
	v_add_u32_e32 v146, 0xb0, v154
	v_lshl_or_b32 v208, s42, 8, v172
	v_mov_b64_e32 v[148:149], s[96:97]
	v_ashrrev_i32_e32 v209, 31, v208
	v_mad_i64_i32 v[210:211], s[20:21], v154, s40, v[148:149]
	s_nop 0
	v_lshlrev_b64 v[154:155], 1, v[208:209]
	v_lshl_add_u64 v[208:209], v[210:211], 0, v[154:155]
	s_mov_b32 s42, s10
	s_mov_b32 s18, s12
	s_mov_b64 s[22:23], s[16:17]
	s_waitcnt vmcnt(8)
	s_waitcnt lgkmcnt(0)
	s_waitcnt lgkmcnt(0)
	v_mov_b32_e32 v178, v228
	v_pk_mul_f32 v[126:127], v[126:127], v[178:179] op_sel_hi:[1,0]
	v_pk_mul_f32 v[124:125], v[124:125], v[178:179] op_sel_hi:[1,0]
	v_pk_mul_f32 v[190:191], v[122:123], v[178:179] op_sel_hi:[1,0]
	v_pk_mul_f32 v[122:123], v[120:121], v[178:179] op_sel_hi:[1,0]
	v_cvt_pk_bf16_f32 v120, v124, v125
	v_cvt_pk_bf16_f32 v121, v126, v127
	v_cvt_pk_bf16_f32 v122, v122, v123
	v_cvt_pk_bf16_f32 v123, v190, v191
	v_pk_mul_f32 v[116:117], v[116:117], v[178:179] op_sel_hi:[1,0]
	global_store_dwordx4 v[208:209], v[120:123], off
	s_nop 0
	v_pk_mul_f32 v[118:119], v[118:119], v[178:179] op_sel_hi:[1,0]
	v_pk_mul_f32 v[120:121], v[110:111], v[178:179] op_sel_hi:[1,0]
	v_pk_mul_f32 v[110:111], v[108:109], v[178:179] op_sel_hi:[1,0]
	v_cvt_pk_bf16_f32 v108, v116, v117
	v_cvt_pk_bf16_f32 v109, v118, v119
	v_cvt_pk_bf16_f32 v110, v110, v111
	v_cvt_pk_bf16_f32 v111, v120, v121
	global_store_dwordx4 v[208:209], v[108:111], off offset:256
	s_nop 1
	v_mov_b32_e32 v108, v229
	v_mad_i64_i32 v[110:111], s[20:21], v206, s40, v[148:149]
	v_pk_mul_f32 v[114:115], v[114:115], v[108:109] op_sel_hi:[1,0]
	v_pk_mul_f32 v[112:113], v[112:113], v[108:109] op_sel_hi:[1,0]
	v_pk_mul_f32 v[116:117], v[106:107], v[108:109] op_sel_hi:[1,0]
	v_pk_mul_f32 v[106:107], v[104:105], v[108:109] op_sel_hi:[1,0]
	v_lshl_add_u64 v[110:111], v[110:111], 0, v[154:155]
	v_cvt_pk_bf16_f32 v104, v112, v113
	v_cvt_pk_bf16_f32 v105, v114, v115
	v_cvt_pk_bf16_f32 v106, v106, v107
	v_cvt_pk_bf16_f32 v107, v116, v117
	global_store_dwordx4 v[110:111], v[104:107], off
	v_pk_mul_f32 v[100:101], v[100:101], v[108:109] op_sel_hi:[1,0]
	v_pk_mul_f32 v[112:113], v[98:99], v[108:109] op_sel_hi:[1,0]
	v_pk_mul_f32 v[98:99], v[96:97], v[108:109] op_sel_hi:[1,0]
	v_cvt_pk_bf16_f32 v96, v100, v101
	v_pk_mul_f32 v[102:103], v[102:103], v[108:109] op_sel_hi:[1,0]
	v_cvt_pk_bf16_f32 v98, v98, v99
	s_waitcnt lgkmcnt(0)
	v_cvt_pk_bf16_f32 v97, v102, v103
	v_cvt_pk_bf16_f32 v99, v112, v113
	global_store_dwordx4 v[110:111], v[96:99], off offset:256
	s_nop 0
	s_waitcnt lgkmcnt(0)
	v_mad_i64_i32 v[98:99], s[20:21], v168, s40, v[148:149]
	v_lshl_add_u64 v[98:99], v[98:99], 0, v[154:155]
	v_mov_b32_e32 v100, v230
	v_pk_mul_f32 v[94:95], v[94:95], v[100:101] op_sel_hi:[1,0]
	v_pk_mul_f32 v[92:93], v[92:93], v[100:101] op_sel_hi:[1,0]
	v_pk_mul_f32 v[102:103], v[90:91], v[100:101] op_sel_hi:[1,0]
	v_pk_mul_f32 v[90:91], v[88:89], v[100:101] op_sel_hi:[1,0]
	v_cvt_pk_bf16_f32 v88, v92, v93
	v_cvt_pk_bf16_f32 v89, v94, v95
	v_cvt_pk_bf16_f32 v90, v90, v91
	v_cvt_pk_bf16_f32 v91, v102, v103
	v_pk_mul_f32 v[84:85], v[84:85], v[100:101] op_sel_hi:[1,0]
	global_store_dwordx4 v[98:99], v[88:91], off
	s_nop 0
	v_pk_mul_f32 v[86:87], v[86:87], v[100:101] op_sel_hi:[1,0]
	v_pk_mul_f32 v[88:89], v[78:79], v[100:101] op_sel_hi:[1,0]
	v_pk_mul_f32 v[78:79], v[76:77], v[100:101] op_sel_hi:[1,0]
	v_cvt_pk_bf16_f32 v76, v84, v85
	v_cvt_pk_bf16_f32 v77, v86, v87
	v_cvt_pk_bf16_f32 v78, v78, v79
	v_cvt_pk_bf16_f32 v79, v88, v89
	global_store_dwordx4 v[98:99], v[76:79], off offset:256
	s_nop 1
	v_mov_b32_e32 v76, v231
	v_mad_i64_i32 v[78:79], s[20:21], v162, s40, v[148:149]
	v_pk_mul_f32 v[82:83], v[82:83], v[76:77] op_sel_hi:[1,0]
	v_pk_mul_f32 v[80:81], v[80:81], v[76:77] op_sel_hi:[1,0]
	v_pk_mul_f32 v[84:85], v[74:75], v[76:77] op_sel_hi:[1,0]
	v_pk_mul_f32 v[74:75], v[72:73], v[76:77] op_sel_hi:[1,0]
	v_lshl_add_u64 v[78:79], v[78:79], 0, v[154:155]
	v_cvt_pk_bf16_f32 v72, v80, v81
	v_cvt_pk_bf16_f32 v73, v82, v83
	v_cvt_pk_bf16_f32 v74, v74, v75
	v_cvt_pk_bf16_f32 v75, v84, v85
	global_store_dwordx4 v[78:79], v[72:75], off
	v_pk_mul_f32 v[68:69], v[68:69], v[76:77] op_sel_hi:[1,0]
	v_pk_mul_f32 v[80:81], v[66:67], v[76:77] op_sel_hi:[1,0]
	v_pk_mul_f32 v[66:67], v[64:65], v[76:77] op_sel_hi:[1,0]
	v_cvt_pk_bf16_f32 v64, v68, v69
	v_pk_mul_f32 v[70:71], v[70:71], v[76:77] op_sel_hi:[1,0]
	v_cvt_pk_bf16_f32 v66, v66, v67
	s_waitcnt lgkmcnt(0)
; __device__ __forceinline__ unsigned pk2(float lo, float hi) { const f32x2 v = (f32x2){lo, hi}; const bf16x2_t b = __builtin_convertvector(v, bf16x2_t); return __builtin_bit_cast(unsigned, b); }
; #define PG8_WAIT_V(n) asm volatile("s_waitcnt vmcnt(" #n ")" ::: "memory")
; #define PG8_BAR __builtin_amdgcn_s_barrier()
;     __device__ __forceinline__ void operator()(const f32x4 (&acc)[2][2][4][2], const Unit& u, int wr, int wc, int fr, int fq, const float (&)[8]) const {
;     ...
;             for (int m = 0; m < 4; ++m) { const int row = row0 + ai * HALF + m * 16; const float rs = rsqrtf(ep[ai * 4 + m] * (1.0f / 1024.0f) + EPS);
;                 u16* rowp = O + (size_t)row * ldc + col0;
; #pragma unroll
;                 for (int bj = 0; bj < 2; ++bj) { f32x4 v0 = acc[ai][bj][m][0] * rs, v1 = acc[ai][bj][m][1] * rs;
;                     if (ACT == 1) {
; #pragma unroll
;                         for (int j = 0; j < 4; ++j) { const float a0 = fmaxf(v0[j], 0.f), a1 = fmaxf(v1[j], 0.f); v0[j] = a0 * a0; v1[j] = a1 * a1; } }
;                     u32x4 w; w.x = pk2(v0[0], v0[1]); w.y = pk2(v0[2], v0[3]); w.z = pk2(v1[0], v1[1]); w.w = pk2(v1[2], v1[3]);
;                     *(u32x4*)(rowp + bj * HALF) = w; } }
; template <class Epi>
; __device__ __forceinline__ void gemm_phase(LAS unsigned char* lds, const Gemm g, const StaticOrder& S, const Epi& E) {
;     ...
;         E(acc, cur, wr, wc, fr, fq, epre);
;         if (!has_next) break;
; #pragma unroll
;         for (int a = 0; a < 2; ++a)
; #pragma unroll
;             for (int b = 0; b < 2; ++b)
; #pragma unroll
;                 for (int m = 0; m < 4; ++m)
; #pragma unroll
;                     for (int n = 0; n < 2; ++n) acc[a][b][m][n] = (f32x4){0.f, 0.f, 0.f, 0.f};
;         cur = nxt; cA = nA; cB = nB; ++ui;
;     }
;     PG8_WAIT_V(0);
;     if (wr == 0) PG8_BAR;
;     PG8_BAR;
	v_cvt_pk_bf16_f32 v65, v70, v71
	v_cvt_pk_bf16_f32 v67, v80, v81
	global_store_dwordx4 v[78:79], v[64:67], off offset:256
	s_waitcnt lgkmcnt(0)
	s_nop 0
	s_nop 0
	s_nop 0
	s_nop 1
	v_mad_i64_i32 v[66:67], s[20:21], v160, s40, v[148:149]
	v_lshl_add_u64 v[66:67], v[66:67], 0, v[154:155]
	v_mov_b32_e32 v68, v232
	v_pk_mul_f32 v[62:63], v[62:63], v[68:69] op_sel_hi:[1,0]
	v_pk_mul_f32 v[60:61], v[60:61], v[68:69] op_sel_hi:[1,0]
	v_pk_mul_f32 v[70:71], v[58:59], v[68:69] op_sel_hi:[1,0]
	v_pk_mul_f32 v[58:59], v[56:57], v[68:69] op_sel_hi:[1,0]
	v_cvt_pk_bf16_f32 v56, v60, v61
	v_cvt_pk_bf16_f32 v57, v62, v63
	v_cvt_pk_bf16_f32 v58, v58, v59
	v_cvt_pk_bf16_f32 v59, v70, v71
	v_pk_mul_f32 v[52:53], v[52:53], v[68:69] op_sel_hi:[1,0]
	global_store_dwordx4 v[66:67], v[56:59], off
	s_nop 0
	v_pk_mul_f32 v[54:55], v[54:55], v[68:69] op_sel_hi:[1,0]
	v_pk_mul_f32 v[56:57], v[46:47], v[68:69] op_sel_hi:[1,0]
	v_pk_mul_f32 v[46:47], v[44:45], v[68:69] op_sel_hi:[1,0]
	v_cvt_pk_bf16_f32 v44, v52, v53
	v_cvt_pk_bf16_f32 v45, v54, v55
	v_cvt_pk_bf16_f32 v46, v46, v47
	v_cvt_pk_bf16_f32 v47, v56, v57
	global_store_dwordx4 v[66:67], v[44:47], off offset:256
	s_nop 1
	v_mov_b32_e32 v44, v233
	v_mad_i64_i32 v[46:47], s[20:21], v156, s40, v[148:149]
	v_pk_mul_f32 v[50:51], v[50:51], v[44:45] op_sel_hi:[1,0]
	v_pk_mul_f32 v[48:49], v[48:49], v[44:45] op_sel_hi:[1,0]
	v_pk_mul_f32 v[52:53], v[42:43], v[44:45] op_sel_hi:[1,0]
	v_pk_mul_f32 v[42:43], v[40:41], v[44:45] op_sel_hi:[1,0]
	v_lshl_add_u64 v[46:47], v[46:47], 0, v[154:155]
	v_cvt_pk_bf16_f32 v40, v48, v49
	v_cvt_pk_bf16_f32 v41, v50, v51
	v_cvt_pk_bf16_f32 v42, v42, v43
	v_cvt_pk_bf16_f32 v43, v52, v53
	global_store_dwordx4 v[46:47], v[40:43], off
	v_pk_mul_f32 v[36:37], v[36:37], v[44:45] op_sel_hi:[1,0]
	v_pk_mul_f32 v[48:49], v[30:31], v[44:45] op_sel_hi:[1,0]
	v_pk_mul_f32 v[30:31], v[28:29], v[44:45] op_sel_hi:[1,0]
	v_cvt_pk_bf16_f32 v28, v36, v37
	v_pk_mul_f32 v[38:39], v[38:39], v[44:45] op_sel_hi:[1,0]
	v_cvt_pk_bf16_f32 v30, v30, v31
	s_waitcnt lgkmcnt(0)
	v_cvt_pk_bf16_f32 v29, v38, v39
	v_cvt_pk_bf16_f32 v31, v48, v49
	global_store_dwordx4 v[46:47], v[28:31], off offset:256
	s_waitcnt lgkmcnt(0)
	s_nop 0
	s_nop 0
	s_nop 0
	s_nop 1
	v_mad_i64_i32 v[30:31], s[20:21], v150, s40, v[148:149]
	v_lshl_add_u64 v[30:31], v[30:31], 0, v[154:155]
	v_mov_b32_e32 v36, v234
	v_pk_mul_f32 v[34:35], v[34:35], v[36:37] op_sel_hi:[1,0]
	v_pk_mul_f32 v[32:33], v[32:33], v[36:37] op_sel_hi:[1,0]
	v_pk_mul_f32 v[38:39], v[26:27], v[36:37] op_sel_hi:[1,0]
	v_pk_mul_f32 v[26:27], v[24:25], v[36:37] op_sel_hi:[1,0]
	v_cvt_pk_bf16_f32 v24, v32, v33
	v_cvt_pk_bf16_f32 v25, v34, v35
	v_cvt_pk_bf16_f32 v26, v26, v27
	v_cvt_pk_bf16_f32 v27, v38, v39
	v_pk_mul_f32 v[20:21], v[20:21], v[36:37] op_sel_hi:[1,0]
	global_store_dwordx4 v[30:31], v[24:27], off
	s_nop 0
	v_pk_mul_f32 v[22:23], v[22:23], v[36:37] op_sel_hi:[1,0]
	v_pk_mul_f32 v[24:25], v[14:15], v[36:37] op_sel_hi:[1,0]
	v_pk_mul_f32 v[14:15], v[12:13], v[36:37] op_sel_hi:[1,0]
	v_cvt_pk_bf16_f32 v12, v20, v21
	v_cvt_pk_bf16_f32 v13, v22, v23
	v_cvt_pk_bf16_f32 v14, v14, v15
	v_cvt_pk_bf16_f32 v15, v24, v25
	global_store_dwordx4 v[30:31], v[12:15], off offset:256
	s_nop 1
	v_mov_b32_e32 v12, v235
	v_mad_i64_i32 v[14:15], s[20:21], v146, s40, v[148:149]
	v_pk_mul_f32 v[18:19], v[18:19], v[12:13] op_sel_hi:[1,0]
	v_pk_mul_f32 v[16:17], v[16:17], v[12:13] op_sel_hi:[1,0]
	v_pk_mul_f32 v[20:21], v[10:11], v[12:13] op_sel_hi:[1,0]
	v_pk_mul_f32 v[10:11], v[8:9], v[12:13] op_sel_hi:[1,0]
	v_lshl_add_u64 v[14:15], v[14:15], 0, v[154:155]
	v_cvt_pk_bf16_f32 v8, v16, v17
	v_cvt_pk_bf16_f32 v9, v18, v19
	v_cvt_pk_bf16_f32 v10, v10, v11
	v_cvt_pk_bf16_f32 v11, v20, v21
	global_store_dwordx4 v[14:15], v[8:11], off
	v_pk_mul_f32 v[6:7], v[6:7], v[12:13] op_sel_hi:[1,0]
	v_pk_mul_f32 v[4:5], v[4:5], v[12:13] op_sel_hi:[1,0]
	v_pk_mul_f32 v[8:9], v[2:3], v[12:13] op_sel_hi:[1,0]
	v_pk_mul_f32 v[2:3], v[0:1], v[12:13] op_sel_hi:[1,0]
	v_cvt_pk_bf16_f32 v0, v4, v5
	v_cvt_pk_bf16_f32 v1, v6, v7
	v_cvt_pk_bf16_f32 v2, v2, v3
	v_cvt_pk_bf16_f32 v3, v8, v9
	s_and_b64 vcc, exec, s[0:1]
	s_mov_b64 s[20:21], s[14:15]
	global_store_dwordx4 v[14:15], v[0:3], off offset:256
	s_cbranch_vccz .LBB0_919
	s_waitcnt vmcnt(0)
	v_readlane_b32 s40, v251, 54
	s_cmpk_gt_u32 s7, 0xff
	v_readlane_b32 s41, v251, 55
	s_cbranch_scc1 .LBB0_926
	s_barrier

; #define PG8_STAGE(bufoff, gbase, voff) do { _Pragma("unroll") for (int _i = 0; _i < 2; ++_i) \
;         __builtin_amdgcn_global_load_lds((const unsigned*)((const char*)(gbase) + (voff)[_i]), (LAS unsigned*)(lds + (bufoff) + ldsw + _i * 8192), 16, 0, 0); } while (0)
; #define PG8_LDA(dst, b, h) do { _Pragma("unroll") for (int m = 0; m < 4; ++m) _Pragma("unroll") for (int k = 0; k < 2; ++k) dst[m][k] = *(const LAS bf16x8*)(lds + PG8_SA(b, h) + aoff + m * 2048 + k * 1024); } while (0)
; #define PG8_LDB(dst, b, h) do { _Pragma("unroll") for (int n = 0; n < 2; ++n) _Pragma("unroll") for (int k = 0; k < 2; ++k) dst[n][k] = *(const LAS bf16x8*)(lds + PG8_SB(b, h) + boff + n * 2048 + k * 1024); } while (0)
; #define PG8_WAIT_V(n) asm volatile("s_waitcnt vmcnt(" #n ")" ::: "memory")
; #define PG8_WAIT_L(n) asm volatile("s_waitcnt lgkmcnt(" #n ")" ::: "memory")
; #define PG8_BAR __builtin_amdgcn_s_barrier()
; #define PG8_SCHED __builtin_amdgcn_sched_barrier(0)
; template <class Epi>
; __device__ __forceinline__ void gemm_phase(LAS unsigned char* lds, const Gemm g, const StaticOrder& S, const Epi& E) {
;     ...
;         const bool has_next = S.next(ui + 1, nxt);
;         const char* nA = has_next ? (const char*)g.A + (size_t)nxt.pm * tstepA : cA; const char* nB = has_next ? (const char*)g.Bt + (size_t)nxt.pn * tstepB : cB;
;         for (int t = 0; t < nt; t += 2) {
;             const bool last = (t == nt - 2);
;             const char* a1 = cA + (size_t)(t + 1) * kstep;
;             const char* a2 = last ? nA : cA + (size_t)(t + 2) * kstep; const char* b2 = last ? nB : cB + (size_t)(t + 2) * kstep;
;             const char* a3 = a2 + kstep; const char* b3 = b2 + kstep;
;             if (last) E.pre(cur, wr, fr, epre);
;             PG8_LDB(B0, 0, 0); PG8_SCHED; PG8_LDA(At, 0, 0); PG8_STAGE(PG8_SA(1, 1), a1 + hstepA, voffA);
;             PG8_WAIT_L(8); PG8_BAR; PG8_WAIT_L(0); PG8_MMA(0, 0, At, B0); PG8_BAR; PG8_SCHED;
;             PG8_LDB(B1, 0, 1); PG8_STAGE(PG8_SB(0, 0), b2, voffB);
;             PG8_BAR; PG8_WAIT_L(0); PG8_MMA(0, 1, At, B1); PG8_BAR;
;             PG8_LDA(At, 0, 1); PG8_STAGE(PG8_SA(0, 0), a2, voffA);
;             PG8_BAR; PG8_WAIT_L(0); PG8_MMA(1, 0, At, B0); PG8_BAR; PG8_SCHED;
;             PG8_STAGE(PG8_SB(0, 1), b2 + hstepB, voffB);
;             PG8_WAIT_V(6); PG8_BAR; PG8_MMA(1, 1, At, B1); PG8_BAR;
.LBB0_1117:
	s_ashr_i32 s17, s16, 31
	s_lshl_b64 s[20:21], s[16:17], 19
	s_add_u32 s20, s27, s20
	s_addc_u32 s21, s28, s21
	s_and_b64 s[4:5], s[4:5], exec
	s_cselect_b32 s17, s21, s23
	s_cselect_b32 s43, s20, s22
	s_add_u32 s4, s24, 0x140080
	s_addc_u32 s5, s25, 0
	s_add_u32 s44, s22, 0x100
	s_addc_u32 s45, s23, 0
	s_mov_b32 s46, -2
	s_waitcnt lgkmcnt(0)
	ds_read_b128 v[128:131], v190
	ds_read_b128 v[132:135], v190 offset:1024
	ds_read_b128 v[136:139], v190 offset:2048
	ds_read_b128 v[140:143], v190 offset:3072
	s_add_u32 s22, s4, 0xffec0080
	s_addc_u32 s23, s5, -1
	s_cmp_eq_u32 s46, 12
	s_cselect_b32 s25, s19, s23
	s_cselect_b32 s24, s18, s22
	s_cselect_b32 s23, s17, s45
	s_cselect_b32 s22, s43, s44
	v_lshl_add_u64 v[186:187], s[4:5], 0, v[162:163]
	s_add_i32 m0, s9, 0xc000
	ds_read_b128 v[144:147], v191
	ds_read_b128 v[148:151], v191 offset:1024
	ds_read_b128 v[170:173], v191 offset:2048
	ds_read_b128 v[174:177], v191 offset:3072
	ds_read_b128 v[178:181], v191 offset:4096
	ds_read_b128 v[182:185], v191 offset:5120
	ds_read_b128 v[194:197], v191 offset:6144
	ds_read_b128 v[198:201], v191 offset:7168
	global_load_lds_dwordx4 v[186:187], off
	v_lshl_add_u64 v[186:187], s[4:5], 0, v[164:165]
	s_add_i32 m0, s9, 0xe000
	s_nop 0
	global_load_lds_dwordx4 v[186:187], off
	s_waitcnt lgkmcnt(8)
	s_barrier
	s_waitcnt lgkmcnt(0)
	s_waitcnt lgkmcnt(0)
	v_mfma_f32_16x16x32_bf16 v[124:127], v[128:131], v[144:147], 0
	v_mfma_f32_16x16x32_bf16 v[120:123], v[136:139], v[144:147], 0
	v_mfma_f32_16x16x32_bf16 v[108:111], v[128:131], v[170:173], 0
	v_mfma_f32_16x16x32_bf16 v[104:107], v[136:139], v[170:173], 0
	v_mfma_f32_16x16x32_bf16 v[92:95], v[128:131], v[178:181], 0
	v_mfma_f32_16x16x32_bf16 v[88:91], v[136:139], v[178:181], 0
	v_mfma_f32_16x16x32_bf16 v[76:79], v[128:131], v[194:197], 0
	v_mfma_f32_16x16x32_bf16 v[72:75], v[136:139], v[194:197], 0
	v_mfma_f32_16x16x32_bf16 v[124:127], v[132:135], v[148:151], v[124:127]
	v_mfma_f32_16x16x32_bf16 v[120:123], v[140:143], v[148:151], v[120:123]
	v_mfma_f32_16x16x32_bf16 v[108:111], v[132:135], v[174:177], v[108:111]
	v_mfma_f32_16x16x32_bf16 v[104:107], v[140:143], v[174:177], v[104:107]
	v_mfma_f32_16x16x32_bf16 v[92:95], v[132:135], v[182:185], v[92:95]
	v_mfma_f32_16x16x32_bf16 v[88:91], v[140:143], v[182:185], v[88:91]
	v_mfma_f32_16x16x32_bf16 v[76:79], v[132:135], v[198:201], v[76:79]
	v_mfma_f32_16x16x32_bf16 v[72:75], v[140:143], v[198:201], v[72:75]
	s_barrier
	s_add_i32 s47, s40, s29
	v_lshl_add_u64 v[186:187], s[22:23], 0, v[156:157]
	s_mov_b32 m0, s47
	ds_read_b128 v[202:205], v192
	ds_read_b128 v[206:209], v192 offset:1024
	ds_read_b128 v[210:213], v192 offset:2048
	ds_read_b128 v[214:217], v192 offset:3072
	global_load_lds_dwordx4 v[186:187], off
	v_lshl_add_u64 v[218:219], s[22:23], 0, v[160:161]
	s_add_i32 m0, s47, 0x2000
	s_nop 0
	global_load_lds_dwordx4 v[218:219], off
	s_barrier
	s_waitcnt lgkmcnt(0)
	s_waitcnt lgkmcnt(0)
	v_mfma_f32_16x16x32_bf16 v[116:119], v[202:205], v[144:147], 0
	v_mfma_f32_16x16x32_bf16 v[112:115], v[210:213], v[144:147], 0
	v_mfma_f32_16x16x32_bf16 v[100:103], v[202:205], v[170:173], 0
	v_mfma_f32_16x16x32_bf16 v[96:99], v[210:213], v[170:173], 0
	v_mfma_f32_16x16x32_bf16 v[84:87], v[202:205], v[178:181], 0
	v_mfma_f32_16x16x32_bf16 v[80:83], v[210:213], v[178:181], 0
	v_mfma_f32_16x16x32_bf16 v[68:71], v[202:205], v[194:197], 0
	v_mfma_f32_16x16x32_bf16 v[64:67], v[210:213], v[194:197], 0
	v_mfma_f32_16x16x32_bf16 v[116:119], v[206:209], v[148:151], v[116:119]
	v_mfma_f32_16x16x32_bf16 v[112:115], v[214:217], v[148:151], v[112:115]
	v_mfma_f32_16x16x32_bf16 v[100:103], v[206:209], v[174:177], v[100:103]
	v_mfma_f32_16x16x32_bf16 v[96:99], v[214:217], v[174:177], v[96:99]
	v_mfma_f32_16x16x32_bf16 v[84:87], v[206:209], v[182:185], v[84:87]
	v_mfma_f32_16x16x32_bf16 v[80:83], v[214:217], v[182:185], v[80:83]
	v_mfma_f32_16x16x32_bf16 v[68:71], v[206:209], v[198:201], v[68:71]
	v_mfma_f32_16x16x32_bf16 v[64:67], v[214:217], v[198:201], v[64:67]
	s_mov_b32 m0, s9
	v_lshl_add_u64 v[220:221], s[24:25], 0, v[154:155]
	s_barrier
	ds_read_b128 v[144:147], v191 offset:16384
	ds_read_b128 v[148:151], v191 offset:17408
	ds_read_b128 v[170:173], v191 offset:18432
	ds_read_b128 v[174:177], v191 offset:19456
	ds_read_b128 v[178:181], v191 offset:20480
	ds_read_b128 v[182:185], v191 offset:21504
	ds_read_b128 v[194:197], v191 offset:22528
	ds_read_b128 v[198:201], v191 offset:23552
	global_load_lds_dwordx4 v[220:221], off
	v_lshl_add_u64 v[222:223], s[24:25], 0, v[158:159]
	s_mov_b32 m0, s30
	s_nop 0
	global_load_lds_dwordx4 v[222:223], off
	s_barrier
	s_waitcnt lgkmcnt(0)
	s_waitcnt lgkmcnt(0)
	v_mfma_f32_16x16x32_bf16 v[60:63], v[128:131], v[144:147], 0
	v_mfma_f32_16x16x32_bf16 v[56:59], v[136:139], v[144:147], 0
	v_mfma_f32_16x16x32_bf16 v[44:47], v[128:131], v[170:173], 0
	v_mfma_f32_16x16x32_bf16 v[40:43], v[136:139], v[170:173], 0
	v_mfma_f32_16x16x32_bf16 v[28:31], v[128:131], v[178:181], 0
	v_mfma_f32_16x16x32_bf16 v[24:27], v[136:139], v[178:181], 0
	v_mfma_f32_16x16x32_bf16 v[12:15], v[128:131], v[194:197], 0
	v_mfma_f32_16x16x32_bf16 v[8:11], v[136:139], v[194:197], 0
	v_mfma_f32_16x16x32_bf16 v[60:63], v[132:135], v[148:151], v[60:63]
	v_mfma_f32_16x16x32_bf16 v[56:59], v[140:143], v[148:151], v[56:59]
	v_mfma_f32_16x16x32_bf16 v[44:47], v[132:135], v[174:177], v[44:47]
	v_mfma_f32_16x16x32_bf16 v[40:43], v[140:143], v[174:177], v[40:43]
	v_mfma_f32_16x16x32_bf16 v[28:31], v[132:135], v[182:185], v[28:31]
	v_mfma_f32_16x16x32_bf16 v[24:27], v[140:143], v[182:185], v[24:27]
	v_mfma_f32_16x16x32_bf16 v[12:15], v[132:135], v[198:201], v[12:15]
	v_mfma_f32_16x16x32_bf16 v[8:11], v[140:143], v[198:201], v[8:11]
	s_barrier
; #define PG8_STAGE(bufoff, gbase, voff) do { _Pragma("unroll") for (int _i = 0; _i < 2; ++_i) \
;         __builtin_amdgcn_global_load_lds((const unsigned*)((const char*)(gbase) + (voff)[_i]), (LAS unsigned*)(lds + (bufoff) + ldsw + _i * 8192), 16, 0, 0); } while (0)
; #define PG8_LDA(dst, b, h) do { _Pragma("unroll") for (int m = 0; m < 4; ++m) _Pragma("unroll") for (int k = 0; k < 2; ++k) dst[m][k] = *(const LAS bf16x8*)(lds + PG8_SA(b, h) + aoff + m * 2048 + k * 1024); } while (0)
; #define PG8_LDB(dst, b, h) do { _Pragma("unroll") for (int n = 0; n < 2; ++n) _Pragma("unroll") for (int k = 0; k < 2; ++k) dst[n][k] = *(const LAS bf16x8*)(lds + PG8_SB(b, h) + boff + n * 2048 + k * 1024); } while (0)
; #define PG8_MMA(ai, bj, At, Bt) do { __builtin_amdgcn_s_setprio(1); _Pragma("unroll") for (int m = 0; m < 4; ++m) _Pragma("unroll") for (int n = 0; n < 2; ++n) _Pragma("unroll") for (int k = 0; k < 2; ++k) \
;         acc[ai][bj][m][n] = __builtin_amdgcn_mfma_f32_16x16x32_bf16(Bt[n][k], At[m][k], acc[ai][bj][m][n], 0, 0, 0); __builtin_amdgcn_s_setprio(0); } while (0)
; #define PG8_WAIT_V(n) asm volatile("s_waitcnt vmcnt(" #n ")" ::: "memory")
; #define PG8_WAIT_L(n) asm volatile("s_waitcnt lgkmcnt(" #n ")" ::: "memory")
; #define PG8_BAR __builtin_amdgcn_s_barrier()
; #define PG8_SCHED __builtin_amdgcn_sched_barrier(0)
; template <class Epi>
; __device__ __forceinline__ void gemm_phase(LAS unsigned char* lds, const Gemm g, const StaticOrder& S, const Epi& E) {
;     ...
;             PG8_BAR; PG8_WAIT_L(0); PG8_MMA(1, 0, At, B0); PG8_BAR; PG8_SCHED;
;             PG8_STAGE(PG8_SB(0, 1), b2 + hstepB, voffB);
;             PG8_WAIT_V(6); PG8_BAR; PG8_MMA(1, 1, At, B1); PG8_BAR;
;             PG8_LDB(B0, 1, 0); PG8_SCHED; PG8_LDA(At, 1, 0); PG8_STAGE(PG8_SA(0, 1), a2 + hstepA, voffA);
;             PG8_WAIT_L(8); PG8_BAR; PG8_WAIT_L(0); PG8_MMA(0, 0, At, B0); PG8_BAR; PG8_SCHED;
;             PG8_LDB(B1, 1, 1); PG8_STAGE(PG8_SB(1, 0), b3, voffB);
;             PG8_BAR; PG8_WAIT_L(0); PG8_MMA(0, 1, At, B1); PG8_BAR;
;             PG8_LDA(At, 1, 1); PG8_STAGE(PG8_SA(1, 0), a3, voffA);
;             PG8_BAR; PG8_WAIT_L(0); PG8_MMA(1, 0, At, B0); PG8_BAR; PG8_SCHED;
	s_add_u32 s48, s22, 0x40000
	s_addc_u32 s49, s23, 0
	s_add_i32 s47, s41, s29
	v_lshl_add_u64 v[128:129], s[48:49], 0, v[156:157]
	s_mov_b32 m0, s47
	s_nop 0
	global_load_lds_dwordx4 v[128:129], off
	v_lshl_add_u64 v[128:129], s[48:49], 0, v[160:161]
	s_add_i32 m0, s47, 0x2000
	s_nop 0
	global_load_lds_dwordx4 v[128:129], off
	s_waitcnt vmcnt(6)
	s_barrier
	v_mfma_f32_16x16x32_bf16 v[52:55], v[202:205], v[144:147], 0
	v_mfma_f32_16x16x32_bf16 v[48:51], v[210:213], v[144:147], 0
	v_mfma_f32_16x16x32_bf16 v[36:39], v[202:205], v[170:173], 0
	v_mfma_f32_16x16x32_bf16 v[32:35], v[210:213], v[170:173], 0
	v_mfma_f32_16x16x32_bf16 v[20:23], v[202:205], v[178:181], 0
	v_mfma_f32_16x16x32_bf16 v[16:19], v[210:213], v[178:181], 0
	v_mfma_f32_16x16x32_bf16 v[4:7], v[202:205], v[194:197], 0
	v_mfma_f32_16x16x32_bf16 v[0:3], v[210:213], v[194:197], 0
	v_mfma_f32_16x16x32_bf16 v[52:55], v[206:209], v[148:151], v[52:55]
	v_mfma_f32_16x16x32_bf16 v[48:51], v[214:217], v[148:151], v[48:51]
	v_mfma_f32_16x16x32_bf16 v[36:39], v[206:209], v[174:177], v[36:39]
	v_mfma_f32_16x16x32_bf16 v[32:35], v[214:217], v[174:177], v[32:35]
	v_mfma_f32_16x16x32_bf16 v[20:23], v[206:209], v[182:185], v[20:23]
	v_mfma_f32_16x16x32_bf16 v[16:19], v[214:217], v[182:185], v[16:19]
	v_mfma_f32_16x16x32_bf16 v[4:7], v[206:209], v[198:201], v[4:7]
	v_mfma_f32_16x16x32_bf16 v[0:3], v[214:217], v[198:201], v[0:3]
	s_add_i32 s47, 0, 0x18000
	v_add_u32_e32 v140, s47, v188
	s_barrier
	ds_read_b128 v[128:131], v140
	ds_read_b128 v[132:135], v140 offset:1024
	ds_read_b128 v[136:139], v140 offset:2048
	ds_read_b128 v[140:143], v140 offset:3072
	s_add_u32 s24, s24, 0x140000
	s_addc_u32 s25, s25, 0
	s_mov_b32 m0, s31
	v_lshl_add_u64 v[202:203], s[24:25], 0, v[154:155]
	ds_read_b128 v[144:147], v191 offset:32768
	ds_read_b128 v[148:151], v191 offset:33792
	ds_read_b128 v[170:173], v191 offset:34816
	ds_read_b128 v[174:177], v191 offset:35840
	ds_read_b128 v[178:181], v191 offset:36864
	ds_read_b128 v[182:185], v191 offset:37888
	ds_read_b128 v[194:197], v191 offset:38912
	ds_read_b128 v[198:201], v191 offset:39936
	global_load_lds_dwordx4 v[202:203], off
	v_lshl_add_u64 v[202:203], s[24:25], 0, v[158:159]
	s_mov_b32 m0, s34
	s_nop 0
	global_load_lds_dwordx4 v[202:203], off
	s_waitcnt lgkmcnt(8)
	s_barrier
	s_waitcnt lgkmcnt(0)
	s_waitcnt lgkmcnt(0)
	v_mfma_f32_16x16x32_bf16 v[124:127], v[128:131], v[144:147], v[124:127]
	v_mfma_f32_16x16x32_bf16 v[120:123], v[136:139], v[144:147], v[120:123]
	v_mfma_f32_16x16x32_bf16 v[108:111], v[128:131], v[170:173], v[108:111]
	v_mfma_f32_16x16x32_bf16 v[104:107], v[136:139], v[170:173], v[104:107]
	v_mfma_f32_16x16x32_bf16 v[92:95], v[128:131], v[178:181], v[92:95]
	v_mfma_f32_16x16x32_bf16 v[88:91], v[136:139], v[178:181], v[88:91]
	v_mfma_f32_16x16x32_bf16 v[76:79], v[128:131], v[194:197], v[76:79]
	v_mfma_f32_16x16x32_bf16 v[72:75], v[136:139], v[194:197], v[72:75]
	v_mfma_f32_16x16x32_bf16 v[124:127], v[132:135], v[148:151], v[124:127]
	v_mfma_f32_16x16x32_bf16 v[120:123], v[140:143], v[148:151], v[120:123]
	v_mfma_f32_16x16x32_bf16 v[108:111], v[132:135], v[174:177], v[108:111]
	v_mfma_f32_16x16x32_bf16 v[104:107], v[140:143], v[174:177], v[104:107]
	v_mfma_f32_16x16x32_bf16 v[92:95], v[132:135], v[182:185], v[92:95]
	v_mfma_f32_16x16x32_bf16 v[88:91], v[140:143], v[182:185], v[88:91]
	v_mfma_f32_16x16x32_bf16 v[76:79], v[132:135], v[198:201], v[76:79]
	v_mfma_f32_16x16x32_bf16 v[72:75], v[140:143], v[198:201], v[72:75]
	s_barrier
	s_add_i32 s24, 0, 0x1c000
	s_add_i32 s25, s47, s29
	v_add_u32_e32 v214, s24, v188
	v_lshl_add_u64 v[186:187], v[186:187], 0, s[14:15]
	s_mov_b32 m0, s25
	ds_read_b128 v[202:205], v214
	ds_read_b128 v[206:209], v214 offset:1024
	ds_read_b128 v[210:213], v214 offset:2048
	ds_read_b128 v[214:217], v214 offset:3072
	global_load_lds_dwordx4 v[186:187], off
	v_lshl_add_u64 v[186:187], v[218:219], 0, s[14:15]
	s_add_i32 m0, s25, 0x2000
	s_nop 0
	global_load_lds_dwordx4 v[186:187], off
	s_barrier
	s_waitcnt lgkmcnt(0)
	s_waitcnt lgkmcnt(0)
	v_mfma_f32_16x16x32_bf16 v[116:119], v[202:205], v[144:147], v[116:119]
	v_mfma_f32_16x16x32_bf16 v[112:115], v[210:213], v[144:147], v[112:115]
	v_mfma_f32_16x16x32_bf16 v[100:103], v[202:205], v[170:173], v[100:103]
	v_mfma_f32_16x16x32_bf16 v[96:99], v[210:213], v[170:173], v[96:99]
	v_mfma_f32_16x16x32_bf16 v[84:87], v[202:205], v[178:181], v[84:87]
	v_mfma_f32_16x16x32_bf16 v[80:83], v[210:213], v[178:181], v[80:83]
	v_mfma_f32_16x16x32_bf16 v[68:71], v[202:205], v[194:197], v[68:71]
	v_mfma_f32_16x16x32_bf16 v[64:67], v[210:213], v[194:197], v[64:67]
	v_mfma_f32_16x16x32_bf16 v[116:119], v[206:209], v[148:151], v[116:119]
	v_mfma_f32_16x16x32_bf16 v[112:115], v[214:217], v[148:151], v[112:115]
	v_mfma_f32_16x16x32_bf16 v[100:103], v[206:209], v[174:177], v[100:103]
	v_mfma_f32_16x16x32_bf16 v[96:99], v[214:217], v[174:177], v[96:99]
	v_mfma_f32_16x16x32_bf16 v[84:87], v[206:209], v[182:185], v[84:87]
	v_mfma_f32_16x16x32_bf16 v[80:83], v[214:217], v[182:185], v[80:83]
	v_mfma_f32_16x16x32_bf16 v[68:71], v[206:209], v[198:201], v[68:71]
	v_mfma_f32_16x16x32_bf16 v[64:67], v[214:217], v[198:201], v[64:67]
	s_mov_b32 m0, s36
	v_lshl_add_u64 v[186:187], v[220:221], 0, s[14:15]
	s_barrier
	ds_read_b128 v[144:147], v191 offset:49152
	ds_read_b128 v[148:151], v191 offset:50176
	ds_read_b128 v[170:173], v191 offset:51200
	ds_read_b128 v[174:177], v191 offset:52224
	ds_read_b128 v[178:181], v191 offset:53248
	ds_read_b128 v[182:185], v191 offset:54272
	ds_read_b128 v[194:197], v191 offset:55296
	ds_read_b128 v[198:201], v191 offset:56320
	global_load_lds_dwordx4 v[186:187], off
	v_lshl_add_u64 v[186:187], v[222:223], 0, s[14:15]
	s_mov_b32 m0, s37
	s_nop 0
	global_load_lds_dwordx4 v[186:187], off
	s_barrier
; #define PG8_STAGE(bufoff, gbase, voff) do { _Pragma("unroll") for (int _i = 0; _i < 2; ++_i) \
;         __builtin_amdgcn_global_load_lds((const unsigned*)((const char*)(gbase) + (voff)[_i]), (LAS unsigned*)(lds + (bufoff) + ldsw + _i * 8192), 16, 0, 0); } while (0)
; #define PG8_LDA(dst, b, h) do { _Pragma("unroll") for (int m = 0; m < 4; ++m) _Pragma("unroll") for (int k = 0; k < 2; ++k) dst[m][k] = *(const LAS bf16x8*)(lds + PG8_SA(b, h) + aoff + m * 2048 + k * 1024); } while (0)
; #define PG8_LDB(dst, b, h) do { _Pragma("unroll") for (int n = 0; n < 2; ++n) _Pragma("unroll") for (int k = 0; k < 2; ++k) dst[n][k] = *(const LAS bf16x8*)(lds + PG8_SB(b, h) + boff + n * 2048 + k * 1024); } while (0)
; #define PG8_MMA(ai, bj, At, Bt) do { __builtin_amdgcn_s_setprio(1); _Pragma("unroll") for (int m = 0; m < 4; ++m) _Pragma("unroll") for (int n = 0; n < 2; ++n) _Pragma("unroll") for (int k = 0; k < 2; ++k) \
;         acc[ai][bj][m][n] = __builtin_amdgcn_mfma_f32_16x16x32_bf16(Bt[n][k], At[m][k], acc[ai][bj][m][n], 0, 0, 0); __builtin_amdgcn_s_setprio(0); } while (0)
; #define PG8_WAIT_V(n) asm volatile("s_waitcnt vmcnt(" #n ")" ::: "memory")
; #define PG8_BAR __builtin_amdgcn_s_barrier()
; template <class Epi>
; __device__ __forceinline__ void gemm_phase(LAS unsigned char* lds, const Gemm g, const StaticOrder& S, const Epi& E) {
;     ...
;             PG8_LDB(B0, 0, 0); PG8_SCHED; PG8_LDA(At, 0, 0); PG8_STAGE(PG8_SA(1, 1), a1 + hstepA, voffA);
;             PG8_WAIT_L(8); PG8_BAR; PG8_WAIT_L(0); PG8_MMA(0, 0, At, B0); PG8_BAR; PG8_SCHED;
;             PG8_LDB(B1, 0, 1); PG8_STAGE(PG8_SB(0, 0), b2, voffB);
;             PG8_BAR; PG8_WAIT_L(0); PG8_MMA(0, 1, At, B1); PG8_BAR;
;     ...
;             PG8_WAIT_V(6); PG8_BAR; PG8_MMA(1, 1, At, B1); PG8_BAR;
;             PG8_LDB(B0, 1, 0); PG8_SCHED; PG8_LDA(At, 1, 0); PG8_STAGE(PG8_SA(0, 1), a2 + hstepA, voffA);
;             PG8_WAIT_L(8); PG8_BAR; PG8_WAIT_L(0); PG8_MMA(0, 0, At, B0); PG8_BAR; PG8_SCHED;
;             PG8_LDB(B1, 1, 1); PG8_STAGE(PG8_SB(1, 0), b3, voffB);
;             PG8_BAR; PG8_WAIT_L(0); PG8_MMA(0, 1, At, B1); PG8_BAR;
;             PG8_LDA(At, 1, 1); PG8_STAGE(PG8_SA(1, 0), a3, voffA);
;             PG8_BAR; PG8_WAIT_L(0); PG8_MMA(1, 0, At, B0); PG8_BAR; PG8_SCHED;
;             PG8_STAGE(PG8_SB(1, 1), b3 + hstepB, voffB);
;             PG8_WAIT_V(6); PG8_BAR; PG8_MMA(1, 1, At, B1); PG8_BAR;
	s_waitcnt lgkmcnt(0)
	s_waitcnt lgkmcnt(0)
	v_mfma_f32_16x16x32_bf16 v[60:63], v[128:131], v[144:147], v[60:63]
	v_mfma_f32_16x16x32_bf16 v[56:59], v[136:139], v[144:147], v[56:59]
	v_mfma_f32_16x16x32_bf16 v[44:47], v[128:131], v[170:173], v[44:47]
	v_mfma_f32_16x16x32_bf16 v[40:43], v[136:139], v[170:173], v[40:43]
	v_mfma_f32_16x16x32_bf16 v[28:31], v[128:131], v[178:181], v[28:31]
	v_mfma_f32_16x16x32_bf16 v[24:27], v[136:139], v[178:181], v[24:27]
	v_mfma_f32_16x16x32_bf16 v[12:15], v[128:131], v[194:197], v[12:15]
	v_mfma_f32_16x16x32_bf16 v[8:11], v[136:139], v[194:197], v[8:11]
	v_mfma_f32_16x16x32_bf16 v[60:63], v[132:135], v[148:151], v[60:63]
	v_mfma_f32_16x16x32_bf16 v[56:59], v[140:143], v[148:151], v[56:59]
	v_mfma_f32_16x16x32_bf16 v[44:47], v[132:135], v[174:177], v[44:47]
	v_mfma_f32_16x16x32_bf16 v[40:43], v[140:143], v[174:177], v[40:43]
	v_mfma_f32_16x16x32_bf16 v[28:31], v[132:135], v[182:185], v[28:31]
	v_mfma_f32_16x16x32_bf16 v[24:27], v[140:143], v[182:185], v[24:27]
	v_mfma_f32_16x16x32_bf16 v[12:15], v[132:135], v[198:201], v[12:15]
	v_mfma_f32_16x16x32_bf16 v[8:11], v[140:143], v[198:201], v[8:11]
	s_barrier
	s_add_u32 s22, s22, 0x40080
	s_addc_u32 s23, s23, 0
	s_add_i32 s24, s24, s29
	v_lshl_add_u64 v[128:129], s[22:23], 0, v[156:157]
	s_mov_b32 m0, s24
	s_nop 0
	global_load_lds_dwordx4 v[128:129], off
	v_lshl_add_u64 v[128:129], s[22:23], 0, v[160:161]
	s_add_i32 m0, s24, 0x2000
	s_nop 0
	global_load_lds_dwordx4 v[128:129], off
	s_waitcnt vmcnt(6)
	s_barrier
	v_mfma_f32_16x16x32_bf16 v[52:55], v[202:205], v[144:147], v[52:55]
	v_mfma_f32_16x16x32_bf16 v[48:51], v[210:213], v[144:147], v[48:51]
	v_mfma_f32_16x16x32_bf16 v[36:39], v[202:205], v[170:173], v[36:39]
	v_mfma_f32_16x16x32_bf16 v[32:35], v[210:213], v[170:173], v[32:35]
	v_mfma_f32_16x16x32_bf16 v[20:23], v[202:205], v[178:181], v[20:23]
	v_mfma_f32_16x16x32_bf16 v[16:19], v[210:213], v[178:181], v[16:19]
	v_mfma_f32_16x16x32_bf16 v[4:7], v[202:205], v[194:197], v[4:7]
	v_mfma_f32_16x16x32_bf16 v[0:3], v[210:213], v[194:197], v[0:3]
	v_mfma_f32_16x16x32_bf16 v[52:55], v[206:209], v[148:151], v[52:55]
	v_mfma_f32_16x16x32_bf16 v[48:51], v[214:217], v[148:151], v[48:51]
	v_mfma_f32_16x16x32_bf16 v[36:39], v[206:209], v[174:177], v[36:39]
	v_mfma_f32_16x16x32_bf16 v[32:35], v[214:217], v[174:177], v[32:35]
	v_mfma_f32_16x16x32_bf16 v[20:23], v[206:209], v[182:185], v[20:23]
	v_mfma_f32_16x16x32_bf16 v[16:19], v[214:217], v[182:185], v[16:19]
	v_mfma_f32_16x16x32_bf16 v[4:7], v[206:209], v[198:201], v[4:7]
	v_mfma_f32_16x16x32_bf16 v[0:3], v[214:217], v[198:201], v[0:3]
	s_add_i32 s46, s46, 2
	s_add_u32 s4, s4, 0x100
	s_addc_u32 s5, s5, 0
	s_add_u32 s44, s44, 0x100
	s_addc_u32 s45, s45, 0
	s_cmp_gt_u32 s46, 13
	s_barrier
.LBB0_1118:
	ds_read_b128 v[128:131], v190
	ds_read_b128 v[132:135], v190 offset:1024
	ds_read_b128 v[136:139], v190 offset:2048
	ds_read_b128 v[140:143], v190 offset:3072
	s_add_u32 s22, s4, 0xffec0080
	s_addc_u32 s23, s5, -1
	s_cmp_eq_u32 s46, 12
	s_cselect_b32 s25, s19, s23
	s_cselect_b32 s24, s18, s22
	s_cselect_b32 s23, s17, s45
	s_cselect_b32 s22, s43, s44
	v_lshl_add_u64 v[186:187], s[4:5], 0, v[162:163]
	s_add_i32 m0, s9, 0xc000
	ds_read_b128 v[144:147], v191
	ds_read_b128 v[148:151], v191 offset:1024
	ds_read_b128 v[170:173], v191 offset:2048
	ds_read_b128 v[174:177], v191 offset:3072
	ds_read_b128 v[178:181], v191 offset:4096
	ds_read_b128 v[182:185], v191 offset:5120
	ds_read_b128 v[194:197], v191 offset:6144
	ds_read_b128 v[198:201], v191 offset:7168
	global_load_lds_dwordx4 v[186:187], off
	v_lshl_add_u64 v[186:187], s[4:5], 0, v[164:165]
	s_add_i32 m0, s9, 0xe000
	s_nop 0
	global_load_lds_dwordx4 v[186:187], off
	s_waitcnt lgkmcnt(8)
	s_barrier
	s_waitcnt lgkmcnt(0)
	s_waitcnt lgkmcnt(0)
	v_mfma_f32_16x16x32_bf16 v[124:127], v[128:131], v[144:147], v[124:127]
	v_mfma_f32_16x16x32_bf16 v[120:123], v[136:139], v[144:147], v[120:123]
	v_mfma_f32_16x16x32_bf16 v[108:111], v[128:131], v[170:173], v[108:111]
	v_mfma_f32_16x16x32_bf16 v[104:107], v[136:139], v[170:173], v[104:107]
	v_mfma_f32_16x16x32_bf16 v[92:95], v[128:131], v[178:181], v[92:95]
	v_mfma_f32_16x16x32_bf16 v[88:91], v[136:139], v[178:181], v[88:91]
	v_mfma_f32_16x16x32_bf16 v[76:79], v[128:131], v[194:197], v[76:79]
	v_mfma_f32_16x16x32_bf16 v[72:75], v[136:139], v[194:197], v[72:75]
	v_mfma_f32_16x16x32_bf16 v[124:127], v[132:135], v[148:151], v[124:127]
	v_mfma_f32_16x16x32_bf16 v[120:123], v[140:143], v[148:151], v[120:123]
	v_mfma_f32_16x16x32_bf16 v[108:111], v[132:135], v[174:177], v[108:111]
	v_mfma_f32_16x16x32_bf16 v[104:107], v[140:143], v[174:177], v[104:107]
	v_mfma_f32_16x16x32_bf16 v[92:95], v[132:135], v[182:185], v[92:95]
	v_mfma_f32_16x16x32_bf16 v[88:91], v[140:143], v[182:185], v[88:91]
	v_mfma_f32_16x16x32_bf16 v[76:79], v[132:135], v[198:201], v[76:79]
	v_mfma_f32_16x16x32_bf16 v[72:75], v[140:143], v[198:201], v[72:75]
	s_barrier
	s_add_i32 s47, s40, s29
	v_lshl_add_u64 v[186:187], s[22:23], 0, v[156:157]
	s_mov_b32 m0, s47
	ds_read_b128 v[202:205], v192
	ds_read_b128 v[206:209], v192 offset:1024
	ds_read_b128 v[210:213], v192 offset:2048
	ds_read_b128 v[214:217], v192 offset:3072
	global_load_lds_dwordx4 v[186:187], off
	v_lshl_add_u64 v[218:219], s[22:23], 0, v[160:161]
	s_add_i32 m0, s47, 0x2000
	s_nop 0
	global_load_lds_dwordx4 v[218:219], off
	s_barrier
; #define PG8_STAGE(bufoff, gbase, voff) do { _Pragma("unroll") for (int _i = 0; _i < 2; ++_i) \
;         __builtin_amdgcn_global_load_lds((const unsigned*)((const char*)(gbase) + (voff)[_i]), (LAS unsigned*)(lds + (bufoff) + ldsw + _i * 8192), 16, 0, 0); } while (0)
; #define PG8_LDA(dst, b, h) do { _Pragma("unroll") for (int m = 0; m < 4; ++m) _Pragma("unroll") for (int k = 0; k < 2; ++k) dst[m][k] = *(const LAS bf16x8*)(lds + PG8_SA(b, h) + aoff + m * 2048 + k * 1024); } while (0)
; #define PG8_LDB(dst, b, h) do { _Pragma("unroll") for (int n = 0; n < 2; ++n) _Pragma("unroll") for (int k = 0; k < 2; ++k) dst[n][k] = *(const LAS bf16x8*)(lds + PG8_SB(b, h) + boff + n * 2048 + k * 1024); } while (0)
; #define PG8_MMA(ai, bj, At, Bt) do { __builtin_amdgcn_s_setprio(1); _Pragma("unroll") for (int m = 0; m < 4; ++m) _Pragma("unroll") for (int n = 0; n < 2; ++n) _Pragma("unroll") for (int k = 0; k < 2; ++k) \
;         acc[ai][bj][m][n] = __builtin_amdgcn_mfma_f32_16x16x32_bf16(Bt[n][k], At[m][k], acc[ai][bj][m][n], 0, 0, 0); __builtin_amdgcn_s_setprio(0); } while (0)
; #define PG8_WAIT_V(n) asm volatile("s_waitcnt vmcnt(" #n ")" ::: "memory")
; #define PG8_WAIT_L(n) asm volatile("s_waitcnt lgkmcnt(" #n ")" ::: "memory")
; #define PG8_BAR __builtin_amdgcn_s_barrier()
; #define PG8_SCHED __builtin_amdgcn_sched_barrier(0)
; template <class Epi>
; __device__ __forceinline__ void gemm_phase(LAS unsigned char* lds, const Gemm g, const StaticOrder& S, const Epi& E) {
;     ...
;             PG8_LDB(B1, 0, 1); PG8_STAGE(PG8_SB(0, 0), b2, voffB);
;             PG8_BAR; PG8_WAIT_L(0); PG8_MMA(0, 1, At, B1); PG8_BAR;
;             PG8_LDA(At, 0, 1); PG8_STAGE(PG8_SA(0, 0), a2, voffA);
;             PG8_BAR; PG8_WAIT_L(0); PG8_MMA(1, 0, At, B0); PG8_BAR; PG8_SCHED;
;             PG8_STAGE(PG8_SB(0, 1), b2 + hstepB, voffB);
;             PG8_WAIT_V(6); PG8_BAR; PG8_MMA(1, 1, At, B1); PG8_BAR;
;             PG8_LDB(B0, 1, 0); PG8_SCHED; PG8_LDA(At, 1, 0); PG8_STAGE(PG8_SA(0, 1), a2 + hstepA, voffA);
;             PG8_WAIT_L(8); PG8_BAR; PG8_WAIT_L(0); PG8_MMA(0, 0, At, B0); PG8_BAR; PG8_SCHED;
;             PG8_LDB(B1, 1, 1); PG8_STAGE(PG8_SB(1, 0), b3, voffB);
;             PG8_BAR; PG8_WAIT_L(0); PG8_MMA(0, 1, At, B1); PG8_BAR;
;             PG8_LDA(At, 1, 1); PG8_STAGE(PG8_SA(1, 0), a3, voffA);
	s_waitcnt lgkmcnt(0)
	s_waitcnt lgkmcnt(0)
	v_mfma_f32_16x16x32_bf16 v[116:119], v[202:205], v[144:147], v[116:119]
	v_mfma_f32_16x16x32_bf16 v[112:115], v[210:213], v[144:147], v[112:115]
	v_mfma_f32_16x16x32_bf16 v[100:103], v[202:205], v[170:173], v[100:103]
	v_mfma_f32_16x16x32_bf16 v[96:99], v[210:213], v[170:173], v[96:99]
	v_mfma_f32_16x16x32_bf16 v[84:87], v[202:205], v[178:181], v[84:87]
	v_mfma_f32_16x16x32_bf16 v[80:83], v[210:213], v[178:181], v[80:83]
	v_mfma_f32_16x16x32_bf16 v[68:71], v[202:205], v[194:197], v[68:71]
	v_mfma_f32_16x16x32_bf16 v[64:67], v[210:213], v[194:197], v[64:67]
	v_mfma_f32_16x16x32_bf16 v[116:119], v[206:209], v[148:151], v[116:119]
	v_mfma_f32_16x16x32_bf16 v[112:115], v[214:217], v[148:151], v[112:115]
	v_mfma_f32_16x16x32_bf16 v[100:103], v[206:209], v[174:177], v[100:103]
	v_mfma_f32_16x16x32_bf16 v[96:99], v[214:217], v[174:177], v[96:99]
	v_mfma_f32_16x16x32_bf16 v[84:87], v[206:209], v[182:185], v[84:87]
	v_mfma_f32_16x16x32_bf16 v[80:83], v[214:217], v[182:185], v[80:83]
	v_mfma_f32_16x16x32_bf16 v[68:71], v[206:209], v[198:201], v[68:71]
	v_mfma_f32_16x16x32_bf16 v[64:67], v[214:217], v[198:201], v[64:67]
	s_mov_b32 m0, s9
	v_lshl_add_u64 v[220:221], s[24:25], 0, v[154:155]
	s_barrier
	ds_read_b128 v[144:147], v191 offset:16384
	ds_read_b128 v[148:151], v191 offset:17408
	ds_read_b128 v[170:173], v191 offset:18432
	ds_read_b128 v[174:177], v191 offset:19456
	ds_read_b128 v[178:181], v191 offset:20480
	ds_read_b128 v[182:185], v191 offset:21504
	ds_read_b128 v[194:197], v191 offset:22528
	ds_read_b128 v[198:201], v191 offset:23552
	global_load_lds_dwordx4 v[220:221], off
	v_lshl_add_u64 v[222:223], s[24:25], 0, v[158:159]
	s_mov_b32 m0, s30
	s_nop 0
	global_load_lds_dwordx4 v[222:223], off
	s_barrier
	s_waitcnt lgkmcnt(0)
	s_waitcnt lgkmcnt(0)
	v_mfma_f32_16x16x32_bf16 v[60:63], v[128:131], v[144:147], v[60:63]
	v_mfma_f32_16x16x32_bf16 v[56:59], v[136:139], v[144:147], v[56:59]
	v_mfma_f32_16x16x32_bf16 v[44:47], v[128:131], v[170:173], v[44:47]
	v_mfma_f32_16x16x32_bf16 v[40:43], v[136:139], v[170:173], v[40:43]
	v_mfma_f32_16x16x32_bf16 v[28:31], v[128:131], v[178:181], v[28:31]
	v_mfma_f32_16x16x32_bf16 v[24:27], v[136:139], v[178:181], v[24:27]
	v_mfma_f32_16x16x32_bf16 v[12:15], v[128:131], v[194:197], v[12:15]
	v_mfma_f32_16x16x32_bf16 v[8:11], v[136:139], v[194:197], v[8:11]
	v_mfma_f32_16x16x32_bf16 v[60:63], v[132:135], v[148:151], v[60:63]
	v_mfma_f32_16x16x32_bf16 v[56:59], v[140:143], v[148:151], v[56:59]
	v_mfma_f32_16x16x32_bf16 v[44:47], v[132:135], v[174:177], v[44:47]
	v_mfma_f32_16x16x32_bf16 v[40:43], v[140:143], v[174:177], v[40:43]
	v_mfma_f32_16x16x32_bf16 v[28:31], v[132:135], v[182:185], v[28:31]
	v_mfma_f32_16x16x32_bf16 v[24:27], v[140:143], v[182:185], v[24:27]
	v_mfma_f32_16x16x32_bf16 v[12:15], v[132:135], v[198:201], v[12:15]
	v_mfma_f32_16x16x32_bf16 v[8:11], v[140:143], v[198:201], v[8:11]
	s_barrier
	s_add_u32 s48, s22, 0x40000
	s_addc_u32 s49, s23, 0
	s_add_i32 s47, s41, s29
	v_lshl_add_u64 v[128:129], s[48:49], 0, v[156:157]
	s_mov_b32 m0, s47
	s_nop 0
	global_load_lds_dwordx4 v[128:129], off
	v_lshl_add_u64 v[128:129], s[48:49], 0, v[160:161]
	s_add_i32 m0, s47, 0x2000
	s_nop 0
	global_load_lds_dwordx4 v[128:129], off
	s_waitcnt vmcnt(6)
	s_barrier
	v_mfma_f32_16x16x32_bf16 v[52:55], v[202:205], v[144:147], v[52:55]
	v_mfma_f32_16x16x32_bf16 v[48:51], v[210:213], v[144:147], v[48:51]
	v_mfma_f32_16x16x32_bf16 v[36:39], v[202:205], v[170:173], v[36:39]
	v_mfma_f32_16x16x32_bf16 v[32:35], v[210:213], v[170:173], v[32:35]
	v_mfma_f32_16x16x32_bf16 v[20:23], v[202:205], v[178:181], v[20:23]
	v_mfma_f32_16x16x32_bf16 v[16:19], v[210:213], v[178:181], v[16:19]
	v_mfma_f32_16x16x32_bf16 v[4:7], v[202:205], v[194:197], v[4:7]
	v_mfma_f32_16x16x32_bf16 v[0:3], v[210:213], v[194:197], v[0:3]
	v_mfma_f32_16x16x32_bf16 v[52:55], v[206:209], v[148:151], v[52:55]
	v_mfma_f32_16x16x32_bf16 v[48:51], v[214:217], v[148:151], v[48:51]
	v_mfma_f32_16x16x32_bf16 v[36:39], v[206:209], v[174:177], v[36:39]
	v_mfma_f32_16x16x32_bf16 v[32:35], v[214:217], v[174:177], v[32:35]
	v_mfma_f32_16x16x32_bf16 v[20:23], v[206:209], v[182:185], v[20:23]
	v_mfma_f32_16x16x32_bf16 v[16:19], v[214:217], v[182:185], v[16:19]
	v_mfma_f32_16x16x32_bf16 v[4:7], v[206:209], v[198:201], v[4:7]
	v_mfma_f32_16x16x32_bf16 v[0:3], v[214:217], v[198:201], v[0:3]
	s_add_i32 s47, 0, 0x18000
	v_add_u32_e32 v140, s47, v188
	s_barrier
	ds_read_b128 v[128:131], v140
	ds_read_b128 v[132:135], v140 offset:1024
	ds_read_b128 v[136:139], v140 offset:2048
	ds_read_b128 v[140:143], v140 offset:3072
	s_add_u32 s24, s24, 0x140000
	s_addc_u32 s25, s25, 0
	s_mov_b32 m0, s31
	v_lshl_add_u64 v[202:203], s[24:25], 0, v[154:155]
	ds_read_b128 v[144:147], v191 offset:32768
	ds_read_b128 v[148:151], v191 offset:33792
	ds_read_b128 v[170:173], v191 offset:34816
	ds_read_b128 v[174:177], v191 offset:35840
	ds_read_b128 v[178:181], v191 offset:36864
	ds_read_b128 v[182:185], v191 offset:37888
	ds_read_b128 v[194:197], v191 offset:38912
	ds_read_b128 v[198:201], v191 offset:39936
	global_load_lds_dwordx4 v[202:203], off
	v_lshl_add_u64 v[202:203], s[24:25], 0, v[158:159]
	s_mov_b32 m0, s34
	s_nop 0
	global_load_lds_dwordx4 v[202:203], off
	s_waitcnt lgkmcnt(8)
	s_barrier
; #define PG8_STAGE(bufoff, gbase, voff) do { _Pragma("unroll") for (int _i = 0; _i < 2; ++_i) \
;         __builtin_amdgcn_global_load_lds((const unsigned*)((const char*)(gbase) + (voff)[_i]), (LAS unsigned*)(lds + (bufoff) + ldsw + _i * 8192), 16, 0, 0); } while (0)
; #define PG8_LDA(dst, b, h) do { _Pragma("unroll") for (int m = 0; m < 4; ++m) _Pragma("unroll") for (int k = 0; k < 2; ++k) dst[m][k] = *(const LAS bf16x8*)(lds + PG8_SA(b, h) + aoff + m * 2048 + k * 1024); } while (0)
; #define PG8_LDB(dst, b, h) do { _Pragma("unroll") for (int n = 0; n < 2; ++n) _Pragma("unroll") for (int k = 0; k < 2; ++k) dst[n][k] = *(const LAS bf16x8*)(lds + PG8_SB(b, h) + boff + n * 2048 + k * 1024); } while (0)
; #define PG8_MMA(ai, bj, At, Bt) do { __builtin_amdgcn_s_setprio(1); _Pragma("unroll") for (int m = 0; m < 4; ++m) _Pragma("unroll") for (int n = 0; n < 2; ++n) _Pragma("unroll") for (int k = 0; k < 2; ++k) \
;         acc[ai][bj][m][n] = __builtin_amdgcn_mfma_f32_16x16x32_bf16(Bt[n][k], At[m][k], acc[ai][bj][m][n], 0, 0, 0); __builtin_amdgcn_s_setprio(0); } while (0)
; #define PG8_WAIT_V(n) asm volatile("s_waitcnt vmcnt(" #n ")" ::: "memory")
; #define PG8_WAIT_L(n) asm volatile("s_waitcnt lgkmcnt(" #n ")" ::: "memory")
; #define PG8_BAR __builtin_amdgcn_s_barrier()
; #define PG8_SCHED __builtin_amdgcn_sched_barrier(0)
; template <class Epi>
; __device__ __forceinline__ void gemm_phase(LAS unsigned char* lds, const Gemm g, const StaticOrder& S, const Epi& E) {
;     ...
;             PG8_WAIT_L(8); PG8_BAR; PG8_WAIT_L(0); PG8_MMA(0, 0, At, B0); PG8_BAR; PG8_SCHED;
;             PG8_LDB(B1, 1, 1); PG8_STAGE(PG8_SB(1, 0), b3, voffB);
;             PG8_BAR; PG8_WAIT_L(0); PG8_MMA(0, 1, At, B1); PG8_BAR;
;             PG8_LDA(At, 1, 1); PG8_STAGE(PG8_SA(1, 0), a3, voffA);
;             PG8_BAR; PG8_WAIT_L(0); PG8_MMA(1, 0, At, B0); PG8_BAR; PG8_SCHED;
;             PG8_STAGE(PG8_SB(1, 1), b3 + hstepB, voffB);
;             PG8_WAIT_V(6); PG8_BAR; PG8_MMA(1, 1, At, B1); PG8_BAR;
	s_waitcnt lgkmcnt(0)
	s_waitcnt lgkmcnt(0)
	v_mfma_f32_16x16x32_bf16 v[124:127], v[128:131], v[144:147], v[124:127]
	v_mfma_f32_16x16x32_bf16 v[120:123], v[136:139], v[144:147], v[120:123]
	v_mfma_f32_16x16x32_bf16 v[108:111], v[128:131], v[170:173], v[108:111]
	v_mfma_f32_16x16x32_bf16 v[104:107], v[136:139], v[170:173], v[104:107]
	v_mfma_f32_16x16x32_bf16 v[92:95], v[128:131], v[178:181], v[92:95]
	v_mfma_f32_16x16x32_bf16 v[88:91], v[136:139], v[178:181], v[88:91]
	v_mfma_f32_16x16x32_bf16 v[76:79], v[128:131], v[194:197], v[76:79]
	v_mfma_f32_16x16x32_bf16 v[72:75], v[136:139], v[194:197], v[72:75]
	v_mfma_f32_16x16x32_bf16 v[124:127], v[132:135], v[148:151], v[124:127]
	v_mfma_f32_16x16x32_bf16 v[120:123], v[140:143], v[148:151], v[120:123]
	v_mfma_f32_16x16x32_bf16 v[108:111], v[132:135], v[174:177], v[108:111]
	v_mfma_f32_16x16x32_bf16 v[104:107], v[140:143], v[174:177], v[104:107]
	v_mfma_f32_16x16x32_bf16 v[92:95], v[132:135], v[182:185], v[92:95]
	v_mfma_f32_16x16x32_bf16 v[88:91], v[140:143], v[182:185], v[88:91]
	v_mfma_f32_16x16x32_bf16 v[76:79], v[132:135], v[198:201], v[76:79]
	v_mfma_f32_16x16x32_bf16 v[72:75], v[140:143], v[198:201], v[72:75]
	s_barrier
	s_add_i32 s24, 0, 0x1c000
	s_add_i32 s25, s47, s29
	v_add_u32_e32 v214, s24, v188
	v_lshl_add_u64 v[186:187], v[186:187], 0, s[14:15]
	s_mov_b32 m0, s25
	ds_read_b128 v[202:205], v214
	ds_read_b128 v[206:209], v214 offset:1024
	ds_read_b128 v[210:213], v214 offset:2048
	ds_read_b128 v[214:217], v214 offset:3072
	global_load_lds_dwordx4 v[186:187], off
	v_lshl_add_u64 v[186:187], v[218:219], 0, s[14:15]
	s_add_i32 m0, s25, 0x2000
	s_nop 0
	global_load_lds_dwordx4 v[186:187], off
	s_barrier
	s_waitcnt lgkmcnt(0)
	s_waitcnt lgkmcnt(0)
	v_mfma_f32_16x16x32_bf16 v[116:119], v[202:205], v[144:147], v[116:119]
	v_mfma_f32_16x16x32_bf16 v[112:115], v[210:213], v[144:147], v[112:115]
	v_mfma_f32_16x16x32_bf16 v[100:103], v[202:205], v[170:173], v[100:103]
	v_mfma_f32_16x16x32_bf16 v[96:99], v[210:213], v[170:173], v[96:99]
	v_mfma_f32_16x16x32_bf16 v[84:87], v[202:205], v[178:181], v[84:87]
	v_mfma_f32_16x16x32_bf16 v[80:83], v[210:213], v[178:181], v[80:83]
	v_mfma_f32_16x16x32_bf16 v[68:71], v[202:205], v[194:197], v[68:71]
	v_mfma_f32_16x16x32_bf16 v[64:67], v[210:213], v[194:197], v[64:67]
	v_mfma_f32_16x16x32_bf16 v[116:119], v[206:209], v[148:151], v[116:119]
	v_mfma_f32_16x16x32_bf16 v[112:115], v[214:217], v[148:151], v[112:115]
	v_mfma_f32_16x16x32_bf16 v[100:103], v[206:209], v[174:177], v[100:103]
	v_mfma_f32_16x16x32_bf16 v[96:99], v[214:217], v[174:177], v[96:99]
	v_mfma_f32_16x16x32_bf16 v[84:87], v[206:209], v[182:185], v[84:87]
	v_mfma_f32_16x16x32_bf16 v[80:83], v[214:217], v[182:185], v[80:83]
	v_mfma_f32_16x16x32_bf16 v[68:71], v[206:209], v[198:201], v[68:71]
	v_mfma_f32_16x16x32_bf16 v[64:67], v[214:217], v[198:201], v[64:67]
	s_mov_b32 m0, s36
	v_lshl_add_u64 v[186:187], v[220:221], 0, s[14:15]
	s_barrier
	ds_read_b128 v[144:147], v191 offset:49152
	ds_read_b128 v[148:151], v191 offset:50176
	ds_read_b128 v[170:173], v191 offset:51200
	ds_read_b128 v[174:177], v191 offset:52224
	ds_read_b128 v[178:181], v191 offset:53248
	ds_read_b128 v[182:185], v191 offset:54272
	ds_read_b128 v[194:197], v191 offset:55296
	ds_read_b128 v[198:201], v191 offset:56320
	global_load_lds_dwordx4 v[186:187], off
	v_lshl_add_u64 v[186:187], v[222:223], 0, s[14:15]
	s_mov_b32 m0, s37
	s_nop 0
	global_load_lds_dwordx4 v[186:187], off
	s_barrier
	s_waitcnt lgkmcnt(0)
	s_waitcnt lgkmcnt(0)
	v_mfma_f32_16x16x32_bf16 v[60:63], v[128:131], v[144:147], v[60:63]
	v_mfma_f32_16x16x32_bf16 v[56:59], v[136:139], v[144:147], v[56:59]
	v_mfma_f32_16x16x32_bf16 v[44:47], v[128:131], v[170:173], v[44:47]
	v_mfma_f32_16x16x32_bf16 v[40:43], v[136:139], v[170:173], v[40:43]
	v_mfma_f32_16x16x32_bf16 v[28:31], v[128:131], v[178:181], v[28:31]
	v_mfma_f32_16x16x32_bf16 v[24:27], v[136:139], v[178:181], v[24:27]
	v_mfma_f32_16x16x32_bf16 v[12:15], v[128:131], v[194:197], v[12:15]
	v_mfma_f32_16x16x32_bf16 v[8:11], v[136:139], v[194:197], v[8:11]
	v_mfma_f32_16x16x32_bf16 v[60:63], v[132:135], v[148:151], v[60:63]
	v_mfma_f32_16x16x32_bf16 v[56:59], v[140:143], v[148:151], v[56:59]
	v_mfma_f32_16x16x32_bf16 v[44:47], v[132:135], v[174:177], v[44:47]
	v_mfma_f32_16x16x32_bf16 v[40:43], v[140:143], v[174:177], v[40:43]
	v_mfma_f32_16x16x32_bf16 v[28:31], v[132:135], v[182:185], v[28:31]
	v_mfma_f32_16x16x32_bf16 v[24:27], v[140:143], v[182:185], v[24:27]
	v_mfma_f32_16x16x32_bf16 v[12:15], v[132:135], v[198:201], v[12:15]
	v_mfma_f32_16x16x32_bf16 v[8:11], v[140:143], v[198:201], v[8:11]
	s_barrier
	s_add_u32 s22, s22, 0x40080
	s_addc_u32 s23, s23, 0
	s_add_i32 s24, s24, s29
	v_lshl_add_u64 v[128:129], s[22:23], 0, v[156:157]
	s_mov_b32 m0, s24
	s_nop 0
	global_load_lds_dwordx4 v[128:129], off
	v_lshl_add_u64 v[128:129], s[22:23], 0, v[160:161]
	s_add_i32 m0, s24, 0x2000
	s_nop 0
	global_load_lds_dwordx4 v[128:129], off
	s_waitcnt vmcnt(6)
	s_barrier
	v_mfma_f32_16x16x32_bf16 v[52:55], v[202:205], v[144:147], v[52:55]
	v_mfma_f32_16x16x32_bf16 v[48:51], v[210:213], v[144:147], v[48:51]
	v_mfma_f32_16x16x32_bf16 v[36:39], v[202:205], v[170:173], v[36:39]
	v_mfma_f32_16x16x32_bf16 v[32:35], v[210:213], v[170:173], v[32:35]
	v_mfma_f32_16x16x32_bf16 v[20:23], v[202:205], v[178:181], v[20:23]
	v_mfma_f32_16x16x32_bf16 v[16:19], v[210:213], v[178:181], v[16:19]
	v_mfma_f32_16x16x32_bf16 v[4:7], v[202:205], v[194:197], v[4:7]
	v_mfma_f32_16x16x32_bf16 v[0:3], v[210:213], v[194:197], v[0:3]
	v_mfma_f32_16x16x32_bf16 v[52:55], v[206:209], v[148:151], v[52:55]
	v_mfma_f32_16x16x32_bf16 v[48:51], v[214:217], v[148:151], v[48:51]
	v_mfma_f32_16x16x32_bf16 v[36:39], v[206:209], v[174:177], v[36:39]
	v_mfma_f32_16x16x32_bf16 v[32:35], v[214:217], v[174:177], v[32:35]
	v_mfma_f32_16x16x32_bf16 v[20:23], v[206:209], v[182:185], v[20:23]
	v_mfma_f32_16x16x32_bf16 v[16:19], v[214:217], v[182:185], v[16:19]
	v_mfma_f32_16x16x32_bf16 v[4:7], v[206:209], v[198:201], v[4:7]
	v_mfma_f32_16x16x32_bf16 v[0:3], v[214:217], v[198:201], v[0:3]
	s_add_i32 s46, s46, 2
	s_add_u32 s4, s4, 0x100
	s_addc_u32 s5, s5, 0
	s_add_u32 s44, s44, 0x100
	s_addc_u32 s45, s45, 0
	s_cmp_gt_u32 s46, 13
	s_barrier
; __device__ __forceinline__ unsigned pk2(float lo, float hi) { const f32x2 v = (f32x2){lo, hi}; const bf16x2_t b = __builtin_convertvector(v, bf16x2_t); return __builtin_bit_cast(unsigned, b); }
; __device__ __forceinline__ void unpack8(const u32x4 v, float* f) { f[0] = bf_lo(v.x); f[1] = bf_hi(v.x); f[2] = bf_lo(v.y); f[3] = bf_hi(v.y); f[4] = bf_lo(v.z); f[5] = bf_hi(v.z); f[6] = bf_lo(v.w); f[7] = bf_hi(v.w); }
;     __device__ __forceinline__ void operator()(const f32x4 (&acc)[2][2][4][2], const Unit& u, int wr, int wc, int fr, int fq, const float (&)[8]) const {
;         const int row0 = u.pm * BM + wr * 64 + fr, col0 = u.pn * BM + wc * 32 + 8 * fq;
; #pragma unroll
;         for (int ai = 0; ai < 2; ++ai) {
;             u32x4 bv[4][2];
; #pragma unroll
;             for (int m = 0; m < 4; ++m)
; #pragma unroll
;                 for (int bj = 0; bj < 2; ++bj) bv[m][bj] = *(const u32x4*)(xb + (size_t)(row0 + ai * HALF + m * 16) * DM + col0 + bj * HALF);
; #pragma unroll
;             for (int m = 0; m < 4; ++m) { const int row = row0 + ai * HALF + m * 16; const size_t ro = (size_t)row * DM + col0; float s = 0.f;
; #pragma unroll
;                 for (int bj = 0; bj < 2; ++bj) { float b8[8]; unpack8(bv[m][bj], b8);
;                     const f32x4 v0 = (f32x4){b8[0], b8[1], b8[2], b8[3]} + acc[ai][bj][m][0], v1 = (f32x4){b8[4], b8[5], b8[6], b8[7]} + acc[ai][bj][m][1];
;                     s += v0[0] * v0[0] + v0[1] * v0[1] + v0[2] * v0[2] + v0[3] * v0[3] + v1[0] * v1[0] + v1[1] * v1[1] + v1[2] * v1[2] + v1[3] * v1[3];
;                     if (LAST) { *(f32x4*)(out + ro + bj * HALF) = v0; *(f32x4*)(out + ro + bj * HALF + 4) = v1; }
;                     else { u32x4 w; w.x = pk2(v0[0], v0[1]); w.y = pk2(v0[2], v0[3]); w.z = pk2(v1[0], v1[1]); w.w = pk2(v1[2], v1[3]); *(u32x4*)(xb + ro + bj * HALF) = w; } }
;                 s += __shfl_xor(s, 16); s += __shfl_xor(s, 32);
;                 if (fq == 0) ss[(size_t)row * 16 + u.pn * 4 + wc] = s; }
	s_cbranch_scc0 .LBB0_1118
	v_lshl_or_b32 v170, s8, 8, v189
	v_lshl_add_u32 v172, s10, 8, v153
	v_ashrrev_i32_e32 v171, 31, v170
	v_lshlrev_b64 v[204:205], 1, v[170:171]
	v_ashrrev_i32_e32 v173, 31, v172
	v_lshl_add_u64 v[174:175], s[76:77], 0, v[204:205]
	v_lshlrev_b64 v[206:207], 11, v[172:173]
	v_lshl_add_u64 v[128:129], v[174:175], 0, v[206:207]
	global_load_dwordx4 v[196:199], v[128:129], off
	global_load_dwordx4 v[200:203], v[128:129], off offset:256
	v_or_b32_e32 v184, 16, v172
	v_or_b32_e32 v180, 32, v172
	v_or_b32_e32 v176, 48, v172
	v_ashrrev_i32_e32 v185, 31, v184
	v_ashrrev_i32_e32 v181, 31, v180
	v_ashrrev_i32_e32 v177, 31, v176
	v_lshlrev_b64 v[186:187], 11, v[184:185]
	v_lshlrev_b64 v[182:183], 11, v[180:181]
	v_lshlrev_b64 v[178:179], 11, v[176:177]
	v_lshl_add_u64 v[128:129], v[174:175], 0, v[186:187]
	v_lshl_add_u64 v[130:131], v[174:175], 0, v[182:183]
	v_lshl_add_u64 v[194:195], v[174:175], 0, v[178:179]
	global_load_dwordx4 v[148:151], v[128:129], off
	global_load_dwordx4 v[144:147], v[128:129], off offset:256
	global_load_dwordx4 v[140:143], v[130:131], off
	global_load_dwordx4 v[136:139], v[130:131], off offset:256
	global_load_dwordx4 v[132:135], v[194:195], off
	s_nop 0
	global_load_dwordx4 v[128:131], v[194:195], off offset:256
	v_add_u32_e32 v226, 0x80, v172
	v_ashrrev_i32_e32 v227, 31, v226
	v_lshlrev_b64 v[226:227], 11, v[226:227]
	v_lshl_add_u64 v[226:227], v[174:175], 0, v[226:227]
	global_load_dwordx4 v[216:219], v[226:227], off
	global_load_dwordx4 v[220:223], v[226:227], off offset:256
	v_add_u32_e32 v226, 0x90, v172
	v_ashrrev_i32_e32 v227, 31, v226
	v_lshlrev_b64 v[226:227], 11, v[226:227]
	v_lshl_add_u64 v[226:227], v[174:175], 0, v[226:227]
	global_load_dwordx4 v[228:231], v[226:227], off
	global_load_dwordx4 v[232:235], v[226:227], off offset:256
	v_add_u32_e32 v226, 0xa0, v172
	v_ashrrev_i32_e32 v227, 31, v226
	v_lshlrev_b64 v[226:227], 11, v[226:227]
	v_lshl_add_u64 v[226:227], v[174:175], 0, v[226:227]
	global_load_dwordx4 v[236:239], v[226:227], off
	global_load_dwordx4 v[240:243], v[226:227], off offset:256
	v_add_u32_e32 v226, 0xb0, v172
	v_ashrrev_i32_e32 v227, 31, v226
	v_lshlrev_b64 v[226:227], 11, v[226:227]
	v_lshl_add_u64 v[226:227], v[174:175], 0, v[226:227]
	global_load_dwordx4 v[244:247], v[226:227], off
	global_load_dwordx4 v[252:255], v[226:227], off offset:256
	v_and_b32_e32 v195, 64, v193
	v_xor_b32_e32 v194, 16, v193
	v_add_u32_e32 v195, 64, v195
	v_xor_b32_e32 v208, 32, v193
	v_cmp_lt_i32_e32 vcc, v194, v195
	s_waitcnt vmcnt(15)
	v_and_b32_e32 v209, 0xffff0000, v196
	v_cndmask_b32_e32 v194, v193, v194, vcc
	v_cmp_lt_i32_e32 vcc, v208, v195
	v_lshlrev_b32_e32 v195, 2, v194
	s_waitcnt vmcnt(14)
	v_lshlrev_b32_e32 v212, 16, v200
	v_cndmask_b32_e32 v208, v193, v208, vcc
	v_lshlrev_b32_e32 v194, 2, v208
	v_lshlrev_b32_e32 v208, 16, v196
	v_and_b32_e32 v213, 0xffff0000, v200
	v_lshlrev_b32_e32 v210, 16, v198
	v_and_b32_e32 v211, 0xffff0000, v198
	v_lshlrev_b32_e32 v198, 16, v199
	v_and_b32_e32 v199, 0xffff0000, v199
	v_lshlrev_b32_e32 v200, 16, v201
	v_and_b32_e32 v201, 0xffff0000, v201
	v_lshlrev_b32_e32 v214, 16, v202
	v_and_b32_e32 v215, 0xffff0000, v202
	v_pk_add_f32 v[124:125], v[124:125], v[208:209]
	v_pk_add_f32 v[116:117], v[116:117], v[212:213]
	v_lshlrev_b32_e32 v196, 16, v197
	v_and_b32_e32 v197, 0xffff0000, v197
	v_pk_add_f32 v[122:123], v[122:123], v[198:199]
	v_pk_add_f32 v[118:119], v[118:119], v[200:201]
	v_pk_add_f32 v[198:199], v[112:113], v[214:215]
	v_mul_f32_e32 v200, v125, v125
	v_cvt_pk_bf16_f32 v112, v124, v125
	v_mul_f32_e32 v125, v117, v117
	v_pk_add_f32 v[126:127], v[126:127], v[196:197]
	v_fmac_f32_e32 v200, v124, v124
	v_fmac_f32_e32 v125, v116, v116
	v_fmac_f32_e32 v200, v126, v126
	v_fmac_f32_e32 v125, v118, v118
	v_pk_add_f32 v[120:121], v[120:121], v[210:211]
	v_fmac_f32_e32 v200, v127, v127
	v_fmac_f32_e32 v125, v119, v119
	v_lshlrev_b32_e32 v202, 16, v203
	v_and_b32_e32 v203, 0xffff0000, v203
	v_fmac_f32_e32 v200, v120, v120
	v_fmac_f32_e32 v125, v198, v198
	v_pk_add_f32 v[196:197], v[114:115], v[202:203]
	v_fmac_f32_e32 v200, v121, v121
	v_fmac_f32_e32 v125, v199, v199
	v_fmac_f32_e32 v200, v122, v122
	v_fmac_f32_e32 v125, v196, v196
	v_fmac_f32_e32 v200, v123, v123
	v_fmac_f32_e32 v125, v197, v197
	v_cvt_pk_bf16_f32 v115, v122, v123
	v_add_f32_e32 v122, v200, v125
	ds_bpermute_b32 v123, v195, v122
	v_cvt_pk_bf16_f32 v114, v120, v121
	v_lshl_add_u64 v[120:121], s[76:77], 0, v[206:207]
	v_cvt_pk_bf16_f32 v113, v126, v127
	v_lshl_add_u64 v[120:121], v[120:121], 0, v[204:205]
	global_store_dwordx4 v[120:121], v[112:115], off
	s_waitcnt lgkmcnt(0)
	s_nop 0
	v_add_f32_e32 v112, v122, v123
	ds_bpermute_b32 v113, v194, v112
	v_cvt_pk_bf16_f32 v114, v116, v117
	v_cvt_pk_bf16_f32 v115, v118, v119
	v_cvt_pk_bf16_f32 v116, v198, v199
	v_cvt_pk_bf16_f32 v117, v196, v197
	global_store_dwordx4 v[120:121], v[114:117], off offset:256
	s_and_saveexec_b64 s[4:5], s[0:1]
	s_cbranch_execz .LBB0_1121
	s_waitcnt lgkmcnt(0)
	v_add_f32_e32 v114, v112, v113
	s_lshl_b32 s22, s8, 2
	v_lshlrev_b64 v[112:113], 6, v[172:173]
	s_ashr_i32 s23, s22, 31
	v_lshl_add_u64 v[112:113], s[12:13], 0, v[112:113]
	v_lshl_add_u64 v[112:113], s[22:23], 2, v[112:113]
	s_lshl_b32 s10, s35, 2
	v_lshl_add_u64 v[112:113], v[112:113], 0, s[10:11]
	global_store_dword v[112:113], v114, off

; #define PG8_STAGE(bufoff, gbase, voff) do { _Pragma("unroll") for (int _i = 0; _i < 2; ++_i) \
;         __builtin_amdgcn_global_load_lds((const unsigned*)((const char*)(gbase) + (voff)[_i]), (LAS unsigned*)(lds + (bufoff) + ldsw + _i * 8192), 16, 0, 0); } while (0)
; #define PG8_LDA(dst, b, h) do { _Pragma("unroll") for (int m = 0; m < 4; ++m) _Pragma("unroll") for (int k = 0; k < 2; ++k) dst[m][k] = *(const LAS bf16x8*)(lds + PG8_SA(b, h) + aoff + m * 2048 + k * 1024); } while (0)
; #define PG8_LDB(dst, b, h) do { _Pragma("unroll") for (int n = 0; n < 2; ++n) _Pragma("unroll") for (int k = 0; k < 2; ++k) dst[n][k] = *(const LAS bf16x8*)(lds + PG8_SB(b, h) + boff + n * 2048 + k * 1024); } while (0)
; #define PG8_WAIT_V(n) asm volatile("s_waitcnt vmcnt(" #n ")" ::: "memory")
; #define PG8_WAIT_L(n) asm volatile("s_waitcnt lgkmcnt(" #n ")" ::: "memory")
; #define PG8_BAR __builtin_amdgcn_s_barrier()
; #define PG8_SCHED __builtin_amdgcn_sched_barrier(0)
; template <class Epi>
; __device__ __forceinline__ void gemm_phase(LAS unsigned char* lds, const Gemm g, const StaticOrder& S, const Epi& E) {
;     ...
;         const bool has_next = S.next(ui + 1, nxt);
;         const char* nA = has_next ? (const char*)g.A + (size_t)nxt.pm * tstepA : cA; const char* nB = has_next ? (const char*)g.Bt + (size_t)nxt.pn * tstepB : cB;
;         for (int t = 0; t < nt; t += 2) {
;             const bool last = (t == nt - 2);
;             const char* a1 = cA + (size_t)(t + 1) * kstep;
;             const char* a2 = last ? nA : cA + (size_t)(t + 2) * kstep; const char* b2 = last ? nB : cB + (size_t)(t + 2) * kstep;
;             const char* a3 = a2 + kstep; const char* b3 = b2 + kstep;
;             if (last) E.pre(cur, wr, fr, epre);
;             PG8_LDB(B0, 0, 0); PG8_SCHED; PG8_LDA(At, 0, 0); PG8_STAGE(PG8_SA(1, 1), a1 + hstepA, voffA);
;             PG8_WAIT_L(8); PG8_BAR; PG8_WAIT_L(0); PG8_MMA(0, 0, At, B0); PG8_BAR; PG8_SCHED;
;             PG8_LDB(B1, 0, 1); PG8_STAGE(PG8_SB(0, 0), b2, voffB);
;             PG8_BAR; PG8_WAIT_L(0); PG8_MMA(0, 1, At, B1); PG8_BAR;
;             PG8_LDA(At, 0, 1); PG8_STAGE(PG8_SA(0, 0), a2, voffA);
;             PG8_BAR; PG8_WAIT_L(0); PG8_MMA(1, 0, At, B0); PG8_BAR; PG8_SCHED;
;             PG8_STAGE(PG8_SB(0, 1), b2 + hstepB, voffB);
;             PG8_WAIT_V(6); PG8_BAR; PG8_MMA(1, 1, At, B1); PG8_BAR;
.LBB0_1203:
	s_ashr_i32 s13, s12, 31
	v_cmp_lt_i64_e32 vcc, s[14:15], v[142:143]
	s_lshl_b64 s[14:15], s[12:13], 19
	s_add_u32 s14, s76, s14
	s_addc_u32 s15, s77, s15
	s_and_b64 s[16:17], vcc, exec
	s_cselect_b32 s13, s15, s21
	s_cselect_b32 s41, s14, s20
	s_ashr_i32 s11, s10, 31
	s_lshl_b64 s[16:17], s[10:11], 19
	s_add_u32 s16, s26, s16
	s_addc_u32 s17, s27, s17
	s_and_b64 s[24:25], vcc, exec
	s_cselect_b32 s11, s17, s23
	s_cselect_b32 s42, s16, s22
	s_add_u32 s20, s20, 0x40080
	s_addc_u32 s21, s21, 0
	s_add_u32 s43, s22, 0x100
	s_addc_u32 s44, s23, 0
	s_mov_b32 s45, -2
	ds_read_b128 v[146:149], v176
	ds_read_b128 v[154:157], v176 offset:1024
	ds_read_b128 v[158:161], v176 offset:2048
	ds_read_b128 v[162:165], v176 offset:3072
	s_add_u32 s22, s20, 0xfffc0080
	s_addc_u32 s23, s21, -1
	s_cmp_eq_u32 s45, 12
	s_cselect_b32 s25, s13, s23
	s_cselect_b32 s24, s41, s22
	s_cselect_b32 s23, s11, s44
	s_cselect_b32 s22, s42, s43
	v_lshl_add_u64 v[150:151], s[20:21], 0, v[138:139]
	s_add_i32 m0, s19, 0xc000
	ds_read_b128 v[166:169], v177
	ds_read_b128 v[170:173], v177 offset:1024
	ds_read_b128 v[180:183], v177 offset:2048
	ds_read_b128 v[184:187], v177 offset:3072
	ds_read_b128 v[188:191], v177 offset:4096
	ds_read_b128 v[192:195], v177 offset:5120
	ds_read_b128 v[196:199], v177 offset:6144
	ds_read_b128 v[200:203], v177 offset:7168
	global_load_lds_dwordx4 v[150:151], off
	v_lshl_add_u64 v[150:151], s[20:21], 0, v[140:141]
	s_add_i32 m0, s19, 0xe000
	s_nop 0
	global_load_lds_dwordx4 v[150:151], off
	s_waitcnt lgkmcnt(8)
	s_barrier
	s_waitcnt lgkmcnt(0)
	s_waitcnt lgkmcnt(0)
	v_mfma_f32_16x16x32_bf16 v[124:127], v[146:149], v[166:169], 0
	v_mfma_f32_16x16x32_bf16 v[120:123], v[158:161], v[166:169], 0
	v_mfma_f32_16x16x32_bf16 v[108:111], v[146:149], v[180:183], 0
	v_mfma_f32_16x16x32_bf16 v[104:107], v[158:161], v[180:183], 0
	v_mfma_f32_16x16x32_bf16 v[92:95], v[146:149], v[188:191], 0
	v_mfma_f32_16x16x32_bf16 v[88:91], v[158:161], v[188:191], 0
	v_mfma_f32_16x16x32_bf16 v[76:79], v[146:149], v[196:199], 0
	v_mfma_f32_16x16x32_bf16 v[72:75], v[158:161], v[196:199], 0
	v_mfma_f32_16x16x32_bf16 v[124:127], v[154:157], v[170:173], v[124:127]
	v_mfma_f32_16x16x32_bf16 v[120:123], v[162:165], v[170:173], v[120:123]
	v_mfma_f32_16x16x32_bf16 v[108:111], v[154:157], v[184:187], v[108:111]
	v_mfma_f32_16x16x32_bf16 v[104:107], v[162:165], v[184:187], v[104:107]
	v_mfma_f32_16x16x32_bf16 v[92:95], v[154:157], v[192:195], v[92:95]
	v_mfma_f32_16x16x32_bf16 v[88:91], v[162:165], v[192:195], v[88:91]
	v_mfma_f32_16x16x32_bf16 v[76:79], v[154:157], v[200:203], v[76:79]
	v_mfma_f32_16x16x32_bf16 v[72:75], v[162:165], v[200:203], v[72:75]
	s_barrier
	s_add_i32 s46, s37, s28
	v_lshl_add_u64 v[150:151], s[22:23], 0, v[130:131]
	s_mov_b32 m0, s46
	ds_read_b128 v[204:207], v178
	ds_read_b128 v[208:211], v178 offset:1024
	ds_read_b128 v[212:215], v178 offset:2048
	ds_read_b128 v[216:219], v178 offset:3072
	global_load_lds_dwordx4 v[150:151], off
	v_lshl_add_u64 v[220:221], s[22:23], 0, v[134:135]
	s_add_i32 m0, s46, 0x2000
	s_nop 0
	global_load_lds_dwordx4 v[220:221], off
	s_barrier
	s_waitcnt lgkmcnt(0)
	s_waitcnt lgkmcnt(0)
	v_mfma_f32_16x16x32_bf16 v[116:119], v[204:207], v[166:169], 0
	v_mfma_f32_16x16x32_bf16 v[112:115], v[212:215], v[166:169], 0
	v_mfma_f32_16x16x32_bf16 v[100:103], v[204:207], v[180:183], 0
	v_mfma_f32_16x16x32_bf16 v[96:99], v[212:215], v[180:183], 0
	v_mfma_f32_16x16x32_bf16 v[84:87], v[204:207], v[188:191], 0
	v_mfma_f32_16x16x32_bf16 v[80:83], v[212:215], v[188:191], 0
	v_mfma_f32_16x16x32_bf16 v[68:71], v[204:207], v[196:199], 0
	v_mfma_f32_16x16x32_bf16 v[64:67], v[212:215], v[196:199], 0
	v_mfma_f32_16x16x32_bf16 v[116:119], v[208:211], v[170:173], v[116:119]
	v_mfma_f32_16x16x32_bf16 v[112:115], v[216:219], v[170:173], v[112:115]
	v_mfma_f32_16x16x32_bf16 v[100:103], v[208:211], v[184:187], v[100:103]
	v_mfma_f32_16x16x32_bf16 v[96:99], v[216:219], v[184:187], v[96:99]
	v_mfma_f32_16x16x32_bf16 v[84:87], v[208:211], v[192:195], v[84:87]
	v_mfma_f32_16x16x32_bf16 v[80:83], v[216:219], v[192:195], v[80:83]
	v_mfma_f32_16x16x32_bf16 v[68:71], v[208:211], v[200:203], v[68:71]
	v_mfma_f32_16x16x32_bf16 v[64:67], v[216:219], v[200:203], v[64:67]
	s_mov_b32 m0, s19
	v_lshl_add_u64 v[222:223], s[24:25], 0, v[128:129]
	s_barrier
	ds_read_b128 v[166:169], v177 offset:16384
	ds_read_b128 v[170:173], v177 offset:17408
	ds_read_b128 v[180:183], v177 offset:18432
	ds_read_b128 v[184:187], v177 offset:19456
	ds_read_b128 v[188:191], v177 offset:20480
	ds_read_b128 v[192:195], v177 offset:21504
	ds_read_b128 v[196:199], v177 offset:22528
	ds_read_b128 v[200:203], v177 offset:23552
	global_load_lds_dwordx4 v[222:223], off
	v_lshl_add_u64 v[224:225], s[24:25], 0, v[132:133]
	s_mov_b32 m0, s29
	s_nop 0
	global_load_lds_dwordx4 v[224:225], off
	s_barrier
	s_waitcnt lgkmcnt(0)
	s_waitcnt lgkmcnt(0)
	v_mfma_f32_16x16x32_bf16 v[60:63], v[146:149], v[166:169], 0
	v_mfma_f32_16x16x32_bf16 v[56:59], v[158:161], v[166:169], 0
	v_mfma_f32_16x16x32_bf16 v[44:47], v[146:149], v[180:183], 0
	v_mfma_f32_16x16x32_bf16 v[40:43], v[158:161], v[180:183], 0
	v_mfma_f32_16x16x32_bf16 v[28:31], v[146:149], v[188:191], 0
	v_mfma_f32_16x16x32_bf16 v[24:27], v[158:161], v[188:191], 0
	v_mfma_f32_16x16x32_bf16 v[12:15], v[146:149], v[196:199], 0
	v_mfma_f32_16x16x32_bf16 v[8:11], v[158:161], v[196:199], 0
	v_mfma_f32_16x16x32_bf16 v[60:63], v[154:157], v[170:173], v[60:63]
	v_mfma_f32_16x16x32_bf16 v[56:59], v[162:165], v[170:173], v[56:59]
	v_mfma_f32_16x16x32_bf16 v[44:47], v[154:157], v[184:187], v[44:47]
	v_mfma_f32_16x16x32_bf16 v[40:43], v[162:165], v[184:187], v[40:43]
	v_mfma_f32_16x16x32_bf16 v[28:31], v[154:157], v[192:195], v[28:31]
	v_mfma_f32_16x16x32_bf16 v[24:27], v[162:165], v[192:195], v[24:27]
	v_mfma_f32_16x16x32_bf16 v[12:15], v[154:157], v[200:203], v[12:15]
	v_mfma_f32_16x16x32_bf16 v[8:11], v[162:165], v[200:203], v[8:11]
	s_barrier
; #define PG8_STAGE(bufoff, gbase, voff) do { _Pragma("unroll") for (int _i = 0; _i < 2; ++_i) \
;         __builtin_amdgcn_global_load_lds((const unsigned*)((const char*)(gbase) + (voff)[_i]), (LAS unsigned*)(lds + (bufoff) + ldsw + _i * 8192), 16, 0, 0); } while (0)
; #define PG8_LDA(dst, b, h) do { _Pragma("unroll") for (int m = 0; m < 4; ++m) _Pragma("unroll") for (int k = 0; k < 2; ++k) dst[m][k] = *(const LAS bf16x8*)(lds + PG8_SA(b, h) + aoff + m * 2048 + k * 1024); } while (0)
; #define PG8_LDB(dst, b, h) do { _Pragma("unroll") for (int n = 0; n < 2; ++n) _Pragma("unroll") for (int k = 0; k < 2; ++k) dst[n][k] = *(const LAS bf16x8*)(lds + PG8_SB(b, h) + boff + n * 2048 + k * 1024); } while (0)
; #define PG8_MMA(ai, bj, At, Bt) do { __builtin_amdgcn_s_setprio(1); _Pragma("unroll") for (int m = 0; m < 4; ++m) _Pragma("unroll") for (int n = 0; n < 2; ++n) _Pragma("unroll") for (int k = 0; k < 2; ++k) \
;         acc[ai][bj][m][n] = __builtin_amdgcn_mfma_f32_16x16x32_bf16(Bt[n][k], At[m][k], acc[ai][bj][m][n], 0, 0, 0); __builtin_amdgcn_s_setprio(0); } while (0)
; #define PG8_WAIT_V(n) asm volatile("s_waitcnt vmcnt(" #n ")" ::: "memory")
; #define PG8_WAIT_L(n) asm volatile("s_waitcnt lgkmcnt(" #n ")" ::: "memory")
; #define PG8_BAR __builtin_amdgcn_s_barrier()
; #define PG8_SCHED __builtin_amdgcn_sched_barrier(0)
; template <class Epi>
; __device__ __forceinline__ void gemm_phase(LAS unsigned char* lds, const Gemm g, const StaticOrder& S, const Epi& E) {
;     ...
;             PG8_BAR; PG8_WAIT_L(0); PG8_MMA(1, 0, At, B0); PG8_BAR; PG8_SCHED;
;             PG8_STAGE(PG8_SB(0, 1), b2 + hstepB, voffB);
;             PG8_WAIT_V(6); PG8_BAR; PG8_MMA(1, 1, At, B1); PG8_BAR;
;             PG8_LDB(B0, 1, 0); PG8_SCHED; PG8_LDA(At, 1, 0); PG8_STAGE(PG8_SA(0, 1), a2 + hstepA, voffA);
;             PG8_WAIT_L(8); PG8_BAR; PG8_WAIT_L(0); PG8_MMA(0, 0, At, B0); PG8_BAR; PG8_SCHED;
;             PG8_LDB(B1, 1, 1); PG8_STAGE(PG8_SB(1, 0), b3, voffB);
;             PG8_BAR; PG8_WAIT_L(0); PG8_MMA(0, 1, At, B1); PG8_BAR;
;             PG8_LDA(At, 1, 1); PG8_STAGE(PG8_SA(1, 0), a3, voffA);
;             PG8_BAR; PG8_WAIT_L(0); PG8_MMA(1, 0, At, B0); PG8_BAR; PG8_SCHED;
	s_add_u32 s46, s22, 0x40000
	s_addc_u32 s47, s23, 0
	s_add_i32 s48, s38, s28
	v_lshl_add_u64 v[146:147], s[46:47], 0, v[130:131]
	s_mov_b32 m0, s48
	s_nop 0
	global_load_lds_dwordx4 v[146:147], off
	v_lshl_add_u64 v[146:147], s[46:47], 0, v[134:135]
	s_add_i32 m0, s48, 0x2000
	s_nop 0
	global_load_lds_dwordx4 v[146:147], off
	s_waitcnt vmcnt(6)
	s_barrier
	v_mfma_f32_16x16x32_bf16 v[52:55], v[204:207], v[166:169], 0
	v_mfma_f32_16x16x32_bf16 v[48:51], v[212:215], v[166:169], 0
	v_mfma_f32_16x16x32_bf16 v[36:39], v[204:207], v[180:183], 0
	v_mfma_f32_16x16x32_bf16 v[32:35], v[212:215], v[180:183], 0
	v_mfma_f32_16x16x32_bf16 v[20:23], v[204:207], v[188:191], 0
	v_mfma_f32_16x16x32_bf16 v[16:19], v[212:215], v[188:191], 0
	v_mfma_f32_16x16x32_bf16 v[4:7], v[204:207], v[196:199], 0
	v_mfma_f32_16x16x32_bf16 v[0:3], v[212:215], v[196:199], 0
	v_mfma_f32_16x16x32_bf16 v[52:55], v[208:211], v[170:173], v[52:55]
	v_mfma_f32_16x16x32_bf16 v[48:51], v[216:219], v[170:173], v[48:51]
	v_mfma_f32_16x16x32_bf16 v[36:39], v[208:211], v[184:187], v[36:39]
	v_mfma_f32_16x16x32_bf16 v[32:35], v[216:219], v[184:187], v[32:35]
	v_mfma_f32_16x16x32_bf16 v[20:23], v[208:211], v[192:195], v[20:23]
	v_mfma_f32_16x16x32_bf16 v[16:19], v[216:219], v[192:195], v[16:19]
	v_mfma_f32_16x16x32_bf16 v[4:7], v[208:211], v[200:203], v[4:7]
	v_mfma_f32_16x16x32_bf16 v[0:3], v[216:219], v[200:203], v[0:3]
	s_add_i32 s46, 0, 0x18000
	v_add_u32_e32 v162, s46, v174
	s_barrier
	ds_read_b128 v[146:149], v162
	ds_read_b128 v[154:157], v162 offset:1024
	ds_read_b128 v[158:161], v162 offset:2048
	ds_read_b128 v[162:165], v162 offset:3072
	s_add_u32 s24, s24, 0x40000
	s_addc_u32 s25, s25, 0
	s_mov_b32 m0, s30
	v_lshl_add_u64 v[204:205], s[24:25], 0, v[128:129]
	ds_read_b128 v[166:169], v177 offset:32768
	ds_read_b128 v[170:173], v177 offset:33792
	ds_read_b128 v[180:183], v177 offset:34816
	ds_read_b128 v[184:187], v177 offset:35840
	ds_read_b128 v[188:191], v177 offset:36864
	ds_read_b128 v[192:195], v177 offset:37888
	ds_read_b128 v[196:199], v177 offset:38912
	ds_read_b128 v[200:203], v177 offset:39936
	global_load_lds_dwordx4 v[204:205], off
	v_lshl_add_u64 v[204:205], s[24:25], 0, v[132:133]
	s_mov_b32 m0, s31
	s_nop 0
	global_load_lds_dwordx4 v[204:205], off
	s_waitcnt lgkmcnt(8)
	s_barrier
	s_waitcnt lgkmcnt(0)
	s_waitcnt lgkmcnt(0)
	v_mfma_f32_16x16x32_bf16 v[124:127], v[146:149], v[166:169], v[124:127]
	v_mfma_f32_16x16x32_bf16 v[120:123], v[158:161], v[166:169], v[120:123]
	v_mfma_f32_16x16x32_bf16 v[108:111], v[146:149], v[180:183], v[108:111]
	v_mfma_f32_16x16x32_bf16 v[104:107], v[158:161], v[180:183], v[104:107]
	v_mfma_f32_16x16x32_bf16 v[92:95], v[146:149], v[188:191], v[92:95]
	v_mfma_f32_16x16x32_bf16 v[88:91], v[158:161], v[188:191], v[88:91]
	v_mfma_f32_16x16x32_bf16 v[76:79], v[146:149], v[196:199], v[76:79]
	v_mfma_f32_16x16x32_bf16 v[72:75], v[158:161], v[196:199], v[72:75]
	v_mfma_f32_16x16x32_bf16 v[124:127], v[154:157], v[170:173], v[124:127]
	v_mfma_f32_16x16x32_bf16 v[120:123], v[162:165], v[170:173], v[120:123]
	v_mfma_f32_16x16x32_bf16 v[108:111], v[154:157], v[184:187], v[108:111]
	v_mfma_f32_16x16x32_bf16 v[104:107], v[162:165], v[184:187], v[104:107]
	v_mfma_f32_16x16x32_bf16 v[92:95], v[154:157], v[192:195], v[92:95]
	v_mfma_f32_16x16x32_bf16 v[88:91], v[162:165], v[192:195], v[88:91]
	v_mfma_f32_16x16x32_bf16 v[76:79], v[154:157], v[200:203], v[76:79]
	v_mfma_f32_16x16x32_bf16 v[72:75], v[162:165], v[200:203], v[72:75]
	s_barrier
	s_add_i32 s24, 0, 0x1c000
	s_add_i32 s25, s46, s28
	v_add_u32_e32 v216, s24, v174
	v_lshl_add_u64 v[150:151], v[150:151], 0, s[4:5]
	s_mov_b32 m0, s25
	ds_read_b128 v[204:207], v216
	ds_read_b128 v[208:211], v216 offset:1024
	ds_read_b128 v[212:215], v216 offset:2048
	ds_read_b128 v[216:219], v216 offset:3072
	global_load_lds_dwordx4 v[150:151], off
	v_lshl_add_u64 v[150:151], v[220:221], 0, s[4:5]
	s_add_i32 m0, s25, 0x2000
	s_nop 0
	global_load_lds_dwordx4 v[150:151], off
	s_barrier
	s_waitcnt lgkmcnt(0)
	s_waitcnt lgkmcnt(0)
	v_mfma_f32_16x16x32_bf16 v[116:119], v[204:207], v[166:169], v[116:119]
	v_mfma_f32_16x16x32_bf16 v[112:115], v[212:215], v[166:169], v[112:115]
	v_mfma_f32_16x16x32_bf16 v[100:103], v[204:207], v[180:183], v[100:103]
	v_mfma_f32_16x16x32_bf16 v[96:99], v[212:215], v[180:183], v[96:99]
	v_mfma_f32_16x16x32_bf16 v[84:87], v[204:207], v[188:191], v[84:87]
	v_mfma_f32_16x16x32_bf16 v[80:83], v[212:215], v[188:191], v[80:83]
	v_mfma_f32_16x16x32_bf16 v[68:71], v[204:207], v[196:199], v[68:71]
	v_mfma_f32_16x16x32_bf16 v[64:67], v[212:215], v[196:199], v[64:67]
	v_mfma_f32_16x16x32_bf16 v[116:119], v[208:211], v[170:173], v[116:119]
	v_mfma_f32_16x16x32_bf16 v[112:115], v[216:219], v[170:173], v[112:115]
	v_mfma_f32_16x16x32_bf16 v[100:103], v[208:211], v[184:187], v[100:103]
	v_mfma_f32_16x16x32_bf16 v[96:99], v[216:219], v[184:187], v[96:99]
	v_mfma_f32_16x16x32_bf16 v[84:87], v[208:211], v[192:195], v[84:87]
	v_mfma_f32_16x16x32_bf16 v[80:83], v[216:219], v[192:195], v[80:83]
	v_mfma_f32_16x16x32_bf16 v[68:71], v[208:211], v[200:203], v[68:71]
	v_mfma_f32_16x16x32_bf16 v[64:67], v[216:219], v[200:203], v[64:67]
	s_mov_b32 m0, s34
	v_lshl_add_u64 v[150:151], v[222:223], 0, s[4:5]
	s_barrier
	ds_read_b128 v[166:169], v177 offset:49152
	ds_read_b128 v[170:173], v177 offset:50176
	ds_read_b128 v[180:183], v177 offset:51200
	ds_read_b128 v[184:187], v177 offset:52224
	ds_read_b128 v[188:191], v177 offset:53248
	ds_read_b128 v[192:195], v177 offset:54272
	ds_read_b128 v[196:199], v177 offset:55296
	ds_read_b128 v[200:203], v177 offset:56320
	global_load_lds_dwordx4 v[150:151], off
	v_lshl_add_u64 v[150:151], v[224:225], 0, s[4:5]
	s_mov_b32 m0, s35
	s_nop 0
	global_load_lds_dwordx4 v[150:151], off
	s_barrier
; #define PG8_STAGE(bufoff, gbase, voff) do { _Pragma("unroll") for (int _i = 0; _i < 2; ++_i) \
;         __builtin_amdgcn_global_load_lds((const unsigned*)((const char*)(gbase) + (voff)[_i]), (LAS unsigned*)(lds + (bufoff) + ldsw + _i * 8192), 16, 0, 0); } while (0)
; #define PG8_LDA(dst, b, h) do { _Pragma("unroll") for (int m = 0; m < 4; ++m) _Pragma("unroll") for (int k = 0; k < 2; ++k) dst[m][k] = *(const LAS bf16x8*)(lds + PG8_SA(b, h) + aoff + m * 2048 + k * 1024); } while (0)
; #define PG8_LDB(dst, b, h) do { _Pragma("unroll") for (int n = 0; n < 2; ++n) _Pragma("unroll") for (int k = 0; k < 2; ++k) dst[n][k] = *(const LAS bf16x8*)(lds + PG8_SB(b, h) + boff + n * 2048 + k * 1024); } while (0)
; #define PG8_MMA(ai, bj, At, Bt) do { __builtin_amdgcn_s_setprio(1); _Pragma("unroll") for (int m = 0; m < 4; ++m) _Pragma("unroll") for (int n = 0; n < 2; ++n) _Pragma("unroll") for (int k = 0; k < 2; ++k) \
;         acc[ai][bj][m][n] = __builtin_amdgcn_mfma_f32_16x16x32_bf16(Bt[n][k], At[m][k], acc[ai][bj][m][n], 0, 0, 0); __builtin_amdgcn_s_setprio(0); } while (0)
; #define PG8_WAIT_V(n) asm volatile("s_waitcnt vmcnt(" #n ")" ::: "memory")
; #define PG8_BAR __builtin_amdgcn_s_barrier()
; template <class Epi>
; __device__ __forceinline__ void gemm_phase(LAS unsigned char* lds, const Gemm g, const StaticOrder& S, const Epi& E) {
;     ...
;             PG8_LDB(B0, 0, 0); PG8_SCHED; PG8_LDA(At, 0, 0); PG8_STAGE(PG8_SA(1, 1), a1 + hstepA, voffA);
;             PG8_WAIT_L(8); PG8_BAR; PG8_WAIT_L(0); PG8_MMA(0, 0, At, B0); PG8_BAR; PG8_SCHED;
;             PG8_LDB(B1, 0, 1); PG8_STAGE(PG8_SB(0, 0), b2, voffB);
;             PG8_BAR; PG8_WAIT_L(0); PG8_MMA(0, 1, At, B1); PG8_BAR;
;     ...
;             PG8_WAIT_V(6); PG8_BAR; PG8_MMA(1, 1, At, B1); PG8_BAR;
;             PG8_LDB(B0, 1, 0); PG8_SCHED; PG8_LDA(At, 1, 0); PG8_STAGE(PG8_SA(0, 1), a2 + hstepA, voffA);
;             PG8_WAIT_L(8); PG8_BAR; PG8_WAIT_L(0); PG8_MMA(0, 0, At, B0); PG8_BAR; PG8_SCHED;
;             PG8_LDB(B1, 1, 1); PG8_STAGE(PG8_SB(1, 0), b3, voffB);
;             PG8_BAR; PG8_WAIT_L(0); PG8_MMA(0, 1, At, B1); PG8_BAR;
;             PG8_LDA(At, 1, 1); PG8_STAGE(PG8_SA(1, 0), a3, voffA);
;             PG8_BAR; PG8_WAIT_L(0); PG8_MMA(1, 0, At, B0); PG8_BAR; PG8_SCHED;
;             PG8_STAGE(PG8_SB(1, 1), b3 + hstepB, voffB);
;             PG8_WAIT_V(6); PG8_BAR; PG8_MMA(1, 1, At, B1); PG8_BAR;
	s_waitcnt lgkmcnt(0)
	s_waitcnt lgkmcnt(0)
	v_mfma_f32_16x16x32_bf16 v[60:63], v[146:149], v[166:169], v[60:63]
	v_mfma_f32_16x16x32_bf16 v[56:59], v[158:161], v[166:169], v[56:59]
	v_mfma_f32_16x16x32_bf16 v[44:47], v[146:149], v[180:183], v[44:47]
	v_mfma_f32_16x16x32_bf16 v[40:43], v[158:161], v[180:183], v[40:43]
	v_mfma_f32_16x16x32_bf16 v[28:31], v[146:149], v[188:191], v[28:31]
	v_mfma_f32_16x16x32_bf16 v[24:27], v[158:161], v[188:191], v[24:27]
	v_mfma_f32_16x16x32_bf16 v[12:15], v[146:149], v[196:199], v[12:15]
	v_mfma_f32_16x16x32_bf16 v[8:11], v[158:161], v[196:199], v[8:11]
	v_mfma_f32_16x16x32_bf16 v[60:63], v[154:157], v[170:173], v[60:63]
	v_mfma_f32_16x16x32_bf16 v[56:59], v[162:165], v[170:173], v[56:59]
	v_mfma_f32_16x16x32_bf16 v[44:47], v[154:157], v[184:187], v[44:47]
	v_mfma_f32_16x16x32_bf16 v[40:43], v[162:165], v[184:187], v[40:43]
	v_mfma_f32_16x16x32_bf16 v[28:31], v[154:157], v[192:195], v[28:31]
	v_mfma_f32_16x16x32_bf16 v[24:27], v[162:165], v[192:195], v[24:27]
	v_mfma_f32_16x16x32_bf16 v[12:15], v[154:157], v[200:203], v[12:15]
	v_mfma_f32_16x16x32_bf16 v[8:11], v[162:165], v[200:203], v[8:11]
	s_barrier
	s_add_u32 s22, s22, 0x40080
	s_addc_u32 s23, s23, 0
	s_add_i32 s24, s24, s28
	v_lshl_add_u64 v[146:147], s[22:23], 0, v[130:131]
	s_mov_b32 m0, s24
	s_nop 0
	global_load_lds_dwordx4 v[146:147], off
	v_lshl_add_u64 v[146:147], s[22:23], 0, v[134:135]
	s_add_i32 m0, s24, 0x2000
	s_nop 0
	global_load_lds_dwordx4 v[146:147], off
	s_waitcnt vmcnt(6)
	s_barrier
	v_mfma_f32_16x16x32_bf16 v[52:55], v[204:207], v[166:169], v[52:55]
	v_mfma_f32_16x16x32_bf16 v[48:51], v[212:215], v[166:169], v[48:51]
	v_mfma_f32_16x16x32_bf16 v[36:39], v[204:207], v[180:183], v[36:39]
	v_mfma_f32_16x16x32_bf16 v[32:35], v[212:215], v[180:183], v[32:35]
	v_mfma_f32_16x16x32_bf16 v[20:23], v[204:207], v[188:191], v[20:23]
	v_mfma_f32_16x16x32_bf16 v[16:19], v[212:215], v[188:191], v[16:19]
	v_mfma_f32_16x16x32_bf16 v[4:7], v[204:207], v[196:199], v[4:7]
	v_mfma_f32_16x16x32_bf16 v[0:3], v[212:215], v[196:199], v[0:3]
	v_mfma_f32_16x16x32_bf16 v[52:55], v[208:211], v[170:173], v[52:55]
	v_mfma_f32_16x16x32_bf16 v[48:51], v[216:219], v[170:173], v[48:51]
	v_mfma_f32_16x16x32_bf16 v[36:39], v[208:211], v[184:187], v[36:39]
	v_mfma_f32_16x16x32_bf16 v[32:35], v[216:219], v[184:187], v[32:35]
	v_mfma_f32_16x16x32_bf16 v[20:23], v[208:211], v[192:195], v[20:23]
	v_mfma_f32_16x16x32_bf16 v[16:19], v[216:219], v[192:195], v[16:19]
	v_mfma_f32_16x16x32_bf16 v[4:7], v[208:211], v[200:203], v[4:7]
	v_mfma_f32_16x16x32_bf16 v[0:3], v[216:219], v[200:203], v[0:3]
	s_add_i32 s45, s45, 2
	s_add_u32 s20, s20, 0x100
	s_addc_u32 s21, s21, 0
	s_add_u32 s43, s43, 0x100
	s_addc_u32 s44, s44, 0
	s_cmp_gt_u32 s45, 13
	s_barrier
.LBB0_1204:
	ds_read_b128 v[146:149], v176
	ds_read_b128 v[154:157], v176 offset:1024
	ds_read_b128 v[158:161], v176 offset:2048
	ds_read_b128 v[162:165], v176 offset:3072
	s_add_u32 s22, s20, 0xfffc0080
	s_addc_u32 s23, s21, -1
	s_cmp_eq_u32 s45, 12
	s_cselect_b32 s25, s13, s23
	s_cselect_b32 s24, s41, s22
	s_cselect_b32 s23, s11, s44
	s_cselect_b32 s22, s42, s43
	v_lshl_add_u64 v[150:151], s[20:21], 0, v[138:139]
	s_add_i32 m0, s19, 0xc000
	ds_read_b128 v[166:169], v177
	ds_read_b128 v[170:173], v177 offset:1024
	ds_read_b128 v[180:183], v177 offset:2048
	ds_read_b128 v[184:187], v177 offset:3072
	ds_read_b128 v[188:191], v177 offset:4096
	ds_read_b128 v[192:195], v177 offset:5120
	ds_read_b128 v[196:199], v177 offset:6144
	ds_read_b128 v[200:203], v177 offset:7168
	global_load_lds_dwordx4 v[150:151], off
	v_lshl_add_u64 v[150:151], s[20:21], 0, v[140:141]
	s_add_i32 m0, s19, 0xe000
	s_nop 0
	global_load_lds_dwordx4 v[150:151], off
	s_waitcnt lgkmcnt(8)
	s_barrier
	s_waitcnt lgkmcnt(0)
	s_waitcnt lgkmcnt(0)
	v_mfma_f32_16x16x32_bf16 v[124:127], v[146:149], v[166:169], v[124:127]
	v_mfma_f32_16x16x32_bf16 v[120:123], v[158:161], v[166:169], v[120:123]
	v_mfma_f32_16x16x32_bf16 v[108:111], v[146:149], v[180:183], v[108:111]
	v_mfma_f32_16x16x32_bf16 v[104:107], v[158:161], v[180:183], v[104:107]
	v_mfma_f32_16x16x32_bf16 v[92:95], v[146:149], v[188:191], v[92:95]
	v_mfma_f32_16x16x32_bf16 v[88:91], v[158:161], v[188:191], v[88:91]
	v_mfma_f32_16x16x32_bf16 v[76:79], v[146:149], v[196:199], v[76:79]
	v_mfma_f32_16x16x32_bf16 v[72:75], v[158:161], v[196:199], v[72:75]
	v_mfma_f32_16x16x32_bf16 v[124:127], v[154:157], v[170:173], v[124:127]
	v_mfma_f32_16x16x32_bf16 v[120:123], v[162:165], v[170:173], v[120:123]
	v_mfma_f32_16x16x32_bf16 v[108:111], v[154:157], v[184:187], v[108:111]
	v_mfma_f32_16x16x32_bf16 v[104:107], v[162:165], v[184:187], v[104:107]
	v_mfma_f32_16x16x32_bf16 v[92:95], v[154:157], v[192:195], v[92:95]
	v_mfma_f32_16x16x32_bf16 v[88:91], v[162:165], v[192:195], v[88:91]
	v_mfma_f32_16x16x32_bf16 v[76:79], v[154:157], v[200:203], v[76:79]
	v_mfma_f32_16x16x32_bf16 v[72:75], v[162:165], v[200:203], v[72:75]
	s_barrier
	s_add_i32 s46, s37, s28
	v_lshl_add_u64 v[150:151], s[22:23], 0, v[130:131]
	s_mov_b32 m0, s46
	ds_read_b128 v[204:207], v178
	ds_read_b128 v[208:211], v178 offset:1024
	ds_read_b128 v[212:215], v178 offset:2048
	ds_read_b128 v[216:219], v178 offset:3072
	global_load_lds_dwordx4 v[150:151], off
	v_lshl_add_u64 v[220:221], s[22:23], 0, v[134:135]
	s_add_i32 m0, s46, 0x2000
	s_nop 0
	global_load_lds_dwordx4 v[220:221], off
	s_barrier
; #define PG8_STAGE(bufoff, gbase, voff) do { _Pragma("unroll") for (int _i = 0; _i < 2; ++_i) \
;         __builtin_amdgcn_global_load_lds((const unsigned*)((const char*)(gbase) + (voff)[_i]), (LAS unsigned*)(lds + (bufoff) + ldsw + _i * 8192), 16, 0, 0); } while (0)
; #define PG8_LDA(dst, b, h) do { _Pragma("unroll") for (int m = 0; m < 4; ++m) _Pragma("unroll") for (int k = 0; k < 2; ++k) dst[m][k] = *(const LAS bf16x8*)(lds + PG8_SA(b, h) + aoff + m * 2048 + k * 1024); } while (0)
; #define PG8_LDB(dst, b, h) do { _Pragma("unroll") for (int n = 0; n < 2; ++n) _Pragma("unroll") for (int k = 0; k < 2; ++k) dst[n][k] = *(const LAS bf16x8*)(lds + PG8_SB(b, h) + boff + n * 2048 + k * 1024); } while (0)
; #define PG8_MMA(ai, bj, At, Bt) do { __builtin_amdgcn_s_setprio(1); _Pragma("unroll") for (int m = 0; m < 4; ++m) _Pragma("unroll") for (int n = 0; n < 2; ++n) _Pragma("unroll") for (int k = 0; k < 2; ++k) \
;         acc[ai][bj][m][n] = __builtin_amdgcn_mfma_f32_16x16x32_bf16(Bt[n][k], At[m][k], acc[ai][bj][m][n], 0, 0, 0); __builtin_amdgcn_s_setprio(0); } while (0)
; #define PG8_WAIT_V(n) asm volatile("s_waitcnt vmcnt(" #n ")" ::: "memory")
; #define PG8_WAIT_L(n) asm volatile("s_waitcnt lgkmcnt(" #n ")" ::: "memory")
; #define PG8_BAR __builtin_amdgcn_s_barrier()
; #define PG8_SCHED __builtin_amdgcn_sched_barrier(0)
; template <class Epi>
; __device__ __forceinline__ void gemm_phase(LAS unsigned char* lds, const Gemm g, const StaticOrder& S, const Epi& E) {
;     ...
;             PG8_LDB(B1, 0, 1); PG8_STAGE(PG8_SB(0, 0), b2, voffB);
;             PG8_BAR; PG8_WAIT_L(0); PG8_MMA(0, 1, At, B1); PG8_BAR;
;             PG8_LDA(At, 0, 1); PG8_STAGE(PG8_SA(0, 0), a2, voffA);
;             PG8_BAR; PG8_WAIT_L(0); PG8_MMA(1, 0, At, B0); PG8_BAR; PG8_SCHED;
;             PG8_STAGE(PG8_SB(0, 1), b2 + hstepB, voffB);
;             PG8_WAIT_V(6); PG8_BAR; PG8_MMA(1, 1, At, B1); PG8_BAR;
;             PG8_LDB(B0, 1, 0); PG8_SCHED; PG8_LDA(At, 1, 0); PG8_STAGE(PG8_SA(0, 1), a2 + hstepA, voffA);
;             PG8_WAIT_L(8); PG8_BAR; PG8_WAIT_L(0); PG8_MMA(0, 0, At, B0); PG8_BAR; PG8_SCHED;
;             PG8_LDB(B1, 1, 1); PG8_STAGE(PG8_SB(1, 0), b3, voffB);
;             PG8_BAR; PG8_WAIT_L(0); PG8_MMA(0, 1, At, B1); PG8_BAR;
;             PG8_LDA(At, 1, 1); PG8_STAGE(PG8_SA(1, 0), a3, voffA);
	s_waitcnt lgkmcnt(0)
	s_waitcnt lgkmcnt(0)
	v_mfma_f32_16x16x32_bf16 v[116:119], v[204:207], v[166:169], v[116:119]
	v_mfma_f32_16x16x32_bf16 v[112:115], v[212:215], v[166:169], v[112:115]
	v_mfma_f32_16x16x32_bf16 v[100:103], v[204:207], v[180:183], v[100:103]
	v_mfma_f32_16x16x32_bf16 v[96:99], v[212:215], v[180:183], v[96:99]
	v_mfma_f32_16x16x32_bf16 v[84:87], v[204:207], v[188:191], v[84:87]
	v_mfma_f32_16x16x32_bf16 v[80:83], v[212:215], v[188:191], v[80:83]
	v_mfma_f32_16x16x32_bf16 v[68:71], v[204:207], v[196:199], v[68:71]
	v_mfma_f32_16x16x32_bf16 v[64:67], v[212:215], v[196:199], v[64:67]
	v_mfma_f32_16x16x32_bf16 v[116:119], v[208:211], v[170:173], v[116:119]
	v_mfma_f32_16x16x32_bf16 v[112:115], v[216:219], v[170:173], v[112:115]
	v_mfma_f32_16x16x32_bf16 v[100:103], v[208:211], v[184:187], v[100:103]
	v_mfma_f32_16x16x32_bf16 v[96:99], v[216:219], v[184:187], v[96:99]
	v_mfma_f32_16x16x32_bf16 v[84:87], v[208:211], v[192:195], v[84:87]
	v_mfma_f32_16x16x32_bf16 v[80:83], v[216:219], v[192:195], v[80:83]
	v_mfma_f32_16x16x32_bf16 v[68:71], v[208:211], v[200:203], v[68:71]
	v_mfma_f32_16x16x32_bf16 v[64:67], v[216:219], v[200:203], v[64:67]
	s_mov_b32 m0, s19
	v_lshl_add_u64 v[222:223], s[24:25], 0, v[128:129]
	s_barrier
	ds_read_b128 v[166:169], v177 offset:16384
	ds_read_b128 v[170:173], v177 offset:17408
	ds_read_b128 v[180:183], v177 offset:18432
	ds_read_b128 v[184:187], v177 offset:19456
	ds_read_b128 v[188:191], v177 offset:20480
	ds_read_b128 v[192:195], v177 offset:21504
	ds_read_b128 v[196:199], v177 offset:22528
	ds_read_b128 v[200:203], v177 offset:23552
	global_load_lds_dwordx4 v[222:223], off
	v_lshl_add_u64 v[224:225], s[24:25], 0, v[132:133]
	s_mov_b32 m0, s29
	s_nop 0
	global_load_lds_dwordx4 v[224:225], off
	s_barrier
	s_waitcnt lgkmcnt(0)
	s_waitcnt lgkmcnt(0)
	v_mfma_f32_16x16x32_bf16 v[60:63], v[146:149], v[166:169], v[60:63]
	v_mfma_f32_16x16x32_bf16 v[56:59], v[158:161], v[166:169], v[56:59]
	v_mfma_f32_16x16x32_bf16 v[44:47], v[146:149], v[180:183], v[44:47]
	v_mfma_f32_16x16x32_bf16 v[40:43], v[158:161], v[180:183], v[40:43]
	v_mfma_f32_16x16x32_bf16 v[28:31], v[146:149], v[188:191], v[28:31]
	v_mfma_f32_16x16x32_bf16 v[24:27], v[158:161], v[188:191], v[24:27]
	v_mfma_f32_16x16x32_bf16 v[12:15], v[146:149], v[196:199], v[12:15]
	v_mfma_f32_16x16x32_bf16 v[8:11], v[158:161], v[196:199], v[8:11]
	v_mfma_f32_16x16x32_bf16 v[60:63], v[154:157], v[170:173], v[60:63]
	v_mfma_f32_16x16x32_bf16 v[56:59], v[162:165], v[170:173], v[56:59]
	v_mfma_f32_16x16x32_bf16 v[44:47], v[154:157], v[184:187], v[44:47]
	v_mfma_f32_16x16x32_bf16 v[40:43], v[162:165], v[184:187], v[40:43]
	v_mfma_f32_16x16x32_bf16 v[28:31], v[154:157], v[192:195], v[28:31]
	v_mfma_f32_16x16x32_bf16 v[24:27], v[162:165], v[192:195], v[24:27]
	v_mfma_f32_16x16x32_bf16 v[12:15], v[154:157], v[200:203], v[12:15]
	v_mfma_f32_16x16x32_bf16 v[8:11], v[162:165], v[200:203], v[8:11]
	s_barrier
	s_add_u32 s46, s22, 0x40000
	s_addc_u32 s47, s23, 0
	s_add_i32 s48, s38, s28
	v_lshl_add_u64 v[146:147], s[46:47], 0, v[130:131]
	s_mov_b32 m0, s48
	s_nop 0
	global_load_lds_dwordx4 v[146:147], off
	v_lshl_add_u64 v[146:147], s[46:47], 0, v[134:135]
	s_add_i32 m0, s48, 0x2000
	s_nop 0
	global_load_lds_dwordx4 v[146:147], off
	s_waitcnt vmcnt(6)
	s_barrier
	v_mfma_f32_16x16x32_bf16 v[52:55], v[204:207], v[166:169], v[52:55]
	v_mfma_f32_16x16x32_bf16 v[48:51], v[212:215], v[166:169], v[48:51]
	v_mfma_f32_16x16x32_bf16 v[36:39], v[204:207], v[180:183], v[36:39]
	v_mfma_f32_16x16x32_bf16 v[32:35], v[212:215], v[180:183], v[32:35]
	v_mfma_f32_16x16x32_bf16 v[20:23], v[204:207], v[188:191], v[20:23]
	v_mfma_f32_16x16x32_bf16 v[16:19], v[212:215], v[188:191], v[16:19]
	v_mfma_f32_16x16x32_bf16 v[4:7], v[204:207], v[196:199], v[4:7]
	v_mfma_f32_16x16x32_bf16 v[0:3], v[212:215], v[196:199], v[0:3]
	v_mfma_f32_16x16x32_bf16 v[52:55], v[208:211], v[170:173], v[52:55]
	v_mfma_f32_16x16x32_bf16 v[48:51], v[216:219], v[170:173], v[48:51]
	v_mfma_f32_16x16x32_bf16 v[36:39], v[208:211], v[184:187], v[36:39]
	v_mfma_f32_16x16x32_bf16 v[32:35], v[216:219], v[184:187], v[32:35]
	v_mfma_f32_16x16x32_bf16 v[20:23], v[208:211], v[192:195], v[20:23]
	v_mfma_f32_16x16x32_bf16 v[16:19], v[216:219], v[192:195], v[16:19]
	v_mfma_f32_16x16x32_bf16 v[4:7], v[208:211], v[200:203], v[4:7]
	v_mfma_f32_16x16x32_bf16 v[0:3], v[216:219], v[200:203], v[0:3]
	s_add_i32 s46, 0, 0x18000
	v_add_u32_e32 v162, s46, v174
	s_barrier
	ds_read_b128 v[146:149], v162
	ds_read_b128 v[154:157], v162 offset:1024
	ds_read_b128 v[158:161], v162 offset:2048
	ds_read_b128 v[162:165], v162 offset:3072
	s_add_u32 s24, s24, 0x40000
	s_addc_u32 s25, s25, 0
	s_mov_b32 m0, s30
	v_lshl_add_u64 v[204:205], s[24:25], 0, v[128:129]
	ds_read_b128 v[166:169], v177 offset:32768
	ds_read_b128 v[170:173], v177 offset:33792
	ds_read_b128 v[180:183], v177 offset:34816
	ds_read_b128 v[184:187], v177 offset:35840
	ds_read_b128 v[188:191], v177 offset:36864
	ds_read_b128 v[192:195], v177 offset:37888
	ds_read_b128 v[196:199], v177 offset:38912
	ds_read_b128 v[200:203], v177 offset:39936
	global_load_lds_dwordx4 v[204:205], off
	v_lshl_add_u64 v[204:205], s[24:25], 0, v[132:133]
	s_mov_b32 m0, s31
	s_nop 0
	global_load_lds_dwordx4 v[204:205], off
	s_waitcnt lgkmcnt(8)
	s_barrier
; #define PG8_STAGE(bufoff, gbase, voff) do { _Pragma("unroll") for (int _i = 0; _i < 2; ++_i) \
;         __builtin_amdgcn_global_load_lds((const unsigned*)((const char*)(gbase) + (voff)[_i]), (LAS unsigned*)(lds + (bufoff) + ldsw + _i * 8192), 16, 0, 0); } while (0)
; #define PG8_LDA(dst, b, h) do { _Pragma("unroll") for (int m = 0; m < 4; ++m) _Pragma("unroll") for (int k = 0; k < 2; ++k) dst[m][k] = *(const LAS bf16x8*)(lds + PG8_SA(b, h) + aoff + m * 2048 + k * 1024); } while (0)
; #define PG8_LDB(dst, b, h) do { _Pragma("unroll") for (int n = 0; n < 2; ++n) _Pragma("unroll") for (int k = 0; k < 2; ++k) dst[n][k] = *(const LAS bf16x8*)(lds + PG8_SB(b, h) + boff + n * 2048 + k * 1024); } while (0)
; #define PG8_MMA(ai, bj, At, Bt) do { __builtin_amdgcn_s_setprio(1); _Pragma("unroll") for (int m = 0; m < 4; ++m) _Pragma("unroll") for (int n = 0; n < 2; ++n) _Pragma("unroll") for (int k = 0; k < 2; ++k) \
;         acc[ai][bj][m][n] = __builtin_amdgcn_mfma_f32_16x16x32_bf16(Bt[n][k], At[m][k], acc[ai][bj][m][n], 0, 0, 0); __builtin_amdgcn_s_setprio(0); } while (0)
; #define PG8_WAIT_V(n) asm volatile("s_waitcnt vmcnt(" #n ")" ::: "memory")
; #define PG8_WAIT_L(n) asm volatile("s_waitcnt lgkmcnt(" #n ")" ::: "memory")
; #define PG8_BAR __builtin_amdgcn_s_barrier()
; #define PG8_SCHED __builtin_amdgcn_sched_barrier(0)
; template <class Epi>
; __device__ __forceinline__ void gemm_phase(LAS unsigned char* lds, const Gemm g, const StaticOrder& S, const Epi& E) {
;     ...
;             PG8_WAIT_L(8); PG8_BAR; PG8_WAIT_L(0); PG8_MMA(0, 0, At, B0); PG8_BAR; PG8_SCHED;
;             PG8_LDB(B1, 1, 1); PG8_STAGE(PG8_SB(1, 0), b3, voffB);
;             PG8_BAR; PG8_WAIT_L(0); PG8_MMA(0, 1, At, B1); PG8_BAR;
;             PG8_LDA(At, 1, 1); PG8_STAGE(PG8_SA(1, 0), a3, voffA);
;             PG8_BAR; PG8_WAIT_L(0); PG8_MMA(1, 0, At, B0); PG8_BAR; PG8_SCHED;
;             PG8_STAGE(PG8_SB(1, 1), b3 + hstepB, voffB);
;             PG8_WAIT_V(6); PG8_BAR; PG8_MMA(1, 1, At, B1); PG8_BAR;
	s_waitcnt lgkmcnt(0)
	s_waitcnt lgkmcnt(0)
	v_mfma_f32_16x16x32_bf16 v[124:127], v[146:149], v[166:169], v[124:127]
	v_mfma_f32_16x16x32_bf16 v[120:123], v[158:161], v[166:169], v[120:123]
	v_mfma_f32_16x16x32_bf16 v[108:111], v[146:149], v[180:183], v[108:111]
	v_mfma_f32_16x16x32_bf16 v[104:107], v[158:161], v[180:183], v[104:107]
	v_mfma_f32_16x16x32_bf16 v[92:95], v[146:149], v[188:191], v[92:95]
	v_mfma_f32_16x16x32_bf16 v[88:91], v[158:161], v[188:191], v[88:91]
	v_mfma_f32_16x16x32_bf16 v[76:79], v[146:149], v[196:199], v[76:79]
	v_mfma_f32_16x16x32_bf16 v[72:75], v[158:161], v[196:199], v[72:75]
	v_mfma_f32_16x16x32_bf16 v[124:127], v[154:157], v[170:173], v[124:127]
	v_mfma_f32_16x16x32_bf16 v[120:123], v[162:165], v[170:173], v[120:123]
	v_mfma_f32_16x16x32_bf16 v[108:111], v[154:157], v[184:187], v[108:111]
	v_mfma_f32_16x16x32_bf16 v[104:107], v[162:165], v[184:187], v[104:107]
	v_mfma_f32_16x16x32_bf16 v[92:95], v[154:157], v[192:195], v[92:95]
	v_mfma_f32_16x16x32_bf16 v[88:91], v[162:165], v[192:195], v[88:91]
	v_mfma_f32_16x16x32_bf16 v[76:79], v[154:157], v[200:203], v[76:79]
	v_mfma_f32_16x16x32_bf16 v[72:75], v[162:165], v[200:203], v[72:75]
	s_barrier
	s_add_i32 s24, 0, 0x1c000
	s_add_i32 s25, s46, s28
	v_add_u32_e32 v216, s24, v174
	v_lshl_add_u64 v[150:151], v[150:151], 0, s[4:5]
	s_mov_b32 m0, s25
	ds_read_b128 v[204:207], v216
	ds_read_b128 v[208:211], v216 offset:1024
	ds_read_b128 v[212:215], v216 offset:2048
	ds_read_b128 v[216:219], v216 offset:3072
	global_load_lds_dwordx4 v[150:151], off
	v_lshl_add_u64 v[150:151], v[220:221], 0, s[4:5]
	s_add_i32 m0, s25, 0x2000
	s_nop 0
	global_load_lds_dwordx4 v[150:151], off
	s_barrier
	s_waitcnt lgkmcnt(0)
	s_waitcnt lgkmcnt(0)
	v_mfma_f32_16x16x32_bf16 v[116:119], v[204:207], v[166:169], v[116:119]
	v_mfma_f32_16x16x32_bf16 v[112:115], v[212:215], v[166:169], v[112:115]
	v_mfma_f32_16x16x32_bf16 v[100:103], v[204:207], v[180:183], v[100:103]
	v_mfma_f32_16x16x32_bf16 v[96:99], v[212:215], v[180:183], v[96:99]
	v_mfma_f32_16x16x32_bf16 v[84:87], v[204:207], v[188:191], v[84:87]
	v_mfma_f32_16x16x32_bf16 v[80:83], v[212:215], v[188:191], v[80:83]
	v_mfma_f32_16x16x32_bf16 v[68:71], v[204:207], v[196:199], v[68:71]
	v_mfma_f32_16x16x32_bf16 v[64:67], v[212:215], v[196:199], v[64:67]
	v_mfma_f32_16x16x32_bf16 v[116:119], v[208:211], v[170:173], v[116:119]
	v_mfma_f32_16x16x32_bf16 v[112:115], v[216:219], v[170:173], v[112:115]
	v_mfma_f32_16x16x32_bf16 v[100:103], v[208:211], v[184:187], v[100:103]
	v_mfma_f32_16x16x32_bf16 v[96:99], v[216:219], v[184:187], v[96:99]
	v_mfma_f32_16x16x32_bf16 v[84:87], v[208:211], v[192:195], v[84:87]
	v_mfma_f32_16x16x32_bf16 v[80:83], v[216:219], v[192:195], v[80:83]
	v_mfma_f32_16x16x32_bf16 v[68:71], v[208:211], v[200:203], v[68:71]
	v_mfma_f32_16x16x32_bf16 v[64:67], v[216:219], v[200:203], v[64:67]
	s_mov_b32 m0, s34
	v_lshl_add_u64 v[150:151], v[222:223], 0, s[4:5]
	s_barrier
	ds_read_b128 v[166:169], v177 offset:49152
	ds_read_b128 v[170:173], v177 offset:50176
	ds_read_b128 v[180:183], v177 offset:51200
	ds_read_b128 v[184:187], v177 offset:52224
	ds_read_b128 v[188:191], v177 offset:53248
	ds_read_b128 v[192:195], v177 offset:54272
	ds_read_b128 v[196:199], v177 offset:55296
	ds_read_b128 v[200:203], v177 offset:56320
	global_load_lds_dwordx4 v[150:151], off
	v_lshl_add_u64 v[150:151], v[224:225], 0, s[4:5]
	s_mov_b32 m0, s35
	s_nop 0
	global_load_lds_dwordx4 v[150:151], off
	s_barrier
	s_waitcnt lgkmcnt(0)
	s_waitcnt lgkmcnt(0)
	v_mfma_f32_16x16x32_bf16 v[60:63], v[146:149], v[166:169], v[60:63]
	v_mfma_f32_16x16x32_bf16 v[56:59], v[158:161], v[166:169], v[56:59]
	v_mfma_f32_16x16x32_bf16 v[44:47], v[146:149], v[180:183], v[44:47]
	v_mfma_f32_16x16x32_bf16 v[40:43], v[158:161], v[180:183], v[40:43]
	v_mfma_f32_16x16x32_bf16 v[28:31], v[146:149], v[188:191], v[28:31]
	v_mfma_f32_16x16x32_bf16 v[24:27], v[158:161], v[188:191], v[24:27]
	v_mfma_f32_16x16x32_bf16 v[12:15], v[146:149], v[196:199], v[12:15]
	v_mfma_f32_16x16x32_bf16 v[8:11], v[158:161], v[196:199], v[8:11]
	v_mfma_f32_16x16x32_bf16 v[60:63], v[154:157], v[170:173], v[60:63]
	v_mfma_f32_16x16x32_bf16 v[56:59], v[162:165], v[170:173], v[56:59]
	v_mfma_f32_16x16x32_bf16 v[44:47], v[154:157], v[184:187], v[44:47]
	v_mfma_f32_16x16x32_bf16 v[40:43], v[162:165], v[184:187], v[40:43]
	v_mfma_f32_16x16x32_bf16 v[28:31], v[154:157], v[192:195], v[28:31]
	v_mfma_f32_16x16x32_bf16 v[24:27], v[162:165], v[192:195], v[24:27]
	v_mfma_f32_16x16x32_bf16 v[12:15], v[154:157], v[200:203], v[12:15]
	v_mfma_f32_16x16x32_bf16 v[8:11], v[162:165], v[200:203], v[8:11]
	s_barrier
	s_add_u32 s22, s22, 0x40080
	s_addc_u32 s23, s23, 0
	s_add_i32 s24, s24, s28
	v_lshl_add_u64 v[146:147], s[22:23], 0, v[130:131]
	s_mov_b32 m0, s24
	s_nop 0
	global_load_lds_dwordx4 v[146:147], off
	v_lshl_add_u64 v[146:147], s[22:23], 0, v[134:135]
	s_add_i32 m0, s24, 0x2000
	s_nop 0
	global_load_lds_dwordx4 v[146:147], off
	s_waitcnt vmcnt(6)
	s_barrier
	v_mfma_f32_16x16x32_bf16 v[52:55], v[204:207], v[166:169], v[52:55]
	v_mfma_f32_16x16x32_bf16 v[48:51], v[212:215], v[166:169], v[48:51]
	v_mfma_f32_16x16x32_bf16 v[36:39], v[204:207], v[180:183], v[36:39]
	v_mfma_f32_16x16x32_bf16 v[32:35], v[212:215], v[180:183], v[32:35]
	v_mfma_f32_16x16x32_bf16 v[20:23], v[204:207], v[188:191], v[20:23]
	v_mfma_f32_16x16x32_bf16 v[16:19], v[212:215], v[188:191], v[16:19]
	v_mfma_f32_16x16x32_bf16 v[4:7], v[204:207], v[196:199], v[4:7]
	v_mfma_f32_16x16x32_bf16 v[0:3], v[212:215], v[196:199], v[0:3]
	v_mfma_f32_16x16x32_bf16 v[52:55], v[208:211], v[170:173], v[52:55]
	v_mfma_f32_16x16x32_bf16 v[48:51], v[216:219], v[170:173], v[48:51]
	v_mfma_f32_16x16x32_bf16 v[36:39], v[208:211], v[184:187], v[36:39]
	v_mfma_f32_16x16x32_bf16 v[32:35], v[216:219], v[184:187], v[32:35]
	v_mfma_f32_16x16x32_bf16 v[20:23], v[208:211], v[192:195], v[20:23]
	v_mfma_f32_16x16x32_bf16 v[16:19], v[216:219], v[192:195], v[16:19]
	v_mfma_f32_16x16x32_bf16 v[4:7], v[208:211], v[200:203], v[4:7]
	v_mfma_f32_16x16x32_bf16 v[0:3], v[216:219], v[200:203], v[0:3]
	s_add_i32 s45, s45, 2
	s_add_u32 s20, s20, 0x100
	s_addc_u32 s21, s21, 0
	s_add_u32 s43, s43, 0x100
	s_addc_u32 s44, s44, 0
	s_cmp_gt_u32 s45, 13
	s_barrier
; __device__ __forceinline__ unsigned pk2(float lo, float hi) { const f32x2 v = (f32x2){lo, hi}; const bf16x2_t b = __builtin_convertvector(v, bf16x2_t); return __builtin_bit_cast(unsigned, b); }
;     __device__ __forceinline__ void operator()(const f32x4 (&acc)[2][2][4][2], const Unit& u, int wr, int wc, int fr, int fq, const float (&)[8]) const {
;     ...
;         const int col0 = u.pn * BM + wc * 32 + 8 * fq;
; #pragma unroll
;         for (int ai = 0; ai < 2; ++ai)
; #pragma unroll
;             for (int m = 0; m < 4; ++m) { const int row = row0 + ai * HALF + m * 16; const float rs = rsqrtf(ep[ai * 4 + m] * (1.0f / 1024.0f) + EPS);
;                 u16* rowp = O + (size_t)row * ldc + col0;
; #pragma unroll
;                 for (int bj = 0; bj < 2; ++bj) { f32x4 v0 = acc[ai][bj][m][0] * rs, v1 = acc[ai][bj][m][1] * rs;
;                     if (ACT == 1) {
; #pragma unroll
;                         for (int j = 0; j < 4; ++j) { const float a0 = fmaxf(v0[j], 0.f), a1 = fmaxf(v1[j], 0.f); v0[j] = a0 * a0; v1[j] = a1 * a1; } }
;                     u32x4 w; w.x = pk2(v0[0], v0[1]); w.y = pk2(v0[2], v0[3]); w.z = pk2(v1[0], v1[1]); w.w = pk2(v1[2], v1[3]);
;                     *(u32x4*)(rowp + bj * HALF) = w; } }
	s_cbranch_scc0 .LBB0_1204
	s_bfe_u32 vcc_lo, s18, 0x20003
	s_lshl_b32 vcc_lo, vcc_lo, 10
	s_add_i32 vcc_lo, vcc_lo, 0x20010
	v_lshl_add_u32 v236, v153, 2, vcc_lo
	ds_read_b32 v228, v236
	ds_read_b32 v229, v236 offset:64
	ds_read_b32 v230, v236 offset:128
	ds_read_b32 v231, v236 offset:192
	ds_read_b32 v232, v236 offset:512
	ds_read_b32 v233, v236 offset:576
	ds_read_b32 v234, v236 offset:640
	ds_read_b32 v235, v236 offset:704
	s_waitcnt lgkmcnt(0)
	v_lshl_add_u32 v148, s18, 8, v153
	v_ashrrev_i32_e32 v149, 31, v148
	v_or_b32_e32 v172, 16, v148
	v_ashrrev_i32_e32 v173, 31, v172
	v_or_b32_e32 v168, 32, v148
	v_or_b32_e32 v164, 48, v148
	v_ashrrev_i32_e32 v169, 31, v168
	v_ashrrev_i32_e32 v165, 31, v164
	v_add_u32_e32 v162, 0x80, v148
	v_add_u32_e32 v156, 0x90, v148
	v_ashrrev_i32_e32 v163, 31, v162
	v_ashrrev_i32_e32 v157, 31, v156
	v_add_u32_e32 v150, 0xa0, v148
	v_ashrrev_i32_e32 v151, 31, v150
	v_add_u32_e32 v146, 0xb0, v148
	v_ashrrev_i32_e32 v147, 31, v146
	v_lshl_or_b32 v166, s40, 8, v175
	v_ashrrev_i32_e32 v167, 31, v166
	v_lshlrev_b64 v[170:171], 13, v[148:149]
	v_lshlrev_b64 v[148:149], 1, v[166:167]
	v_lshl_add_u64 v[166:167], s[96:97], 0, v[170:171]
	v_lshl_add_u64 v[210:211], v[166:167], 0, v[148:149]
	s_mov_b32 s40, s10
	s_mov_b32 s18, s12
	s_mov_b64 s[22:23], s[16:17]
	s_mov_b64 s[20:21], s[14:15]
	s_waitcnt vmcnt(8)
	s_waitcnt lgkmcnt(0)
	s_waitcnt lgkmcnt(0)
	v_mov_b32_e32 v182, v228
	v_pk_mul_f32 v[120:121], v[120:121], v[182:183] op_sel_hi:[1,0]
	v_pk_mul_f32 v[126:127], v[126:127], v[182:183] op_sel_hi:[1,0]
	v_pk_mul_f32 v[124:125], v[124:125], v[182:183] op_sel_hi:[1,0]
	v_pk_mul_f32 v[122:123], v[122:123], v[182:183] op_sel_hi:[1,0]
	v_max_f32_e32 v120, 0, v120
	v_max_f32_e32 v121, 0, v121
	v_max_f32_e32 v124, 0, v124
	v_max_f32_e32 v125, 0, v125
	v_pk_mul_f32 v[188:189], v[120:121], v[120:121]
	v_max_f32_e32 v120, 0, v126
	v_max_f32_e32 v122, 0, v122
	v_max_f32_e32 v121, 0, v127
	v_max_f32_e32 v123, 0, v123
	v_pk_mul_f32 v[124:125], v[124:125], v[124:125]
	v_pk_mul_f32 v[126:127], v[120:121], v[120:121]
	v_pk_mul_f32 v[192:193], v[122:123], v[122:123]
	v_pk_mul_f32 v[114:115], v[114:115], v[182:183] op_sel_hi:[1,0]
	v_cvt_pk_bf16_f32 v120, v124, v125
	v_cvt_pk_bf16_f32 v121, v126, v127
	v_cvt_pk_bf16_f32 v122, v188, v189
	v_cvt_pk_bf16_f32 v123, v192, v193
	v_pk_mul_f32 v[116:117], v[116:117], v[182:183] op_sel_hi:[1,0]
	v_pk_mul_f32 v[112:113], v[112:113], v[182:183] op_sel_hi:[1,0]
	v_max_f32_e32 v114, 0, v114
	v_max_f32_e32 v115, 0, v115
	global_store_dwordx4 v[210:211], v[120:123], off
	v_pk_mul_f32 v[118:119], v[118:119], v[182:183] op_sel_hi:[1,0]
	v_max_f32_e32 v116, 0, v116
	v_max_f32_e32 v112, 0, v112
	v_max_f32_e32 v117, 0, v117
	v_max_f32_e32 v113, 0, v113
	v_pk_mul_f32 v[122:123], v[114:115], v[114:115]
	v_pk_mul_f32 v[116:117], v[116:117], v[116:117]
	v_pk_mul_f32 v[120:121], v[112:113], v[112:113]
	v_max_f32_e32 v112, 0, v118
	v_max_f32_e32 v113, 0, v119
	v_pk_mul_f32 v[118:119], v[112:113], v[112:113]
	v_cvt_pk_bf16_f32 v112, v116, v117
	v_cvt_pk_bf16_f32 v113, v118, v119
	v_cvt_pk_bf16_f32 v114, v120, v121
	v_cvt_pk_bf16_f32 v115, v122, v123
	global_store_dwordx4 v[210:211], v[112:115], off offset:256
	s_nop 1
	v_mov_b32_e32 v112, v229
	v_pk_mul_f32 v[104:105], v[104:105], v[112:113] op_sel_hi:[1,0]
	v_pk_mul_f32 v[110:111], v[110:111], v[112:113] op_sel_hi:[1,0]
	v_pk_mul_f32 v[108:109], v[108:109], v[112:113] op_sel_hi:[1,0]
	v_pk_mul_f32 v[106:107], v[106:107], v[112:113] op_sel_hi:[1,0]
	v_max_f32_e32 v104, 0, v104
	v_max_f32_e32 v105, 0, v105
	v_lshlrev_b64 v[114:115], 13, v[172:173]
	v_max_f32_e32 v108, 0, v108
	v_max_f32_e32 v109, 0, v109
	v_pk_mul_f32 v[116:117], v[104:105], v[104:105]
	v_max_f32_e32 v104, 0, v110
	v_max_f32_e32 v106, 0, v106
	v_max_f32_e32 v105, 0, v111
	v_max_f32_e32 v107, 0, v107
	v_lshl_add_u64 v[114:115], s[96:97], 0, v[114:115]
	v_pk_mul_f32 v[108:109], v[108:109], v[108:109]
	v_pk_mul_f32 v[110:111], v[104:105], v[104:105]
	v_pk_mul_f32 v[118:119], v[106:107], v[106:107]
	v_pk_mul_f32 v[96:97], v[96:97], v[112:113] op_sel_hi:[1,0]
	v_lshl_add_u64 v[114:115], v[114:115], 0, v[148:149]
	v_cvt_pk_bf16_f32 v104, v108, v109
	v_cvt_pk_bf16_f32 v105, v110, v111
	v_cvt_pk_bf16_f32 v106, v116, v117
	v_cvt_pk_bf16_f32 v107, v118, v119
	v_pk_mul_f32 v[102:103], v[102:103], v[112:113] op_sel_hi:[1,0]
	v_max_f32_e32 v96, 0, v96
	v_max_f32_e32 v97, 0, v97
	global_store_dwordx4 v[114:115], v[104:107], off
	v_pk_mul_f32 v[100:101], v[100:101], v[112:113] op_sel_hi:[1,0]
	v_pk_mul_f32 v[98:99], v[98:99], v[112:113] op_sel_hi:[1,0]
	v_pk_mul_f32 v[104:105], v[96:97], v[96:97]
	v_max_f32_e32 v96, 0, v102
	v_max_f32_e32 v97, 0, v103
	v_max_f32_e32 v100, 0, v100
	v_max_f32_e32 v101, 0, v101
	v_pk_mul_f32 v[100:101], v[100:101], v[100:101]
	v_pk_mul_f32 v[108:109], v[96:97], v[96:97]
	v_cvt_pk_bf16_f32 v96, v100, v101
	s_waitcnt lgkmcnt(0)
	v_max_f32_e32 v98, 0, v98
	v_max_f32_e32 v99, 0, v99
	v_pk_mul_f32 v[110:111], v[98:99], v[98:99]
	v_cvt_pk_bf16_f32 v97, v108, v109
	v_cvt_pk_bf16_f32 v98, v104, v105
	v_cvt_pk_bf16_f32 v99, v110, v111
	global_store_dwordx4 v[114:115], v[96:99], off offset:256
	s_waitcnt lgkmcnt(0)
; __device__ __forceinline__ unsigned pk2(float lo, float hi) { const f32x2 v = (f32x2){lo, hi}; const bf16x2_t b = __builtin_convertvector(v, bf16x2_t); return __builtin_bit_cast(unsigned, b); }
;     __device__ __forceinline__ void operator()(const f32x4 (&acc)[2][2][4][2], const Unit& u, int wr, int wc, int fr, int fq, const float (&)[8]) const {
;     ...
;             for (int m = 0; m < 4; ++m) { const int row = row0 + ai * HALF + m * 16; const float rs = rsqrtf(ep[ai * 4 + m] * (1.0f / 1024.0f) + EPS);
;                 u16* rowp = O + (size_t)row * ldc + col0;
; #pragma unroll
;                 for (int bj = 0; bj < 2; ++bj) { f32x4 v0 = acc[ai][bj][m][0] * rs, v1 = acc[ai][bj][m][1] * rs;
;                     if (ACT == 1) {
; #pragma unroll
;                         for (int j = 0; j < 4; ++j) { const float a0 = fmaxf(v0[j], 0.f), a1 = fmaxf(v1[j], 0.f); v0[j] = a0 * a0; v1[j] = a1 * a1; } }
;                     u32x4 w; w.x = pk2(v0[0], v0[1]); w.y = pk2(v0[2], v0[3]); w.z = pk2(v1[0], v1[1]); w.w = pk2(v1[2], v1[3]);
;                     *(u32x4*)(rowp + bj * HALF) = w; } }
	s_nop 0
	s_nop 0
	s_nop 0
	s_nop 1
	v_lshlrev_b64 v[98:99], 13, v[168:169]
	v_lshl_add_u64 v[98:99], s[96:97], 0, v[98:99]
	v_lshl_add_u64 v[98:99], v[98:99], 0, v[148:149]
	v_mov_b32_e32 v100, v230
	v_pk_mul_f32 v[88:89], v[88:89], v[100:101] op_sel_hi:[1,0]
	v_pk_mul_f32 v[94:95], v[94:95], v[100:101] op_sel_hi:[1,0]
	v_pk_mul_f32 v[92:93], v[92:93], v[100:101] op_sel_hi:[1,0]
	v_pk_mul_f32 v[90:91], v[90:91], v[100:101] op_sel_hi:[1,0]
	v_max_f32_e32 v88, 0, v88
	v_max_f32_e32 v89, 0, v89
	v_max_f32_e32 v92, 0, v92
	v_max_f32_e32 v93, 0, v93
	v_pk_mul_f32 v[102:103], v[88:89], v[88:89]
	v_max_f32_e32 v88, 0, v94
	v_max_f32_e32 v90, 0, v90
	v_max_f32_e32 v89, 0, v95
	v_max_f32_e32 v91, 0, v91
	v_pk_mul_f32 v[92:93], v[92:93], v[92:93]
	v_pk_mul_f32 v[94:95], v[88:89], v[88:89]
	v_pk_mul_f32 v[104:105], v[90:91], v[90:91]
	v_pk_mul_f32 v[82:83], v[82:83], v[100:101] op_sel_hi:[1,0]
	v_cvt_pk_bf16_f32 v88, v92, v93
	v_cvt_pk_bf16_f32 v89, v94, v95
	v_cvt_pk_bf16_f32 v90, v102, v103
	v_cvt_pk_bf16_f32 v91, v104, v105
	v_pk_mul_f32 v[84:85], v[84:85], v[100:101] op_sel_hi:[1,0]
	v_pk_mul_f32 v[80:81], v[80:81], v[100:101] op_sel_hi:[1,0]
	v_max_f32_e32 v82, 0, v82
	v_max_f32_e32 v83, 0, v83
	global_store_dwordx4 v[98:99], v[88:91], off
	v_pk_mul_f32 v[86:87], v[86:87], v[100:101] op_sel_hi:[1,0]
	v_max_f32_e32 v84, 0, v84
	v_max_f32_e32 v80, 0, v80
	v_max_f32_e32 v85, 0, v85
	v_max_f32_e32 v81, 0, v81
	v_pk_mul_f32 v[90:91], v[82:83], v[82:83]
	v_pk_mul_f32 v[84:85], v[84:85], v[84:85]
	v_pk_mul_f32 v[88:89], v[80:81], v[80:81]
	v_max_f32_e32 v80, 0, v86
	v_max_f32_e32 v81, 0, v87
	v_pk_mul_f32 v[86:87], v[80:81], v[80:81]
	v_cvt_pk_bf16_f32 v80, v84, v85
	v_cvt_pk_bf16_f32 v81, v86, v87
	v_cvt_pk_bf16_f32 v82, v88, v89
	v_cvt_pk_bf16_f32 v83, v90, v91
	global_store_dwordx4 v[98:99], v[80:83], off offset:256
	s_nop 1
	v_mov_b32_e32 v80, v231
	v_pk_mul_f32 v[72:73], v[72:73], v[80:81] op_sel_hi:[1,0]
	v_pk_mul_f32 v[78:79], v[78:79], v[80:81] op_sel_hi:[1,0]
	v_pk_mul_f32 v[76:77], v[76:77], v[80:81] op_sel_hi:[1,0]
	v_pk_mul_f32 v[74:75], v[74:75], v[80:81] op_sel_hi:[1,0]
	v_max_f32_e32 v72, 0, v72
	v_max_f32_e32 v73, 0, v73
	v_lshlrev_b64 v[82:83], 13, v[164:165]
	v_max_f32_e32 v76, 0, v76
	v_max_f32_e32 v77, 0, v77
	v_pk_mul_f32 v[84:85], v[72:73], v[72:73]
	v_max_f32_e32 v72, 0, v78
	v_max_f32_e32 v74, 0, v74
	v_max_f32_e32 v73, 0, v79
	v_max_f32_e32 v75, 0, v75
	v_lshl_add_u64 v[82:83], s[96:97], 0, v[82:83]
	v_pk_mul_f32 v[76:77], v[76:77], v[76:77]
	v_pk_mul_f32 v[78:79], v[72:73], v[72:73]
	v_pk_mul_f32 v[86:87], v[74:75], v[74:75]
	v_pk_mul_f32 v[64:65], v[64:65], v[80:81] op_sel_hi:[1,0]
	v_lshl_add_u64 v[82:83], v[82:83], 0, v[148:149]
	v_cvt_pk_bf16_f32 v72, v76, v77
	v_cvt_pk_bf16_f32 v73, v78, v79
	v_cvt_pk_bf16_f32 v74, v84, v85
	v_cvt_pk_bf16_f32 v75, v86, v87
	v_pk_mul_f32 v[70:71], v[70:71], v[80:81] op_sel_hi:[1,0]
	v_max_f32_e32 v64, 0, v64
	v_max_f32_e32 v65, 0, v65
	global_store_dwordx4 v[82:83], v[72:75], off
	v_pk_mul_f32 v[68:69], v[68:69], v[80:81] op_sel_hi:[1,0]
	v_pk_mul_f32 v[66:67], v[66:67], v[80:81] op_sel_hi:[1,0]
	v_pk_mul_f32 v[72:73], v[64:65], v[64:65]
	v_max_f32_e32 v64, 0, v70
	v_max_f32_e32 v65, 0, v71
	v_max_f32_e32 v68, 0, v68
	v_max_f32_e32 v69, 0, v69
	v_pk_mul_f32 v[68:69], v[68:69], v[68:69]
	v_pk_mul_f32 v[76:77], v[64:65], v[64:65]
	v_cvt_pk_bf16_f32 v64, v68, v69
	s_waitcnt lgkmcnt(0)
	v_max_f32_e32 v66, 0, v66
	v_max_f32_e32 v67, 0, v67
	v_pk_mul_f32 v[78:79], v[66:67], v[66:67]
	v_cvt_pk_bf16_f32 v65, v76, v77
	v_cvt_pk_bf16_f32 v66, v72, v73
	v_cvt_pk_bf16_f32 v67, v78, v79
	global_store_dwordx4 v[82:83], v[64:67], off offset:256
	s_waitcnt lgkmcnt(0)
	s_nop 0
	s_nop 0
	s_nop 0
	s_nop 1
	v_lshlrev_b64 v[66:67], 13, v[162:163]
	v_lshl_add_u64 v[66:67], s[96:97], 0, v[66:67]
	v_lshl_add_u64 v[66:67], v[66:67], 0, v[148:149]
	v_mov_b32_e32 v68, v232
	v_pk_mul_f32 v[56:57], v[56:57], v[68:69] op_sel_hi:[1,0]
	v_pk_mul_f32 v[62:63], v[62:63], v[68:69] op_sel_hi:[1,0]
	v_pk_mul_f32 v[60:61], v[60:61], v[68:69] op_sel_hi:[1,0]
	v_pk_mul_f32 v[58:59], v[58:59], v[68:69] op_sel_hi:[1,0]
	v_max_f32_e32 v56, 0, v56
	v_max_f32_e32 v57, 0, v57
	v_max_f32_e32 v60, 0, v60
	v_max_f32_e32 v61, 0, v61
	v_pk_mul_f32 v[70:71], v[56:57], v[56:57]
	v_max_f32_e32 v56, 0, v62
	v_max_f32_e32 v58, 0, v58
	v_max_f32_e32 v57, 0, v63
	v_max_f32_e32 v59, 0, v59
	v_pk_mul_f32 v[60:61], v[60:61], v[60:61]
	v_pk_mul_f32 v[62:63], v[56:57], v[56:57]
	v_pk_mul_f32 v[72:73], v[58:59], v[58:59]
	v_pk_mul_f32 v[50:51], v[50:51], v[68:69] op_sel_hi:[1,0]
	v_cvt_pk_bf16_f32 v56, v60, v61
	v_cvt_pk_bf16_f32 v57, v62, v63
	v_cvt_pk_bf16_f32 v58, v70, v71
	v_cvt_pk_bf16_f32 v59, v72, v73
	v_pk_mul_f32 v[52:53], v[52:53], v[68:69] op_sel_hi:[1,0]
	v_pk_mul_f32 v[48:49], v[48:49], v[68:69] op_sel_hi:[1,0]
	v_max_f32_e32 v50, 0, v50
	v_max_f32_e32 v51, 0, v51
	global_store_dwordx4 v[66:67], v[56:59], off
	v_pk_mul_f32 v[54:55], v[54:55], v[68:69] op_sel_hi:[1,0]
	v_max_f32_e32 v52, 0, v52
	v_max_f32_e32 v48, 0, v48
	v_max_f32_e32 v53, 0, v53
	v_max_f32_e32 v49, 0, v49
	v_pk_mul_f32 v[58:59], v[50:51], v[50:51]
	v_pk_mul_f32 v[52:53], v[52:53], v[52:53]
	v_pk_mul_f32 v[56:57], v[48:49], v[48:49]
	v_max_f32_e32 v48, 0, v54
	v_max_f32_e32 v49, 0, v55
	v_pk_mul_f32 v[54:55], v[48:49], v[48:49]
	v_cvt_pk_bf16_f32 v48, v52, v53
	v_cvt_pk_bf16_f32 v49, v54, v55
	v_cvt_pk_bf16_f32 v50, v56, v57
	v_cvt_pk_bf16_f32 v51, v58, v59
	global_store_dwordx4 v[66:67], v[48:51], off offset:256
	s_nop 1
	v_mov_b32_e32 v48, v233
	v_pk_mul_f32 v[40:41], v[40:41], v[48:49] op_sel_hi:[1,0]
	v_pk_mul_f32 v[46:47], v[46:47], v[48:49] op_sel_hi:[1,0]
	v_pk_mul_f32 v[44:45], v[44:45], v[48:49] op_sel_hi:[1,0]
	v_pk_mul_f32 v[42:43], v[42:43], v[48:49] op_sel_hi:[1,0]
	v_max_f32_e32 v40, 0, v40
	v_max_f32_e32 v41, 0, v41
	v_lshlrev_b64 v[50:51], 13, v[156:157]
	v_max_f32_e32 v44, 0, v44
	v_max_f32_e32 v45, 0, v45
	v_pk_mul_f32 v[52:53], v[40:41], v[40:41]
	v_max_f32_e32 v40, 0, v46
	v_max_f32_e32 v42, 0, v42
	v_max_f32_e32 v41, 0, v47
	v_max_f32_e32 v43, 0, v43
	v_lshl_add_u64 v[50:51], s[96:97], 0, v[50:51]
	v_pk_mul_f32 v[44:45], v[44:45], v[44:45]
	v_pk_mul_f32 v[46:47], v[40:41], v[40:41]
	v_pk_mul_f32 v[54:55], v[42:43], v[42:43]
	v_pk_mul_f32 v[32:33], v[32:33], v[48:49] op_sel_hi:[1,0]
	v_lshl_add_u64 v[50:51], v[50:51], 0, v[148:149]
	v_cvt_pk_bf16_f32 v40, v44, v45
	v_cvt_pk_bf16_f32 v41, v46, v47
	v_cvt_pk_bf16_f32 v42, v52, v53
	v_cvt_pk_bf16_f32 v43, v54, v55
	v_pk_mul_f32 v[38:39], v[38:39], v[48:49] op_sel_hi:[1,0]
	v_max_f32_e32 v32, 0, v32
	v_max_f32_e32 v33, 0, v33
	global_store_dwordx4 v[50:51], v[40:43], off
	v_pk_mul_f32 v[36:37], v[36:37], v[48:49] op_sel_hi:[1,0]
	v_pk_mul_f32 v[34:35], v[34:35], v[48:49] op_sel_hi:[1,0]
	v_pk_mul_f32 v[40:41], v[32:33], v[32:33]
	v_max_f32_e32 v32, 0, v38
	v_max_f32_e32 v33, 0, v39
	v_max_f32_e32 v36, 0, v36
	v_max_f32_e32 v37, 0, v37
	v_pk_mul_f32 v[36:37], v[36:37], v[36:37]
	v_pk_mul_f32 v[44:45], v[32:33], v[32:33]
	v_cvt_pk_bf16_f32 v32, v36, v37
	s_waitcnt lgkmcnt(0)
; __device__ __forceinline__ unsigned pk2(float lo, float hi) { const f32x2 v = (f32x2){lo, hi}; const bf16x2_t b = __builtin_convertvector(v, bf16x2_t); return __builtin_bit_cast(unsigned, b); }
; #define PG8_WAIT_V(n) asm volatile("s_waitcnt vmcnt(" #n ")" ::: "memory")
; #define PG8_BAR __builtin_amdgcn_s_barrier()
;     __device__ __forceinline__ void operator()(const f32x4 (&acc)[2][2][4][2], const Unit& u, int wr, int wc, int fr, int fq, const float (&)[8]) const {
;     ...
;             for (int m = 0; m < 4; ++m) { const int row = row0 + ai * HALF + m * 16; const float rs = rsqrtf(ep[ai * 4 + m] * (1.0f / 1024.0f) + EPS);
;                 u16* rowp = O + (size_t)row * ldc + col0;
; #pragma unroll
;                 for (int bj = 0; bj < 2; ++bj) { f32x4 v0 = acc[ai][bj][m][0] * rs, v1 = acc[ai][bj][m][1] * rs;
;                     if (ACT == 1) {
; #pragma unroll
;                         for (int j = 0; j < 4; ++j) { const float a0 = fmaxf(v0[j], 0.f), a1 = fmaxf(v1[j], 0.f); v0[j] = a0 * a0; v1[j] = a1 * a1; } }
;                     u32x4 w; w.x = pk2(v0[0], v0[1]); w.y = pk2(v0[2], v0[3]); w.z = pk2(v1[0], v1[1]); w.w = pk2(v1[2], v1[3]);
;                     *(u32x4*)(rowp + bj * HALF) = w; } }
; template <class Epi>
; __device__ __forceinline__ void gemm_phase(LAS unsigned char* lds, const Gemm g, const StaticOrder& S, const Epi& E) {
;     ...
;     PG8_WAIT_V(0);
;     if (wr == 0) PG8_BAR;
;     PG8_BAR;
	v_max_f32_e32 v34, 0, v34
	v_max_f32_e32 v35, 0, v35
	v_pk_mul_f32 v[46:47], v[34:35], v[34:35]
	v_cvt_pk_bf16_f32 v33, v44, v45
	v_cvt_pk_bf16_f32 v34, v40, v41
	v_cvt_pk_bf16_f32 v35, v46, v47
	global_store_dwordx4 v[50:51], v[32:35], off offset:256
	s_waitcnt lgkmcnt(0)
	s_nop 0
	s_nop 0
	s_nop 0
	s_nop 1
	v_lshlrev_b64 v[34:35], 13, v[150:151]
	v_lshl_add_u64 v[34:35], s[96:97], 0, v[34:35]
	v_lshl_add_u64 v[34:35], v[34:35], 0, v[148:149]
	v_mov_b32_e32 v36, v234
	v_pk_mul_f32 v[24:25], v[24:25], v[36:37] op_sel_hi:[1,0]
	v_pk_mul_f32 v[30:31], v[30:31], v[36:37] op_sel_hi:[1,0]
	v_pk_mul_f32 v[28:29], v[28:29], v[36:37] op_sel_hi:[1,0]
	v_pk_mul_f32 v[26:27], v[26:27], v[36:37] op_sel_hi:[1,0]
	v_max_f32_e32 v24, 0, v24
	v_max_f32_e32 v25, 0, v25
	v_max_f32_e32 v28, 0, v28
	v_max_f32_e32 v29, 0, v29
	v_pk_mul_f32 v[38:39], v[24:25], v[24:25]
	v_max_f32_e32 v24, 0, v30
	v_max_f32_e32 v26, 0, v26
	v_max_f32_e32 v25, 0, v31
	v_max_f32_e32 v27, 0, v27
	v_pk_mul_f32 v[28:29], v[28:29], v[28:29]
	v_pk_mul_f32 v[30:31], v[24:25], v[24:25]
	v_pk_mul_f32 v[40:41], v[26:27], v[26:27]
	v_pk_mul_f32 v[18:19], v[18:19], v[36:37] op_sel_hi:[1,0]
	v_cvt_pk_bf16_f32 v24, v28, v29
	v_cvt_pk_bf16_f32 v25, v30, v31
	v_cvt_pk_bf16_f32 v26, v38, v39
	v_cvt_pk_bf16_f32 v27, v40, v41
	v_pk_mul_f32 v[20:21], v[20:21], v[36:37] op_sel_hi:[1,0]
	v_pk_mul_f32 v[16:17], v[16:17], v[36:37] op_sel_hi:[1,0]
	v_max_f32_e32 v18, 0, v18
	v_max_f32_e32 v19, 0, v19
	global_store_dwordx4 v[34:35], v[24:27], off
	v_pk_mul_f32 v[22:23], v[22:23], v[36:37] op_sel_hi:[1,0]
	v_max_f32_e32 v20, 0, v20
	v_max_f32_e32 v16, 0, v16
	v_max_f32_e32 v21, 0, v21
	v_max_f32_e32 v17, 0, v17
	v_pk_mul_f32 v[26:27], v[18:19], v[18:19]
	v_pk_mul_f32 v[20:21], v[20:21], v[20:21]
	v_pk_mul_f32 v[24:25], v[16:17], v[16:17]
	v_max_f32_e32 v16, 0, v22
	v_max_f32_e32 v17, 0, v23
	v_pk_mul_f32 v[22:23], v[16:17], v[16:17]
	v_cvt_pk_bf16_f32 v16, v20, v21
	v_cvt_pk_bf16_f32 v17, v22, v23
	v_cvt_pk_bf16_f32 v18, v24, v25
	v_cvt_pk_bf16_f32 v19, v26, v27
	global_store_dwordx4 v[34:35], v[16:19], off offset:256
	s_nop 1
	v_mov_b32_e32 v16, v235
	v_pk_mul_f32 v[8:9], v[8:9], v[16:17] op_sel_hi:[1,0]
	v_pk_mul_f32 v[14:15], v[14:15], v[16:17] op_sel_hi:[1,0]
	v_pk_mul_f32 v[12:13], v[12:13], v[16:17] op_sel_hi:[1,0]
	v_pk_mul_f32 v[10:11], v[10:11], v[16:17] op_sel_hi:[1,0]
	v_max_f32_e32 v8, 0, v8
	v_max_f32_e32 v9, 0, v9
	v_lshlrev_b64 v[18:19], 13, v[146:147]
	v_max_f32_e32 v12, 0, v12
	v_max_f32_e32 v13, 0, v13
	v_pk_mul_f32 v[20:21], v[8:9], v[8:9]
	v_max_f32_e32 v8, 0, v14
	v_max_f32_e32 v10, 0, v10
	v_max_f32_e32 v9, 0, v15
	v_max_f32_e32 v11, 0, v11
	v_lshl_add_u64 v[18:19], s[96:97], 0, v[18:19]
	v_pk_mul_f32 v[12:13], v[12:13], v[12:13]
	v_pk_mul_f32 v[14:15], v[8:9], v[8:9]
	v_pk_mul_f32 v[22:23], v[10:11], v[10:11]
	v_pk_mul_f32 v[0:1], v[0:1], v[16:17] op_sel_hi:[1,0]
	v_lshl_add_u64 v[18:19], v[18:19], 0, v[148:149]
	v_cvt_pk_bf16_f32 v8, v12, v13
	v_cvt_pk_bf16_f32 v9, v14, v15
	v_cvt_pk_bf16_f32 v10, v20, v21
	v_cvt_pk_bf16_f32 v11, v22, v23
	v_pk_mul_f32 v[6:7], v[6:7], v[16:17] op_sel_hi:[1,0]
	v_pk_mul_f32 v[4:5], v[4:5], v[16:17] op_sel_hi:[1,0]
	v_pk_mul_f32 v[2:3], v[2:3], v[16:17] op_sel_hi:[1,0]
	v_max_f32_e32 v0, 0, v0
	v_max_f32_e32 v1, 0, v1
	global_store_dwordx4 v[18:19], v[8:11], off
	v_max_f32_e32 v4, 0, v4
	v_max_f32_e32 v5, 0, v5
	v_pk_mul_f32 v[8:9], v[0:1], v[0:1]
	v_max_f32_e32 v0, 0, v6
	v_max_f32_e32 v2, 0, v2
	v_max_f32_e32 v1, 0, v7
	v_max_f32_e32 v3, 0, v3
	v_pk_mul_f32 v[4:5], v[4:5], v[4:5]
	v_pk_mul_f32 v[6:7], v[0:1], v[0:1]
	v_pk_mul_f32 v[10:11], v[2:3], v[2:3]
	v_cvt_pk_bf16_f32 v0, v4, v5
	v_cvt_pk_bf16_f32 v1, v6, v7
	v_cvt_pk_bf16_f32 v2, v8, v9
	v_cvt_pk_bf16_f32 v3, v10, v11
	s_and_b64 vcc, exec, s[0:1]
	global_store_dwordx4 v[18:19], v[0:3], off offset:256
	s_cbranch_vccz .LBB0_1197
	s_waitcnt vmcnt(0)
	s_cmpk_gt_u32 s7, 0xff
	s_cbranch_scc1 .LBB0_1208
	s_barrier

; #define PG8_STAGE(bufoff, gbase, voff) do { _Pragma("unroll") for (int _i = 0; _i < 2; ++_i) \
;         __builtin_amdgcn_global_load_lds((const unsigned*)((const char*)(gbase) + (voff)[_i]), (LAS unsigned*)(lds + (bufoff) + ldsw + _i * 8192), 16, 0, 0); } while (0)
; #define PG8_LDA(dst, b, h) do { _Pragma("unroll") for (int m = 0; m < 4; ++m) _Pragma("unroll") for (int k = 0; k < 2; ++k) dst[m][k] = *(const LAS bf16x8*)(lds + PG8_SA(b, h) + aoff + m * 2048 + k * 1024); } while (0)
; #define PG8_LDB(dst, b, h) do { _Pragma("unroll") for (int n = 0; n < 2; ++n) _Pragma("unroll") for (int k = 0; k < 2; ++k) dst[n][k] = *(const LAS bf16x8*)(lds + PG8_SB(b, h) + boff + n * 2048 + k * 1024); } while (0)
; #define PG8_WAIT_V(n) asm volatile("s_waitcnt vmcnt(" #n ")" ::: "memory")
; #define PG8_WAIT_L(n) asm volatile("s_waitcnt lgkmcnt(" #n ")" ::: "memory")
; #define PG8_BAR __builtin_amdgcn_s_barrier()
; #define PG8_SCHED __builtin_amdgcn_sched_barrier(0)
; template <class Epi>
; __device__ __forceinline__ void gemm_phase(LAS unsigned char* lds, const Gemm g, const StaticOrder& S, const Epi& E) {
;     ...
;         const bool has_next = S.next(ui + 1, nxt);
;         const char* nA = has_next ? (const char*)g.A + (size_t)nxt.pm * tstepA : cA; const char* nB = has_next ? (const char*)g.Bt + (size_t)nxt.pn * tstepB : cB;
;         for (int t = 0; t < nt; t += 2) {
;             const bool last = (t == nt - 2);
;             const char* a1 = cA + (size_t)(t + 1) * kstep;
;             const char* a2 = last ? nA : cA + (size_t)(t + 2) * kstep; const char* b2 = last ? nB : cB + (size_t)(t + 2) * kstep;
;             const char* a3 = a2 + kstep; const char* b3 = b2 + kstep;
;             if (last) E.pre(cur, wr, fr, epre);
;             PG8_LDB(B0, 0, 0); PG8_SCHED; PG8_LDA(At, 0, 0); PG8_STAGE(PG8_SA(1, 1), a1 + hstepA, voffA);
;             PG8_WAIT_L(8); PG8_BAR; PG8_WAIT_L(0); PG8_MMA(0, 0, At, B0); PG8_BAR; PG8_SCHED;
;             PG8_LDB(B1, 0, 1); PG8_STAGE(PG8_SB(0, 0), b2, voffB);
;             PG8_BAR; PG8_WAIT_L(0); PG8_MMA(0, 1, At, B1); PG8_BAR;
;             PG8_LDA(At, 0, 1); PG8_STAGE(PG8_SA(0, 0), a2, voffA);
;             PG8_BAR; PG8_WAIT_L(0); PG8_MMA(1, 0, At, B0); PG8_BAR; PG8_SCHED;
;             PG8_STAGE(PG8_SB(0, 1), b2 + hstepB, voffB);
;             PG8_WAIT_V(6); PG8_BAR; PG8_MMA(1, 1, At, B1); PG8_BAR;
.LBB0_1277:
	s_ashr_i32 s17, s16, 31
	v_cmp_lt_i64_e32 vcc, s[18:19], v[166:167]
	s_lshl_b64 s[18:19], s[16:17], 21
	s_add_u32 s18, s96, s18
	s_addc_u32 s19, s97, s19
	s_and_b64 s[20:21], vcc, exec
	s_cselect_b32 s17, s19, s23
	s_cselect_b32 s44, s18, s22
	s_ashr_i32 s15, s14, 31
	s_lshl_b64 s[20:21], s[14:15], 21
	s_add_u32 s20, s29, s20
	s_addc_u32 s21, s30, s21
	s_and_b64 s[26:27], vcc, exec
	s_cselect_b32 s15, s21, s25
	s_cselect_b32 s45, s20, s24
	s_add_u32 s22, s22, 0x100080
	s_addc_u32 s23, s23, 0
	s_add_u32 s46, s24, 0x100
	s_addc_u32 s47, s25, 0
	s_mov_b32 s48, -2
	s_waitcnt lgkmcnt(0)
	ds_read_b128 v[128:131], v190
	ds_read_b128 v[132:135], v190 offset:1024
	ds_read_b128 v[136:139], v190 offset:2048
	ds_read_b128 v[140:143], v190 offset:3072
	s_add_u32 s24, s22, 0xfff00080
	s_addc_u32 s25, s23, -1
	s_cmp_eq_u32 s48, 60
	s_cselect_b32 s27, s17, s25
	s_cselect_b32 s26, s44, s24
	s_cselect_b32 s25, s15, s47
	s_cselect_b32 s24, s45, s46
	v_lshl_add_u64 v[186:187], s[22:23], 0, v[162:163]
	s_add_i32 m0, s7, 0xc000
	ds_read_b128 v[144:147], v191
	ds_read_b128 v[148:151], v191 offset:1024
	ds_read_b128 v[170:173], v191 offset:2048
	ds_read_b128 v[174:177], v191 offset:3072
	ds_read_b128 v[178:181], v191 offset:4096
	ds_read_b128 v[182:185], v191 offset:5120
	ds_read_b128 v[194:197], v191 offset:6144
	ds_read_b128 v[198:201], v191 offset:7168
	global_load_lds_dwordx4 v[186:187], off
	v_lshl_add_u64 v[186:187], s[22:23], 0, v[164:165]
	s_add_i32 m0, s7, 0xe000
	s_nop 0
	global_load_lds_dwordx4 v[186:187], off
	s_waitcnt lgkmcnt(8)
	s_barrier
	s_waitcnt lgkmcnt(0)
	s_waitcnt lgkmcnt(0)
	v_mfma_f32_16x16x32_bf16 v[124:127], v[128:131], v[144:147], 0
	v_mfma_f32_16x16x32_bf16 v[120:123], v[136:139], v[144:147], 0
	v_mfma_f32_16x16x32_bf16 v[108:111], v[128:131], v[170:173], 0
	v_mfma_f32_16x16x32_bf16 v[104:107], v[136:139], v[170:173], 0
	v_mfma_f32_16x16x32_bf16 v[92:95], v[128:131], v[178:181], 0
	v_mfma_f32_16x16x32_bf16 v[88:91], v[136:139], v[178:181], 0
	v_mfma_f32_16x16x32_bf16 v[76:79], v[128:131], v[194:197], 0
	v_mfma_f32_16x16x32_bf16 v[72:75], v[136:139], v[194:197], 0
	v_mfma_f32_16x16x32_bf16 v[124:127], v[132:135], v[148:151], v[124:127]
	v_mfma_f32_16x16x32_bf16 v[120:123], v[140:143], v[148:151], v[120:123]
	v_mfma_f32_16x16x32_bf16 v[108:111], v[132:135], v[174:177], v[108:111]
	v_mfma_f32_16x16x32_bf16 v[104:107], v[140:143], v[174:177], v[104:107]
	v_mfma_f32_16x16x32_bf16 v[92:95], v[132:135], v[182:185], v[92:95]
	v_mfma_f32_16x16x32_bf16 v[88:91], v[140:143], v[182:185], v[88:91]
	v_mfma_f32_16x16x32_bf16 v[76:79], v[132:135], v[198:201], v[76:79]
	v_mfma_f32_16x16x32_bf16 v[72:75], v[140:143], v[198:201], v[72:75]
	s_barrier
	s_add_i32 s49, s42, s31
	v_lshl_add_u64 v[186:187], s[24:25], 0, v[156:157]
	s_mov_b32 m0, s49
	ds_read_b128 v[202:205], v192
	ds_read_b128 v[206:209], v192 offset:1024
	ds_read_b128 v[210:213], v192 offset:2048
	ds_read_b128 v[214:217], v192 offset:3072
	global_load_lds_dwordx4 v[186:187], off
	v_lshl_add_u64 v[218:219], s[24:25], 0, v[160:161]
	s_add_i32 m0, s49, 0x2000
	s_nop 0
	global_load_lds_dwordx4 v[218:219], off
	s_barrier
	s_waitcnt lgkmcnt(0)
	s_waitcnt lgkmcnt(0)
	v_mfma_f32_16x16x32_bf16 v[116:119], v[202:205], v[144:147], 0
	v_mfma_f32_16x16x32_bf16 v[112:115], v[210:213], v[144:147], 0
	v_mfma_f32_16x16x32_bf16 v[100:103], v[202:205], v[170:173], 0
	v_mfma_f32_16x16x32_bf16 v[96:99], v[210:213], v[170:173], 0
	v_mfma_f32_16x16x32_bf16 v[84:87], v[202:205], v[178:181], 0
	v_mfma_f32_16x16x32_bf16 v[80:83], v[210:213], v[178:181], 0
	v_mfma_f32_16x16x32_bf16 v[68:71], v[202:205], v[194:197], 0
	v_mfma_f32_16x16x32_bf16 v[64:67], v[210:213], v[194:197], 0
	v_mfma_f32_16x16x32_bf16 v[116:119], v[206:209], v[148:151], v[116:119]
	v_mfma_f32_16x16x32_bf16 v[112:115], v[214:217], v[148:151], v[112:115]
	v_mfma_f32_16x16x32_bf16 v[100:103], v[206:209], v[174:177], v[100:103]
	v_mfma_f32_16x16x32_bf16 v[96:99], v[214:217], v[174:177], v[96:99]
	v_mfma_f32_16x16x32_bf16 v[84:87], v[206:209], v[182:185], v[84:87]
	v_mfma_f32_16x16x32_bf16 v[80:83], v[214:217], v[182:185], v[80:83]
	v_mfma_f32_16x16x32_bf16 v[68:71], v[206:209], v[198:201], v[68:71]
	v_mfma_f32_16x16x32_bf16 v[64:67], v[214:217], v[198:201], v[64:67]
	s_mov_b32 m0, s7
	v_lshl_add_u64 v[220:221], s[26:27], 0, v[154:155]
	s_barrier
	ds_read_b128 v[144:147], v191 offset:16384
	ds_read_b128 v[148:151], v191 offset:17408
	ds_read_b128 v[170:173], v191 offset:18432
	ds_read_b128 v[174:177], v191 offset:19456
	ds_read_b128 v[178:181], v191 offset:20480
	ds_read_b128 v[182:185], v191 offset:21504
	ds_read_b128 v[194:197], v191 offset:22528
	ds_read_b128 v[198:201], v191 offset:23552
	global_load_lds_dwordx4 v[220:221], off
	v_lshl_add_u64 v[222:223], s[26:27], 0, v[158:159]
	s_mov_b32 m0, s34
	s_nop 0
	global_load_lds_dwordx4 v[222:223], off
	s_barrier
	s_waitcnt lgkmcnt(0)
	s_waitcnt lgkmcnt(0)
	v_mfma_f32_16x16x32_bf16 v[60:63], v[128:131], v[144:147], 0
	v_mfma_f32_16x16x32_bf16 v[56:59], v[136:139], v[144:147], 0
	v_mfma_f32_16x16x32_bf16 v[44:47], v[128:131], v[170:173], 0
	v_mfma_f32_16x16x32_bf16 v[40:43], v[136:139], v[170:173], 0
	v_mfma_f32_16x16x32_bf16 v[28:31], v[128:131], v[178:181], 0
	v_mfma_f32_16x16x32_bf16 v[24:27], v[136:139], v[178:181], 0
	v_mfma_f32_16x16x32_bf16 v[12:15], v[128:131], v[194:197], 0
	v_mfma_f32_16x16x32_bf16 v[8:11], v[136:139], v[194:197], 0
	v_mfma_f32_16x16x32_bf16 v[60:63], v[132:135], v[148:151], v[60:63]
	v_mfma_f32_16x16x32_bf16 v[56:59], v[140:143], v[148:151], v[56:59]
	v_mfma_f32_16x16x32_bf16 v[44:47], v[132:135], v[174:177], v[44:47]
	v_mfma_f32_16x16x32_bf16 v[40:43], v[140:143], v[174:177], v[40:43]
	v_mfma_f32_16x16x32_bf16 v[28:31], v[132:135], v[182:185], v[28:31]
	v_mfma_f32_16x16x32_bf16 v[24:27], v[140:143], v[182:185], v[24:27]
	v_mfma_f32_16x16x32_bf16 v[12:15], v[132:135], v[198:201], v[12:15]
	v_mfma_f32_16x16x32_bf16 v[8:11], v[140:143], v[198:201], v[8:11]
	s_barrier
; #define PG8_STAGE(bufoff, gbase, voff) do { _Pragma("unroll") for (int _i = 0; _i < 2; ++_i) \
;         __builtin_amdgcn_global_load_lds((const unsigned*)((const char*)(gbase) + (voff)[_i]), (LAS unsigned*)(lds + (bufoff) + ldsw + _i * 8192), 16, 0, 0); } while (0)
; #define PG8_LDA(dst, b, h) do { _Pragma("unroll") for (int m = 0; m < 4; ++m) _Pragma("unroll") for (int k = 0; k < 2; ++k) dst[m][k] = *(const LAS bf16x8*)(lds + PG8_SA(b, h) + aoff + m * 2048 + k * 1024); } while (0)
; #define PG8_LDB(dst, b, h) do { _Pragma("unroll") for (int n = 0; n < 2; ++n) _Pragma("unroll") for (int k = 0; k < 2; ++k) dst[n][k] = *(const LAS bf16x8*)(lds + PG8_SB(b, h) + boff + n * 2048 + k * 1024); } while (0)
; #define PG8_MMA(ai, bj, At, Bt) do { __builtin_amdgcn_s_setprio(1); _Pragma("unroll") for (int m = 0; m < 4; ++m) _Pragma("unroll") for (int n = 0; n < 2; ++n) _Pragma("unroll") for (int k = 0; k < 2; ++k) \
;         acc[ai][bj][m][n] = __builtin_amdgcn_mfma_f32_16x16x32_bf16(Bt[n][k], At[m][k], acc[ai][bj][m][n], 0, 0, 0); __builtin_amdgcn_s_setprio(0); } while (0)
; #define PG8_WAIT_V(n) asm volatile("s_waitcnt vmcnt(" #n ")" ::: "memory")
; #define PG8_WAIT_L(n) asm volatile("s_waitcnt lgkmcnt(" #n ")" ::: "memory")
; #define PG8_BAR __builtin_amdgcn_s_barrier()
; #define PG8_SCHED __builtin_amdgcn_sched_barrier(0)
; template <class Epi>
; __device__ __forceinline__ void gemm_phase(LAS unsigned char* lds, const Gemm g, const StaticOrder& S, const Epi& E) {
;     ...
;             PG8_STAGE(PG8_SB(0, 1), b2 + hstepB, voffB);
;             PG8_WAIT_V(6); PG8_BAR; PG8_MMA(1, 1, At, B1); PG8_BAR;
;             PG8_LDB(B0, 1, 0); PG8_SCHED; PG8_LDA(At, 1, 0); PG8_STAGE(PG8_SA(0, 1), a2 + hstepA, voffA);
;             PG8_WAIT_L(8); PG8_BAR; PG8_WAIT_L(0); PG8_MMA(0, 0, At, B0); PG8_BAR; PG8_SCHED;
;             PG8_LDB(B1, 1, 1); PG8_STAGE(PG8_SB(1, 0), b3, voffB);
;             PG8_BAR; PG8_WAIT_L(0); PG8_MMA(0, 1, At, B1); PG8_BAR;
;             PG8_LDA(At, 1, 1); PG8_STAGE(PG8_SA(1, 0), a3, voffA);
;             PG8_BAR; PG8_WAIT_L(0); PG8_MMA(1, 0, At, B0); PG8_BAR; PG8_SCHED;
;             PG8_STAGE(PG8_SB(1, 1), b3 + hstepB, voffB);
;             PG8_WAIT_V(6); PG8_BAR; PG8_MMA(1, 1, At, B1); PG8_BAR;
	s_add_u32 s50, s24, 0x100000
	s_addc_u32 s51, s25, 0
	s_add_i32 s49, s43, s31
	v_lshl_add_u64 v[128:129], s[50:51], 0, v[156:157]
	s_mov_b32 m0, s49
	s_nop 0
	global_load_lds_dwordx4 v[128:129], off
	v_lshl_add_u64 v[128:129], s[50:51], 0, v[160:161]
	s_add_i32 m0, s49, 0x2000
	s_nop 0
	global_load_lds_dwordx4 v[128:129], off
	s_waitcnt vmcnt(6)
	s_barrier
	v_mfma_f32_16x16x32_bf16 v[52:55], v[202:205], v[144:147], 0
	v_mfma_f32_16x16x32_bf16 v[48:51], v[210:213], v[144:147], 0
	v_mfma_f32_16x16x32_bf16 v[36:39], v[202:205], v[170:173], 0
	v_mfma_f32_16x16x32_bf16 v[32:35], v[210:213], v[170:173], 0
	v_mfma_f32_16x16x32_bf16 v[20:23], v[202:205], v[178:181], 0
	v_mfma_f32_16x16x32_bf16 v[16:19], v[210:213], v[178:181], 0
	v_mfma_f32_16x16x32_bf16 v[4:7], v[202:205], v[194:197], 0
	v_mfma_f32_16x16x32_bf16 v[0:3], v[210:213], v[194:197], 0
	v_mfma_f32_16x16x32_bf16 v[52:55], v[206:209], v[148:151], v[52:55]
	v_mfma_f32_16x16x32_bf16 v[48:51], v[214:217], v[148:151], v[48:51]
	v_mfma_f32_16x16x32_bf16 v[36:39], v[206:209], v[174:177], v[36:39]
	v_mfma_f32_16x16x32_bf16 v[32:35], v[214:217], v[174:177], v[32:35]
	v_mfma_f32_16x16x32_bf16 v[20:23], v[206:209], v[182:185], v[20:23]
	v_mfma_f32_16x16x32_bf16 v[16:19], v[214:217], v[182:185], v[16:19]
	v_mfma_f32_16x16x32_bf16 v[4:7], v[206:209], v[198:201], v[4:7]
	v_mfma_f32_16x16x32_bf16 v[0:3], v[214:217], v[198:201], v[0:3]
	s_add_i32 s49, 0, 0x18000
	v_add_u32_e32 v140, s49, v188
	s_barrier
	ds_read_b128 v[128:131], v140
	ds_read_b128 v[132:135], v140 offset:1024
	ds_read_b128 v[136:139], v140 offset:2048
	ds_read_b128 v[140:143], v140 offset:3072
	s_add_u32 s26, s26, 0x100000
	s_addc_u32 s27, s27, 0
	s_mov_b32 m0, s35
	v_lshl_add_u64 v[202:203], s[26:27], 0, v[154:155]
	ds_read_b128 v[144:147], v191 offset:32768
	ds_read_b128 v[148:151], v191 offset:33792
	ds_read_b128 v[170:173], v191 offset:34816
	ds_read_b128 v[174:177], v191 offset:35840
	ds_read_b128 v[178:181], v191 offset:36864
	ds_read_b128 v[182:185], v191 offset:37888
	ds_read_b128 v[194:197], v191 offset:38912
	ds_read_b128 v[198:201], v191 offset:39936
	global_load_lds_dwordx4 v[202:203], off
	v_lshl_add_u64 v[202:203], s[26:27], 0, v[158:159]
	s_mov_b32 m0, s36
	s_nop 0
	global_load_lds_dwordx4 v[202:203], off
	s_waitcnt lgkmcnt(8)
	s_barrier
	s_waitcnt lgkmcnt(0)
	s_waitcnt lgkmcnt(0)
	v_mfma_f32_16x16x32_bf16 v[124:127], v[128:131], v[144:147], v[124:127]
	v_mfma_f32_16x16x32_bf16 v[120:123], v[136:139], v[144:147], v[120:123]
	v_mfma_f32_16x16x32_bf16 v[108:111], v[128:131], v[170:173], v[108:111]
	v_mfma_f32_16x16x32_bf16 v[104:107], v[136:139], v[170:173], v[104:107]
	v_mfma_f32_16x16x32_bf16 v[92:95], v[128:131], v[178:181], v[92:95]
	v_mfma_f32_16x16x32_bf16 v[88:91], v[136:139], v[178:181], v[88:91]
	v_mfma_f32_16x16x32_bf16 v[76:79], v[128:131], v[194:197], v[76:79]
	v_mfma_f32_16x16x32_bf16 v[72:75], v[136:139], v[194:197], v[72:75]
	v_mfma_f32_16x16x32_bf16 v[124:127], v[132:135], v[148:151], v[124:127]
	v_mfma_f32_16x16x32_bf16 v[120:123], v[140:143], v[148:151], v[120:123]
	v_mfma_f32_16x16x32_bf16 v[108:111], v[132:135], v[174:177], v[108:111]
	v_mfma_f32_16x16x32_bf16 v[104:107], v[140:143], v[174:177], v[104:107]
	v_mfma_f32_16x16x32_bf16 v[92:95], v[132:135], v[182:185], v[92:95]
	v_mfma_f32_16x16x32_bf16 v[88:91], v[140:143], v[182:185], v[88:91]
	v_mfma_f32_16x16x32_bf16 v[76:79], v[132:135], v[198:201], v[76:79]
	v_mfma_f32_16x16x32_bf16 v[72:75], v[140:143], v[198:201], v[72:75]
	s_barrier
	s_add_i32 s26, 0, 0x1c000
	s_add_i32 s27, s49, s31
	v_add_u32_e32 v214, s26, v188
	v_lshl_add_u64 v[186:187], v[186:187], 0, s[12:13]
	s_mov_b32 m0, s27
	ds_read_b128 v[202:205], v214
	ds_read_b128 v[206:209], v214 offset:1024
	ds_read_b128 v[210:213], v214 offset:2048
	ds_read_b128 v[214:217], v214 offset:3072
	global_load_lds_dwordx4 v[186:187], off
	v_lshl_add_u64 v[186:187], v[218:219], 0, s[12:13]
	s_add_i32 m0, s27, 0x2000
	s_nop 0
	global_load_lds_dwordx4 v[186:187], off
	s_barrier
	s_waitcnt lgkmcnt(0)
	s_waitcnt lgkmcnt(0)
	v_mfma_f32_16x16x32_bf16 v[116:119], v[202:205], v[144:147], v[116:119]
	v_mfma_f32_16x16x32_bf16 v[112:115], v[210:213], v[144:147], v[112:115]
	v_mfma_f32_16x16x32_bf16 v[100:103], v[202:205], v[170:173], v[100:103]
	v_mfma_f32_16x16x32_bf16 v[96:99], v[210:213], v[170:173], v[96:99]
	v_mfma_f32_16x16x32_bf16 v[84:87], v[202:205], v[178:181], v[84:87]
	v_mfma_f32_16x16x32_bf16 v[80:83], v[210:213], v[178:181], v[80:83]
	v_mfma_f32_16x16x32_bf16 v[68:71], v[202:205], v[194:197], v[68:71]
	v_mfma_f32_16x16x32_bf16 v[64:67], v[210:213], v[194:197], v[64:67]
	v_mfma_f32_16x16x32_bf16 v[116:119], v[206:209], v[148:151], v[116:119]
	v_mfma_f32_16x16x32_bf16 v[112:115], v[214:217], v[148:151], v[112:115]
	v_mfma_f32_16x16x32_bf16 v[100:103], v[206:209], v[174:177], v[100:103]
	v_mfma_f32_16x16x32_bf16 v[96:99], v[214:217], v[174:177], v[96:99]
	v_mfma_f32_16x16x32_bf16 v[84:87], v[206:209], v[182:185], v[84:87]
	v_mfma_f32_16x16x32_bf16 v[80:83], v[214:217], v[182:185], v[80:83]
	v_mfma_f32_16x16x32_bf16 v[68:71], v[206:209], v[198:201], v[68:71]
	v_mfma_f32_16x16x32_bf16 v[64:67], v[214:217], v[198:201], v[64:67]
	s_mov_b32 m0, s38
	v_lshl_add_u64 v[186:187], v[220:221], 0, s[12:13]
	s_barrier
	ds_read_b128 v[144:147], v191 offset:49152
	ds_read_b128 v[148:151], v191 offset:50176
	ds_read_b128 v[170:173], v191 offset:51200
	ds_read_b128 v[174:177], v191 offset:52224
	ds_read_b128 v[178:181], v191 offset:53248
	ds_read_b128 v[182:185], v191 offset:54272
	ds_read_b128 v[194:197], v191 offset:55296
	ds_read_b128 v[198:201], v191 offset:56320
	global_load_lds_dwordx4 v[186:187], off
	v_lshl_add_u64 v[186:187], v[222:223], 0, s[12:13]
	s_mov_b32 m0, s39
	s_nop 0
	global_load_lds_dwordx4 v[186:187], off
	s_barrier
; #define PG8_STAGE(bufoff, gbase, voff) do { _Pragma("unroll") for (int _i = 0; _i < 2; ++_i) \
;         __builtin_amdgcn_global_load_lds((const unsigned*)((const char*)(gbase) + (voff)[_i]), (LAS unsigned*)(lds + (bufoff) + ldsw + _i * 8192), 16, 0, 0); } while (0)
; #define PG8_LDA(dst, b, h) do { _Pragma("unroll") for (int m = 0; m < 4; ++m) _Pragma("unroll") for (int k = 0; k < 2; ++k) dst[m][k] = *(const LAS bf16x8*)(lds + PG8_SA(b, h) + aoff + m * 2048 + k * 1024); } while (0)
; #define PG8_LDB(dst, b, h) do { _Pragma("unroll") for (int n = 0; n < 2; ++n) _Pragma("unroll") for (int k = 0; k < 2; ++k) dst[n][k] = *(const LAS bf16x8*)(lds + PG8_SB(b, h) + boff + n * 2048 + k * 1024); } while (0)
; #define PG8_WAIT_V(n) asm volatile("s_waitcnt vmcnt(" #n ")" ::: "memory")
; #define PG8_WAIT_L(n) asm volatile("s_waitcnt lgkmcnt(" #n ")" ::: "memory")
; #define PG8_BAR __builtin_amdgcn_s_barrier()
; #define PG8_SCHED __builtin_amdgcn_sched_barrier(0)
; template <class Epi>
; __device__ __forceinline__ void gemm_phase(LAS unsigned char* lds, const Gemm g, const StaticOrder& S, const Epi& E) {
;     ...
;             PG8_LDB(B0, 0, 0); PG8_SCHED; PG8_LDA(At, 0, 0); PG8_STAGE(PG8_SA(1, 1), a1 + hstepA, voffA);
;             PG8_WAIT_L(8); PG8_BAR; PG8_WAIT_L(0); PG8_MMA(0, 0, At, B0); PG8_BAR; PG8_SCHED;
;             PG8_LDB(B1, 0, 1); PG8_STAGE(PG8_SB(0, 0), b2, voffB);
;             PG8_BAR; PG8_WAIT_L(0); PG8_MMA(0, 1, At, B1); PG8_BAR;
;             PG8_LDA(At, 0, 1); PG8_STAGE(PG8_SA(0, 0), a2, voffA);
;             PG8_BAR; PG8_WAIT_L(0); PG8_MMA(1, 0, At, B0); PG8_BAR; PG8_SCHED;
;             PG8_STAGE(PG8_SB(0, 1), b2 + hstepB, voffB);
;             PG8_WAIT_V(6); PG8_BAR; PG8_MMA(1, 1, At, B1); PG8_BAR;
;             PG8_LDB(B0, 1, 0); PG8_SCHED; PG8_LDA(At, 1, 0); PG8_STAGE(PG8_SA(0, 1), a2 + hstepA, voffA);
;             PG8_WAIT_L(8); PG8_BAR; PG8_WAIT_L(0); PG8_MMA(0, 0, At, B0); PG8_BAR; PG8_SCHED;
;             PG8_LDB(B1, 1, 1); PG8_STAGE(PG8_SB(1, 0), b3, voffB);
;             PG8_BAR; PG8_WAIT_L(0); PG8_MMA(0, 1, At, B1); PG8_BAR;
;             PG8_LDA(At, 1, 1); PG8_STAGE(PG8_SA(1, 0), a3, voffA);
;             PG8_BAR; PG8_WAIT_L(0); PG8_MMA(1, 0, At, B0); PG8_BAR; PG8_SCHED;
;             PG8_STAGE(PG8_SB(1, 1), b3 + hstepB, voffB);
;             PG8_WAIT_V(6); PG8_BAR; PG8_MMA(1, 1, At, B1); PG8_BAR;
	s_waitcnt lgkmcnt(0)
	s_waitcnt lgkmcnt(0)
	v_mfma_f32_16x16x32_bf16 v[60:63], v[128:131], v[144:147], v[60:63]
	v_mfma_f32_16x16x32_bf16 v[56:59], v[136:139], v[144:147], v[56:59]
	v_mfma_f32_16x16x32_bf16 v[44:47], v[128:131], v[170:173], v[44:47]
	v_mfma_f32_16x16x32_bf16 v[40:43], v[136:139], v[170:173], v[40:43]
	v_mfma_f32_16x16x32_bf16 v[28:31], v[128:131], v[178:181], v[28:31]
	v_mfma_f32_16x16x32_bf16 v[24:27], v[136:139], v[178:181], v[24:27]
	v_mfma_f32_16x16x32_bf16 v[12:15], v[128:131], v[194:197], v[12:15]
	v_mfma_f32_16x16x32_bf16 v[8:11], v[136:139], v[194:197], v[8:11]
	v_mfma_f32_16x16x32_bf16 v[60:63], v[132:135], v[148:151], v[60:63]
	v_mfma_f32_16x16x32_bf16 v[56:59], v[140:143], v[148:151], v[56:59]
	v_mfma_f32_16x16x32_bf16 v[44:47], v[132:135], v[174:177], v[44:47]
	v_mfma_f32_16x16x32_bf16 v[40:43], v[140:143], v[174:177], v[40:43]
	v_mfma_f32_16x16x32_bf16 v[28:31], v[132:135], v[182:185], v[28:31]
	v_mfma_f32_16x16x32_bf16 v[24:27], v[140:143], v[182:185], v[24:27]
	v_mfma_f32_16x16x32_bf16 v[12:15], v[132:135], v[198:201], v[12:15]
	v_mfma_f32_16x16x32_bf16 v[8:11], v[140:143], v[198:201], v[8:11]
	s_barrier
	s_add_u32 s24, s24, 0x100080
	s_addc_u32 s25, s25, 0
	s_add_i32 s26, s26, s31
	v_lshl_add_u64 v[128:129], s[24:25], 0, v[156:157]
	s_mov_b32 m0, s26
	s_nop 0
	global_load_lds_dwordx4 v[128:129], off
	v_lshl_add_u64 v[128:129], s[24:25], 0, v[160:161]
	s_add_i32 m0, s26, 0x2000
	s_nop 0
	global_load_lds_dwordx4 v[128:129], off
	s_waitcnt vmcnt(6)
	s_barrier
	v_mfma_f32_16x16x32_bf16 v[52:55], v[202:205], v[144:147], v[52:55]
	v_mfma_f32_16x16x32_bf16 v[48:51], v[210:213], v[144:147], v[48:51]
	v_mfma_f32_16x16x32_bf16 v[36:39], v[202:205], v[170:173], v[36:39]
	v_mfma_f32_16x16x32_bf16 v[32:35], v[210:213], v[170:173], v[32:35]
	v_mfma_f32_16x16x32_bf16 v[20:23], v[202:205], v[178:181], v[20:23]
	v_mfma_f32_16x16x32_bf16 v[16:19], v[210:213], v[178:181], v[16:19]
	v_mfma_f32_16x16x32_bf16 v[4:7], v[202:205], v[194:197], v[4:7]
	v_mfma_f32_16x16x32_bf16 v[0:3], v[210:213], v[194:197], v[0:3]
	v_mfma_f32_16x16x32_bf16 v[52:55], v[206:209], v[148:151], v[52:55]
	v_mfma_f32_16x16x32_bf16 v[48:51], v[214:217], v[148:151], v[48:51]
	v_mfma_f32_16x16x32_bf16 v[36:39], v[206:209], v[174:177], v[36:39]
	v_mfma_f32_16x16x32_bf16 v[32:35], v[214:217], v[174:177], v[32:35]
	v_mfma_f32_16x16x32_bf16 v[20:23], v[206:209], v[182:185], v[20:23]
	v_mfma_f32_16x16x32_bf16 v[16:19], v[214:217], v[182:185], v[16:19]
	v_mfma_f32_16x16x32_bf16 v[4:7], v[206:209], v[198:201], v[4:7]
	v_mfma_f32_16x16x32_bf16 v[0:3], v[214:217], v[198:201], v[0:3]
	s_add_i32 s48, s48, 2
	s_add_u32 s22, s22, 0x100
	s_addc_u32 s23, s23, 0
	s_add_u32 s46, s46, 0x100
	s_addc_u32 s47, s47, 0
	s_cmp_gt_u32 s48, 61
	s_barrier
.LBB0_1278:
	ds_read_b128 v[128:131], v190
	ds_read_b128 v[132:135], v190 offset:1024
	ds_read_b128 v[136:139], v190 offset:2048
	ds_read_b128 v[140:143], v190 offset:3072
	s_add_u32 s24, s22, 0xfff00080
	s_addc_u32 s25, s23, -1
	s_cmp_eq_u32 s48, 60
	s_cselect_b32 s27, s17, s25
	s_cselect_b32 s26, s44, s24
	s_cselect_b32 s25, s15, s47
	s_cselect_b32 s24, s45, s46
	v_lshl_add_u64 v[186:187], s[22:23], 0, v[162:163]
	s_add_i32 m0, s7, 0xc000
	ds_read_b128 v[144:147], v191
	ds_read_b128 v[148:151], v191 offset:1024
	ds_read_b128 v[170:173], v191 offset:2048
	ds_read_b128 v[174:177], v191 offset:3072
	ds_read_b128 v[178:181], v191 offset:4096
	ds_read_b128 v[182:185], v191 offset:5120
	ds_read_b128 v[194:197], v191 offset:6144
	ds_read_b128 v[198:201], v191 offset:7168
	global_load_lds_dwordx4 v[186:187], off
	v_lshl_add_u64 v[186:187], s[22:23], 0, v[164:165]
	s_add_i32 m0, s7, 0xe000
	s_nop 0
	global_load_lds_dwordx4 v[186:187], off
	s_waitcnt lgkmcnt(8)
	s_barrier
	s_waitcnt lgkmcnt(0)
	s_waitcnt lgkmcnt(0)
	v_mfma_f32_16x16x32_bf16 v[124:127], v[128:131], v[144:147], v[124:127]
	v_mfma_f32_16x16x32_bf16 v[120:123], v[136:139], v[144:147], v[120:123]
	v_mfma_f32_16x16x32_bf16 v[108:111], v[128:131], v[170:173], v[108:111]
	v_mfma_f32_16x16x32_bf16 v[104:107], v[136:139], v[170:173], v[104:107]
	v_mfma_f32_16x16x32_bf16 v[92:95], v[128:131], v[178:181], v[92:95]
	v_mfma_f32_16x16x32_bf16 v[88:91], v[136:139], v[178:181], v[88:91]
	v_mfma_f32_16x16x32_bf16 v[76:79], v[128:131], v[194:197], v[76:79]
	v_mfma_f32_16x16x32_bf16 v[72:75], v[136:139], v[194:197], v[72:75]
	v_mfma_f32_16x16x32_bf16 v[124:127], v[132:135], v[148:151], v[124:127]
	v_mfma_f32_16x16x32_bf16 v[120:123], v[140:143], v[148:151], v[120:123]
	v_mfma_f32_16x16x32_bf16 v[108:111], v[132:135], v[174:177], v[108:111]
	v_mfma_f32_16x16x32_bf16 v[104:107], v[140:143], v[174:177], v[104:107]
	v_mfma_f32_16x16x32_bf16 v[92:95], v[132:135], v[182:185], v[92:95]
	v_mfma_f32_16x16x32_bf16 v[88:91], v[140:143], v[182:185], v[88:91]
	v_mfma_f32_16x16x32_bf16 v[76:79], v[132:135], v[198:201], v[76:79]
	v_mfma_f32_16x16x32_bf16 v[72:75], v[140:143], v[198:201], v[72:75]
	s_barrier
	s_add_i32 s49, s42, s31
	v_lshl_add_u64 v[186:187], s[24:25], 0, v[156:157]
	s_mov_b32 m0, s49
	ds_read_b128 v[202:205], v192
	ds_read_b128 v[206:209], v192 offset:1024
	ds_read_b128 v[210:213], v192 offset:2048
	ds_read_b128 v[214:217], v192 offset:3072
	global_load_lds_dwordx4 v[186:187], off
	v_lshl_add_u64 v[218:219], s[24:25], 0, v[160:161]
	s_add_i32 m0, s49, 0x2000
	s_nop 0
	global_load_lds_dwordx4 v[218:219], off
	s_barrier
; #define PG8_STAGE(bufoff, gbase, voff) do { _Pragma("unroll") for (int _i = 0; _i < 2; ++_i) \
;         __builtin_amdgcn_global_load_lds((const unsigned*)((const char*)(gbase) + (voff)[_i]), (LAS unsigned*)(lds + (bufoff) + ldsw + _i * 8192), 16, 0, 0); } while (0)
; #define PG8_LDA(dst, b, h) do { _Pragma("unroll") for (int m = 0; m < 4; ++m) _Pragma("unroll") for (int k = 0; k < 2; ++k) dst[m][k] = *(const LAS bf16x8*)(lds + PG8_SA(b, h) + aoff + m * 2048 + k * 1024); } while (0)
; #define PG8_LDB(dst, b, h) do { _Pragma("unroll") for (int n = 0; n < 2; ++n) _Pragma("unroll") for (int k = 0; k < 2; ++k) dst[n][k] = *(const LAS bf16x8*)(lds + PG8_SB(b, h) + boff + n * 2048 + k * 1024); } while (0)
; #define PG8_MMA(ai, bj, At, Bt) do { __builtin_amdgcn_s_setprio(1); _Pragma("unroll") for (int m = 0; m < 4; ++m) _Pragma("unroll") for (int n = 0; n < 2; ++n) _Pragma("unroll") for (int k = 0; k < 2; ++k) \
;         acc[ai][bj][m][n] = __builtin_amdgcn_mfma_f32_16x16x32_bf16(Bt[n][k], At[m][k], acc[ai][bj][m][n], 0, 0, 0); __builtin_amdgcn_s_setprio(0); } while (0)
; #define PG8_WAIT_V(n) asm volatile("s_waitcnt vmcnt(" #n ")" ::: "memory")
; #define PG8_WAIT_L(n) asm volatile("s_waitcnt lgkmcnt(" #n ")" ::: "memory")
; #define PG8_BAR __builtin_amdgcn_s_barrier()
; #define PG8_SCHED __builtin_amdgcn_sched_barrier(0)
; template <class Epi>
; __device__ __forceinline__ void gemm_phase(LAS unsigned char* lds, const Gemm g, const StaticOrder& S, const Epi& E) {
;     ...
;             PG8_BAR; PG8_WAIT_L(0); PG8_MMA(0, 1, At, B1); PG8_BAR;
;             PG8_LDA(At, 0, 1); PG8_STAGE(PG8_SA(0, 0), a2, voffA);
;             PG8_BAR; PG8_WAIT_L(0); PG8_MMA(1, 0, At, B0); PG8_BAR; PG8_SCHED;
;             PG8_STAGE(PG8_SB(0, 1), b2 + hstepB, voffB);
;             PG8_WAIT_V(6); PG8_BAR; PG8_MMA(1, 1, At, B1); PG8_BAR;
;             PG8_LDB(B0, 1, 0); PG8_SCHED; PG8_LDA(At, 1, 0); PG8_STAGE(PG8_SA(0, 1), a2 + hstepA, voffA);
;             PG8_WAIT_L(8); PG8_BAR; PG8_WAIT_L(0); PG8_MMA(0, 0, At, B0); PG8_BAR; PG8_SCHED;
;             PG8_LDB(B1, 1, 1); PG8_STAGE(PG8_SB(1, 0), b3, voffB);
;             PG8_BAR; PG8_WAIT_L(0); PG8_MMA(0, 1, At, B1); PG8_BAR;
;             PG8_LDA(At, 1, 1); PG8_STAGE(PG8_SA(1, 0), a3, voffA);
	s_waitcnt lgkmcnt(0)
	s_waitcnt lgkmcnt(0)
	v_mfma_f32_16x16x32_bf16 v[116:119], v[202:205], v[144:147], v[116:119]
	v_mfma_f32_16x16x32_bf16 v[112:115], v[210:213], v[144:147], v[112:115]
	v_mfma_f32_16x16x32_bf16 v[100:103], v[202:205], v[170:173], v[100:103]
	v_mfma_f32_16x16x32_bf16 v[96:99], v[210:213], v[170:173], v[96:99]
	v_mfma_f32_16x16x32_bf16 v[84:87], v[202:205], v[178:181], v[84:87]
	v_mfma_f32_16x16x32_bf16 v[80:83], v[210:213], v[178:181], v[80:83]
	v_mfma_f32_16x16x32_bf16 v[68:71], v[202:205], v[194:197], v[68:71]
	v_mfma_f32_16x16x32_bf16 v[64:67], v[210:213], v[194:197], v[64:67]
	v_mfma_f32_16x16x32_bf16 v[116:119], v[206:209], v[148:151], v[116:119]
	v_mfma_f32_16x16x32_bf16 v[112:115], v[214:217], v[148:151], v[112:115]
	v_mfma_f32_16x16x32_bf16 v[100:103], v[206:209], v[174:177], v[100:103]
	v_mfma_f32_16x16x32_bf16 v[96:99], v[214:217], v[174:177], v[96:99]
	v_mfma_f32_16x16x32_bf16 v[84:87], v[206:209], v[182:185], v[84:87]
	v_mfma_f32_16x16x32_bf16 v[80:83], v[214:217], v[182:185], v[80:83]
	v_mfma_f32_16x16x32_bf16 v[68:71], v[206:209], v[198:201], v[68:71]
	v_mfma_f32_16x16x32_bf16 v[64:67], v[214:217], v[198:201], v[64:67]
	s_mov_b32 m0, s7
	v_lshl_add_u64 v[220:221], s[26:27], 0, v[154:155]
	s_barrier
	ds_read_b128 v[144:147], v191 offset:16384
	ds_read_b128 v[148:151], v191 offset:17408
	ds_read_b128 v[170:173], v191 offset:18432
	ds_read_b128 v[174:177], v191 offset:19456
	ds_read_b128 v[178:181], v191 offset:20480
	ds_read_b128 v[182:185], v191 offset:21504
	ds_read_b128 v[194:197], v191 offset:22528
	ds_read_b128 v[198:201], v191 offset:23552
	global_load_lds_dwordx4 v[220:221], off
	v_lshl_add_u64 v[222:223], s[26:27], 0, v[158:159]
	s_mov_b32 m0, s34
	s_nop 0
	global_load_lds_dwordx4 v[222:223], off
	s_barrier
	s_waitcnt lgkmcnt(0)
	s_waitcnt lgkmcnt(0)
	v_mfma_f32_16x16x32_bf16 v[60:63], v[128:131], v[144:147], v[60:63]
	v_mfma_f32_16x16x32_bf16 v[56:59], v[136:139], v[144:147], v[56:59]
	v_mfma_f32_16x16x32_bf16 v[44:47], v[128:131], v[170:173], v[44:47]
	v_mfma_f32_16x16x32_bf16 v[40:43], v[136:139], v[170:173], v[40:43]
	v_mfma_f32_16x16x32_bf16 v[28:31], v[128:131], v[178:181], v[28:31]
	v_mfma_f32_16x16x32_bf16 v[24:27], v[136:139], v[178:181], v[24:27]
	v_mfma_f32_16x16x32_bf16 v[12:15], v[128:131], v[194:197], v[12:15]
	v_mfma_f32_16x16x32_bf16 v[8:11], v[136:139], v[194:197], v[8:11]
	v_mfma_f32_16x16x32_bf16 v[60:63], v[132:135], v[148:151], v[60:63]
	v_mfma_f32_16x16x32_bf16 v[56:59], v[140:143], v[148:151], v[56:59]
	v_mfma_f32_16x16x32_bf16 v[44:47], v[132:135], v[174:177], v[44:47]
	v_mfma_f32_16x16x32_bf16 v[40:43], v[140:143], v[174:177], v[40:43]
	v_mfma_f32_16x16x32_bf16 v[28:31], v[132:135], v[182:185], v[28:31]
	v_mfma_f32_16x16x32_bf16 v[24:27], v[140:143], v[182:185], v[24:27]
	v_mfma_f32_16x16x32_bf16 v[12:15], v[132:135], v[198:201], v[12:15]
	v_mfma_f32_16x16x32_bf16 v[8:11], v[140:143], v[198:201], v[8:11]
	s_barrier
	s_add_u32 s50, s24, 0x100000
	s_addc_u32 s51, s25, 0
	s_add_i32 s49, s43, s31
	v_lshl_add_u64 v[128:129], s[50:51], 0, v[156:157]
	s_mov_b32 m0, s49
	s_nop 0
	global_load_lds_dwordx4 v[128:129], off
	v_lshl_add_u64 v[128:129], s[50:51], 0, v[160:161]
	s_add_i32 m0, s49, 0x2000
	s_nop 0
	global_load_lds_dwordx4 v[128:129], off
	s_waitcnt vmcnt(6)
	s_barrier
	v_mfma_f32_16x16x32_bf16 v[52:55], v[202:205], v[144:147], v[52:55]
	v_mfma_f32_16x16x32_bf16 v[48:51], v[210:213], v[144:147], v[48:51]
	v_mfma_f32_16x16x32_bf16 v[36:39], v[202:205], v[170:173], v[36:39]
	v_mfma_f32_16x16x32_bf16 v[32:35], v[210:213], v[170:173], v[32:35]
	v_mfma_f32_16x16x32_bf16 v[20:23], v[202:205], v[178:181], v[20:23]
	v_mfma_f32_16x16x32_bf16 v[16:19], v[210:213], v[178:181], v[16:19]
	v_mfma_f32_16x16x32_bf16 v[4:7], v[202:205], v[194:197], v[4:7]
	v_mfma_f32_16x16x32_bf16 v[0:3], v[210:213], v[194:197], v[0:3]
	v_mfma_f32_16x16x32_bf16 v[52:55], v[206:209], v[148:151], v[52:55]
	v_mfma_f32_16x16x32_bf16 v[48:51], v[214:217], v[148:151], v[48:51]
	v_mfma_f32_16x16x32_bf16 v[36:39], v[206:209], v[174:177], v[36:39]
	v_mfma_f32_16x16x32_bf16 v[32:35], v[214:217], v[174:177], v[32:35]
	v_mfma_f32_16x16x32_bf16 v[20:23], v[206:209], v[182:185], v[20:23]
	v_mfma_f32_16x16x32_bf16 v[16:19], v[214:217], v[182:185], v[16:19]
	v_mfma_f32_16x16x32_bf16 v[4:7], v[206:209], v[198:201], v[4:7]
	v_mfma_f32_16x16x32_bf16 v[0:3], v[214:217], v[198:201], v[0:3]
	s_add_i32 s49, 0, 0x18000
	v_add_u32_e32 v140, s49, v188
	s_barrier
	ds_read_b128 v[128:131], v140
	ds_read_b128 v[132:135], v140 offset:1024
	ds_read_b128 v[136:139], v140 offset:2048
	ds_read_b128 v[140:143], v140 offset:3072
	s_add_u32 s26, s26, 0x100000
	s_addc_u32 s27, s27, 0
	s_mov_b32 m0, s35
	v_lshl_add_u64 v[202:203], s[26:27], 0, v[154:155]
	ds_read_b128 v[144:147], v191 offset:32768
	ds_read_b128 v[148:151], v191 offset:33792
	ds_read_b128 v[170:173], v191 offset:34816
	ds_read_b128 v[174:177], v191 offset:35840
	ds_read_b128 v[178:181], v191 offset:36864
	ds_read_b128 v[182:185], v191 offset:37888
	ds_read_b128 v[194:197], v191 offset:38912
	ds_read_b128 v[198:201], v191 offset:39936
	global_load_lds_dwordx4 v[202:203], off
	v_lshl_add_u64 v[202:203], s[26:27], 0, v[158:159]
	s_mov_b32 m0, s36
	s_nop 0
	global_load_lds_dwordx4 v[202:203], off
	s_waitcnt lgkmcnt(8)
	s_barrier
; #define PG8_STAGE(bufoff, gbase, voff) do { _Pragma("unroll") for (int _i = 0; _i < 2; ++_i) \
;         __builtin_amdgcn_global_load_lds((const unsigned*)((const char*)(gbase) + (voff)[_i]), (LAS unsigned*)(lds + (bufoff) + ldsw + _i * 8192), 16, 0, 0); } while (0)
; #define PG8_LDA(dst, b, h) do { _Pragma("unroll") for (int m = 0; m < 4; ++m) _Pragma("unroll") for (int k = 0; k < 2; ++k) dst[m][k] = *(const LAS bf16x8*)(lds + PG8_SA(b, h) + aoff + m * 2048 + k * 1024); } while (0)
; #define PG8_LDB(dst, b, h) do { _Pragma("unroll") for (int n = 0; n < 2; ++n) _Pragma("unroll") for (int k = 0; k < 2; ++k) dst[n][k] = *(const LAS bf16x8*)(lds + PG8_SB(b, h) + boff + n * 2048 + k * 1024); } while (0)
; #define PG8_WAIT_V(n) asm volatile("s_waitcnt vmcnt(" #n ")" ::: "memory")
; #define PG8_WAIT_L(n) asm volatile("s_waitcnt lgkmcnt(" #n ")" ::: "memory")
; #define PG8_BAR __builtin_amdgcn_s_barrier()
; #define PG8_SCHED __builtin_amdgcn_sched_barrier(0)
; template <class Epi>
; __device__ __forceinline__ void gemm_phase(LAS unsigned char* lds, const Gemm g, const StaticOrder& S, const Epi& E) {
;     ...
;             PG8_LDB(B0, 0, 0); PG8_SCHED; PG8_LDA(At, 0, 0); PG8_STAGE(PG8_SA(1, 1), a1 + hstepA, voffA);
;             PG8_WAIT_L(8); PG8_BAR; PG8_WAIT_L(0); PG8_MMA(0, 0, At, B0); PG8_BAR; PG8_SCHED;
;             PG8_LDB(B1, 0, 1); PG8_STAGE(PG8_SB(0, 0), b2, voffB);
;             PG8_BAR; PG8_WAIT_L(0); PG8_MMA(0, 1, At, B1); PG8_BAR;
;             PG8_LDA(At, 0, 1); PG8_STAGE(PG8_SA(0, 0), a2, voffA);
;             PG8_BAR; PG8_WAIT_L(0); PG8_MMA(1, 0, At, B0); PG8_BAR; PG8_SCHED;
;             PG8_STAGE(PG8_SB(0, 1), b2 + hstepB, voffB);
;             PG8_WAIT_V(6); PG8_BAR; PG8_MMA(1, 1, At, B1); PG8_BAR;
;             PG8_LDB(B0, 1, 0); PG8_SCHED; PG8_LDA(At, 1, 0); PG8_STAGE(PG8_SA(0, 1), a2 + hstepA, voffA);
;             PG8_WAIT_L(8); PG8_BAR; PG8_WAIT_L(0); PG8_MMA(0, 0, At, B0); PG8_BAR; PG8_SCHED;
;             PG8_LDB(B1, 1, 1); PG8_STAGE(PG8_SB(1, 0), b3, voffB);
;             PG8_BAR; PG8_WAIT_L(0); PG8_MMA(0, 1, At, B1); PG8_BAR;
;             PG8_LDA(At, 1, 1); PG8_STAGE(PG8_SA(1, 0), a3, voffA);
;             PG8_BAR; PG8_WAIT_L(0); PG8_MMA(1, 0, At, B0); PG8_BAR; PG8_SCHED;
;             PG8_STAGE(PG8_SB(1, 1), b3 + hstepB, voffB);
;             PG8_WAIT_V(6); PG8_BAR; PG8_MMA(1, 1, At, B1); PG8_BAR;
	s_waitcnt lgkmcnt(0)
	s_waitcnt lgkmcnt(0)
	v_mfma_f32_16x16x32_bf16 v[124:127], v[128:131], v[144:147], v[124:127]
	v_mfma_f32_16x16x32_bf16 v[120:123], v[136:139], v[144:147], v[120:123]
	v_mfma_f32_16x16x32_bf16 v[108:111], v[128:131], v[170:173], v[108:111]
	v_mfma_f32_16x16x32_bf16 v[104:107], v[136:139], v[170:173], v[104:107]
	v_mfma_f32_16x16x32_bf16 v[92:95], v[128:131], v[178:181], v[92:95]
	v_mfma_f32_16x16x32_bf16 v[88:91], v[136:139], v[178:181], v[88:91]
	v_mfma_f32_16x16x32_bf16 v[76:79], v[128:131], v[194:197], v[76:79]
	v_mfma_f32_16x16x32_bf16 v[72:75], v[136:139], v[194:197], v[72:75]
	v_mfma_f32_16x16x32_bf16 v[124:127], v[132:135], v[148:151], v[124:127]
	v_mfma_f32_16x16x32_bf16 v[120:123], v[140:143], v[148:151], v[120:123]
	v_mfma_f32_16x16x32_bf16 v[108:111], v[132:135], v[174:177], v[108:111]
	v_mfma_f32_16x16x32_bf16 v[104:107], v[140:143], v[174:177], v[104:107]
	v_mfma_f32_16x16x32_bf16 v[92:95], v[132:135], v[182:185], v[92:95]
	v_mfma_f32_16x16x32_bf16 v[88:91], v[140:143], v[182:185], v[88:91]
	v_mfma_f32_16x16x32_bf16 v[76:79], v[132:135], v[198:201], v[76:79]
	v_mfma_f32_16x16x32_bf16 v[72:75], v[140:143], v[198:201], v[72:75]
	s_barrier
	s_add_i32 s26, 0, 0x1c000
	s_add_i32 s27, s49, s31
	v_add_u32_e32 v214, s26, v188
	v_lshl_add_u64 v[186:187], v[186:187], 0, s[12:13]
	s_mov_b32 m0, s27
	ds_read_b128 v[202:205], v214
	ds_read_b128 v[206:209], v214 offset:1024
	ds_read_b128 v[210:213], v214 offset:2048
	ds_read_b128 v[214:217], v214 offset:3072
	global_load_lds_dwordx4 v[186:187], off
	v_lshl_add_u64 v[186:187], v[218:219], 0, s[12:13]
	s_add_i32 m0, s27, 0x2000
	s_nop 0
	global_load_lds_dwordx4 v[186:187], off
	s_barrier
	s_waitcnt lgkmcnt(0)
	s_waitcnt lgkmcnt(0)
	v_mfma_f32_16x16x32_bf16 v[116:119], v[202:205], v[144:147], v[116:119]
	v_mfma_f32_16x16x32_bf16 v[112:115], v[210:213], v[144:147], v[112:115]
	v_mfma_f32_16x16x32_bf16 v[100:103], v[202:205], v[170:173], v[100:103]
	v_mfma_f32_16x16x32_bf16 v[96:99], v[210:213], v[170:173], v[96:99]
	v_mfma_f32_16x16x32_bf16 v[84:87], v[202:205], v[178:181], v[84:87]
	v_mfma_f32_16x16x32_bf16 v[80:83], v[210:213], v[178:181], v[80:83]
	v_mfma_f32_16x16x32_bf16 v[68:71], v[202:205], v[194:197], v[68:71]
	v_mfma_f32_16x16x32_bf16 v[64:67], v[210:213], v[194:197], v[64:67]
	v_mfma_f32_16x16x32_bf16 v[116:119], v[206:209], v[148:151], v[116:119]
	v_mfma_f32_16x16x32_bf16 v[112:115], v[214:217], v[148:151], v[112:115]
	v_mfma_f32_16x16x32_bf16 v[100:103], v[206:209], v[174:177], v[100:103]
	v_mfma_f32_16x16x32_bf16 v[96:99], v[214:217], v[174:177], v[96:99]
	v_mfma_f32_16x16x32_bf16 v[84:87], v[206:209], v[182:185], v[84:87]
	v_mfma_f32_16x16x32_bf16 v[80:83], v[214:217], v[182:185], v[80:83]
	v_mfma_f32_16x16x32_bf16 v[68:71], v[206:209], v[198:201], v[68:71]
	v_mfma_f32_16x16x32_bf16 v[64:67], v[214:217], v[198:201], v[64:67]
	s_mov_b32 m0, s38
	v_lshl_add_u64 v[186:187], v[220:221], 0, s[12:13]
	s_barrier
	ds_read_b128 v[144:147], v191 offset:49152
	ds_read_b128 v[148:151], v191 offset:50176
	ds_read_b128 v[170:173], v191 offset:51200
	ds_read_b128 v[174:177], v191 offset:52224
	ds_read_b128 v[178:181], v191 offset:53248
	ds_read_b128 v[182:185], v191 offset:54272
	ds_read_b128 v[194:197], v191 offset:55296
	ds_read_b128 v[198:201], v191 offset:56320
	global_load_lds_dwordx4 v[186:187], off
	v_lshl_add_u64 v[186:187], v[222:223], 0, s[12:13]
	s_mov_b32 m0, s39
	s_nop 0
	global_load_lds_dwordx4 v[186:187], off
	s_barrier
	s_waitcnt lgkmcnt(0)
	s_waitcnt lgkmcnt(0)
	v_mfma_f32_16x16x32_bf16 v[60:63], v[128:131], v[144:147], v[60:63]
	v_mfma_f32_16x16x32_bf16 v[56:59], v[136:139], v[144:147], v[56:59]
	v_mfma_f32_16x16x32_bf16 v[44:47], v[128:131], v[170:173], v[44:47]
	v_mfma_f32_16x16x32_bf16 v[40:43], v[136:139], v[170:173], v[40:43]
	v_mfma_f32_16x16x32_bf16 v[28:31], v[128:131], v[178:181], v[28:31]
	v_mfma_f32_16x16x32_bf16 v[24:27], v[136:139], v[178:181], v[24:27]
	v_mfma_f32_16x16x32_bf16 v[12:15], v[128:131], v[194:197], v[12:15]
	v_mfma_f32_16x16x32_bf16 v[8:11], v[136:139], v[194:197], v[8:11]
	v_mfma_f32_16x16x32_bf16 v[60:63], v[132:135], v[148:151], v[60:63]
	v_mfma_f32_16x16x32_bf16 v[56:59], v[140:143], v[148:151], v[56:59]
	v_mfma_f32_16x16x32_bf16 v[44:47], v[132:135], v[174:177], v[44:47]
	v_mfma_f32_16x16x32_bf16 v[40:43], v[140:143], v[174:177], v[40:43]
	v_mfma_f32_16x16x32_bf16 v[28:31], v[132:135], v[182:185], v[28:31]
	v_mfma_f32_16x16x32_bf16 v[24:27], v[140:143], v[182:185], v[24:27]
	v_mfma_f32_16x16x32_bf16 v[12:15], v[132:135], v[198:201], v[12:15]
	v_mfma_f32_16x16x32_bf16 v[8:11], v[140:143], v[198:201], v[8:11]
	s_barrier
	s_add_u32 s24, s24, 0x100080
	s_addc_u32 s25, s25, 0
	s_add_i32 s26, s26, s31
	v_lshl_add_u64 v[128:129], s[24:25], 0, v[156:157]
	s_mov_b32 m0, s26
	s_nop 0
	global_load_lds_dwordx4 v[128:129], off
	v_lshl_add_u64 v[128:129], s[24:25], 0, v[160:161]
	s_add_i32 m0, s26, 0x2000
	s_nop 0
	global_load_lds_dwordx4 v[128:129], off
	s_waitcnt vmcnt(6)
	s_barrier
	v_mfma_f32_16x16x32_bf16 v[52:55], v[202:205], v[144:147], v[52:55]
	v_mfma_f32_16x16x32_bf16 v[48:51], v[210:213], v[144:147], v[48:51]
	v_mfma_f32_16x16x32_bf16 v[36:39], v[202:205], v[170:173], v[36:39]
	v_mfma_f32_16x16x32_bf16 v[32:35], v[210:213], v[170:173], v[32:35]
	v_mfma_f32_16x16x32_bf16 v[20:23], v[202:205], v[178:181], v[20:23]
	v_mfma_f32_16x16x32_bf16 v[16:19], v[210:213], v[178:181], v[16:19]
	v_mfma_f32_16x16x32_bf16 v[4:7], v[202:205], v[194:197], v[4:7]
	v_mfma_f32_16x16x32_bf16 v[0:3], v[210:213], v[194:197], v[0:3]
	v_mfma_f32_16x16x32_bf16 v[52:55], v[206:209], v[148:151], v[52:55]
	v_mfma_f32_16x16x32_bf16 v[48:51], v[214:217], v[148:151], v[48:51]
	v_mfma_f32_16x16x32_bf16 v[36:39], v[206:209], v[174:177], v[36:39]
	v_mfma_f32_16x16x32_bf16 v[32:35], v[214:217], v[174:177], v[32:35]
	v_mfma_f32_16x16x32_bf16 v[20:23], v[206:209], v[182:185], v[20:23]
	v_mfma_f32_16x16x32_bf16 v[16:19], v[214:217], v[182:185], v[16:19]
	v_mfma_f32_16x16x32_bf16 v[4:7], v[206:209], v[198:201], v[4:7]
	v_mfma_f32_16x16x32_bf16 v[0:3], v[214:217], v[198:201], v[0:3]
	s_add_i32 s48, s48, 2
	s_add_u32 s22, s22, 0x100
	s_addc_u32 s23, s23, 0
	s_add_u32 s46, s46, 0x100
	s_addc_u32 s47, s47, 0
	s_cmp_gt_u32 s48, 61
	s_barrier
; __device__ __forceinline__ unsigned pk2(float lo, float hi) { const f32x2 v = (f32x2){lo, hi}; const bf16x2_t b = __builtin_convertvector(v, bf16x2_t); return __builtin_bit_cast(unsigned, b); }
; __device__ __forceinline__ void unpack8(const u32x4 v, float* f) { f[0] = bf_lo(v.x); f[1] = bf_hi(v.x); f[2] = bf_lo(v.y); f[3] = bf_hi(v.y); f[4] = bf_lo(v.z); f[5] = bf_hi(v.z); f[6] = bf_lo(v.w); f[7] = bf_hi(v.w); }
;     __device__ __forceinline__ void operator()(const f32x4 (&acc)[2][2][4][2], const Unit& u, int wr, int wc, int fr, int fq, const float (&)[8]) const {
;         const int row0 = u.pm * BM + wr * 64 + fr, col0 = u.pn * BM + wc * 32 + 8 * fq;
; #pragma unroll
;         for (int ai = 0; ai < 2; ++ai) {
;             u32x4 bv[4][2];
; #pragma unroll
;             for (int m = 0; m < 4; ++m)
; #pragma unroll
;                 for (int bj = 0; bj < 2; ++bj) bv[m][bj] = *(const u32x4*)(xb + (size_t)(row0 + ai * HALF + m * 16) * DM + col0 + bj * HALF);
; #pragma unroll
;             for (int m = 0; m < 4; ++m) { const int row = row0 + ai * HALF + m * 16; const size_t ro = (size_t)row * DM + col0; float s = 0.f;
; #pragma unroll
;                 for (int bj = 0; bj < 2; ++bj) { float b8[8]; unpack8(bv[m][bj], b8);
;                     const f32x4 v0 = (f32x4){b8[0], b8[1], b8[2], b8[3]} + acc[ai][bj][m][0], v1 = (f32x4){b8[4], b8[5], b8[6], b8[7]} + acc[ai][bj][m][1];
;                     s += v0[0] * v0[0] + v0[1] * v0[1] + v0[2] * v0[2] + v0[3] * v0[3] + v1[0] * v1[0] + v1[1] * v1[1] + v1[2] * v1[2] + v1[3] * v1[3];
;                     if (LAST) { *(f32x4*)(out + ro + bj * HALF) = v0; *(f32x4*)(out + ro + bj * HALF + 4) = v1; }
;                     else { u32x4 w; w.x = pk2(v0[0], v0[1]); w.y = pk2(v0[2], v0[3]); w.z = pk2(v1[0], v1[1]); w.w = pk2(v1[2], v1[3]); *(u32x4*)(xb + ro + bj * HALF) = w; } }
;                 s += __shfl_xor(s, 16); s += __shfl_xor(s, 32);
;                 if (fq == 0) ss[(size_t)row * 16 + u.pn * 4 + wc] = s; }
	s_cbranch_scc0 .LBB0_1278
	v_lshl_or_b32 v170, s6, 8, v189
	v_lshl_add_u32 v172, s8, 8, v153
	v_ashrrev_i32_e32 v171, 31, v170
	v_lshlrev_b64 v[204:205], 1, v[170:171]
	v_ashrrev_i32_e32 v173, 31, v172
	v_lshl_add_u64 v[174:175], s[76:77], 0, v[204:205]
	v_lshlrev_b64 v[206:207], 11, v[172:173]
	v_lshl_add_u64 v[128:129], v[174:175], 0, v[206:207]
	global_load_dwordx4 v[196:199], v[128:129], off
	global_load_dwordx4 v[200:203], v[128:129], off offset:256
	v_or_b32_e32 v184, 16, v172
	v_or_b32_e32 v180, 32, v172
	v_or_b32_e32 v176, 48, v172
	v_ashrrev_i32_e32 v185, 31, v184
	v_ashrrev_i32_e32 v181, 31, v180
	v_ashrrev_i32_e32 v177, 31, v176
	v_lshlrev_b64 v[186:187], 11, v[184:185]
	v_lshlrev_b64 v[182:183], 11, v[180:181]
	v_lshlrev_b64 v[178:179], 11, v[176:177]
	v_lshl_add_u64 v[128:129], v[174:175], 0, v[186:187]
	v_lshl_add_u64 v[130:131], v[174:175], 0, v[182:183]
	v_lshl_add_u64 v[194:195], v[174:175], 0, v[178:179]
	global_load_dwordx4 v[148:151], v[128:129], off
	global_load_dwordx4 v[144:147], v[128:129], off offset:256
	global_load_dwordx4 v[140:143], v[130:131], off
	global_load_dwordx4 v[136:139], v[130:131], off offset:256
	global_load_dwordx4 v[132:135], v[194:195], off
	s_nop 0
	global_load_dwordx4 v[128:131], v[194:195], off offset:256
	v_add_u32_e32 v226, 0x80, v172
	v_ashrrev_i32_e32 v227, 31, v226
	v_lshlrev_b64 v[226:227], 11, v[226:227]
	v_lshl_add_u64 v[226:227], v[174:175], 0, v[226:227]
	global_load_dwordx4 v[216:219], v[226:227], off
	global_load_dwordx4 v[220:223], v[226:227], off offset:256
	v_add_u32_e32 v226, 0x90, v172
	v_ashrrev_i32_e32 v227, 31, v226
	v_lshlrev_b64 v[226:227], 11, v[226:227]
	v_lshl_add_u64 v[226:227], v[174:175], 0, v[226:227]
	global_load_dwordx4 v[228:231], v[226:227], off
	global_load_dwordx4 v[232:235], v[226:227], off offset:256
	v_add_u32_e32 v226, 0xa0, v172
	v_ashrrev_i32_e32 v227, 31, v226
	v_lshlrev_b64 v[226:227], 11, v[226:227]
	v_lshl_add_u64 v[226:227], v[174:175], 0, v[226:227]
	global_load_dwordx4 v[236:239], v[226:227], off
	global_load_dwordx4 v[240:243], v[226:227], off offset:256
	v_add_u32_e32 v226, 0xb0, v172
	v_ashrrev_i32_e32 v227, 31, v226
	v_lshlrev_b64 v[226:227], 11, v[226:227]
	v_lshl_add_u64 v[226:227], v[174:175], 0, v[226:227]
	global_load_dwordx4 v[244:247], v[226:227], off
	global_load_dwordx4 v[252:255], v[226:227], off offset:256
	v_and_b32_e32 v195, 64, v193
	v_xor_b32_e32 v194, 16, v193
	v_add_u32_e32 v195, 64, v195
	v_xor_b32_e32 v208, 32, v193
	v_cmp_lt_i32_e32 vcc, v194, v195
	s_waitcnt vmcnt(15)
	v_and_b32_e32 v209, 0xffff0000, v196
	v_cndmask_b32_e32 v194, v193, v194, vcc
	v_cmp_lt_i32_e32 vcc, v208, v195
	v_lshlrev_b32_e32 v195, 2, v194
	s_waitcnt vmcnt(14)
	v_lshlrev_b32_e32 v212, 16, v200
	v_cndmask_b32_e32 v208, v193, v208, vcc
	v_lshlrev_b32_e32 v194, 2, v208
	v_lshlrev_b32_e32 v208, 16, v196
	v_and_b32_e32 v213, 0xffff0000, v200
	v_lshlrev_b32_e32 v210, 16, v198
	v_and_b32_e32 v211, 0xffff0000, v198
	v_lshlrev_b32_e32 v198, 16, v199
	v_and_b32_e32 v199, 0xffff0000, v199
	v_lshlrev_b32_e32 v200, 16, v201
	v_and_b32_e32 v201, 0xffff0000, v201
	v_lshlrev_b32_e32 v214, 16, v202
	v_and_b32_e32 v215, 0xffff0000, v202
	v_pk_add_f32 v[124:125], v[124:125], v[208:209]
	v_pk_add_f32 v[116:117], v[116:117], v[212:213]
	v_lshlrev_b32_e32 v196, 16, v197
	v_and_b32_e32 v197, 0xffff0000, v197
	v_pk_add_f32 v[122:123], v[122:123], v[198:199]
	v_pk_add_f32 v[118:119], v[118:119], v[200:201]
	v_pk_add_f32 v[198:199], v[112:113], v[214:215]
	v_mul_f32_e32 v200, v125, v125
	v_cvt_pk_bf16_f32 v112, v124, v125
	v_mul_f32_e32 v125, v117, v117
	v_pk_add_f32 v[126:127], v[126:127], v[196:197]
	v_fmac_f32_e32 v200, v124, v124
	v_fmac_f32_e32 v125, v116, v116
	v_fmac_f32_e32 v200, v126, v126
	v_fmac_f32_e32 v125, v118, v118
	v_pk_add_f32 v[120:121], v[120:121], v[210:211]
	v_fmac_f32_e32 v200, v127, v127
	v_fmac_f32_e32 v125, v119, v119
	v_lshlrev_b32_e32 v202, 16, v203
	v_and_b32_e32 v203, 0xffff0000, v203
	v_fmac_f32_e32 v200, v120, v120
	v_fmac_f32_e32 v125, v198, v198
	v_pk_add_f32 v[196:197], v[114:115], v[202:203]
	v_fmac_f32_e32 v200, v121, v121
	v_fmac_f32_e32 v125, v199, v199
	v_fmac_f32_e32 v200, v122, v122
	v_fmac_f32_e32 v125, v196, v196
	v_fmac_f32_e32 v200, v123, v123
	v_fmac_f32_e32 v125, v197, v197
	v_cvt_pk_bf16_f32 v115, v122, v123
	v_add_f32_e32 v122, v200, v125
	ds_bpermute_b32 v123, v195, v122
	v_cvt_pk_bf16_f32 v114, v120, v121
	v_lshl_add_u64 v[120:121], s[76:77], 0, v[206:207]
	v_cvt_pk_bf16_f32 v113, v126, v127
	v_lshl_add_u64 v[120:121], v[120:121], 0, v[204:205]
	global_store_dwordx4 v[120:121], v[112:115], off
	s_waitcnt lgkmcnt(0)
	s_nop 0
	v_add_f32_e32 v112, v122, v123
	ds_bpermute_b32 v113, v194, v112
	v_cvt_pk_bf16_f32 v114, v116, v117
	v_cvt_pk_bf16_f32 v115, v118, v119
	v_cvt_pk_bf16_f32 v116, v198, v199
	v_cvt_pk_bf16_f32 v117, v196, v197
	global_store_dwordx4 v[120:121], v[114:117], off offset:256
	s_and_saveexec_b64 s[22:23], s[0:1]
	s_cbranch_execz .LBB0_1281
	s_waitcnt lgkmcnt(0)
	v_add_f32_e32 v114, v112, v113
	s_lshl_b32 s24, s6, 2
	v_lshlrev_b64 v[112:113], 6, v[172:173]
	s_ashr_i32 s25, s24, 31
	v_lshl_add_u64 v[112:113], s[10:11], 0, v[112:113]
	v_lshl_add_u64 v[112:113], s[24:25], 2, v[112:113]
	s_lshl_b32 s8, s37, 2
	v_lshl_add_u64 v[112:113], v[112:113], 0, s[8:9]
	global_store_dword v[112:113], v114, off
